# out-GEMM epilogue de-serialised: all 16 x-row loads of each half issued up front with counted waits (on top of v40)
# speedup vs baseline: 1.0987x; 1.0146x over previous
.LBB0_656:
	s_lshr_b32 s6, s10, 3
	s_add_i32 s6, s6, s11
	s_lshl_b32 s8, s6, 19
	v_lshl_add_u64 v[0:1], v[10:11], 0, s[8:9]
	v_add_co_u32_e32 v4, vcc, 0x10000, v0
	s_and_b32 s20, s10, 7
	s_nop 0
	v_addc_co_u32_e32 v5, vcc, 0, v1, vcc
	v_add_co_u32_e32 v6, vcc, 0x20000, v0
	s_lshl_b32 s8, s20, 18
	s_nop 0
	v_addc_co_u32_e32 v7, vcc, 0, v1, vcc
	v_add_co_u32_e32 v18, vcc, 0x30000, v0
	v_lshl_add_u64 v[2:3], v[12:13], 0, s[8:9]
	s_nop 0
	v_addc_co_u32_e32 v19, vcc, 0, v1, vcc
	v_add_co_u32_e32 v20, vcc, 0x40000, v0
	global_load_dwordx4 v[100:103], v[0:1], off
	global_load_dwordx4 v[104:107], v[0:1], off offset:128
	v_addc_co_u32_e32 v21, vcc, 0, v1, vcc
	v_add_co_u32_e32 v22, vcc, 0x50000, v0
	global_load_dwordx4 v[108:111], v[2:3], off
	global_load_dwordx4 v[112:115], v[2:3], off offset:128
	v_addc_co_u32_e32 v23, vcc, 0, v1, vcc
	v_add_co_u32_e32 v24, vcc, 0x60000, v0
	global_load_dwordx4 v[116:119], v[4:5], off
	global_load_dwordx4 v[120:123], v[4:5], off offset:128
	v_addc_co_u32_e32 v25, vcc, 0, v1, vcc
	v_add_co_u32_e32 v26, vcc, 0x70000, v0
	global_load_dwordx4 v[124:127], v[6:7], off
	global_load_dwordx4 v[128:131], v[6:7], off offset:128
	v_addc_co_u32_e32 v27, vcc, 0, v1, vcc
	v_add_co_u32_e32 v28, vcc, s16, v2
	global_load_dwordx4 v[136:139], v[18:19], off
	global_load_dwordx4 v[140:143], v[18:19], off offset:128
	v_addc_co_u32_e32 v29, vcc, 0, v3, vcc
	s_waitcnt vmcnt(14)
	v_add_co_u32_e32 v30, vcc, s17, v2
	global_load_dwordx4 v[144:147], v[20:21], off
	global_load_dwordx4 v[148:151], v[20:21], off offset:128
	v_addc_co_u32_e32 v31, vcc, 0, v3, vcc
	v_add_co_u32_e32 v32, vcc, s18, v2
	global_load_dwordx4 v[152:155], v[22:23], off
	global_load_dwordx4 v[156:159], v[22:23], off offset:128
	global_load_dwordx4 v[160:163], v[24:25], off
	global_load_dwordx4 v[164:167], v[24:25], off offset:128
	global_load_dwordx4 v[168:171], v[26:27], off
	global_load_dwordx4 v[172:175], v[26:27], off offset:128
	global_load_dwordx4 v[176:179], v[28:29], off
	global_load_dwordx4 v[180:183], v[28:29], off offset:128
	v_addc_co_u32_e32 v33, vcc, 0, v3, vcc
	global_load_dwordx4 v[184:187], v[30:31], off
	global_load_dwordx4 v[188:191], v[30:31], off offset:128
	global_load_dwordx4 v[192:195], v[32:33], off
	global_load_dwordx4 v[196:199], v[32:33], off offset:128
	s_lshl_b32 s21, s6, 8
	s_cmp_lt_u32 s6, 32
	s_cselect_b64 s[6:7], -1, 0
	s_add_i32 s8, s21, 0xffffe000
	s_lshr_b32 s8, s8, 12
	s_add_i32 s8, s8, 1
	s_and_b64 s[22:23], s[6:7], exec
	s_cselect_b32 s8, 0, s8
	s_mul_hi_u32 s22, s8, 0x6000
	s_mulk_i32 s8, 0x6000
	s_add_u32 s23, s2, s8
	s_addc_u32 s24, s3, s22
	s_lshl_b32 s8, s20, 9
	s_add_u32 s22, s23, s8
	s_addc_u32 s23, s24, 0
	s_waitcnt vmcnt(23)
	ds_write_b128 v60, v[100:103]
	s_waitcnt vmcnt(21)
	ds_write_b128 v60, v[108:111] offset:36864
	s_waitcnt vmcnt(19)
	ds_write_b128 v60, v[116:119] offset:4608
	s_waitcnt vmcnt(17)
	ds_write_b128 v60, v[124:127] offset:9216
	s_waitcnt vmcnt(15)
	ds_write_b128 v60, v[136:139] offset:13824
	s_waitcnt vmcnt(13)
	ds_write_b128 v60, v[144:147] offset:18432
	s_waitcnt vmcnt(11)
	ds_write_b128 v60, v[152:155] offset:23040
	s_waitcnt vmcnt(9)
	ds_write_b128 v60, v[160:163] offset:27648
	s_waitcnt vmcnt(7)
	ds_write_b128 v60, v[168:171] offset:32256
	s_waitcnt vmcnt(5)
	ds_write_b128 v60, v[176:179] offset:41472
	s_waitcnt vmcnt(3)
	ds_write_b128 v60, v[184:187] offset:46080
	s_waitcnt vmcnt(1)
	ds_write_b128 v60, v[192:195] offset:50688
	s_waitcnt lgkmcnt(0)
	s_barrier
	ds_read_b128 v[100:103], v59
	ds_read_b128 v[108:111], v62 offset:36864
	ds_read_b128 v[116:119], v59 offset:4608
	ds_read_b128 v[124:127], v61
	ds_read_b128 v[136:139], v62 offset:41472
	s_waitcnt lgkmcnt(3)
	v_mfma_f32_32x32x16_bf16 a[112:127], v[100:103], v[108:111], 0
	s_waitcnt lgkmcnt(0)
	v_mfma_f32_32x32x16_bf16 a[96:111], v[100:103], v[136:139], 0
	ds_read_b128 v[100:103], v59 offset:9216
	ds_write_b128 v60, v[104:107] offset:55296
	ds_write_b128 v60, v[120:123] offset:59904
	ds_write_b128 v60, v[128:131] offset:64512
	ds_write_b128 v63, v[140:143] offset:55296
	ds_write_b128 v64, v[148:151] offset:55296
	ds_write_b128 v65, v[156:159] offset:55296
	ds_write_b128 v66, v[164:167] offset:55296
	ds_write_b128 v67, v[172:175] offset:55296
	ds_write_b128 v68, v[112:115]
	ds_write_b128 v68, v[180:183] offset:4608
	ds_write_b128 v68, v[188:191] offset:9216
	s_waitcnt vmcnt(0)
	ds_write_b128 v68, v[196:199] offset:13824
	v_mfma_f32_32x32x16_bf16 a[80:95], v[116:119], v[108:111], 0
	v_mfma_f32_32x32x16_bf16 a[64:79], v[116:119], v[136:139], 0
	s_waitcnt lgkmcnt(12)
	v_mfma_f32_32x32x16_bf16 a[48:63], v[100:103], v[108:111], 0
	v_mfma_f32_32x32x16_bf16 a[32:47], v[100:103], v[136:139], 0
	v_mfma_f32_32x32x16_bf16 a[16:31], v[124:127], v[108:111], 0
	ds_read_b128 v[100:103], v59 offset:32
	ds_read_b128 v[104:107], v62 offset:36896
	ds_read_b128 v[108:111], v62 offset:36928
	ds_read_b128 v[112:115], v59 offset:64
	ds_read_b128 v[116:119], v62 offset:41504
	ds_read_b128 v[120:123], v62 offset:36960
	v_mfma_f32_32x32x16_bf16 a[0:15], v[124:127], v[136:139], 0
	s_waitcnt lgkmcnt(4)
	v_mfma_f32_32x32x16_bf16 a[112:127], v[100:103], v[104:107], a[112:127]
	s_waitcnt lgkmcnt(1)
	v_mfma_f32_32x32x16_bf16 a[96:111], v[100:103], v[116:119], a[96:111]
	ds_read_b128 v[100:103], v59 offset:4640
	ds_read_b128 v[124:127], v59 offset:96
	s_waitcnt lgkmcnt(1)
	v_mfma_f32_32x32x16_bf16 a[80:95], v[100:103], v[104:107], a[80:95]
	v_mfma_f32_32x32x16_bf16 a[64:79], v[100:103], v[116:119], a[64:79]
	ds_read_b128 v[100:103], v59 offset:9248
	ds_read_b128 v[128:131], v59 offset:9280
	s_waitcnt lgkmcnt(1)
	v_mfma_f32_32x32x16_bf16 a[48:63], v[100:103], v[104:107], a[48:63]
	v_mfma_f32_32x32x16_bf16 a[32:47], v[100:103], v[116:119], a[32:47]
	ds_read_b128 v[100:103], v61 offset:32
	ds_read_b128 v[136:139], v59 offset:9312
	s_waitcnt lgkmcnt(1)
	v_mfma_f32_32x32x16_bf16 a[16:31], v[100:103], v[104:107], a[16:31]
	v_mfma_f32_32x32x16_bf16 a[0:15], v[100:103], v[116:119], a[0:15]
	ds_read_b128 v[100:103], v62 offset:41536
	ds_read_b128 v[104:107], v62 offset:41568
	v_mfma_f32_32x32x16_bf16 a[112:127], v[112:115], v[108:111], a[112:127]
	s_waitcnt lgkmcnt(1)
	v_mfma_f32_32x32x16_bf16 a[96:111], v[112:115], v[100:103], a[96:111]
	ds_read_b128 v[112:115], v59 offset:4672
	ds_read_b128 v[116:119], v59 offset:4704
	s_waitcnt lgkmcnt(1)
	v_mfma_f32_32x32x16_bf16 a[80:95], v[112:115], v[108:111], a[80:95]
	v_mfma_f32_32x32x16_bf16 a[64:79], v[112:115], v[100:103], a[64:79]
	v_mfma_f32_32x32x16_bf16 a[48:63], v[128:131], v[108:111], a[48:63]
	v_mfma_f32_32x32x16_bf16 a[32:47], v[128:131], v[100:103], a[32:47]
	ds_read_b128 v[112:115], v61 offset:64
	ds_read_b128 v[128:131], v61 offset:96
	s_waitcnt lgkmcnt(1)
	v_mfma_f32_32x32x16_bf16 a[16:31], v[112:115], v[108:111], a[16:31]
	v_mfma_f32_32x32x16_bf16 a[0:15], v[112:115], v[100:103], a[0:15]
	global_load_dwordx4 v[100:103], v[32:33], off offset:256
	v_mfma_f32_32x32x16_bf16 a[112:127], v[124:127], v[120:123], a[112:127]
	v_mfma_f32_32x32x16_bf16 a[96:111], v[124:127], v[104:107], a[96:111]
	v_mfma_f32_32x32x16_bf16 a[80:95], v[116:119], v[120:123], a[80:95]
	v_mfma_f32_32x32x16_bf16 a[64:79], v[116:119], v[104:107], a[64:79]
	v_mfma_f32_32x32x16_bf16 a[48:63], v[136:139], v[120:123], a[48:63]
	v_mfma_f32_32x32x16_bf16 a[32:47], v[136:139], v[104:107], a[32:47]
	global_load_dwordx4 v[108:111], v[30:31], off offset:256
	global_load_dwordx4 v[112:115], v[18:19], off offset:256
	global_load_dwordx4 v[116:119], v[6:7], off offset:256
	global_load_dwordx4 v[124:127], v[4:5], off offset:256
	global_load_dwordx4 v[136:139], v[0:1], off offset:256
	global_load_dwordx4 v[140:143], v[22:23], off offset:256
	global_load_dwordx4 v[144:147], v[20:21], off offset:256
	s_waitcnt lgkmcnt(0)
	v_mfma_f32_32x32x16_bf16 a[16:31], v[128:131], v[120:123], a[16:31]
	global_load_dwordx4 v[120:123], v[26:27], off offset:256
	global_load_dwordx4 v[148:151], v[24:25], off offset:256
	global_load_dwordx4 v[152:155], v[28:29], off offset:256
	global_load_dwordx4 v[156:159], v[2:3], off offset:256
	s_barrier
	v_mfma_f32_32x32x16_bf16 a[0:15], v[128:131], v[104:107], a[0:15]
	ds_read_b128 v[104:107], v59 offset:55296
	ds_read_b128 v[128:131], v69
	ds_read_b128 v[160:163], v59 offset:59904
	ds_read_b128 v[164:167], v61 offset:55296
	ds_read_b128 v[168:171], v69 offset:4608
	s_waitcnt lgkmcnt(3)
	v_mfma_f32_32x32x16_bf16 a[112:127], v[104:107], v[128:131], a[112:127]
	s_waitcnt lgkmcnt(0)
	v_mfma_f32_32x32x16_bf16 a[96:111], v[104:107], v[168:171], a[96:111]
	ds_read_b128 v[104:107], v59 offset:64512
	s_waitcnt vmcnt(6)
	ds_write_b128 v60, v[136:139]
	ds_write_b128 v60, v[124:127] offset:4608
	ds_write_b128 v60, v[116:119] offset:9216
	ds_write_b128 v60, v[112:115] offset:13824
	s_waitcnt vmcnt(4)
	ds_write_b128 v60, v[144:147] offset:18432
	ds_write_b128 v60, v[140:143] offset:23040
	s_waitcnt vmcnt(2)
	ds_write_b128 v60, v[148:151] offset:27648
	ds_write_b128 v60, v[120:123] offset:32256
	s_waitcnt vmcnt(0)
	ds_write_b128 v60, v[156:159] offset:36864
	ds_write_b128 v60, v[152:155] offset:41472
	ds_write_b128 v60, v[108:111] offset:46080
	ds_write_b128 v60, v[100:103] offset:50688
	v_mfma_f32_32x32x16_bf16 a[80:95], v[160:163], v[128:131], a[80:95]
	v_mfma_f32_32x32x16_bf16 a[64:79], v[160:163], v[168:171], a[64:79]
	s_waitcnt lgkmcnt(12)
	v_mfma_f32_32x32x16_bf16 a[48:63], v[104:107], v[128:131], a[48:63]
	v_mfma_f32_32x32x16_bf16 a[32:47], v[104:107], v[168:171], a[32:47]
	ds_read_b128 v[100:103], v59 offset:55328
	ds_read_b128 v[104:107], v69 offset:32
	ds_read_b128 v[108:111], v69 offset:64
	ds_read_b128 v[112:115], v59 offset:55360
	ds_read_b128 v[116:119], v69 offset:4640
	ds_read_b128 v[120:123], v69 offset:96
	s_waitcnt lgkmcnt(4)
	v_mfma_f32_32x32x16_bf16 a[112:127], v[100:103], v[104:107], a[112:127]
	s_waitcnt lgkmcnt(1)
	v_mfma_f32_32x32x16_bf16 a[96:111], v[100:103], v[116:119], a[96:111]
	ds_read_b128 v[100:103], v59 offset:59936
	ds_read_b128 v[124:127], v59 offset:55392
	v_mfma_f32_32x32x16_bf16 a[16:31], v[164:167], v[128:131], a[16:31]
	v_mfma_f32_32x32x16_bf16 a[0:15], v[164:167], v[168:171], a[0:15]
	s_waitcnt lgkmcnt(1)
	v_mfma_f32_32x32x16_bf16 a[80:95], v[100:103], v[104:107], a[80:95]
	v_mfma_f32_32x32x16_bf16 a[64:79], v[100:103], v[116:119], a[64:79]
	ds_read_b128 v[100:103], v59 offset:64544
	ds_read_b128 v[128:131], v59 offset:64576
	s_waitcnt lgkmcnt(1)
	v_mfma_f32_32x32x16_bf16 a[48:63], v[100:103], v[104:107], a[48:63]
	v_mfma_f32_32x32x16_bf16 a[32:47], v[100:103], v[116:119], a[32:47]
	ds_read_b128 v[100:103], v61 offset:55328
	ds_read_b128 v[136:139], v59 offset:64608
	s_waitcnt lgkmcnt(1)
	v_mfma_f32_32x32x16_bf16 a[16:31], v[100:103], v[104:107], a[16:31]
	v_mfma_f32_32x32x16_bf16 a[0:15], v[100:103], v[116:119], a[0:15]
	ds_read_b128 v[100:103], v69 offset:4672
	ds_read_b128 v[104:107], v69 offset:4704
	v_mfma_f32_32x32x16_bf16 a[112:127], v[112:115], v[108:111], a[112:127]
	s_waitcnt lgkmcnt(1)
	v_mfma_f32_32x32x16_bf16 a[96:111], v[112:115], v[100:103], a[96:111]
	ds_read_b128 v[112:115], v59 offset:59968
	ds_read_b128 v[116:119], v59 offset:60000
	s_waitcnt lgkmcnt(1)
	v_mfma_f32_32x32x16_bf16 a[80:95], v[112:115], v[108:111], a[80:95]
	v_mfma_f32_32x32x16_bf16 a[64:79], v[112:115], v[100:103], a[64:79]
	v_mfma_f32_32x32x16_bf16 a[48:63], v[128:131], v[108:111], a[48:63]
	v_mfma_f32_32x32x16_bf16 a[32:47], v[128:131], v[100:103], a[32:47]
	ds_read_b128 v[112:115], v61 offset:55360
	ds_read_b128 v[128:131], v61 offset:55392
	s_waitcnt lgkmcnt(1)
	v_mfma_f32_32x32x16_bf16 a[16:31], v[112:115], v[108:111], a[16:31]
	v_mfma_f32_32x32x16_bf16 a[0:15], v[112:115], v[100:103], a[0:15]
	v_mfma_f32_32x32x16_bf16 a[112:127], v[124:127], v[120:123], a[112:127]
	v_mfma_f32_32x32x16_bf16 a[96:111], v[124:127], v[104:107], a[96:111]
	v_mfma_f32_32x32x16_bf16 a[80:95], v[116:119], v[120:123], a[80:95]
	v_mfma_f32_32x32x16_bf16 a[64:79], v[116:119], v[104:107], a[64:79]
	global_load_dwordx4 v[100:103], v[4:5], off offset:384
	global_load_dwordx4 v[108:111], v[0:1], off offset:384
	global_load_dwordx4 v[112:115], v[18:19], off offset:384
	global_load_dwordx4 v[116:119], v[6:7], off offset:384
	v_mfma_f32_32x32x16_bf16 a[48:63], v[136:139], v[120:123], a[48:63]
	v_mfma_f32_32x32x16_bf16 a[32:47], v[136:139], v[104:107], a[32:47]
	global_load_dwordx4 v[124:127], v[20:21], off offset:384
	global_load_dwordx4 v[136:139], v[22:23], off offset:384
	global_load_dwordx4 v[140:143], v[26:27], off offset:384
	global_load_dwordx4 v[144:147], v[24:25], off offset:384
	global_load_dwordx4 v[148:151], v[28:29], off offset:384
	global_load_dwordx4 v[152:155], v[2:3], off offset:384
	global_load_dwordx4 v[156:159], v[30:31], off offset:384
	s_waitcnt lgkmcnt(0)
	v_mfma_f32_32x32x16_bf16 a[16:31], v[128:131], v[120:123], a[16:31]
	global_load_dwordx4 v[120:123], v[32:33], off offset:384
	s_barrier
	v_mfma_f32_32x32x16_bf16 a[0:15], v[128:131], v[104:107], a[0:15]
	ds_read_b128 v[104:107], v59
	ds_read_b128 v[128:131], v62 offset:36864
	ds_read_b128 v[160:163], v59 offset:4608
	ds_read_b128 v[164:167], v61
	ds_read_b128 v[168:171], v62 offset:41472
	s_waitcnt lgkmcnt(3)
	v_mfma_f32_32x32x16_bf16 a[112:127], v[104:107], v[128:131], a[112:127]
	s_waitcnt lgkmcnt(0)
	v_mfma_f32_32x32x16_bf16 a[96:111], v[104:107], v[168:171], a[96:111]
	ds_read_b128 v[104:107], v59 offset:9216
	s_waitcnt vmcnt(10)
	ds_write_b128 v60, v[108:111] offset:55296
	ds_write_b128 v60, v[100:103] offset:59904
	s_waitcnt vmcnt(8)
	ds_write_b128 v60, v[116:119] offset:64512
	ds_write_b128 v63, v[112:115] offset:55296
	s_waitcnt vmcnt(7)
	ds_write_b128 v64, v[124:127] offset:55296
	s_waitcnt vmcnt(6)
	ds_write_b128 v65, v[136:139] offset:55296
	s_waitcnt vmcnt(4)
	ds_write_b128 v66, v[144:147] offset:55296
	ds_write_b128 v67, v[140:143] offset:55296
	s_waitcnt vmcnt(2)
	ds_write_b128 v68, v[152:155]
	ds_write_b128 v68, v[148:151] offset:4608
	s_waitcnt vmcnt(1)
	ds_write_b128 v68, v[156:159] offset:9216
	s_waitcnt vmcnt(0)
	ds_write_b128 v68, v[120:123] offset:13824
	v_mfma_f32_32x32x16_bf16 a[80:95], v[160:163], v[128:131], a[80:95]
	v_mfma_f32_32x32x16_bf16 a[64:79], v[160:163], v[168:171], a[64:79]
	s_waitcnt lgkmcnt(12)
	v_mfma_f32_32x32x16_bf16 a[48:63], v[104:107], v[128:131], a[48:63]
	v_mfma_f32_32x32x16_bf16 a[32:47], v[104:107], v[168:171], a[32:47]
	ds_read_b128 v[100:103], v59 offset:32
	ds_read_b128 v[104:107], v62 offset:36896
	ds_read_b128 v[108:111], v62 offset:36928
	ds_read_b128 v[112:115], v59 offset:64
	ds_read_b128 v[116:119], v62 offset:41504
	ds_read_b128 v[120:123], v62 offset:36960
	s_waitcnt lgkmcnt(4)
	v_mfma_f32_32x32x16_bf16 a[112:127], v[100:103], v[104:107], a[112:127]
	s_waitcnt lgkmcnt(1)
	v_mfma_f32_32x32x16_bf16 a[96:111], v[100:103], v[116:119], a[96:111]
	ds_read_b128 v[100:103], v59 offset:4640
	ds_read_b128 v[124:127], v59 offset:96
	v_mfma_f32_32x32x16_bf16 a[16:31], v[164:167], v[128:131], a[16:31]
	v_mfma_f32_32x32x16_bf16 a[0:15], v[164:167], v[168:171], a[0:15]
	s_waitcnt lgkmcnt(1)
	v_mfma_f32_32x32x16_bf16 a[80:95], v[100:103], v[104:107], a[80:95]
	v_mfma_f32_32x32x16_bf16 a[64:79], v[100:103], v[116:119], a[64:79]
	ds_read_b128 v[100:103], v59 offset:9248
	ds_read_b128 v[128:131], v59 offset:9280
	s_waitcnt lgkmcnt(1)
	v_mfma_f32_32x32x16_bf16 a[48:63], v[100:103], v[104:107], a[48:63]
	v_mfma_f32_32x32x16_bf16 a[32:47], v[100:103], v[116:119], a[32:47]
	ds_read_b128 v[100:103], v61 offset:32
	ds_read_b128 v[136:139], v59 offset:9312
	s_waitcnt lgkmcnt(1)
	v_mfma_f32_32x32x16_bf16 a[16:31], v[100:103], v[104:107], a[16:31]
	v_mfma_f32_32x32x16_bf16 a[0:15], v[100:103], v[116:119], a[0:15]
	ds_read_b128 v[100:103], v62 offset:41536
	ds_read_b128 v[104:107], v62 offset:41568
	v_mfma_f32_32x32x16_bf16 a[112:127], v[112:115], v[108:111], a[112:127]
	s_waitcnt lgkmcnt(1)
	v_mfma_f32_32x32x16_bf16 a[96:111], v[112:115], v[100:103], a[96:111]
	ds_read_b128 v[112:115], v59 offset:4672
	ds_read_b128 v[116:119], v59 offset:4704
	s_waitcnt lgkmcnt(1)
	v_mfma_f32_32x32x16_bf16 a[80:95], v[112:115], v[108:111], a[80:95]
	v_mfma_f32_32x32x16_bf16 a[64:79], v[112:115], v[100:103], a[64:79]
	v_mfma_f32_32x32x16_bf16 a[48:63], v[128:131], v[108:111], a[48:63]
	v_mfma_f32_32x32x16_bf16 a[32:47], v[128:131], v[100:103], a[32:47]
	ds_read_b128 v[112:115], v61 offset:64
	ds_read_b128 v[128:131], v61 offset:96
	s_waitcnt lgkmcnt(1)
	v_mfma_f32_32x32x16_bf16 a[16:31], v[112:115], v[108:111], a[16:31]
	v_mfma_f32_32x32x16_bf16 a[0:15], v[112:115], v[100:103], a[0:15]
	global_load_dwordx4 v[100:103], v[32:33], off offset:512
	v_mfma_f32_32x32x16_bf16 a[112:127], v[124:127], v[120:123], a[112:127]
	v_mfma_f32_32x32x16_bf16 a[96:111], v[124:127], v[104:107], a[96:111]
	v_mfma_f32_32x32x16_bf16 a[80:95], v[116:119], v[120:123], a[80:95]
	v_mfma_f32_32x32x16_bf16 a[64:79], v[116:119], v[104:107], a[64:79]
	v_mfma_f32_32x32x16_bf16 a[48:63], v[136:139], v[120:123], a[48:63]
	v_mfma_f32_32x32x16_bf16 a[32:47], v[136:139], v[104:107], a[32:47]
	global_load_dwordx4 v[108:111], v[30:31], off offset:512
	global_load_dwordx4 v[112:115], v[18:19], off offset:512
	global_load_dwordx4 v[116:119], v[6:7], off offset:512
	global_load_dwordx4 v[124:127], v[4:5], off offset:512
	global_load_dwordx4 v[136:139], v[0:1], off offset:512
	global_load_dwordx4 v[140:143], v[22:23], off offset:512
	global_load_dwordx4 v[144:147], v[20:21], off offset:512
	s_waitcnt lgkmcnt(0)
	v_mfma_f32_32x32x16_bf16 a[16:31], v[128:131], v[120:123], a[16:31]
	global_load_dwordx4 v[120:123], v[26:27], off offset:512
	global_load_dwordx4 v[148:151], v[24:25], off offset:512
	global_load_dwordx4 v[152:155], v[28:29], off offset:512
	global_load_dwordx4 v[156:159], v[2:3], off offset:512
	s_barrier
	v_mfma_f32_32x32x16_bf16 a[0:15], v[128:131], v[104:107], a[0:15]
	ds_read_b128 v[104:107], v59 offset:55296
	ds_read_b128 v[128:131], v69
	ds_read_b128 v[160:163], v59 offset:59904
	ds_read_b128 v[164:167], v61 offset:55296
	ds_read_b128 v[168:171], v69 offset:4608
	s_waitcnt lgkmcnt(3)
	v_mfma_f32_32x32x16_bf16 a[112:127], v[104:107], v[128:131], a[112:127]
	s_waitcnt lgkmcnt(0)
	v_mfma_f32_32x32x16_bf16 a[96:111], v[104:107], v[168:171], a[96:111]
	ds_read_b128 v[104:107], v59 offset:64512
	s_waitcnt vmcnt(6)
	ds_write_b128 v60, v[136:139]
	ds_write_b128 v60, v[124:127] offset:4608
	ds_write_b128 v60, v[116:119] offset:9216
	ds_write_b128 v60, v[112:115] offset:13824
	s_waitcnt vmcnt(4)
	ds_write_b128 v60, v[144:147] offset:18432
	ds_write_b128 v60, v[140:143] offset:23040
	s_waitcnt vmcnt(2)
	ds_write_b128 v60, v[148:151] offset:27648
	ds_write_b128 v60, v[120:123] offset:32256
	s_waitcnt vmcnt(0)
	ds_write_b128 v60, v[156:159] offset:36864
	ds_write_b128 v60, v[152:155] offset:41472
	ds_write_b128 v60, v[108:111] offset:46080
	ds_write_b128 v60, v[100:103] offset:50688
	v_mfma_f32_32x32x16_bf16 a[80:95], v[160:163], v[128:131], a[80:95]
	v_mfma_f32_32x32x16_bf16 a[64:79], v[160:163], v[168:171], a[64:79]
	s_waitcnt lgkmcnt(12)
	v_mfma_f32_32x32x16_bf16 a[48:63], v[104:107], v[128:131], a[48:63]
	v_mfma_f32_32x32x16_bf16 a[32:47], v[104:107], v[168:171], a[32:47]
	ds_read_b128 v[100:103], v59 offset:55328
	ds_read_b128 v[104:107], v69 offset:32
	ds_read_b128 v[108:111], v69 offset:64
	ds_read_b128 v[112:115], v59 offset:55360
	ds_read_b128 v[116:119], v69 offset:4640
	ds_read_b128 v[120:123], v69 offset:96
	s_waitcnt lgkmcnt(4)
	v_mfma_f32_32x32x16_bf16 a[112:127], v[100:103], v[104:107], a[112:127]
	s_waitcnt lgkmcnt(1)
	v_mfma_f32_32x32x16_bf16 a[96:111], v[100:103], v[116:119], a[96:111]
	ds_read_b128 v[100:103], v59 offset:59936
	ds_read_b128 v[124:127], v59 offset:55392
	v_mfma_f32_32x32x16_bf16 a[16:31], v[164:167], v[128:131], a[16:31]
	v_mfma_f32_32x32x16_bf16 a[0:15], v[164:167], v[168:171], a[0:15]
	s_waitcnt lgkmcnt(1)
	v_mfma_f32_32x32x16_bf16 a[80:95], v[100:103], v[104:107], a[80:95]
	v_mfma_f32_32x32x16_bf16 a[64:79], v[100:103], v[116:119], a[64:79]
	ds_read_b128 v[100:103], v59 offset:64544
	ds_read_b128 v[128:131], v59 offset:64576
	s_waitcnt lgkmcnt(1)
	v_mfma_f32_32x32x16_bf16 a[48:63], v[100:103], v[104:107], a[48:63]
	v_mfma_f32_32x32x16_bf16 a[32:47], v[100:103], v[116:119], a[32:47]
	ds_read_b128 v[100:103], v61 offset:55328
	ds_read_b128 v[136:139], v59 offset:64608
	s_waitcnt lgkmcnt(1)
	v_mfma_f32_32x32x16_bf16 a[16:31], v[100:103], v[104:107], a[16:31]
	v_mfma_f32_32x32x16_bf16 a[0:15], v[100:103], v[116:119], a[0:15]
	ds_read_b128 v[100:103], v69 offset:4672
	ds_read_b128 v[104:107], v69 offset:4704
	v_mfma_f32_32x32x16_bf16 a[112:127], v[112:115], v[108:111], a[112:127]
	s_waitcnt lgkmcnt(1)
	v_mfma_f32_32x32x16_bf16 a[96:111], v[112:115], v[100:103], a[96:111]
	ds_read_b128 v[112:115], v59 offset:59968
	ds_read_b128 v[116:119], v59 offset:60000
	s_waitcnt lgkmcnt(1)
	v_mfma_f32_32x32x16_bf16 a[80:95], v[112:115], v[108:111], a[80:95]
	v_mfma_f32_32x32x16_bf16 a[64:79], v[112:115], v[100:103], a[64:79]
	v_mfma_f32_32x32x16_bf16 a[48:63], v[128:131], v[108:111], a[48:63]
	v_mfma_f32_32x32x16_bf16 a[32:47], v[128:131], v[100:103], a[32:47]
	ds_read_b128 v[112:115], v61 offset:55360
	ds_read_b128 v[128:131], v61 offset:55392
	s_waitcnt lgkmcnt(1)
	v_mfma_f32_32x32x16_bf16 a[16:31], v[112:115], v[108:111], a[16:31]
	v_mfma_f32_32x32x16_bf16 a[0:15], v[112:115], v[100:103], a[0:15]
	v_mfma_f32_32x32x16_bf16 a[112:127], v[124:127], v[120:123], a[112:127]
	v_mfma_f32_32x32x16_bf16 a[96:111], v[124:127], v[104:107], a[96:111]
	v_mfma_f32_32x32x16_bf16 a[80:95], v[116:119], v[120:123], a[80:95]
	v_mfma_f32_32x32x16_bf16 a[64:79], v[116:119], v[104:107], a[64:79]
	global_load_dwordx4 v[100:103], v[4:5], off offset:640
	global_load_dwordx4 v[108:111], v[0:1], off offset:640
	global_load_dwordx4 v[112:115], v[18:19], off offset:640
	global_load_dwordx4 v[116:119], v[6:7], off offset:640
	v_mfma_f32_32x32x16_bf16 a[48:63], v[136:139], v[120:123], a[48:63]
	v_mfma_f32_32x32x16_bf16 a[32:47], v[136:139], v[104:107], a[32:47]
	global_load_dwordx4 v[124:127], v[20:21], off offset:640
	global_load_dwordx4 v[136:139], v[22:23], off offset:640
	global_load_dwordx4 v[140:143], v[26:27], off offset:640
	global_load_dwordx4 v[144:147], v[24:25], off offset:640
	global_load_dwordx4 v[148:151], v[28:29], off offset:640
	global_load_dwordx4 v[152:155], v[2:3], off offset:640
	global_load_dwordx4 v[156:159], v[30:31], off offset:640
	s_waitcnt lgkmcnt(0)
	v_mfma_f32_32x32x16_bf16 a[16:31], v[128:131], v[120:123], a[16:31]
	global_load_dwordx4 v[120:123], v[32:33], off offset:640
	s_barrier
	v_mfma_f32_32x32x16_bf16 a[0:15], v[128:131], v[104:107], a[0:15]
	ds_read_b128 v[104:107], v59
	ds_read_b128 v[128:131], v62 offset:36864
	ds_read_b128 v[160:163], v59 offset:4608
	ds_read_b128 v[164:167], v61
	ds_read_b128 v[168:171], v62 offset:41472
	s_waitcnt lgkmcnt(3)
	v_mfma_f32_32x32x16_bf16 a[112:127], v[104:107], v[128:131], a[112:127]
	s_waitcnt lgkmcnt(0)
	v_mfma_f32_32x32x16_bf16 a[96:111], v[104:107], v[168:171], a[96:111]
	ds_read_b128 v[104:107], v59 offset:9216
	s_waitcnt vmcnt(10)
	ds_write_b128 v60, v[108:111] offset:55296
	ds_write_b128 v60, v[100:103] offset:59904
	s_waitcnt vmcnt(8)
	ds_write_b128 v60, v[116:119] offset:64512
	ds_write_b128 v63, v[112:115] offset:55296
	s_waitcnt vmcnt(7)
	ds_write_b128 v64, v[124:127] offset:55296
	s_waitcnt vmcnt(6)
	ds_write_b128 v65, v[136:139] offset:55296
	s_waitcnt vmcnt(4)
	ds_write_b128 v66, v[144:147] offset:55296
	ds_write_b128 v67, v[140:143] offset:55296
	s_waitcnt vmcnt(2)
	ds_write_b128 v68, v[152:155]
	ds_write_b128 v68, v[148:151] offset:4608
	s_waitcnt vmcnt(1)
	ds_write_b128 v68, v[156:159] offset:9216
	s_waitcnt vmcnt(0)
	ds_write_b128 v68, v[120:123] offset:13824
	v_mfma_f32_32x32x16_bf16 a[80:95], v[160:163], v[128:131], a[80:95]
	v_mfma_f32_32x32x16_bf16 a[64:79], v[160:163], v[168:171], a[64:79]
	s_waitcnt lgkmcnt(12)
	v_mfma_f32_32x32x16_bf16 a[48:63], v[104:107], v[128:131], a[48:63]
	v_mfma_f32_32x32x16_bf16 a[32:47], v[104:107], v[168:171], a[32:47]
	ds_read_b128 v[100:103], v59 offset:32
	ds_read_b128 v[104:107], v62 offset:36896
	ds_read_b128 v[108:111], v62 offset:36928
	ds_read_b128 v[112:115], v59 offset:64
	ds_read_b128 v[116:119], v62 offset:41504
	ds_read_b128 v[120:123], v62 offset:36960
	s_waitcnt lgkmcnt(4)
	v_mfma_f32_32x32x16_bf16 a[112:127], v[100:103], v[104:107], a[112:127]
	s_waitcnt lgkmcnt(1)
	v_mfma_f32_32x32x16_bf16 a[96:111], v[100:103], v[116:119], a[96:111]
	ds_read_b128 v[100:103], v59 offset:4640
	ds_read_b128 v[124:127], v59 offset:96
	v_mfma_f32_32x32x16_bf16 a[16:31], v[164:167], v[128:131], a[16:31]
	v_mfma_f32_32x32x16_bf16 a[0:15], v[164:167], v[168:171], a[0:15]
	s_waitcnt lgkmcnt(1)
	v_mfma_f32_32x32x16_bf16 a[80:95], v[100:103], v[104:107], a[80:95]
	v_mfma_f32_32x32x16_bf16 a[64:79], v[100:103], v[116:119], a[64:79]
	ds_read_b128 v[100:103], v59 offset:9248
	ds_read_b128 v[128:131], v59 offset:9280
	s_waitcnt lgkmcnt(1)
	v_mfma_f32_32x32x16_bf16 a[48:63], v[100:103], v[104:107], a[48:63]
	v_mfma_f32_32x32x16_bf16 a[32:47], v[100:103], v[116:119], a[32:47]
	ds_read_b128 v[100:103], v61 offset:32
	ds_read_b128 v[136:139], v59 offset:9312
	s_waitcnt lgkmcnt(1)
	v_mfma_f32_32x32x16_bf16 a[16:31], v[100:103], v[104:107], a[16:31]
	v_mfma_f32_32x32x16_bf16 a[0:15], v[100:103], v[116:119], a[0:15]
	ds_read_b128 v[100:103], v62 offset:41536
	ds_read_b128 v[104:107], v62 offset:41568
	v_mfma_f32_32x32x16_bf16 a[112:127], v[112:115], v[108:111], a[112:127]
	s_waitcnt lgkmcnt(1)
	v_mfma_f32_32x32x16_bf16 a[96:111], v[112:115], v[100:103], a[96:111]
	ds_read_b128 v[112:115], v59 offset:4672
	ds_read_b128 v[116:119], v59 offset:4704
	s_waitcnt lgkmcnt(1)
	v_mfma_f32_32x32x16_bf16 a[80:95], v[112:115], v[108:111], a[80:95]
	v_mfma_f32_32x32x16_bf16 a[64:79], v[112:115], v[100:103], a[64:79]
	v_mfma_f32_32x32x16_bf16 a[48:63], v[128:131], v[108:111], a[48:63]
	v_mfma_f32_32x32x16_bf16 a[32:47], v[128:131], v[100:103], a[32:47]
	ds_read_b128 v[112:115], v61 offset:64
	ds_read_b128 v[128:131], v61 offset:96
	s_waitcnt lgkmcnt(1)
	v_mfma_f32_32x32x16_bf16 a[16:31], v[112:115], v[108:111], a[16:31]
	v_mfma_f32_32x32x16_bf16 a[0:15], v[112:115], v[100:103], a[0:15]
	global_load_dwordx4 v[100:103], v[32:33], off offset:768
	v_mfma_f32_32x32x16_bf16 a[112:127], v[124:127], v[120:123], a[112:127]
	v_mfma_f32_32x32x16_bf16 a[96:111], v[124:127], v[104:107], a[96:111]
	v_mfma_f32_32x32x16_bf16 a[80:95], v[116:119], v[120:123], a[80:95]
	v_mfma_f32_32x32x16_bf16 a[64:79], v[116:119], v[104:107], a[64:79]
	v_mfma_f32_32x32x16_bf16 a[48:63], v[136:139], v[120:123], a[48:63]
	v_mfma_f32_32x32x16_bf16 a[32:47], v[136:139], v[104:107], a[32:47]
	global_load_dwordx4 v[108:111], v[30:31], off offset:768
	global_load_dwordx4 v[112:115], v[18:19], off offset:768
	global_load_dwordx4 v[116:119], v[6:7], off offset:768
	global_load_dwordx4 v[124:127], v[4:5], off offset:768
	global_load_dwordx4 v[136:139], v[0:1], off offset:768
	global_load_dwordx4 v[140:143], v[22:23], off offset:768
	global_load_dwordx4 v[144:147], v[20:21], off offset:768
	s_waitcnt lgkmcnt(0)
	v_mfma_f32_32x32x16_bf16 a[16:31], v[128:131], v[120:123], a[16:31]
	global_load_dwordx4 v[120:123], v[26:27], off offset:768
	global_load_dwordx4 v[148:151], v[24:25], off offset:768
	global_load_dwordx4 v[152:155], v[28:29], off offset:768
	global_load_dwordx4 v[156:159], v[2:3], off offset:768
	s_barrier
	v_mfma_f32_32x32x16_bf16 a[0:15], v[128:131], v[104:107], a[0:15]
	ds_read_b128 v[104:107], v59 offset:55296
	ds_read_b128 v[128:131], v69
	ds_read_b128 v[160:163], v59 offset:59904
	ds_read_b128 v[164:167], v61 offset:55296
	ds_read_b128 v[168:171], v69 offset:4608
	s_waitcnt lgkmcnt(3)
	v_mfma_f32_32x32x16_bf16 a[112:127], v[104:107], v[128:131], a[112:127]
	s_waitcnt lgkmcnt(0)
	v_mfma_f32_32x32x16_bf16 a[96:111], v[104:107], v[168:171], a[96:111]
	ds_read_b128 v[104:107], v59 offset:64512
	s_waitcnt vmcnt(6)
	ds_write_b128 v60, v[136:139]
	ds_write_b128 v60, v[124:127] offset:4608
	ds_write_b128 v60, v[116:119] offset:9216
	ds_write_b128 v60, v[112:115] offset:13824
	s_waitcnt vmcnt(4)
	ds_write_b128 v60, v[144:147] offset:18432
	ds_write_b128 v60, v[140:143] offset:23040
	s_waitcnt vmcnt(2)
	ds_write_b128 v60, v[148:151] offset:27648
	ds_write_b128 v60, v[120:123] offset:32256
	s_waitcnt vmcnt(0)
	ds_write_b128 v60, v[156:159] offset:36864
	ds_write_b128 v60, v[152:155] offset:41472
	ds_write_b128 v60, v[108:111] offset:46080
	ds_write_b128 v60, v[100:103] offset:50688
	v_mfma_f32_32x32x16_bf16 a[80:95], v[160:163], v[128:131], a[80:95]
	v_mfma_f32_32x32x16_bf16 a[64:79], v[160:163], v[168:171], a[64:79]
	s_waitcnt lgkmcnt(12)
	v_mfma_f32_32x32x16_bf16 a[48:63], v[104:107], v[128:131], a[48:63]
	v_mfma_f32_32x32x16_bf16 a[32:47], v[104:107], v[168:171], a[32:47]
	ds_read_b128 v[100:103], v59 offset:55328
	ds_read_b128 v[104:107], v69 offset:32
	ds_read_b128 v[108:111], v69 offset:64
	ds_read_b128 v[112:115], v59 offset:55360
	ds_read_b128 v[116:119], v69 offset:4640
	ds_read_b128 v[120:123], v69 offset:96
	s_waitcnt lgkmcnt(4)
	v_mfma_f32_32x32x16_bf16 a[112:127], v[100:103], v[104:107], a[112:127]
	s_waitcnt lgkmcnt(1)
	v_mfma_f32_32x32x16_bf16 a[96:111], v[100:103], v[116:119], a[96:111]
	ds_read_b128 v[100:103], v59 offset:59936
	ds_read_b128 v[124:127], v59 offset:55392
	v_mfma_f32_32x32x16_bf16 a[16:31], v[164:167], v[128:131], a[16:31]
	v_mfma_f32_32x32x16_bf16 a[0:15], v[164:167], v[168:171], a[0:15]
	s_waitcnt lgkmcnt(1)
	v_mfma_f32_32x32x16_bf16 a[80:95], v[100:103], v[104:107], a[80:95]
	v_mfma_f32_32x32x16_bf16 a[64:79], v[100:103], v[116:119], a[64:79]
	ds_read_b128 v[100:103], v59 offset:64544
	ds_read_b128 v[128:131], v59 offset:64576
	s_waitcnt lgkmcnt(1)
	v_mfma_f32_32x32x16_bf16 a[48:63], v[100:103], v[104:107], a[48:63]
	v_mfma_f32_32x32x16_bf16 a[32:47], v[100:103], v[116:119], a[32:47]
	ds_read_b128 v[100:103], v61 offset:55328
	ds_read_b128 v[136:139], v59 offset:64608
	s_waitcnt lgkmcnt(1)
	v_mfma_f32_32x32x16_bf16 a[16:31], v[100:103], v[104:107], a[16:31]
	v_mfma_f32_32x32x16_bf16 a[0:15], v[100:103], v[116:119], a[0:15]
	ds_read_b128 v[100:103], v69 offset:4672
	ds_read_b128 v[104:107], v69 offset:4704
	v_mfma_f32_32x32x16_bf16 a[112:127], v[112:115], v[108:111], a[112:127]
	s_waitcnt lgkmcnt(1)
	v_mfma_f32_32x32x16_bf16 a[96:111], v[112:115], v[100:103], a[96:111]
	ds_read_b128 v[112:115], v59 offset:59968
	ds_read_b128 v[116:119], v59 offset:60000
	s_waitcnt lgkmcnt(1)
	v_mfma_f32_32x32x16_bf16 a[80:95], v[112:115], v[108:111], a[80:95]
	v_mfma_f32_32x32x16_bf16 a[64:79], v[112:115], v[100:103], a[64:79]
	v_mfma_f32_32x32x16_bf16 a[48:63], v[128:131], v[108:111], a[48:63]
	v_mfma_f32_32x32x16_bf16 a[32:47], v[128:131], v[100:103], a[32:47]
	ds_read_b128 v[112:115], v61 offset:55360
	ds_read_b128 v[128:131], v61 offset:55392
	s_waitcnt lgkmcnt(1)
	v_mfma_f32_32x32x16_bf16 a[16:31], v[112:115], v[108:111], a[16:31]
	v_mfma_f32_32x32x16_bf16 a[0:15], v[112:115], v[100:103], a[0:15]
	v_mfma_f32_32x32x16_bf16 a[112:127], v[124:127], v[120:123], a[112:127]
	v_mfma_f32_32x32x16_bf16 a[96:111], v[124:127], v[104:107], a[96:111]
	v_mfma_f32_32x32x16_bf16 a[80:95], v[116:119], v[120:123], a[80:95]
	v_mfma_f32_32x32x16_bf16 a[64:79], v[116:119], v[104:107], a[64:79]
	global_load_dwordx4 v[100:103], v[4:5], off offset:896
	global_load_dwordx4 v[108:111], v[0:1], off offset:896
	global_load_dwordx4 v[112:115], v[18:19], off offset:896
	global_load_dwordx4 v[116:119], v[6:7], off offset:896
	v_mfma_f32_32x32x16_bf16 a[48:63], v[136:139], v[120:123], a[48:63]
	v_mfma_f32_32x32x16_bf16 a[32:47], v[136:139], v[104:107], a[32:47]
	global_load_dwordx4 v[124:127], v[20:21], off offset:896
	global_load_dwordx4 v[136:139], v[22:23], off offset:896
	global_load_dwordx4 v[140:143], v[26:27], off offset:896
	global_load_dwordx4 v[144:147], v[24:25], off offset:896
	global_load_dwordx4 v[148:151], v[28:29], off offset:896
	global_load_dwordx4 v[152:155], v[2:3], off offset:896
	global_load_dwordx4 v[156:159], v[30:31], off offset:896
	s_waitcnt lgkmcnt(0)
	v_mfma_f32_32x32x16_bf16 a[16:31], v[128:131], v[120:123], a[16:31]
	global_load_dwordx4 v[120:123], v[32:33], off offset:896
	s_barrier
	v_mfma_f32_32x32x16_bf16 a[0:15], v[128:131], v[104:107], a[0:15]
	ds_read_b128 v[104:107], v59
	ds_read_b128 v[128:131], v62 offset:36864
	ds_read_b128 v[160:163], v59 offset:4608
	ds_read_b128 v[164:167], v61
	ds_read_b128 v[168:171], v62 offset:41472
	s_waitcnt lgkmcnt(3)
	v_mfma_f32_32x32x16_bf16 a[112:127], v[104:107], v[128:131], a[112:127]
	s_waitcnt lgkmcnt(0)
	v_mfma_f32_32x32x16_bf16 a[96:111], v[104:107], v[168:171], a[96:111]
	ds_read_b128 v[104:107], v59 offset:9216
	s_waitcnt vmcnt(10)
	ds_write_b128 v60, v[108:111] offset:55296
	ds_write_b128 v60, v[100:103] offset:59904
	s_waitcnt vmcnt(8)
	ds_write_b128 v60, v[116:119] offset:64512
	ds_write_b128 v63, v[112:115] offset:55296
	s_waitcnt vmcnt(7)
	ds_write_b128 v64, v[124:127] offset:55296
	s_waitcnt vmcnt(6)
	ds_write_b128 v65, v[136:139] offset:55296
	s_waitcnt vmcnt(4)
	ds_write_b128 v66, v[144:147] offset:55296
	ds_write_b128 v67, v[140:143] offset:55296
	s_waitcnt vmcnt(2)
	ds_write_b128 v68, v[152:155]
	ds_write_b128 v68, v[148:151] offset:4608
	s_waitcnt vmcnt(1)
	ds_write_b128 v68, v[156:159] offset:9216
	s_waitcnt vmcnt(0)
	ds_write_b128 v68, v[120:123] offset:13824
	v_mfma_f32_32x32x16_bf16 a[80:95], v[160:163], v[128:131], a[80:95]
	v_mfma_f32_32x32x16_bf16 a[64:79], v[160:163], v[168:171], a[64:79]
	s_waitcnt lgkmcnt(12)
	v_mfma_f32_32x32x16_bf16 a[48:63], v[104:107], v[128:131], a[48:63]
	v_mfma_f32_32x32x16_bf16 a[32:47], v[104:107], v[168:171], a[32:47]
	ds_read_b128 v[100:103], v59 offset:32
	ds_read_b128 v[104:107], v62 offset:36896
	ds_read_b128 v[108:111], v62 offset:36928
	ds_read_b128 v[112:115], v59 offset:64
	ds_read_b128 v[116:119], v62 offset:41504
	ds_read_b128 v[120:123], v62 offset:36960
	s_waitcnt lgkmcnt(4)
	v_mfma_f32_32x32x16_bf16 a[112:127], v[100:103], v[104:107], a[112:127]
	s_waitcnt lgkmcnt(1)
	v_mfma_f32_32x32x16_bf16 a[96:111], v[100:103], v[116:119], a[96:111]
	ds_read_b128 v[100:103], v59 offset:4640
	ds_read_b128 v[124:127], v59 offset:96
	v_mfma_f32_32x32x16_bf16 a[16:31], v[164:167], v[128:131], a[16:31]
	v_mfma_f32_32x32x16_bf16 a[0:15], v[164:167], v[168:171], a[0:15]
	s_waitcnt lgkmcnt(1)
	v_mfma_f32_32x32x16_bf16 a[80:95], v[100:103], v[104:107], a[80:95]
	v_mfma_f32_32x32x16_bf16 a[64:79], v[100:103], v[116:119], a[64:79]
	ds_read_b128 v[100:103], v59 offset:9248
	ds_read_b128 v[128:131], v59 offset:9280
	s_waitcnt lgkmcnt(1)
	v_mfma_f32_32x32x16_bf16 a[48:63], v[100:103], v[104:107], a[48:63]
	v_mfma_f32_32x32x16_bf16 a[32:47], v[100:103], v[116:119], a[32:47]
	ds_read_b128 v[100:103], v61 offset:32
	ds_read_b128 v[136:139], v59 offset:9312
	s_waitcnt lgkmcnt(1)
	v_mfma_f32_32x32x16_bf16 a[16:31], v[100:103], v[104:107], a[16:31]
	v_mfma_f32_32x32x16_bf16 a[0:15], v[100:103], v[116:119], a[0:15]
	ds_read_b128 v[100:103], v62 offset:41536
	ds_read_b128 v[104:107], v62 offset:41568
	v_mfma_f32_32x32x16_bf16 a[112:127], v[112:115], v[108:111], a[112:127]
	s_waitcnt lgkmcnt(1)
	v_mfma_f32_32x32x16_bf16 a[96:111], v[112:115], v[100:103], a[96:111]
	ds_read_b128 v[112:115], v59 offset:4672
	ds_read_b128 v[116:119], v59 offset:4704
	s_waitcnt lgkmcnt(1)
	v_mfma_f32_32x32x16_bf16 a[80:95], v[112:115], v[108:111], a[80:95]
	v_mfma_f32_32x32x16_bf16 a[64:79], v[112:115], v[100:103], a[64:79]
	v_mfma_f32_32x32x16_bf16 a[48:63], v[128:131], v[108:111], a[48:63]
	v_mfma_f32_32x32x16_bf16 a[32:47], v[128:131], v[100:103], a[32:47]
	ds_read_b128 v[112:115], v61 offset:64
	ds_read_b128 v[128:131], v61 offset:96
	s_waitcnt lgkmcnt(1)
	v_mfma_f32_32x32x16_bf16 a[16:31], v[112:115], v[108:111], a[16:31]
	v_mfma_f32_32x32x16_bf16 a[0:15], v[112:115], v[100:103], a[0:15]
	global_load_dwordx4 v[100:103], v[32:33], off offset:1024
	v_mfma_f32_32x32x16_bf16 a[112:127], v[124:127], v[120:123], a[112:127]
	v_mfma_f32_32x32x16_bf16 a[96:111], v[124:127], v[104:107], a[96:111]
	v_mfma_f32_32x32x16_bf16 a[80:95], v[116:119], v[120:123], a[80:95]
	v_mfma_f32_32x32x16_bf16 a[64:79], v[116:119], v[104:107], a[64:79]
	v_mfma_f32_32x32x16_bf16 a[48:63], v[136:139], v[120:123], a[48:63]
	v_mfma_f32_32x32x16_bf16 a[32:47], v[136:139], v[104:107], a[32:47]
	global_load_dwordx4 v[108:111], v[30:31], off offset:1024
	global_load_dwordx4 v[112:115], v[18:19], off offset:1024
	global_load_dwordx4 v[116:119], v[6:7], off offset:1024
	global_load_dwordx4 v[124:127], v[4:5], off offset:1024
	global_load_dwordx4 v[136:139], v[0:1], off offset:1024
	global_load_dwordx4 v[140:143], v[22:23], off offset:1024
	global_load_dwordx4 v[144:147], v[20:21], off offset:1024
	s_waitcnt lgkmcnt(0)
	v_mfma_f32_32x32x16_bf16 a[16:31], v[128:131], v[120:123], a[16:31]
	global_load_dwordx4 v[120:123], v[26:27], off offset:1024
	global_load_dwordx4 v[148:151], v[24:25], off offset:1024
	global_load_dwordx4 v[152:155], v[28:29], off offset:1024
	global_load_dwordx4 v[156:159], v[2:3], off offset:1024
	s_barrier
	v_mfma_f32_32x32x16_bf16 a[0:15], v[128:131], v[104:107], a[0:15]
	ds_read_b128 v[104:107], v59 offset:55296
	ds_read_b128 v[128:131], v69
	ds_read_b128 v[160:163], v59 offset:59904
	ds_read_b128 v[164:167], v61 offset:55296
	ds_read_b128 v[168:171], v69 offset:4608
	s_waitcnt lgkmcnt(3)
	v_mfma_f32_32x32x16_bf16 a[112:127], v[104:107], v[128:131], a[112:127]
	s_waitcnt lgkmcnt(0)
	v_mfma_f32_32x32x16_bf16 a[96:111], v[104:107], v[168:171], a[96:111]
	ds_read_b128 v[104:107], v59 offset:64512
	s_waitcnt vmcnt(6)
	ds_write_b128 v60, v[136:139]
	ds_write_b128 v60, v[124:127] offset:4608
	ds_write_b128 v60, v[116:119] offset:9216
	ds_write_b128 v60, v[112:115] offset:13824
	s_waitcnt vmcnt(4)
	ds_write_b128 v60, v[144:147] offset:18432
	ds_write_b128 v60, v[140:143] offset:23040
	s_waitcnt vmcnt(2)
	ds_write_b128 v60, v[148:151] offset:27648
	ds_write_b128 v60, v[120:123] offset:32256
	s_waitcnt vmcnt(0)
	ds_write_b128 v60, v[156:159] offset:36864
	ds_write_b128 v60, v[152:155] offset:41472
	ds_write_b128 v60, v[108:111] offset:46080
	ds_write_b128 v60, v[100:103] offset:50688
	v_mfma_f32_32x32x16_bf16 a[80:95], v[160:163], v[128:131], a[80:95]
	v_mfma_f32_32x32x16_bf16 a[64:79], v[160:163], v[168:171], a[64:79]
	s_waitcnt lgkmcnt(12)
	v_mfma_f32_32x32x16_bf16 a[48:63], v[104:107], v[128:131], a[48:63]
	v_mfma_f32_32x32x16_bf16 a[32:47], v[104:107], v[168:171], a[32:47]
	ds_read_b128 v[100:103], v59 offset:55328
	ds_read_b128 v[104:107], v69 offset:32
	ds_read_b128 v[108:111], v69 offset:64
	ds_read_b128 v[112:115], v59 offset:55360
	ds_read_b128 v[116:119], v69 offset:4640
	ds_read_b128 v[120:123], v69 offset:96
	s_waitcnt lgkmcnt(4)
	v_mfma_f32_32x32x16_bf16 a[112:127], v[100:103], v[104:107], a[112:127]
	s_waitcnt lgkmcnt(1)
	v_mfma_f32_32x32x16_bf16 a[96:111], v[100:103], v[116:119], a[96:111]
	ds_read_b128 v[100:103], v59 offset:59936
	ds_read_b128 v[124:127], v59 offset:55392
	v_mfma_f32_32x32x16_bf16 a[16:31], v[164:167], v[128:131], a[16:31]
	v_mfma_f32_32x32x16_bf16 a[0:15], v[164:167], v[168:171], a[0:15]
	s_waitcnt lgkmcnt(1)
	v_mfma_f32_32x32x16_bf16 a[80:95], v[100:103], v[104:107], a[80:95]
	v_mfma_f32_32x32x16_bf16 a[64:79], v[100:103], v[116:119], a[64:79]
	ds_read_b128 v[100:103], v59 offset:64544
	ds_read_b128 v[128:131], v59 offset:64576
	s_waitcnt lgkmcnt(1)
	v_mfma_f32_32x32x16_bf16 a[48:63], v[100:103], v[104:107], a[48:63]
	v_mfma_f32_32x32x16_bf16 a[32:47], v[100:103], v[116:119], a[32:47]
	ds_read_b128 v[100:103], v61 offset:55328
	ds_read_b128 v[136:139], v59 offset:64608
	s_waitcnt lgkmcnt(1)
	v_mfma_f32_32x32x16_bf16 a[16:31], v[100:103], v[104:107], a[16:31]
	v_mfma_f32_32x32x16_bf16 a[0:15], v[100:103], v[116:119], a[0:15]
	ds_read_b128 v[100:103], v69 offset:4672
	ds_read_b128 v[104:107], v69 offset:4704
	v_mfma_f32_32x32x16_bf16 a[112:127], v[112:115], v[108:111], a[112:127]
	s_waitcnt lgkmcnt(1)
	v_mfma_f32_32x32x16_bf16 a[96:111], v[112:115], v[100:103], a[96:111]
	ds_read_b128 v[112:115], v59 offset:59968
	ds_read_b128 v[116:119], v59 offset:60000
	s_waitcnt lgkmcnt(1)
	v_mfma_f32_32x32x16_bf16 a[80:95], v[112:115], v[108:111], a[80:95]
	v_mfma_f32_32x32x16_bf16 a[64:79], v[112:115], v[100:103], a[64:79]
	v_mfma_f32_32x32x16_bf16 a[48:63], v[128:131], v[108:111], a[48:63]
	v_mfma_f32_32x32x16_bf16 a[32:47], v[128:131], v[100:103], a[32:47]
	ds_read_b128 v[112:115], v61 offset:55360
	ds_read_b128 v[128:131], v61 offset:55392
	s_waitcnt lgkmcnt(1)
	v_mfma_f32_32x32x16_bf16 a[16:31], v[112:115], v[108:111], a[16:31]
	v_mfma_f32_32x32x16_bf16 a[0:15], v[112:115], v[100:103], a[0:15]
	v_mfma_f32_32x32x16_bf16 a[112:127], v[124:127], v[120:123], a[112:127]
	v_mfma_f32_32x32x16_bf16 a[96:111], v[124:127], v[104:107], a[96:111]
	v_mfma_f32_32x32x16_bf16 a[80:95], v[116:119], v[120:123], a[80:95]
	v_mfma_f32_32x32x16_bf16 a[64:79], v[116:119], v[104:107], a[64:79]
	global_load_dwordx4 v[100:103], v[4:5], off offset:1152
	global_load_dwordx4 v[108:111], v[0:1], off offset:1152
	global_load_dwordx4 v[112:115], v[18:19], off offset:1152
	global_load_dwordx4 v[116:119], v[6:7], off offset:1152
	v_mfma_f32_32x32x16_bf16 a[48:63], v[136:139], v[120:123], a[48:63]
	v_mfma_f32_32x32x16_bf16 a[32:47], v[136:139], v[104:107], a[32:47]
	global_load_dwordx4 v[124:127], v[20:21], off offset:1152
	global_load_dwordx4 v[136:139], v[22:23], off offset:1152
	global_load_dwordx4 v[140:143], v[26:27], off offset:1152
	global_load_dwordx4 v[144:147], v[24:25], off offset:1152
	global_load_dwordx4 v[148:151], v[28:29], off offset:1152
	global_load_dwordx4 v[152:155], v[2:3], off offset:1152
	global_load_dwordx4 v[156:159], v[30:31], off offset:1152
	s_waitcnt lgkmcnt(0)
	v_mfma_f32_32x32x16_bf16 a[16:31], v[128:131], v[120:123], a[16:31]
	global_load_dwordx4 v[120:123], v[32:33], off offset:1152
	s_barrier
	v_mfma_f32_32x32x16_bf16 a[0:15], v[128:131], v[104:107], a[0:15]
	ds_read_b128 v[104:107], v59
	ds_read_b128 v[128:131], v62 offset:36864
	ds_read_b128 v[160:163], v59 offset:4608
	ds_read_b128 v[164:167], v61
	ds_read_b128 v[168:171], v62 offset:41472
	s_waitcnt lgkmcnt(3)
	v_mfma_f32_32x32x16_bf16 a[112:127], v[104:107], v[128:131], a[112:127]
	s_waitcnt lgkmcnt(0)
	v_mfma_f32_32x32x16_bf16 a[96:111], v[104:107], v[168:171], a[96:111]
	ds_read_b128 v[104:107], v59 offset:9216
	s_waitcnt vmcnt(10)
	ds_write_b128 v60, v[108:111] offset:55296
	ds_write_b128 v60, v[100:103] offset:59904
	s_waitcnt vmcnt(8)
	ds_write_b128 v60, v[116:119] offset:64512
	ds_write_b128 v63, v[112:115] offset:55296
	s_waitcnt vmcnt(7)
	ds_write_b128 v64, v[124:127] offset:55296
	s_waitcnt vmcnt(6)
	ds_write_b128 v65, v[136:139] offset:55296
	s_waitcnt vmcnt(4)
	ds_write_b128 v66, v[144:147] offset:55296
	ds_write_b128 v67, v[140:143] offset:55296
	s_waitcnt vmcnt(2)
	ds_write_b128 v68, v[152:155]
	ds_write_b128 v68, v[148:151] offset:4608
	s_waitcnt vmcnt(1)
	ds_write_b128 v68, v[156:159] offset:9216
	s_waitcnt vmcnt(0)
	ds_write_b128 v68, v[120:123] offset:13824
	v_mfma_f32_32x32x16_bf16 a[80:95], v[160:163], v[128:131], a[80:95]
	v_mfma_f32_32x32x16_bf16 a[64:79], v[160:163], v[168:171], a[64:79]
	s_waitcnt lgkmcnt(12)
	v_mfma_f32_32x32x16_bf16 a[48:63], v[104:107], v[128:131], a[48:63]
	v_mfma_f32_32x32x16_bf16 a[32:47], v[104:107], v[168:171], a[32:47]
	ds_read_b128 v[100:103], v59 offset:32
	ds_read_b128 v[104:107], v62 offset:36896
	ds_read_b128 v[108:111], v62 offset:36928
	ds_read_b128 v[112:115], v59 offset:64
	ds_read_b128 v[116:119], v62 offset:41504
	ds_read_b128 v[120:123], v62 offset:36960
	s_waitcnt lgkmcnt(4)
	v_mfma_f32_32x32x16_bf16 a[112:127], v[100:103], v[104:107], a[112:127]
	s_waitcnt lgkmcnt(1)
	v_mfma_f32_32x32x16_bf16 a[96:111], v[100:103], v[116:119], a[96:111]
	ds_read_b128 v[100:103], v59 offset:4640
	ds_read_b128 v[124:127], v59 offset:96
	v_mfma_f32_32x32x16_bf16 a[16:31], v[164:167], v[128:131], a[16:31]
	v_mfma_f32_32x32x16_bf16 a[0:15], v[164:167], v[168:171], a[0:15]
	s_waitcnt lgkmcnt(1)
	v_mfma_f32_32x32x16_bf16 a[80:95], v[100:103], v[104:107], a[80:95]
	v_mfma_f32_32x32x16_bf16 a[64:79], v[100:103], v[116:119], a[64:79]
	ds_read_b128 v[100:103], v59 offset:9248
	ds_read_b128 v[128:131], v59 offset:9280
	s_waitcnt lgkmcnt(1)
	v_mfma_f32_32x32x16_bf16 a[48:63], v[100:103], v[104:107], a[48:63]
	v_mfma_f32_32x32x16_bf16 a[32:47], v[100:103], v[116:119], a[32:47]
	ds_read_b128 v[100:103], v61 offset:32
	ds_read_b128 v[136:139], v59 offset:9312
	s_waitcnt lgkmcnt(1)
	v_mfma_f32_32x32x16_bf16 a[16:31], v[100:103], v[104:107], a[16:31]
	v_mfma_f32_32x32x16_bf16 a[0:15], v[100:103], v[116:119], a[0:15]
	ds_read_b128 v[100:103], v62 offset:41536
	ds_read_b128 v[104:107], v62 offset:41568
	v_mfma_f32_32x32x16_bf16 a[112:127], v[112:115], v[108:111], a[112:127]
	s_waitcnt lgkmcnt(1)
	v_mfma_f32_32x32x16_bf16 a[96:111], v[112:115], v[100:103], a[96:111]
	ds_read_b128 v[112:115], v59 offset:4672
	ds_read_b128 v[116:119], v59 offset:4704
	s_waitcnt lgkmcnt(1)
	v_mfma_f32_32x32x16_bf16 a[80:95], v[112:115], v[108:111], a[80:95]
	v_mfma_f32_32x32x16_bf16 a[64:79], v[112:115], v[100:103], a[64:79]
	v_mfma_f32_32x32x16_bf16 a[48:63], v[128:131], v[108:111], a[48:63]
	v_mfma_f32_32x32x16_bf16 a[32:47], v[128:131], v[100:103], a[32:47]
	ds_read_b128 v[112:115], v61 offset:64
	ds_read_b128 v[128:131], v61 offset:96
	s_waitcnt lgkmcnt(1)
	v_mfma_f32_32x32x16_bf16 a[16:31], v[112:115], v[108:111], a[16:31]
	v_mfma_f32_32x32x16_bf16 a[0:15], v[112:115], v[100:103], a[0:15]
	global_load_dwordx4 v[100:103], v[32:33], off offset:1280
	v_mfma_f32_32x32x16_bf16 a[112:127], v[124:127], v[120:123], a[112:127]
	v_mfma_f32_32x32x16_bf16 a[96:111], v[124:127], v[104:107], a[96:111]
	v_mfma_f32_32x32x16_bf16 a[80:95], v[116:119], v[120:123], a[80:95]
	v_mfma_f32_32x32x16_bf16 a[64:79], v[116:119], v[104:107], a[64:79]
	v_mfma_f32_32x32x16_bf16 a[48:63], v[136:139], v[120:123], a[48:63]
	v_mfma_f32_32x32x16_bf16 a[32:47], v[136:139], v[104:107], a[32:47]
	global_load_dwordx4 v[108:111], v[30:31], off offset:1280
	global_load_dwordx4 v[112:115], v[18:19], off offset:1280
	global_load_dwordx4 v[116:119], v[6:7], off offset:1280
	global_load_dwordx4 v[124:127], v[4:5], off offset:1280
	global_load_dwordx4 v[136:139], v[0:1], off offset:1280
	global_load_dwordx4 v[140:143], v[22:23], off offset:1280
	global_load_dwordx4 v[144:147], v[20:21], off offset:1280
	s_waitcnt lgkmcnt(0)
	v_mfma_f32_32x32x16_bf16 a[16:31], v[128:131], v[120:123], a[16:31]
	global_load_dwordx4 v[120:123], v[26:27], off offset:1280
	global_load_dwordx4 v[148:151], v[24:25], off offset:1280
	global_load_dwordx4 v[152:155], v[28:29], off offset:1280
	global_load_dwordx4 v[156:159], v[2:3], off offset:1280
	s_barrier
	v_mfma_f32_32x32x16_bf16 a[0:15], v[128:131], v[104:107], a[0:15]
	ds_read_b128 v[104:107], v59 offset:55296
	ds_read_b128 v[128:131], v69
	ds_read_b128 v[160:163], v59 offset:59904
	ds_read_b128 v[164:167], v61 offset:55296
	ds_read_b128 v[168:171], v69 offset:4608
	s_waitcnt lgkmcnt(3)
	v_mfma_f32_32x32x16_bf16 a[112:127], v[104:107], v[128:131], a[112:127]
	s_waitcnt lgkmcnt(0)
	v_mfma_f32_32x32x16_bf16 a[96:111], v[104:107], v[168:171], a[96:111]
	ds_read_b128 v[104:107], v59 offset:64512
	s_waitcnt vmcnt(6)
	ds_write_b128 v60, v[136:139]
	ds_write_b128 v60, v[124:127] offset:4608
	ds_write_b128 v60, v[116:119] offset:9216
	ds_write_b128 v60, v[112:115] offset:13824
	s_waitcnt vmcnt(4)
	ds_write_b128 v60, v[144:147] offset:18432
	ds_write_b128 v60, v[140:143] offset:23040
	s_waitcnt vmcnt(2)
	ds_write_b128 v60, v[148:151] offset:27648
	ds_write_b128 v60, v[120:123] offset:32256
	s_waitcnt vmcnt(0)
	ds_write_b128 v60, v[156:159] offset:36864
	ds_write_b128 v60, v[152:155] offset:41472
	ds_write_b128 v60, v[108:111] offset:46080
	ds_write_b128 v60, v[100:103] offset:50688
	v_mfma_f32_32x32x16_bf16 a[80:95], v[160:163], v[128:131], a[80:95]
	v_mfma_f32_32x32x16_bf16 a[64:79], v[160:163], v[168:171], a[64:79]
	s_waitcnt lgkmcnt(12)
	v_mfma_f32_32x32x16_bf16 a[48:63], v[104:107], v[128:131], a[48:63]
	v_mfma_f32_32x32x16_bf16 a[32:47], v[104:107], v[168:171], a[32:47]
	ds_read_b128 v[100:103], v59 offset:55328
	ds_read_b128 v[104:107], v69 offset:32
	ds_read_b128 v[108:111], v69 offset:64
	ds_read_b128 v[112:115], v59 offset:55360
	ds_read_b128 v[116:119], v69 offset:4640
	ds_read_b128 v[120:123], v69 offset:96
	s_waitcnt lgkmcnt(4)
	v_mfma_f32_32x32x16_bf16 a[112:127], v[100:103], v[104:107], a[112:127]
	s_waitcnt lgkmcnt(1)
	v_mfma_f32_32x32x16_bf16 a[96:111], v[100:103], v[116:119], a[96:111]
	ds_read_b128 v[100:103], v59 offset:59936
	ds_read_b128 v[124:127], v59 offset:55392
	v_mfma_f32_32x32x16_bf16 a[16:31], v[164:167], v[128:131], a[16:31]
	v_mfma_f32_32x32x16_bf16 a[0:15], v[164:167], v[168:171], a[0:15]
	s_waitcnt lgkmcnt(1)
	v_mfma_f32_32x32x16_bf16 a[80:95], v[100:103], v[104:107], a[80:95]
	v_mfma_f32_32x32x16_bf16 a[64:79], v[100:103], v[116:119], a[64:79]
	ds_read_b128 v[100:103], v59 offset:64544
	ds_read_b128 v[128:131], v59 offset:64576
	s_waitcnt lgkmcnt(1)
	v_mfma_f32_32x32x16_bf16 a[48:63], v[100:103], v[104:107], a[48:63]
	v_mfma_f32_32x32x16_bf16 a[32:47], v[100:103], v[116:119], a[32:47]
	ds_read_b128 v[100:103], v61 offset:55328
	ds_read_b128 v[136:139], v59 offset:64608
	s_waitcnt lgkmcnt(1)
	v_mfma_f32_32x32x16_bf16 a[16:31], v[100:103], v[104:107], a[16:31]
	v_mfma_f32_32x32x16_bf16 a[0:15], v[100:103], v[116:119], a[0:15]
	ds_read_b128 v[100:103], v69 offset:4672
	ds_read_b128 v[104:107], v69 offset:4704
	v_mfma_f32_32x32x16_bf16 a[112:127], v[112:115], v[108:111], a[112:127]
	s_waitcnt lgkmcnt(1)
	v_mfma_f32_32x32x16_bf16 a[96:111], v[112:115], v[100:103], a[96:111]
	ds_read_b128 v[112:115], v59 offset:59968
	ds_read_b128 v[116:119], v59 offset:60000
	s_waitcnt lgkmcnt(1)
	v_mfma_f32_32x32x16_bf16 a[80:95], v[112:115], v[108:111], a[80:95]
	v_mfma_f32_32x32x16_bf16 a[64:79], v[112:115], v[100:103], a[64:79]
	v_mfma_f32_32x32x16_bf16 a[48:63], v[128:131], v[108:111], a[48:63]
	v_mfma_f32_32x32x16_bf16 a[32:47], v[128:131], v[100:103], a[32:47]
	ds_read_b128 v[112:115], v61 offset:55360
	ds_read_b128 v[128:131], v61 offset:55392
	s_waitcnt lgkmcnt(1)
	v_mfma_f32_32x32x16_bf16 a[16:31], v[112:115], v[108:111], a[16:31]
	v_mfma_f32_32x32x16_bf16 a[0:15], v[112:115], v[100:103], a[0:15]
	v_mfma_f32_32x32x16_bf16 a[112:127], v[124:127], v[120:123], a[112:127]
	v_mfma_f32_32x32x16_bf16 a[96:111], v[124:127], v[104:107], a[96:111]
	v_mfma_f32_32x32x16_bf16 a[80:95], v[116:119], v[120:123], a[80:95]
	v_mfma_f32_32x32x16_bf16 a[64:79], v[116:119], v[104:107], a[64:79]
	global_load_dwordx4 v[100:103], v[4:5], off offset:1408
	global_load_dwordx4 v[108:111], v[0:1], off offset:1408
	global_load_dwordx4 v[112:115], v[18:19], off offset:1408
	global_load_dwordx4 v[116:119], v[6:7], off offset:1408
	v_mfma_f32_32x32x16_bf16 a[48:63], v[136:139], v[120:123], a[48:63]
	v_mfma_f32_32x32x16_bf16 a[32:47], v[136:139], v[104:107], a[32:47]
	global_load_dwordx4 v[124:127], v[20:21], off offset:1408
	global_load_dwordx4 v[136:139], v[22:23], off offset:1408
	global_load_dwordx4 v[140:143], v[26:27], off offset:1408
	global_load_dwordx4 v[144:147], v[24:25], off offset:1408
	global_load_dwordx4 v[148:151], v[28:29], off offset:1408
	global_load_dwordx4 v[152:155], v[2:3], off offset:1408
	global_load_dwordx4 v[156:159], v[30:31], off offset:1408
	s_waitcnt lgkmcnt(0)
	v_mfma_f32_32x32x16_bf16 a[16:31], v[128:131], v[120:123], a[16:31]
	global_load_dwordx4 v[120:123], v[32:33], off offset:1408
	s_barrier
	v_mfma_f32_32x32x16_bf16 a[0:15], v[128:131], v[104:107], a[0:15]
	ds_read_b128 v[104:107], v59
	ds_read_b128 v[128:131], v62 offset:36864
	ds_read_b128 v[160:163], v59 offset:4608
	ds_read_b128 v[164:167], v61
	ds_read_b128 v[168:171], v62 offset:41472
	s_waitcnt lgkmcnt(3)
	v_mfma_f32_32x32x16_bf16 a[112:127], v[104:107], v[128:131], a[112:127]
	s_waitcnt lgkmcnt(0)
	v_mfma_f32_32x32x16_bf16 a[96:111], v[104:107], v[168:171], a[96:111]
	ds_read_b128 v[104:107], v59 offset:9216
	s_waitcnt vmcnt(10)
	ds_write_b128 v60, v[108:111] offset:55296
	ds_write_b128 v60, v[100:103] offset:59904
	s_waitcnt vmcnt(8)
	ds_write_b128 v60, v[116:119] offset:64512
	ds_write_b128 v63, v[112:115] offset:55296
	s_waitcnt vmcnt(7)
	ds_write_b128 v64, v[124:127] offset:55296
	s_waitcnt vmcnt(6)
	ds_write_b128 v65, v[136:139] offset:55296
	s_waitcnt vmcnt(4)
	ds_write_b128 v66, v[144:147] offset:55296
	ds_write_b128 v67, v[140:143] offset:55296
	s_waitcnt vmcnt(2)
	ds_write_b128 v68, v[152:155]
	ds_write_b128 v68, v[148:151] offset:4608
	s_waitcnt vmcnt(1)
	ds_write_b128 v68, v[156:159] offset:9216
	s_waitcnt vmcnt(0)
	ds_write_b128 v68, v[120:123] offset:13824
	v_mfma_f32_32x32x16_bf16 a[80:95], v[160:163], v[128:131], a[80:95]
	v_mfma_f32_32x32x16_bf16 a[64:79], v[160:163], v[168:171], a[64:79]
	s_waitcnt lgkmcnt(12)
	v_mfma_f32_32x32x16_bf16 a[48:63], v[104:107], v[128:131], a[48:63]
	v_mfma_f32_32x32x16_bf16 a[32:47], v[104:107], v[168:171], a[32:47]
	ds_read_b128 v[100:103], v59 offset:32
	ds_read_b128 v[104:107], v62 offset:36896
	ds_read_b128 v[108:111], v62 offset:36928
	ds_read_b128 v[112:115], v59 offset:64
	ds_read_b128 v[116:119], v62 offset:41504
	ds_read_b128 v[120:123], v62 offset:36960
	s_waitcnt lgkmcnt(4)
	v_mfma_f32_32x32x16_bf16 a[112:127], v[100:103], v[104:107], a[112:127]
	s_waitcnt lgkmcnt(1)
	v_mfma_f32_32x32x16_bf16 a[96:111], v[100:103], v[116:119], a[96:111]
	ds_read_b128 v[100:103], v59 offset:4640
	ds_read_b128 v[124:127], v59 offset:96
	v_mfma_f32_32x32x16_bf16 a[16:31], v[164:167], v[128:131], a[16:31]
	v_mfma_f32_32x32x16_bf16 a[0:15], v[164:167], v[168:171], a[0:15]
	s_waitcnt lgkmcnt(1)
	v_mfma_f32_32x32x16_bf16 a[80:95], v[100:103], v[104:107], a[80:95]
	v_mfma_f32_32x32x16_bf16 a[64:79], v[100:103], v[116:119], a[64:79]
	ds_read_b128 v[100:103], v59 offset:9248
	ds_read_b128 v[128:131], v59 offset:9280
	s_waitcnt lgkmcnt(1)
	v_mfma_f32_32x32x16_bf16 a[48:63], v[100:103], v[104:107], a[48:63]
	v_mfma_f32_32x32x16_bf16 a[32:47], v[100:103], v[116:119], a[32:47]
	ds_read_b128 v[100:103], v61 offset:32
	ds_read_b128 v[136:139], v59 offset:9312
	s_waitcnt lgkmcnt(1)
	v_mfma_f32_32x32x16_bf16 a[16:31], v[100:103], v[104:107], a[16:31]
	v_mfma_f32_32x32x16_bf16 a[0:15], v[100:103], v[116:119], a[0:15]
	ds_read_b128 v[100:103], v62 offset:41536
	ds_read_b128 v[104:107], v62 offset:41568
	v_mfma_f32_32x32x16_bf16 a[112:127], v[112:115], v[108:111], a[112:127]
	s_waitcnt lgkmcnt(1)
	v_mfma_f32_32x32x16_bf16 a[96:111], v[112:115], v[100:103], a[96:111]
	ds_read_b128 v[112:115], v59 offset:4672
	ds_read_b128 v[116:119], v59 offset:4704
	s_waitcnt lgkmcnt(1)
	v_mfma_f32_32x32x16_bf16 a[80:95], v[112:115], v[108:111], a[80:95]
	v_mfma_f32_32x32x16_bf16 a[64:79], v[112:115], v[100:103], a[64:79]
	v_mfma_f32_32x32x16_bf16 a[48:63], v[128:131], v[108:111], a[48:63]
	v_mfma_f32_32x32x16_bf16 a[32:47], v[128:131], v[100:103], a[32:47]
	ds_read_b128 v[112:115], v61 offset:64
	ds_read_b128 v[128:131], v61 offset:96
	s_waitcnt lgkmcnt(1)
	v_mfma_f32_32x32x16_bf16 a[16:31], v[112:115], v[108:111], a[16:31]
	v_mfma_f32_32x32x16_bf16 a[0:15], v[112:115], v[100:103], a[0:15]
	global_load_dwordx4 v[100:103], v[32:33], off offset:1536
	v_mfma_f32_32x32x16_bf16 a[112:127], v[124:127], v[120:123], a[112:127]
	v_mfma_f32_32x32x16_bf16 a[96:111], v[124:127], v[104:107], a[96:111]
	v_mfma_f32_32x32x16_bf16 a[80:95], v[116:119], v[120:123], a[80:95]
	v_mfma_f32_32x32x16_bf16 a[64:79], v[116:119], v[104:107], a[64:79]
	v_mfma_f32_32x32x16_bf16 a[48:63], v[136:139], v[120:123], a[48:63]
	v_mfma_f32_32x32x16_bf16 a[32:47], v[136:139], v[104:107], a[32:47]
	global_load_dwordx4 v[108:111], v[30:31], off offset:1536
	global_load_dwordx4 v[112:115], v[18:19], off offset:1536
	global_load_dwordx4 v[116:119], v[6:7], off offset:1536
	global_load_dwordx4 v[124:127], v[4:5], off offset:1536
	global_load_dwordx4 v[136:139], v[0:1], off offset:1536
	global_load_dwordx4 v[140:143], v[22:23], off offset:1536
	global_load_dwordx4 v[144:147], v[20:21], off offset:1536
	s_waitcnt lgkmcnt(0)
	v_mfma_f32_32x32x16_bf16 a[16:31], v[128:131], v[120:123], a[16:31]
	global_load_dwordx4 v[120:123], v[26:27], off offset:1536
	global_load_dwordx4 v[148:151], v[24:25], off offset:1536
	global_load_dwordx4 v[152:155], v[28:29], off offset:1536
	global_load_dwordx4 v[156:159], v[2:3], off offset:1536
	s_barrier
	v_mfma_f32_32x32x16_bf16 a[0:15], v[128:131], v[104:107], a[0:15]
	ds_read_b128 v[104:107], v59 offset:55296
	ds_read_b128 v[128:131], v69
	ds_read_b128 v[160:163], v59 offset:59904
	ds_read_b128 v[164:167], v61 offset:55296
	ds_read_b128 v[168:171], v69 offset:4608
	s_waitcnt lgkmcnt(3)
	v_mfma_f32_32x32x16_bf16 a[112:127], v[104:107], v[128:131], a[112:127]
	s_waitcnt lgkmcnt(0)
	v_mfma_f32_32x32x16_bf16 a[96:111], v[104:107], v[168:171], a[96:111]
	ds_read_b128 v[104:107], v59 offset:64512
	s_waitcnt vmcnt(6)
	ds_write_b128 v60, v[136:139]
	ds_write_b128 v60, v[124:127] offset:4608
	ds_write_b128 v60, v[116:119] offset:9216
	ds_write_b128 v60, v[112:115] offset:13824
	s_waitcnt vmcnt(4)
	ds_write_b128 v60, v[144:147] offset:18432
	ds_write_b128 v60, v[140:143] offset:23040
	s_waitcnt vmcnt(2)
	ds_write_b128 v60, v[148:151] offset:27648
	ds_write_b128 v60, v[120:123] offset:32256
	s_waitcnt vmcnt(0)
	ds_write_b128 v60, v[156:159] offset:36864
	ds_write_b128 v60, v[152:155] offset:41472
	ds_write_b128 v60, v[108:111] offset:46080
	ds_write_b128 v60, v[100:103] offset:50688
	v_mfma_f32_32x32x16_bf16 a[80:95], v[160:163], v[128:131], a[80:95]
	v_mfma_f32_32x32x16_bf16 a[64:79], v[160:163], v[168:171], a[64:79]
	s_waitcnt lgkmcnt(12)
	v_mfma_f32_32x32x16_bf16 a[48:63], v[104:107], v[128:131], a[48:63]
	v_mfma_f32_32x32x16_bf16 a[32:47], v[104:107], v[168:171], a[32:47]
	ds_read_b128 v[100:103], v59 offset:55328
	ds_read_b128 v[104:107], v69 offset:32
	ds_read_b128 v[108:111], v69 offset:64
	ds_read_b128 v[112:115], v59 offset:55360
	ds_read_b128 v[116:119], v69 offset:4640
	ds_read_b128 v[120:123], v69 offset:96
	s_waitcnt lgkmcnt(4)
	v_mfma_f32_32x32x16_bf16 a[112:127], v[100:103], v[104:107], a[112:127]
	s_waitcnt lgkmcnt(1)
	v_mfma_f32_32x32x16_bf16 a[96:111], v[100:103], v[116:119], a[96:111]
	ds_read_b128 v[100:103], v59 offset:59936
	ds_read_b128 v[124:127], v59 offset:55392
	v_mfma_f32_32x32x16_bf16 a[16:31], v[164:167], v[128:131], a[16:31]
	v_mfma_f32_32x32x16_bf16 a[0:15], v[164:167], v[168:171], a[0:15]
	s_waitcnt lgkmcnt(1)
	v_mfma_f32_32x32x16_bf16 a[80:95], v[100:103], v[104:107], a[80:95]
	v_mfma_f32_32x32x16_bf16 a[64:79], v[100:103], v[116:119], a[64:79]
	ds_read_b128 v[100:103], v59 offset:64544
	ds_read_b128 v[128:131], v59 offset:64576
	s_waitcnt lgkmcnt(1)
	v_mfma_f32_32x32x16_bf16 a[48:63], v[100:103], v[104:107], a[48:63]
	v_mfma_f32_32x32x16_bf16 a[32:47], v[100:103], v[116:119], a[32:47]
	ds_read_b128 v[100:103], v61 offset:55328
	ds_read_b128 v[136:139], v59 offset:64608
	s_waitcnt lgkmcnt(1)
	v_mfma_f32_32x32x16_bf16 a[16:31], v[100:103], v[104:107], a[16:31]
	v_mfma_f32_32x32x16_bf16 a[0:15], v[100:103], v[116:119], a[0:15]
	ds_read_b128 v[100:103], v69 offset:4672
	ds_read_b128 v[104:107], v69 offset:4704
	v_mfma_f32_32x32x16_bf16 a[112:127], v[112:115], v[108:111], a[112:127]
	s_waitcnt lgkmcnt(1)
	v_mfma_f32_32x32x16_bf16 a[96:111], v[112:115], v[100:103], a[96:111]
	ds_read_b128 v[112:115], v59 offset:59968
	ds_read_b128 v[116:119], v59 offset:60000
	s_waitcnt lgkmcnt(1)
	v_mfma_f32_32x32x16_bf16 a[80:95], v[112:115], v[108:111], a[80:95]
	v_mfma_f32_32x32x16_bf16 a[64:79], v[112:115], v[100:103], a[64:79]
	v_mfma_f32_32x32x16_bf16 a[48:63], v[128:131], v[108:111], a[48:63]
	v_mfma_f32_32x32x16_bf16 a[32:47], v[128:131], v[100:103], a[32:47]
	ds_read_b128 v[112:115], v61 offset:55360
	ds_read_b128 v[128:131], v61 offset:55392
	s_waitcnt lgkmcnt(1)
	v_mfma_f32_32x32x16_bf16 a[16:31], v[112:115], v[108:111], a[16:31]
	v_mfma_f32_32x32x16_bf16 a[0:15], v[112:115], v[100:103], a[0:15]
	v_mfma_f32_32x32x16_bf16 a[112:127], v[124:127], v[120:123], a[112:127]
	v_mfma_f32_32x32x16_bf16 a[96:111], v[124:127], v[104:107], a[96:111]
	v_mfma_f32_32x32x16_bf16 a[80:95], v[116:119], v[120:123], a[80:95]
	v_mfma_f32_32x32x16_bf16 a[64:79], v[116:119], v[104:107], a[64:79]
	global_load_dwordx4 v[100:103], v[4:5], off offset:1664
	global_load_dwordx4 v[108:111], v[0:1], off offset:1664
	global_load_dwordx4 v[112:115], v[18:19], off offset:1664
	global_load_dwordx4 v[116:119], v[6:7], off offset:1664
	v_mfma_f32_32x32x16_bf16 a[48:63], v[136:139], v[120:123], a[48:63]
	v_mfma_f32_32x32x16_bf16 a[32:47], v[136:139], v[104:107], a[32:47]
	global_load_dwordx4 v[124:127], v[20:21], off offset:1664
	global_load_dwordx4 v[136:139], v[22:23], off offset:1664
	global_load_dwordx4 v[140:143], v[26:27], off offset:1664
	global_load_dwordx4 v[144:147], v[24:25], off offset:1664
	global_load_dwordx4 v[148:151], v[28:29], off offset:1664
	global_load_dwordx4 v[152:155], v[2:3], off offset:1664
	global_load_dwordx4 v[156:159], v[30:31], off offset:1664
	s_waitcnt lgkmcnt(0)
	v_mfma_f32_32x32x16_bf16 a[16:31], v[128:131], v[120:123], a[16:31]
	global_load_dwordx4 v[120:123], v[32:33], off offset:1664
	s_barrier
	v_mfma_f32_32x32x16_bf16 a[0:15], v[128:131], v[104:107], a[0:15]
	ds_read_b128 v[104:107], v59
	ds_read_b128 v[128:131], v62 offset:36864
	ds_read_b128 v[160:163], v59 offset:4608
	ds_read_b128 v[164:167], v61
	ds_read_b128 v[168:171], v62 offset:41472
	s_waitcnt lgkmcnt(3)
	v_mfma_f32_32x32x16_bf16 a[112:127], v[104:107], v[128:131], a[112:127]
	s_waitcnt lgkmcnt(0)
	v_mfma_f32_32x32x16_bf16 a[96:111], v[104:107], v[168:171], a[96:111]
	ds_read_b128 v[104:107], v59 offset:9216
	s_waitcnt vmcnt(10)
	ds_write_b128 v60, v[108:111] offset:55296
	ds_write_b128 v60, v[100:103] offset:59904
	s_waitcnt vmcnt(8)
	ds_write_b128 v60, v[116:119] offset:64512
	ds_write_b128 v63, v[112:115] offset:55296
	s_waitcnt vmcnt(7)
	ds_write_b128 v64, v[124:127] offset:55296
	s_waitcnt vmcnt(6)
	ds_write_b128 v65, v[136:139] offset:55296
	s_waitcnt vmcnt(4)
	ds_write_b128 v66, v[144:147] offset:55296
	ds_write_b128 v67, v[140:143] offset:55296
	s_waitcnt vmcnt(2)
	ds_write_b128 v68, v[152:155]
	ds_write_b128 v68, v[148:151] offset:4608
	s_waitcnt vmcnt(1)
	ds_write_b128 v68, v[156:159] offset:9216
	s_waitcnt vmcnt(0)
	ds_write_b128 v68, v[120:123] offset:13824
	v_mfma_f32_32x32x16_bf16 a[80:95], v[160:163], v[128:131], a[80:95]
	v_mfma_f32_32x32x16_bf16 a[64:79], v[160:163], v[168:171], a[64:79]
	s_waitcnt lgkmcnt(12)
	v_mfma_f32_32x32x16_bf16 a[48:63], v[104:107], v[128:131], a[48:63]
	v_mfma_f32_32x32x16_bf16 a[32:47], v[104:107], v[168:171], a[32:47]
	ds_read_b128 v[100:103], v59 offset:32
	ds_read_b128 v[104:107], v62 offset:36896
	ds_read_b128 v[108:111], v62 offset:36928
	ds_read_b128 v[112:115], v59 offset:64
	ds_read_b128 v[116:119], v62 offset:41504
	ds_read_b128 v[120:123], v62 offset:36960
	s_waitcnt lgkmcnt(4)
	v_mfma_f32_32x32x16_bf16 a[112:127], v[100:103], v[104:107], a[112:127]
	s_waitcnt lgkmcnt(1)
	v_mfma_f32_32x32x16_bf16 a[96:111], v[100:103], v[116:119], a[96:111]
	ds_read_b128 v[100:103], v59 offset:4640
	ds_read_b128 v[124:127], v59 offset:96
	v_mfma_f32_32x32x16_bf16 a[16:31], v[164:167], v[128:131], a[16:31]
	v_mfma_f32_32x32x16_bf16 a[0:15], v[164:167], v[168:171], a[0:15]
	s_waitcnt lgkmcnt(1)
	v_mfma_f32_32x32x16_bf16 a[80:95], v[100:103], v[104:107], a[80:95]
	v_mfma_f32_32x32x16_bf16 a[64:79], v[100:103], v[116:119], a[64:79]
	ds_read_b128 v[100:103], v59 offset:9248
	ds_read_b128 v[128:131], v59 offset:9280
	s_waitcnt lgkmcnt(1)
	v_mfma_f32_32x32x16_bf16 a[48:63], v[100:103], v[104:107], a[48:63]
	v_mfma_f32_32x32x16_bf16 a[32:47], v[100:103], v[116:119], a[32:47]
	ds_read_b128 v[100:103], v61 offset:32
	ds_read_b128 v[136:139], v59 offset:9312
	s_waitcnt lgkmcnt(1)
	v_mfma_f32_32x32x16_bf16 a[16:31], v[100:103], v[104:107], a[16:31]
	v_mfma_f32_32x32x16_bf16 a[0:15], v[100:103], v[116:119], a[0:15]
	ds_read_b128 v[100:103], v62 offset:41536
	ds_read_b128 v[104:107], v62 offset:41568
	v_mfma_f32_32x32x16_bf16 a[112:127], v[112:115], v[108:111], a[112:127]
	s_waitcnt lgkmcnt(1)
	v_mfma_f32_32x32x16_bf16 a[96:111], v[112:115], v[100:103], a[96:111]
	ds_read_b128 v[112:115], v59 offset:4672
	ds_read_b128 v[116:119], v59 offset:4704
	s_waitcnt lgkmcnt(1)
	v_mfma_f32_32x32x16_bf16 a[80:95], v[112:115], v[108:111], a[80:95]
	v_mfma_f32_32x32x16_bf16 a[64:79], v[112:115], v[100:103], a[64:79]
	v_mfma_f32_32x32x16_bf16 a[48:63], v[128:131], v[108:111], a[48:63]
	v_mfma_f32_32x32x16_bf16 a[32:47], v[128:131], v[100:103], a[32:47]
	ds_read_b128 v[112:115], v61 offset:64
	ds_read_b128 v[128:131], v61 offset:96
	s_waitcnt lgkmcnt(1)
	v_mfma_f32_32x32x16_bf16 a[16:31], v[112:115], v[108:111], a[16:31]
	v_mfma_f32_32x32x16_bf16 a[0:15], v[112:115], v[100:103], a[0:15]
	global_load_dwordx4 v[100:103], v[32:33], off offset:1792
	v_mfma_f32_32x32x16_bf16 a[112:127], v[124:127], v[120:123], a[112:127]
	v_mfma_f32_32x32x16_bf16 a[96:111], v[124:127], v[104:107], a[96:111]
	v_mfma_f32_32x32x16_bf16 a[80:95], v[116:119], v[120:123], a[80:95]
	v_mfma_f32_32x32x16_bf16 a[64:79], v[116:119], v[104:107], a[64:79]
	v_mfma_f32_32x32x16_bf16 a[48:63], v[136:139], v[120:123], a[48:63]
	v_mfma_f32_32x32x16_bf16 a[32:47], v[136:139], v[104:107], a[32:47]
	global_load_dwordx4 v[108:111], v[30:31], off offset:1792
	global_load_dwordx4 v[112:115], v[18:19], off offset:1792
	global_load_dwordx4 v[116:119], v[6:7], off offset:1792
	global_load_dwordx4 v[124:127], v[4:5], off offset:1792
	global_load_dwordx4 v[136:139], v[0:1], off offset:1792
	global_load_dwordx4 v[140:143], v[22:23], off offset:1792
	global_load_dwordx4 v[144:147], v[20:21], off offset:1792
	s_waitcnt lgkmcnt(0)
	v_mfma_f32_32x32x16_bf16 a[16:31], v[128:131], v[120:123], a[16:31]
	global_load_dwordx4 v[120:123], v[26:27], off offset:1792
	global_load_dwordx4 v[148:151], v[24:25], off offset:1792
	global_load_dwordx4 v[152:155], v[28:29], off offset:1792
	global_load_dwordx4 v[156:159], v[2:3], off offset:1792
	s_barrier
	v_mfma_f32_32x32x16_bf16 a[0:15], v[128:131], v[104:107], a[0:15]
	ds_read_b128 v[104:107], v59 offset:55296
	ds_read_b128 v[128:131], v69
	ds_read_b128 v[160:163], v59 offset:59904
	ds_read_b128 v[164:167], v61 offset:55296
	ds_read_b128 v[168:171], v69 offset:4608
	s_waitcnt lgkmcnt(3)
	v_mfma_f32_32x32x16_bf16 a[112:127], v[104:107], v[128:131], a[112:127]
	s_waitcnt lgkmcnt(0)
	v_mfma_f32_32x32x16_bf16 a[96:111], v[104:107], v[168:171], a[96:111]
	ds_read_b128 v[104:107], v59 offset:64512
	s_waitcnt vmcnt(6)
	ds_write_b128 v60, v[136:139]
	ds_write_b128 v60, v[124:127] offset:4608
	ds_write_b128 v60, v[116:119] offset:9216
	ds_write_b128 v60, v[112:115] offset:13824
	s_waitcnt vmcnt(4)
	ds_write_b128 v60, v[144:147] offset:18432
	ds_write_b128 v60, v[140:143] offset:23040
	s_waitcnt vmcnt(2)
	ds_write_b128 v60, v[148:151] offset:27648
	ds_write_b128 v60, v[120:123] offset:32256
	s_waitcnt vmcnt(0)
	ds_write_b128 v60, v[156:159] offset:36864
	ds_write_b128 v60, v[152:155] offset:41472
	ds_write_b128 v60, v[108:111] offset:46080
	ds_write_b128 v60, v[100:103] offset:50688
	v_mfma_f32_32x32x16_bf16 a[80:95], v[160:163], v[128:131], a[80:95]
	v_mfma_f32_32x32x16_bf16 a[64:79], v[160:163], v[168:171], a[64:79]
	s_waitcnt lgkmcnt(12)
	v_mfma_f32_32x32x16_bf16 a[48:63], v[104:107], v[128:131], a[48:63]
	v_mfma_f32_32x32x16_bf16 a[32:47], v[104:107], v[168:171], a[32:47]
	ds_read_b128 v[100:103], v59 offset:55328
	ds_read_b128 v[104:107], v69 offset:32
	ds_read_b128 v[108:111], v69 offset:64
	ds_read_b128 v[112:115], v59 offset:55360
	ds_read_b128 v[116:119], v69 offset:4640
	ds_read_b128 v[120:123], v69 offset:96
	s_waitcnt lgkmcnt(4)
	v_mfma_f32_32x32x16_bf16 a[112:127], v[100:103], v[104:107], a[112:127]
	s_waitcnt lgkmcnt(1)
	v_mfma_f32_32x32x16_bf16 a[96:111], v[100:103], v[116:119], a[96:111]
	ds_read_b128 v[100:103], v59 offset:59936
	ds_read_b128 v[124:127], v59 offset:55392
	v_mfma_f32_32x32x16_bf16 a[16:31], v[164:167], v[128:131], a[16:31]
	v_mfma_f32_32x32x16_bf16 a[0:15], v[164:167], v[168:171], a[0:15]
	s_waitcnt lgkmcnt(1)
	v_mfma_f32_32x32x16_bf16 a[80:95], v[100:103], v[104:107], a[80:95]
	v_mfma_f32_32x32x16_bf16 a[64:79], v[100:103], v[116:119], a[64:79]
	ds_read_b128 v[100:103], v59 offset:64544
	ds_read_b128 v[128:131], v59 offset:64576
	s_waitcnt lgkmcnt(1)
	v_mfma_f32_32x32x16_bf16 a[48:63], v[100:103], v[104:107], a[48:63]
	v_mfma_f32_32x32x16_bf16 a[32:47], v[100:103], v[116:119], a[32:47]
	ds_read_b128 v[100:103], v61 offset:55328
	ds_read_b128 v[136:139], v59 offset:64608
	s_waitcnt lgkmcnt(1)
	v_mfma_f32_32x32x16_bf16 a[16:31], v[100:103], v[104:107], a[16:31]
	v_mfma_f32_32x32x16_bf16 a[0:15], v[100:103], v[116:119], a[0:15]
	ds_read_b128 v[100:103], v69 offset:4672
	ds_read_b128 v[104:107], v69 offset:4704
	v_mfma_f32_32x32x16_bf16 a[112:127], v[112:115], v[108:111], a[112:127]
	s_waitcnt lgkmcnt(1)
	v_mfma_f32_32x32x16_bf16 a[96:111], v[112:115], v[100:103], a[96:111]
	ds_read_b128 v[112:115], v59 offset:59968
	ds_read_b128 v[116:119], v59 offset:60000
	s_waitcnt lgkmcnt(1)
	v_mfma_f32_32x32x16_bf16 a[80:95], v[112:115], v[108:111], a[80:95]
	v_mfma_f32_32x32x16_bf16 a[64:79], v[112:115], v[100:103], a[64:79]
	v_mfma_f32_32x32x16_bf16 a[48:63], v[128:131], v[108:111], a[48:63]
	v_mfma_f32_32x32x16_bf16 a[32:47], v[128:131], v[100:103], a[32:47]
	ds_read_b128 v[112:115], v61 offset:55360
	ds_read_b128 v[128:131], v61 offset:55392
	s_waitcnt lgkmcnt(1)
	v_mfma_f32_32x32x16_bf16 a[16:31], v[112:115], v[108:111], a[16:31]
	v_mfma_f32_32x32x16_bf16 a[0:15], v[112:115], v[100:103], a[0:15]
	global_load_dwordx4 v[100:103], v[4:5], off offset:1920
	global_load_dwordx4 v[108:111], v[0:1], off offset:1920
	global_load_dwordx4 v[112:115], v[18:19], off offset:1920
	s_nop 0
	global_load_dwordx4 v[4:7], v[6:7], off offset:1920
	v_mfma_f32_32x32x16_bf16 a[112:127], v[124:127], v[120:123], a[112:127]
	v_mfma_f32_32x32x16_bf16 a[96:111], v[124:127], v[104:107], a[96:111]
	v_mfma_f32_32x32x16_bf16 a[80:95], v[116:119], v[120:123], a[80:95]
	v_mfma_f32_32x32x16_bf16 a[64:79], v[116:119], v[104:107], a[64:79]
	v_mfma_f32_32x32x16_bf16 a[48:63], v[136:139], v[120:123], a[48:63]
	v_mfma_f32_32x32x16_bf16 a[32:47], v[136:139], v[104:107], a[32:47]
	global_load_dwordx4 v[18:21], v[20:21], off offset:1920
	s_nop 0
	global_load_dwordx4 v[116:119], v[22:23], off offset:1920
	global_load_dwordx4 v[124:127], v[26:27], off offset:1920
	s_nop 0
	global_load_dwordx4 v[22:25], v[24:25], off offset:1920
	s_nop 0
	global_load_dwordx4 v[26:29], v[28:29], off offset:1920
	s_nop 0
	global_load_dwordx4 v[0:3], v[2:3], off offset:1920
	s_nop 0
	global_load_dwordx4 v[136:139], v[30:31], off offset:1920
	s_nop 0
	global_load_dwordx4 v[30:33], v[32:33], off offset:1920
	s_waitcnt lgkmcnt(0)
	s_barrier
	v_mfma_f32_32x32x16_bf16 a[16:31], v[128:131], v[120:123], a[16:31]
	v_mfma_f32_32x32x16_bf16 a[0:15], v[128:131], v[104:107], a[0:15]
	ds_read_b128 v[104:107], v59
	ds_read_b128 v[120:123], v62 offset:36864
	ds_read_b128 v[128:131], v59 offset:4608
	ds_read_b128 v[140:143], v62 offset:41472
	s_waitcnt lgkmcnt(2)
	v_mfma_f32_32x32x16_bf16 a[112:127], v[104:107], v[120:123], a[112:127]
	s_waitcnt lgkmcnt(0)
	v_mfma_f32_32x32x16_bf16 a[96:111], v[104:107], v[140:143], a[96:111]
	v_mfma_f32_32x32x16_bf16 a[80:95], v[128:131], v[120:123], a[80:95]
	v_mfma_f32_32x32x16_bf16 a[64:79], v[128:131], v[140:143], a[64:79]
	ds_read_b128 v[104:107], v59 offset:9216
	ds_read_b128 v[128:131], v61
	s_waitcnt vmcnt(10)
	ds_write_b128 v60, v[108:111] offset:55296
	ds_write_b128 v60, v[100:103] offset:59904
	s_waitcnt vmcnt(8)
	ds_write_b128 v60, v[4:7] offset:64512
	ds_write_b128 v63, v[112:115] offset:55296
	s_waitcnt vmcnt(7)
	ds_write_b128 v64, v[18:21] offset:55296
	s_waitcnt vmcnt(6)
	ds_write_b128 v65, v[116:119] offset:55296
	s_waitcnt vmcnt(4)
	ds_write_b128 v66, v[22:25] offset:55296
	ds_write_b128 v67, v[124:127] offset:55296
	s_waitcnt vmcnt(2)
	ds_write_b128 v68, v[0:3]
	ds_write_b128 v68, v[26:29] offset:4608
	s_waitcnt vmcnt(1)
	ds_write_b128 v68, v[136:139] offset:9216
	s_waitcnt lgkmcnt(12)
	v_mfma_f32_32x32x16_bf16 a[48:63], v[104:107], v[120:123], a[48:63]
	s_waitcnt vmcnt(0)
	ds_write_b128 v68, v[30:33] offset:13824
	ds_read_b128 v[0:3], v59 offset:32
	ds_read_b128 v[4:7], v62 offset:36896
	ds_read_b128 v[18:21], v62 offset:36928
	ds_read_b128 v[22:25], v59 offset:64
	ds_read_b128 v[26:29], v62 offset:41504
	ds_read_b128 v[30:33], v62 offset:36960
	v_accvgpr_read_b32 v112, a220
	v_accvgpr_read_b32 v113, a221
	v_accvgpr_read_b32 v114, a222
	v_accvgpr_read_b32 v115, a223
	v_mfma_f32_32x32x16_bf16 a[32:47], v[104:107], v[140:143], a[32:47]
	v_accvgpr_read_b32 v116, a224
	s_waitcnt lgkmcnt(4)
	v_mfma_f32_32x32x16_bf16 a[112:127], v[0:3], v[4:7], a[112:127]
	s_waitcnt lgkmcnt(1)
	v_mfma_f32_32x32x16_bf16 a[96:111], v[0:3], v[26:29], a[96:111]
	ds_read_b128 v[0:3], v59 offset:4640
	ds_read_b128 v[100:103], v59 offset:96
	v_mfma_f32_32x32x16_bf16 a[16:31], v[128:131], v[120:123], a[16:31]
	v_mfma_f32_32x32x16_bf16 a[0:15], v[128:131], v[140:143], a[0:15]
	s_waitcnt lgkmcnt(1)
	v_mfma_f32_32x32x16_bf16 a[80:95], v[0:3], v[4:7], a[80:95]
	v_mfma_f32_32x32x16_bf16 a[64:79], v[0:3], v[26:29], a[64:79]
	ds_read_b128 v[0:3], v59 offset:9248
	ds_read_b128 v[104:107], v59 offset:9280
	s_waitcnt lgkmcnt(1)
	v_mfma_f32_32x32x16_bf16 a[48:63], v[0:3], v[4:7], a[48:63]
	v_mfma_f32_32x32x16_bf16 a[32:47], v[0:3], v[26:29], a[32:47]
	ds_read_b128 v[0:3], v61 offset:32
	ds_read_b128 v[108:111], v59 offset:9312
	s_waitcnt lgkmcnt(1)
	v_mfma_f32_32x32x16_bf16 a[16:31], v[0:3], v[4:7], a[16:31]
	v_mfma_f32_32x32x16_bf16 a[0:15], v[0:3], v[26:29], a[0:15]
	ds_read_b128 v[0:3], v62 offset:41536
	ds_read_b128 v[4:7], v62 offset:41568
	v_mfma_f32_32x32x16_bf16 a[112:127], v[22:25], v[18:21], a[112:127]
	s_waitcnt lgkmcnt(1)
	v_mfma_f32_32x32x16_bf16 a[96:111], v[22:25], v[0:3], a[96:111]
	ds_read_b128 v[22:25], v59 offset:4672
	ds_read_b128 v[26:29], v59 offset:4704
	s_waitcnt lgkmcnt(1)
	v_mfma_f32_32x32x16_bf16 a[80:95], v[22:25], v[18:21], a[80:95]
	v_mfma_f32_32x32x16_bf16 a[64:79], v[22:25], v[0:3], a[64:79]
	v_mfma_f32_32x32x16_bf16 a[48:63], v[104:107], v[18:21], a[48:63]
	v_mfma_f32_32x32x16_bf16 a[32:47], v[104:107], v[0:3], a[32:47]
	ds_read_b128 v[22:25], v61 offset:64
	ds_read_b128 v[104:107], v61 offset:96
	s_waitcnt lgkmcnt(0)
	s_barrier
	v_mfma_f32_32x32x16_bf16 a[16:31], v[22:25], v[18:21], a[16:31]
	v_mfma_f32_32x32x16_bf16 a[0:15], v[22:25], v[0:3], a[0:15]
	v_mfma_f32_32x32x16_bf16 a[112:127], v[100:103], v[30:33], a[112:127]
	v_mfma_f32_32x32x16_bf16 a[96:111], v[100:103], v[4:7], a[96:111]
	v_mfma_f32_32x32x16_bf16 a[80:95], v[26:29], v[30:33], a[80:95]
	v_mfma_f32_32x32x16_bf16 a[64:79], v[26:29], v[4:7], a[64:79]
	v_mfma_f32_32x32x16_bf16 a[48:63], v[108:111], v[30:33], a[48:63]
	v_mfma_f32_32x32x16_bf16 a[32:47], v[108:111], v[4:7], a[32:47]
	v_mfma_f32_32x32x16_bf16 a[16:31], v[104:107], v[30:33], a[16:31]
	v_mfma_f32_32x32x16_bf16 a[0:15], v[104:107], v[4:7], a[0:15]
	ds_read_b128 v[0:3], v59 offset:55296
	ds_read_b128 v[4:7], v69
	ds_read_b128 v[18:21], v59 offset:55328
	ds_read_b128 v[22:25], v69 offset:32
	ds_read_b128 v[26:29], v69 offset:4608
	ds_read_b128 v[30:33], v69 offset:4640
	s_waitcnt lgkmcnt(4)
	v_mfma_f32_32x32x16_bf16 a[112:127], v[0:3], v[4:7], a[112:127]
	s_waitcnt lgkmcnt(1)
	v_mfma_f32_32x32x16_bf16 a[96:111], v[0:3], v[26:29], a[96:111]
	ds_read_b128 v[0:3], v59 offset:59904
	ds_read_b128 v[100:103], v59 offset:59936
	s_waitcnt lgkmcnt(1)
	v_mfma_f32_32x32x16_bf16 a[80:95], v[0:3], v[4:7], a[80:95]
	v_mfma_f32_32x32x16_bf16 a[64:79], v[0:3], v[26:29], a[64:79]
	ds_read_b128 v[0:3], v59 offset:64512
	ds_read_b128 v[104:107], v59 offset:64544
	s_waitcnt lgkmcnt(1)
	v_mfma_f32_32x32x16_bf16 a[48:63], v[0:3], v[4:7], a[48:63]
	v_mfma_f32_32x32x16_bf16 a[32:47], v[0:3], v[26:29], a[32:47]
	ds_read_b128 v[0:3], v61 offset:55296
	ds_read_b128 v[108:111], v61 offset:55328
	s_waitcnt lgkmcnt(1)
	v_mfma_f32_32x32x16_bf16 a[16:31], v[0:3], v[4:7], a[16:31]
	v_mfma_f32_32x32x16_bf16 a[0:15], v[0:3], v[26:29], a[0:15]
	v_mfma_f32_32x32x16_bf16 a[112:127], v[18:21], v[22:25], a[112:127]
	v_mfma_f32_32x32x16_bf16 a[96:111], v[18:21], v[30:33], a[96:111]
	v_mfma_f32_32x32x16_bf16 a[80:95], v[100:103], v[22:25], a[80:95]
	v_mfma_f32_32x32x16_bf16 a[64:79], v[100:103], v[30:33], a[64:79]
	v_mfma_f32_32x32x16_bf16 a[48:63], v[104:107], v[22:25], a[48:63]
	v_mfma_f32_32x32x16_bf16 a[32:47], v[104:107], v[30:33], a[32:47]
	s_waitcnt lgkmcnt(0)
	v_mfma_f32_32x32x16_bf16 a[16:31], v[108:111], v[22:25], a[16:31]
	ds_read_b128 v[0:3], v59 offset:55360
	ds_read_b128 v[4:7], v69 offset:64
	ds_read_b128 v[18:21], v59 offset:55392
	ds_read_b128 v[22:25], v69 offset:96
	v_mfma_f32_32x32x16_bf16 a[0:15], v[108:111], v[30:33], a[0:15]
	ds_read_b128 v[26:29], v69 offset:4672
	ds_read_b128 v[30:33], v69 offset:4704
	s_waitcnt lgkmcnt(4)
	v_mfma_f32_32x32x16_bf16 a[112:127], v[0:3], v[4:7], a[112:127]
	s_waitcnt lgkmcnt(1)
	v_mfma_f32_32x32x16_bf16 a[96:111], v[0:3], v[26:29], a[96:111]
	ds_read_b128 v[0:3], v59 offset:59968
	ds_read_b128 v[100:103], v59 offset:60000
	s_waitcnt lgkmcnt(1)
	v_mfma_f32_32x32x16_bf16 a[80:95], v[0:3], v[4:7], a[80:95]
	v_mfma_f32_32x32x16_bf16 a[64:79], v[0:3], v[26:29], a[64:79]
	ds_read_b128 v[0:3], v59 offset:64576
	ds_read_b128 v[104:107], v59 offset:64608
	s_waitcnt lgkmcnt(1)
	v_mfma_f32_32x32x16_bf16 a[48:63], v[0:3], v[4:7], a[48:63]
	v_mfma_f32_32x32x16_bf16 a[32:47], v[0:3], v[26:29], a[32:47]
	ds_read_b128 v[0:3], v61 offset:55360
	ds_read_b128 v[108:111], v61 offset:55392
	s_waitcnt lgkmcnt(0)
	s_barrier
	v_mfma_f32_32x32x16_bf16 a[16:31], v[0:3], v[4:7], a[16:31]
	v_mfma_f32_32x32x16_bf16 a[0:15], v[0:3], v[26:29], a[0:15]
	v_or_b32_e32 v0, s21, v132
	v_lshlrev_b32_e32 v8, 10, v0
	v_lshl_add_u64 v[0:1], s[22:23], 0, v[16:17]
	s_and_b64 s[22:23], s[6:7], exec
	s_cselect_b32 s22, s4, s14
	s_cselect_b32 s20, s5, s15
	s_add_u32 s22, s22, s8
	v_mfma_f32_32x32x16_bf16 a[112:127], v[18:21], v[22:25], a[112:127]
	s_addc_u32 s23, s20, 0
	v_lshlrev_b64 v[26:27], 2, v[8:9]
	v_add_co_u32_e32 v0, vcc, s19, v0
	v_or_b32_e32 v8, s21, v133
	s_nop 0
	v_addc_co_u32_e32 v1, vcc, 0, v1, vcc
	v_mfma_f32_32x32x16_bf16 a[96:111], v[18:21], v[30:33], a[96:111]
	v_lshl_add_u64 v[18:19], s[22:23], 0, v[16:17]
	v_lshl_add_u64 v[4:5], v[18:19], 0, v[26:27]
	v_lshlrev_b32_e32 v8, 10, v8
	v_lshl_add_u64 v[20:21], v[14:15], 0, s[8:9]
	s_or_b32 s20, s21, 0x80
	v_mfma_f32_32x32x16_bf16 a[80:95], v[100:103], v[22:25], a[80:95]
	v_mfma_f32_32x32x16_bf16 a[64:79], v[100:103], v[30:33], a[64:79]
	v_mfma_f32_32x32x16_bf16 a[48:63], v[104:107], v[22:25], a[48:63]
	v_mfma_f32_32x32x16_bf16 a[32:47], v[104:107], v[30:33], a[32:47]
	v_mfma_f32_32x32x16_bf16 a[16:31], v[108:111], v[22:25], a[16:31]
	v_lshlrev_b64 v[22:23], 2, v[8:9]
	v_lshl_add_u64 v[24:25], v[20:21], 0, v[26:27]
	v_lshl_add_u64 v[26:27], v[18:19], 0, v[22:23]
	v_or_b32_e32 v8, s21, v112
	v_lshlrev_b32_e32 v8, 10, v8
	v_lshl_add_u64 v[22:23], v[20:21], 0, v[22:23]
	v_mfma_f32_32x32x16_bf16 a[0:15], v[108:111], v[30:33], a[0:15]
	ds_write_b32 v58, a112
	ds_write_b32 v58, a113 offset:516
	ds_write_b32 v58, a114 offset:1032
	ds_write_b32 v58, a115 offset:1548
	ds_write_b32 v58, a116 offset:4128
	ds_write_b32 v58, a117 offset:4644
	ds_write_b32 v58, a118 offset:5160
	ds_write_b32 v58, a119 offset:5676
	ds_write_b32 v58, a120 offset:8256
	ds_write_b32 v58, a121 offset:8772
	ds_write_b32 v58, a122 offset:9288
	ds_write_b32 v58, a123 offset:9804
	ds_write_b32 v58, a124 offset:12384
	ds_write_b32 v58, a125 offset:12900
	ds_write_b32 v58, a126 offset:13416
	ds_write_b32 v58, a127 offset:13932
	ds_write_b32 v58, a96 offset:128
	ds_write_b32 v58, a97 offset:644
	ds_write_b32 v58, a98 offset:1160
	ds_write_b32 v58, a99 offset:1676
	ds_write_b32 v58, a100 offset:4256
	ds_write_b32 v58, a101 offset:4772
	ds_write_b32 v58, a102 offset:5288
	ds_write_b32 v58, a103 offset:5804
	ds_write_b32 v58, a104 offset:8384
	ds_write_b32 v58, a105 offset:8900
	ds_write_b32 v58, a106 offset:9416
	ds_write_b32 v58, a107 offset:9932
	ds_write_b32 v58, a108 offset:12512
	ds_write_b32 v58, a109 offset:13028
	ds_write_b32 v58, a110 offset:13544
	ds_write_b32 v58, a111 offset:14060
	ds_write_b32 v58, a80 offset:16512
	ds_write_b32 v58, a81 offset:17028
	ds_write_b32 v58, a82 offset:17544
	ds_write_b32 v58, a83 offset:18060
	ds_write_b32 v58, a84 offset:20640
	ds_write_b32 v58, a85 offset:21156
	ds_write_b32 v58, a86 offset:21672
	ds_write_b32 v58, a87 offset:22188
	ds_write_b32 v58, a88 offset:24768
	ds_write_b32 v58, a89 offset:25284
	ds_write_b32 v58, a90 offset:25800
	ds_write_b32 v58, a91 offset:26316
	ds_write_b32 v58, a92 offset:28896
	ds_write_b32 v58, a93 offset:29412
	ds_write_b32 v58, a94 offset:29928
	ds_write_b32 v58, a95 offset:30444
	ds_write_b32 v58, a64 offset:16640
	ds_write_b32 v58, a65 offset:17156
	ds_write_b32 v58, a66 offset:17672
	ds_write_b32 v58, a67 offset:18188
	ds_write_b32 v58, a68 offset:20768
	ds_write_b32 v58, a69 offset:21284
	ds_write_b32 v58, a70 offset:21800
	ds_write_b32 v58, a71 offset:22316
	ds_write_b32 v58, a72 offset:24896
	ds_write_b32 v58, a73 offset:25412
	ds_write_b32 v58, a74 offset:25928
	ds_write_b32 v58, a75 offset:26444
	ds_write_b32 v58, a76 offset:29024
	ds_write_b32 v58, a77 offset:29540
	ds_write_b32 v58, a78 offset:30056
	ds_write_b32 v58, a79 offset:30572
	ds_write_b32 v58, a48 offset:33024
	ds_write_b32 v58, a49 offset:33540
	ds_write_b32 v58, a50 offset:34056
	ds_write_b32 v58, a51 offset:34572
	ds_write_b32 v58, a52 offset:37152
	ds_write_b32 v58, a53 offset:37668
	ds_write_b32 v58, a54 offset:38184
	ds_write_b32 v58, a55 offset:38700
	ds_write_b32 v58, a56 offset:41280
	ds_write_b32 v58, a57 offset:41796
	ds_write_b32 v58, a58 offset:42312
	ds_write_b32 v58, a59 offset:42828
	ds_write_b32 v58, a60 offset:45408
	ds_write_b32 v58, a61 offset:45924
	ds_write_b32 v58, a62 offset:46440
	ds_write_b32 v58, a63 offset:46956
	ds_write_b32 v58, a32 offset:33152
	ds_write_b32 v58, a33 offset:33668
	ds_write_b32 v58, a34 offset:34184
	ds_write_b32 v58, a35 offset:34700
	ds_write_b32 v58, a36 offset:37280
	ds_write_b32 v58, a37 offset:37796
	ds_write_b32 v58, a38 offset:38312
	ds_write_b32 v58, a39 offset:38828
	ds_write_b32 v58, a40 offset:41408
	ds_write_b32 v58, a41 offset:41924
	ds_write_b32 v58, a42 offset:42440
	ds_write_b32 v58, a43 offset:42956
	ds_write_b32 v58, a44 offset:45536
	ds_write_b32 v58, a45 offset:46052
	ds_write_b32 v58, a46 offset:46568
	ds_write_b32 v58, a47 offset:47084
	ds_write_b32 v58, a16 offset:49536
	ds_write_b32 v58, a17 offset:50052
	ds_write_b32 v58, a18 offset:50568
	ds_write_b32 v58, a19 offset:51084
	ds_write_b32 v58, a20 offset:53664
	ds_write_b32 v58, a21 offset:54180
	ds_write_b32 v58, a22 offset:54696
	ds_write_b32 v58, a23 offset:55212
	ds_write_b32 v58, a24 offset:57792
	ds_write_b32 v58, a25 offset:58308
	ds_write_b32 v58, a26 offset:58824
	ds_write_b32 v58, a27 offset:59340
	ds_write_b32 v58, a28 offset:61920
	ds_write_b32 v58, a29 offset:62436
	ds_write_b32 v58, a30 offset:62952
	ds_write_b32 v58, a31 offset:63468
	ds_write_b32 v58, a0 offset:49664
	ds_write_b32 v58, a1 offset:50180
	ds_write_b32 v58, a2 offset:50696
	ds_write_b32 v58, a3 offset:51212
	ds_write_b32 v58, a4 offset:53792
	ds_write_b32 v58, a5 offset:54308
	ds_write_b32 v58, a6 offset:54824
	ds_write_b32 v58, a7 offset:55340
	ds_write_b32 v58, a8 offset:57920
	ds_write_b32 v58, a9 offset:58436
	ds_write_b32 v58, a10 offset:58952
	ds_write_b32 v58, a11 offset:59468
	ds_write_b32 v58, a12 offset:62048
	ds_write_b32 v58, a13 offset:62564
	ds_write_b32 v58, a14 offset:63080
	ds_write_b32 v58, a15 offset:63596
	s_waitcnt lgkmcnt(0)
	s_barrier
	global_load_dwordx4 v[0:3], v[0:1], off
	s_nop 0
	v_mov_b32_e32 v110, v8
	v_mov_b32_e32 v111, v9
	v_mov_b32_e32 v118, v22
	v_mov_b32_e32 v119, v23
	v_mov_b32_e32 v120, v24
	v_mov_b32_e32 v121, v25
	v_mov_b32_e32 v122, v26
	v_mov_b32_e32 v123, v27
	global_load_dwordx4 v[250:253], v[4:5], off
	global_load_dwordx4 v[246:249], v[122:123], off
	v_lshlrev_b64 v[120:121], 2, v[110:111]
	v_lshl_add_u64 v[122:123], v[18:19], 0, v[120:121]
	v_or_b32_e32 v110, s21, v113
	v_lshlrev_b32_e32 v110, 10, v110
	global_load_dwordx4 v[242:245], v[122:123], off
	v_lshlrev_b64 v[118:119], 2, v[110:111]
	v_lshl_add_u64 v[122:123], v[18:19], 0, v[118:119]
	v_or_b32_e32 v110, s21, v114
	v_lshlrev_b32_e32 v110, 10, v110
	global_load_dwordx4 v[238:241], v[122:123], off
	v_lshlrev_b64 v[120:121], 2, v[110:111]
	v_lshl_add_u64 v[122:123], v[18:19], 0, v[120:121]
	v_or_b32_e32 v110, s21, v115
	v_lshlrev_b32_e32 v110, 10, v110
	global_load_dwordx4 v[234:237], v[122:123], off
	v_lshlrev_b64 v[118:119], 2, v[110:111]
	v_lshl_add_u64 v[122:123], v[18:19], 0, v[118:119]
	v_or_b32_e32 v110, s21, v116
	v_lshlrev_b32_e32 v110, 10, v110
	global_load_dwordx4 v[212:215], v[122:123], off
	v_lshlrev_b64 v[120:121], 2, v[110:111]
	v_lshl_add_u64 v[122:123], v[18:19], 0, v[120:121]
	v_or_b32_e32 v110, s21, v135
	v_lshlrev_b32_e32 v110, 10, v110
	global_load_dwordx4 v[208:211], v[122:123], off
	v_lshlrev_b64 v[118:119], 2, v[110:111]
	v_lshl_add_u64 v[122:123], v[18:19], 0, v[118:119]
	v_or_b32_e32 v110, s21, v200
	v_lshlrev_b32_e32 v110, 10, v110
	global_load_dwordx4 v[204:207], v[122:123], off
	v_lshlrev_b64 v[120:121], 2, v[110:111]
	v_lshl_add_u64 v[122:123], v[18:19], 0, v[120:121]
	v_or_b32_e32 v110, s21, v35
	v_lshlrev_b32_e32 v110, 10, v110
	global_load_dwordx4 v[196:199], v[122:123], off
	v_lshlrev_b64 v[120:121], 2, v[110:111]
	v_lshl_add_u64 v[122:123], v[18:19], 0, v[120:121]
	v_or_b32_e32 v110, s21, v36
	v_lshlrev_b32_e32 v110, 10, v110
	global_load_dwordx4 v[192:195], v[122:123], off
	v_lshlrev_b64 v[120:121], 2, v[110:111]
	v_lshl_add_u64 v[122:123], v[18:19], 0, v[120:121]
	v_or_b32_e32 v110, s21, v37
	v_lshlrev_b32_e32 v110, 10, v110
	global_load_dwordx4 v[188:191], v[122:123], off
	v_lshlrev_b64 v[120:121], 2, v[110:111]
	v_lshl_add_u64 v[122:123], v[18:19], 0, v[120:121]
	v_or_b32_e32 v110, s21, v38
	v_lshlrev_b32_e32 v110, 10, v110
	global_load_dwordx4 v[184:187], v[122:123], off
	v_lshlrev_b64 v[120:121], 2, v[110:111]
	v_lshl_add_u64 v[122:123], v[18:19], 0, v[120:121]
	v_or_b32_e32 v110, s21, v39
	v_lshlrev_b32_e32 v110, 10, v110
	global_load_dwordx4 v[180:183], v[122:123], off
	v_lshlrev_b64 v[120:121], 2, v[110:111]
	v_lshl_add_u64 v[122:123], v[18:19], 0, v[120:121]
	v_or_b32_e32 v110, s21, v40
	v_lshlrev_b32_e32 v110, 10, v110
	global_load_dwordx4 v[176:179], v[122:123], off
	v_lshlrev_b64 v[120:121], 2, v[110:111]
	v_lshl_add_u64 v[122:123], v[18:19], 0, v[120:121]
	v_or_b32_e32 v110, s21, v41
	v_lshlrev_b32_e32 v110, 10, v110
	global_load_dwordx4 v[172:175], v[122:123], off
	v_lshlrev_b64 v[120:121], 2, v[110:111]
	v_lshl_add_u64 v[122:123], v[18:19], 0, v[120:121]
	global_load_dwordx4 v[168:171], v[122:123], off
	s_waitcnt vmcnt(15)
	s_nop 1
	v_mov_b64_e32 v[4:5], v[250:251]
	v_mov_b64_e32 v[6:7], v[252:253]
	ds_read2_b32 v[28:29], v34 offset0:2 offset1:3
	ds_read2_b32 v[30:31], v42 offset1:1
	ds_read2_b32 v[32:33], v42 offset0:2 offset1:3
	ds_read2_b32 v[100:101], v34 offset1:1
	s_waitcnt lgkmcnt(3)
	v_pk_fma_f32 v[6:7], v[2:3], v[28:29], v[6:7]
	s_waitcnt lgkmcnt(0)
	v_pk_fma_f32 v[4:5], v[0:1], v[100:101], v[4:5]
	global_store_dwordx4 v[24:25], v[4:7], off
	s_waitcnt vmcnt(15)
	s_nop 1
	v_mov_b64_e32 v[4:5], v[246:247]
	v_mov_b64_e32 v[6:7], v[248:249]
	ds_read2_b32 v[28:29], v71 offset1:1
	ds_read2_b32 v[100:101], v72 offset1:1
	ds_read2_b32 v[102:103], v73 offset1:1
	ds_read2_b32 v[104:105], v70 offset1:1
	v_lshlrev_b64 v[24:25], 2, v[8:9]
	v_lshl_add_u64 v[26:27], v[18:19], 0, v[24:25]
	v_or_b32_e32 v8, s21, v113
	v_lshlrev_b32_e32 v8, 10, v8
	v_lshl_add_u64 v[24:25], v[20:21], 0, v[24:25]
	s_waitcnt lgkmcnt(3)
	v_pk_fma_f32 v[6:7], v[2:3], v[28:29], v[6:7]
	s_waitcnt lgkmcnt(0)
	v_pk_fma_f32 v[4:5], v[0:1], v[104:105], v[4:5]
	global_store_dwordx4 v[22:23], v[4:7], off
	s_waitcnt vmcnt(15)
	s_nop 1
	v_mov_b64_e32 v[4:5], v[242:243]
	v_mov_b64_e32 v[6:7], v[244:245]
	v_lshlrev_b64 v[22:23], 2, v[8:9]
	v_lshl_add_u64 v[26:27], v[18:19], 0, v[22:23]
	v_or_b32_e32 v8, s21, v114
	v_lshlrev_b32_e32 v8, 10, v8
	v_lshl_add_u64 v[22:23], v[20:21], 0, v[22:23]
	v_pk_fma_f32 v[6:7], v[2:3], v[102:103], v[6:7]
	v_pk_fma_f32 v[4:5], v[0:1], v[100:101], v[4:5]
	global_store_dwordx4 v[24:25], v[4:7], off
	s_waitcnt vmcnt(15)
	s_nop 1
	v_mov_b64_e32 v[4:5], v[238:239]
	v_mov_b64_e32 v[6:7], v[240:241]
	ds_read2_b32 v[28:29], v75 offset1:1
	ds_read2_b32 v[100:101], v76 offset1:1
	ds_read2_b32 v[102:103], v77 offset1:1
	ds_read2_b32 v[104:105], v74 offset1:1
	v_lshlrev_b64 v[24:25], 2, v[8:9]
	v_lshl_add_u64 v[26:27], v[18:19], 0, v[24:25]
	v_or_b32_e32 v8, s21, v115
	v_lshlrev_b32_e32 v8, 10, v8
	v_lshl_add_u64 v[24:25], v[20:21], 0, v[24:25]
	s_waitcnt lgkmcnt(3)
	v_pk_fma_f32 v[6:7], v[2:3], v[28:29], v[6:7]
	s_waitcnt lgkmcnt(0)
	v_pk_fma_f32 v[4:5], v[0:1], v[104:105], v[4:5]
	global_store_dwordx4 v[22:23], v[4:7], off
	s_waitcnt vmcnt(15)
	s_nop 1
	v_mov_b64_e32 v[4:5], v[234:235]
	v_mov_b64_e32 v[6:7], v[236:237]
	v_lshlrev_b64 v[22:23], 2, v[8:9]
	v_lshl_add_u64 v[26:27], v[18:19], 0, v[22:23]
	v_or_b32_e32 v8, s21, v116
	v_lshlrev_b32_e32 v8, 10, v8
	v_lshl_add_u64 v[22:23], v[20:21], 0, v[22:23]
	v_pk_fma_f32 v[6:7], v[2:3], v[102:103], v[6:7]
	v_pk_fma_f32 v[4:5], v[0:1], v[100:101], v[4:5]
	global_store_dwordx4 v[24:25], v[4:7], off
	s_waitcnt vmcnt(15)
	s_nop 1
	v_mov_b64_e32 v[4:5], v[212:213]
	v_mov_b64_e32 v[6:7], v[214:215]
	ds_read2_b32 v[28:29], v79 offset1:1
	ds_read2_b32 v[100:101], v80 offset1:1
	ds_read2_b32 v[102:103], v81 offset1:1
	ds_read2_b32 v[104:105], v78 offset1:1
	v_lshlrev_b64 v[24:25], 2, v[8:9]
	v_lshl_add_u64 v[26:27], v[18:19], 0, v[24:25]
	v_or_b32_e32 v8, s21, v135
	v_lshlrev_b32_e32 v8, 10, v8
	v_lshl_add_u64 v[24:25], v[20:21], 0, v[24:25]
	s_waitcnt lgkmcnt(3)
	v_pk_fma_f32 v[6:7], v[2:3], v[28:29], v[6:7]
	s_waitcnt lgkmcnt(0)
	v_pk_fma_f32 v[4:5], v[0:1], v[104:105], v[4:5]
	global_store_dwordx4 v[22:23], v[4:7], off
	s_waitcnt vmcnt(15)
	s_nop 1
	v_mov_b64_e32 v[4:5], v[208:209]
	v_mov_b64_e32 v[6:7], v[210:211]
	v_lshlrev_b64 v[22:23], 2, v[8:9]
	v_lshl_add_u64 v[26:27], v[18:19], 0, v[22:23]
	v_or_b32_e32 v8, s21, v200
	v_lshlrev_b32_e32 v8, 10, v8
	v_lshl_add_u64 v[22:23], v[20:21], 0, v[22:23]
	v_pk_fma_f32 v[6:7], v[2:3], v[102:103], v[6:7]
	v_pk_fma_f32 v[4:5], v[0:1], v[100:101], v[4:5]
	global_store_dwordx4 v[24:25], v[4:7], off
	s_waitcnt vmcnt(15)
	s_nop 1
	v_mov_b64_e32 v[4:5], v[204:205]
	v_mov_b64_e32 v[6:7], v[206:207]
	ds_read2_b32 v[28:29], v83 offset1:1
	ds_read2_b32 v[100:101], v84 offset1:1
	ds_read2_b32 v[102:103], v85 offset1:1
	ds_read2_b32 v[104:105], v82 offset1:1
	v_lshlrev_b64 v[24:25], 2, v[8:9]
	v_lshl_add_u64 v[26:27], v[18:19], 0, v[24:25]
	v_or_b32_e32 v8, s21, v35
	v_lshlrev_b32_e32 v8, 10, v8
	s_waitcnt lgkmcnt(3)
	v_pk_fma_f32 v[6:7], v[2:3], v[28:29], v[6:7]
	s_waitcnt lgkmcnt(0)
	v_pk_fma_f32 v[4:5], v[0:1], v[104:105], v[4:5]
	global_store_dwordx4 v[22:23], v[4:7], off
	s_waitcnt vmcnt(15)
	s_nop 1
	v_mov_b64_e32 v[4:5], v[196:197]
	v_mov_b64_e32 v[6:7], v[198:199]
	v_lshl_add_u64 v[22:23], v[20:21], 0, v[24:25]
	v_lshlrev_b64 v[24:25], 2, v[8:9]
	v_lshl_add_u64 v[26:27], v[18:19], 0, v[24:25]
	v_or_b32_e32 v8, s21, v36
	v_lshlrev_b32_e32 v8, 10, v8
	v_pk_fma_f32 v[6:7], v[2:3], v[102:103], v[6:7]
	v_pk_fma_f32 v[4:5], v[0:1], v[100:101], v[4:5]
	global_store_dwordx4 v[22:23], v[4:7], off
	s_waitcnt vmcnt(15)
	s_nop 1
	v_mov_b64_e32 v[4:5], v[192:193]
	v_mov_b64_e32 v[6:7], v[194:195]
	ds_read2_b32 v[28:29], v87 offset1:1
	ds_read2_b32 v[100:101], v88 offset1:1
	ds_read2_b32 v[102:103], v89 offset1:1
	ds_read2_b32 v[104:105], v86 offset1:1
	v_lshl_add_u64 v[22:23], v[20:21], 0, v[24:25]
	v_lshlrev_b64 v[24:25], 2, v[8:9]
	v_lshl_add_u64 v[26:27], v[18:19], 0, v[24:25]
	v_or_b32_e32 v8, s21, v37
	v_lshlrev_b32_e32 v8, 10, v8
	s_waitcnt lgkmcnt(3)
	v_pk_fma_f32 v[6:7], v[2:3], v[28:29], v[6:7]
	s_waitcnt lgkmcnt(0)
	v_pk_fma_f32 v[4:5], v[0:1], v[104:105], v[4:5]
	global_store_dwordx4 v[22:23], v[4:7], off
	s_waitcnt vmcnt(15)
	s_nop 1
	v_mov_b64_e32 v[4:5], v[188:189]
	v_mov_b64_e32 v[6:7], v[190:191]
	v_lshl_add_u64 v[22:23], v[20:21], 0, v[24:25]
	v_lshlrev_b64 v[24:25], 2, v[8:9]
	v_lshl_add_u64 v[26:27], v[18:19], 0, v[24:25]
	v_or_b32_e32 v8, s21, v38
	v_lshlrev_b32_e32 v8, 10, v8
	v_pk_fma_f32 v[6:7], v[2:3], v[102:103], v[6:7]
	v_pk_fma_f32 v[4:5], v[0:1], v[100:101], v[4:5]
	global_store_dwordx4 v[22:23], v[4:7], off
	s_waitcnt vmcnt(15)
	s_nop 1
	v_mov_b64_e32 v[4:5], v[184:185]
	v_mov_b64_e32 v[6:7], v[186:187]
	ds_read2_b32 v[28:29], v91 offset1:1
	ds_read2_b32 v[100:101], v92 offset1:1
	ds_read2_b32 v[102:103], v93 offset1:1
	ds_read2_b32 v[104:105], v90 offset1:1
	v_lshl_add_u64 v[22:23], v[20:21], 0, v[24:25]
	v_lshlrev_b64 v[24:25], 2, v[8:9]
	v_lshl_add_u64 v[26:27], v[18:19], 0, v[24:25]
	v_or_b32_e32 v8, s21, v39
	v_lshlrev_b32_e32 v8, 10, v8
	s_waitcnt lgkmcnt(3)
	v_pk_fma_f32 v[6:7], v[2:3], v[28:29], v[6:7]
	s_waitcnt lgkmcnt(0)
	v_pk_fma_f32 v[4:5], v[0:1], v[104:105], v[4:5]
	global_store_dwordx4 v[22:23], v[4:7], off
	s_waitcnt vmcnt(15)
	s_nop 1
	v_mov_b64_e32 v[4:5], v[180:181]
	v_mov_b64_e32 v[6:7], v[182:183]
	v_lshl_add_u64 v[22:23], v[20:21], 0, v[24:25]
	v_lshlrev_b64 v[24:25], 2, v[8:9]
	v_lshl_add_u64 v[26:27], v[18:19], 0, v[24:25]
	v_or_b32_e32 v8, s21, v40
	v_lshlrev_b32_e32 v8, 10, v8
	v_pk_fma_f32 v[6:7], v[2:3], v[102:103], v[6:7]
	v_pk_fma_f32 v[4:5], v[0:1], v[100:101], v[4:5]
	global_store_dwordx4 v[22:23], v[4:7], off
	s_waitcnt vmcnt(15)
	s_nop 1
	v_mov_b64_e32 v[4:5], v[176:177]
	v_mov_b64_e32 v[6:7], v[178:179]
	ds_read2_b32 v[28:29], v95 offset1:1
	ds_read2_b32 v[100:101], v96 offset1:1
	ds_read2_b32 v[102:103], v97 offset1:1
	ds_read2_b32 v[104:105], v94 offset1:1
	v_lshl_add_u64 v[22:23], v[20:21], 0, v[24:25]
	v_lshlrev_b64 v[24:25], 2, v[8:9]
	v_lshl_add_u64 v[26:27], v[18:19], 0, v[24:25]
	v_or_b32_e32 v8, s21, v41
	v_lshlrev_b32_e32 v8, 10, v8
	s_addk_i32 s21, 0xe080
	s_lshr_b32 s21, s21, 12
	s_add_i32 s21, s21, 1
	s_and_b64 s[6:7], s[6:7], exec
	s_cselect_b32 s6, 0, s21
	s_mul_hi_u32 s7, s6, 0x6000
	s_mulk_i32 s6, 0x6000
	s_add_u32 s6, s2, s6
	s_addc_u32 s7, s3, s7
	s_add_u32 s6, s6, s8
	s_addc_u32 s7, s7, 0
	s_add_i32 s10, s10, s79
	s_cmpk_lt_u32 s10, 0x60
	s_waitcnt lgkmcnt(3)
	v_pk_fma_f32 v[6:7], v[2:3], v[28:29], v[6:7]
	s_waitcnt lgkmcnt(0)
	v_pk_fma_f32 v[4:5], v[0:1], v[104:105], v[4:5]
	global_store_dwordx4 v[22:23], v[4:7], off
	s_waitcnt vmcnt(15)
	s_nop 1
	v_mov_b64_e32 v[4:5], v[172:173]
	v_mov_b64_e32 v[6:7], v[174:175]
	v_lshl_add_u64 v[22:23], v[20:21], 0, v[24:25]
	v_lshlrev_b64 v[24:25], 2, v[8:9]
	v_lshl_add_u64 v[26:27], v[18:19], 0, v[24:25]
	v_or_b32_e32 v8, s20, v132
	v_lshl_add_u64 v[28:29], s[6:7], 0, v[16:17]
	v_lshlrev_b32_e32 v8, 10, v8
	v_add_co_u32_e32 v28, vcc, s19, v28
	v_pk_fma_f32 v[6:7], v[2:3], v[102:103], v[6:7]
	v_pk_fma_f32 v[4:5], v[0:1], v[100:101], v[4:5]
	global_store_dwordx4 v[22:23], v[4:7], off
	s_waitcnt vmcnt(15)
	s_nop 1
	v_mov_b64_e32 v[4:5], v[168:169]
	v_mov_b64_e32 v[6:7], v[170:171]
	ds_read2_b32 v[100:101], v99 offset1:1
	ds_read2_b32 v[102:103], v98 offset1:1
	v_lshl_add_u64 v[22:23], v[20:21], 0, v[24:25]
	v_lshlrev_b64 v[24:25], 2, v[8:9]
	v_addc_co_u32_e32 v29, vcc, 0, v29, vcc
	v_lshl_add_u64 v[26:27], v[18:19], 0, v[24:25]
	v_or_b32_e32 v8, s20, v133
	v_lshlrev_b32_e32 v8, 10, v8
	s_waitcnt lgkmcnt(1)
	v_pk_fma_f32 v[2:3], v[2:3], v[100:101], v[6:7]
	s_waitcnt lgkmcnt(0)
	v_pk_fma_f32 v[0:1], v[0:1], v[102:103], v[4:5]
	global_store_dwordx4 v[22:23], v[0:3], off
	global_load_dwordx4 v[0:3], v[28:29], off
	s_nop 0
	v_mov_b32_e32 v104, v8
	v_mov_b32_e32 v105, v9
	v_mov_b32_e32 v110, v18
	v_mov_b32_e32 v111, v19
	v_mov_b32_e32 v118, v24
	v_mov_b32_e32 v119, v25
	v_mov_b32_e32 v120, v26
	v_mov_b32_e32 v121, v27
	global_load_dwordx4 v[250:253], v[120:121], off
	v_lshlrev_b64 v[118:119], 2, v[104:105]
	v_lshl_add_u64 v[120:121], v[110:111], 0, v[118:119]
	v_or_b32_e32 v104, s20, v112
	v_lshlrev_b32_e32 v104, 10, v104
	global_load_dwordx4 v[246:249], v[120:121], off
	v_lshlrev_b64 v[118:119], 2, v[104:105]
	v_lshl_add_u64 v[120:121], v[110:111], 0, v[118:119]
	v_or_b32_e32 v104, s20, v113
	v_lshlrev_b32_e32 v104, 10, v104
	global_load_dwordx4 v[242:245], v[120:121], off
	v_lshlrev_b64 v[118:119], 2, v[104:105]
	v_lshl_add_u64 v[120:121], v[110:111], 0, v[118:119]
	v_or_b32_e32 v104, s20, v114
	v_lshlrev_b32_e32 v104, 10, v104
	global_load_dwordx4 v[238:241], v[120:121], off
	v_lshlrev_b64 v[118:119], 2, v[104:105]
	v_lshl_add_u64 v[120:121], v[110:111], 0, v[118:119]
	v_or_b32_e32 v104, s20, v115
	v_lshlrev_b32_e32 v104, 10, v104
	global_load_dwordx4 v[234:237], v[120:121], off
	v_lshlrev_b64 v[118:119], 2, v[104:105]
	v_lshl_add_u64 v[120:121], v[110:111], 0, v[118:119]
	v_or_b32_e32 v104, s20, v116
	v_lshlrev_b32_e32 v104, 10, v104
	global_load_dwordx4 v[212:215], v[120:121], off
	v_lshlrev_b64 v[118:119], 2, v[104:105]
	v_lshl_add_u64 v[120:121], v[110:111], 0, v[118:119]
	v_or_b32_e32 v104, s20, v135
	v_lshlrev_b32_e32 v104, 10, v104
	global_load_dwordx4 v[208:211], v[120:121], off
	v_lshlrev_b64 v[118:119], 2, v[104:105]
	v_lshl_add_u64 v[120:121], v[110:111], 0, v[118:119]
	v_or_b32_e32 v104, s20, v200
	v_lshlrev_b32_e32 v104, 10, v104
	global_load_dwordx4 v[204:207], v[120:121], off
	v_lshlrev_b64 v[118:119], 2, v[104:105]
	v_lshl_add_u64 v[120:121], v[110:111], 0, v[118:119]
	v_or_b32_e32 v104, s20, v35
	v_lshlrev_b32_e32 v104, 10, v104
	global_load_dwordx4 v[196:199], v[120:121], off
	v_lshlrev_b64 v[118:119], 2, v[104:105]
	v_lshl_add_u64 v[120:121], v[110:111], 0, v[118:119]
	v_or_b32_e32 v104, s20, v36
	v_lshlrev_b32_e32 v104, 10, v104
	global_load_dwordx4 v[192:195], v[120:121], off
	v_lshlrev_b64 v[118:119], 2, v[104:105]
	v_lshl_add_u64 v[120:121], v[110:111], 0, v[118:119]
	v_or_b32_e32 v104, s20, v37
	v_lshlrev_b32_e32 v104, 10, v104
	global_load_dwordx4 v[188:191], v[120:121], off
	v_lshlrev_b64 v[118:119], 2, v[104:105]
	v_lshl_add_u64 v[120:121], v[110:111], 0, v[118:119]
	v_or_b32_e32 v104, s20, v38
	v_lshlrev_b32_e32 v104, 10, v104
	global_load_dwordx4 v[184:187], v[120:121], off
	v_lshlrev_b64 v[118:119], 2, v[104:105]
	v_lshl_add_u64 v[120:121], v[110:111], 0, v[118:119]
	v_add_lshl_u32 v104, s20, v39, 10
	global_load_dwordx4 v[180:183], v[120:121], off
	v_lshlrev_b64 v[118:119], 2, v[104:105]
	v_lshl_add_u64 v[120:121], v[110:111], 0, v[118:119]
	v_add_lshl_u32 v104, s20, v40, 10
	global_load_dwordx4 v[176:179], v[120:121], off
	v_lshlrev_b64 v[118:119], 2, v[104:105]
	v_lshl_add_u64 v[120:121], v[110:111], 0, v[118:119]
	v_add_lshl_u32 v104, s20, v41, 10
	global_load_dwordx4 v[172:175], v[120:121], off
	v_lshlrev_b64 v[118:119], 2, v[104:105]
	v_lshl_add_u64 v[110:111], v[110:111], 0, v[118:119]
	global_load_dwordx4 v[168:171], v[110:111], off
	s_waitcnt vmcnt(15)
	s_nop 1
	v_mov_b64_e32 v[4:5], v[250:251]
	v_mov_b64_e32 v[6:7], v[252:253]
	v_lshl_add_u64 v[22:23], v[20:21], 0, v[24:25]
	v_lshlrev_b64 v[24:25], 2, v[8:9]
	v_lshl_add_u64 v[26:27], v[18:19], 0, v[24:25]
	v_or_b32_e32 v8, s20, v112
	v_lshlrev_b32_e32 v8, 10, v8
	v_pk_fma_f32 v[6:7], v[2:3], v[32:33], v[6:7]
	v_pk_fma_f32 v[4:5], v[0:1], v[30:31], v[4:5]
	global_store_dwordx4 v[22:23], v[4:7], off
	s_waitcnt vmcnt(15)
	s_nop 1
	v_mov_b64_e32 v[4:5], v[246:247]
	v_mov_b64_e32 v[6:7], v[248:249]
	ds_read2_b32 v[28:29], v43 offset0:2 offset1:3
	ds_read2_b32 v[30:31], v44 offset1:1
	ds_read2_b32 v[32:33], v44 offset0:2 offset1:3
	ds_read2_b32 v[100:101], v43 offset1:1
	v_lshl_add_u64 v[22:23], v[20:21], 0, v[24:25]
	v_lshlrev_b64 v[24:25], 2, v[8:9]
	v_lshl_add_u64 v[26:27], v[18:19], 0, v[24:25]
	v_or_b32_e32 v8, s20, v113
	v_lshlrev_b32_e32 v8, 10, v8
	s_waitcnt lgkmcnt(3)
	v_pk_fma_f32 v[6:7], v[2:3], v[28:29], v[6:7]
	s_waitcnt lgkmcnt(0)
	v_pk_fma_f32 v[4:5], v[0:1], v[100:101], v[4:5]
	global_store_dwordx4 v[22:23], v[4:7], off
	s_waitcnt vmcnt(15)
	s_nop 1
	v_mov_b64_e32 v[4:5], v[242:243]
	v_mov_b64_e32 v[6:7], v[244:245]
	v_lshl_add_u64 v[22:23], v[20:21], 0, v[24:25]
	v_lshlrev_b64 v[24:25], 2, v[8:9]
	v_lshl_add_u64 v[26:27], v[18:19], 0, v[24:25]
	v_or_b32_e32 v8, s20, v114
	v_lshlrev_b32_e32 v8, 10, v8
	v_pk_fma_f32 v[6:7], v[2:3], v[32:33], v[6:7]
	v_pk_fma_f32 v[4:5], v[0:1], v[30:31], v[4:5]
	global_store_dwordx4 v[22:23], v[4:7], off
	s_waitcnt vmcnt(15)
	s_nop 1
	v_mov_b64_e32 v[4:5], v[238:239]
	v_mov_b64_e32 v[6:7], v[240:241]
	ds_read2_b32 v[28:29], v45 offset0:2 offset1:3
	ds_read2_b32 v[30:31], v46 offset1:1
	ds_read2_b32 v[32:33], v46 offset0:2 offset1:3
	ds_read2_b32 v[100:101], v45 offset1:1
	v_lshl_add_u64 v[22:23], v[20:21], 0, v[24:25]
	v_lshlrev_b64 v[24:25], 2, v[8:9]
	v_lshl_add_u64 v[26:27], v[18:19], 0, v[24:25]
	v_or_b32_e32 v8, s20, v115
	v_lshlrev_b32_e32 v8, 10, v8
	s_waitcnt lgkmcnt(3)
	v_pk_fma_f32 v[6:7], v[2:3], v[28:29], v[6:7]
	s_waitcnt lgkmcnt(0)
	v_pk_fma_f32 v[4:5], v[0:1], v[100:101], v[4:5]
	global_store_dwordx4 v[22:23], v[4:7], off
	s_waitcnt vmcnt(15)
	s_nop 1
	v_mov_b64_e32 v[4:5], v[234:235]
	v_mov_b64_e32 v[6:7], v[236:237]
	v_lshl_add_u64 v[22:23], v[20:21], 0, v[24:25]
	v_lshlrev_b64 v[24:25], 2, v[8:9]
	v_lshl_add_u64 v[26:27], v[18:19], 0, v[24:25]
	v_or_b32_e32 v8, s20, v116
	v_lshlrev_b32_e32 v8, 10, v8
	v_pk_fma_f32 v[6:7], v[2:3], v[32:33], v[6:7]
	v_pk_fma_f32 v[4:5], v[0:1], v[30:31], v[4:5]
	global_store_dwordx4 v[22:23], v[4:7], off
	s_waitcnt vmcnt(15)
	s_nop 1
	v_mov_b64_e32 v[4:5], v[212:213]
	v_mov_b64_e32 v[6:7], v[214:215]
	ds_read2_b32 v[28:29], v47 offset0:2 offset1:3
	ds_read2_b32 v[30:31], v48 offset1:1
	ds_read2_b32 v[32:33], v48 offset0:2 offset1:3
	ds_read2_b32 v[100:101], v47 offset1:1
	v_lshl_add_u64 v[22:23], v[20:21], 0, v[24:25]
	v_lshlrev_b64 v[24:25], 2, v[8:9]
	v_lshl_add_u64 v[26:27], v[18:19], 0, v[24:25]
	v_or_b32_e32 v8, s20, v135
	v_lshlrev_b32_e32 v8, 10, v8
	s_waitcnt lgkmcnt(3)
	v_pk_fma_f32 v[6:7], v[2:3], v[28:29], v[6:7]
	s_waitcnt lgkmcnt(0)
	v_pk_fma_f32 v[4:5], v[0:1], v[100:101], v[4:5]
	global_store_dwordx4 v[22:23], v[4:7], off
	s_waitcnt vmcnt(15)
	s_nop 1
	v_mov_b64_e32 v[4:5], v[208:209]
	v_mov_b64_e32 v[6:7], v[210:211]
	v_lshl_add_u64 v[22:23], v[20:21], 0, v[24:25]
	v_lshlrev_b64 v[24:25], 2, v[8:9]
	v_lshl_add_u64 v[26:27], v[18:19], 0, v[24:25]
	v_or_b32_e32 v8, s20, v200
	v_lshlrev_b32_e32 v8, 10, v8
	v_pk_fma_f32 v[6:7], v[2:3], v[32:33], v[6:7]
	v_pk_fma_f32 v[4:5], v[0:1], v[30:31], v[4:5]
	global_store_dwordx4 v[22:23], v[4:7], off
	s_waitcnt vmcnt(15)
	s_nop 1
	v_mov_b64_e32 v[4:5], v[204:205]
	v_mov_b64_e32 v[6:7], v[206:207]
	ds_read2_b32 v[28:29], v49 offset0:2 offset1:3
	ds_read2_b32 v[30:31], v50 offset1:1
	ds_read2_b32 v[32:33], v50 offset0:2 offset1:3
	ds_read2_b32 v[100:101], v49 offset1:1
	v_lshl_add_u64 v[22:23], v[20:21], 0, v[24:25]
	v_lshlrev_b64 v[24:25], 2, v[8:9]
	v_lshl_add_u64 v[26:27], v[18:19], 0, v[24:25]
	v_or_b32_e32 v8, s20, v35
	v_lshlrev_b32_e32 v8, 10, v8
	s_waitcnt lgkmcnt(3)
	v_pk_fma_f32 v[6:7], v[2:3], v[28:29], v[6:7]
	s_waitcnt lgkmcnt(0)
	v_pk_fma_f32 v[4:5], v[0:1], v[100:101], v[4:5]
	global_store_dwordx4 v[22:23], v[4:7], off
	s_waitcnt vmcnt(15)
	s_nop 1
	v_mov_b64_e32 v[4:5], v[196:197]
	v_mov_b64_e32 v[6:7], v[198:199]
	v_lshl_add_u64 v[22:23], v[20:21], 0, v[24:25]
	v_lshlrev_b64 v[24:25], 2, v[8:9]
	v_lshl_add_u64 v[26:27], v[18:19], 0, v[24:25]
	v_or_b32_e32 v8, s20, v36
	v_lshlrev_b32_e32 v8, 10, v8
	v_pk_fma_f32 v[6:7], v[2:3], v[32:33], v[6:7]
	v_pk_fma_f32 v[4:5], v[0:1], v[30:31], v[4:5]
	global_store_dwordx4 v[22:23], v[4:7], off
	s_waitcnt vmcnt(15)
	s_nop 1
	v_mov_b64_e32 v[4:5], v[192:193]
	v_mov_b64_e32 v[6:7], v[194:195]
	ds_read2_b32 v[28:29], v51 offset0:2 offset1:3
	ds_read2_b32 v[30:31], v52 offset1:1
	ds_read2_b32 v[32:33], v52 offset0:2 offset1:3
	ds_read2_b32 v[100:101], v51 offset1:1
	v_lshl_add_u64 v[22:23], v[20:21], 0, v[24:25]
	v_lshlrev_b64 v[24:25], 2, v[8:9]
	v_lshl_add_u64 v[26:27], v[18:19], 0, v[24:25]
	v_or_b32_e32 v8, s20, v37
	v_lshlrev_b32_e32 v8, 10, v8
	s_waitcnt lgkmcnt(3)
	v_pk_fma_f32 v[6:7], v[2:3], v[28:29], v[6:7]
	s_waitcnt lgkmcnt(0)
	v_pk_fma_f32 v[4:5], v[0:1], v[100:101], v[4:5]
	global_store_dwordx4 v[22:23], v[4:7], off
	s_waitcnt vmcnt(15)
	s_nop 1
	v_mov_b64_e32 v[4:5], v[188:189]
	v_mov_b64_e32 v[6:7], v[190:191]
	v_lshl_add_u64 v[22:23], v[20:21], 0, v[24:25]
	v_lshlrev_b64 v[24:25], 2, v[8:9]
	v_lshl_add_u64 v[26:27], v[18:19], 0, v[24:25]
	v_or_b32_e32 v8, s20, v38
	v_lshlrev_b32_e32 v8, 10, v8
	v_pk_fma_f32 v[6:7], v[2:3], v[32:33], v[6:7]
	v_pk_fma_f32 v[4:5], v[0:1], v[30:31], v[4:5]
	global_store_dwordx4 v[22:23], v[4:7], off
	s_waitcnt vmcnt(15)
	s_nop 1
	v_mov_b64_e32 v[4:5], v[184:185]
	v_mov_b64_e32 v[6:7], v[186:187]
	ds_read2_b32 v[28:29], v53 offset0:2 offset1:3
	ds_read2_b32 v[30:31], v54 offset1:1
	ds_read2_b32 v[32:33], v54 offset0:2 offset1:3
	ds_read2_b32 v[100:101], v53 offset1:1
	v_lshl_add_u64 v[22:23], v[20:21], 0, v[24:25]
	v_lshlrev_b64 v[24:25], 2, v[8:9]
	v_lshl_add_u64 v[26:27], v[18:19], 0, v[24:25]
	v_add_lshl_u32 v8, s20, v39, 10
	s_waitcnt lgkmcnt(3)
	v_pk_fma_f32 v[6:7], v[2:3], v[28:29], v[6:7]
	s_waitcnt lgkmcnt(0)
	v_pk_fma_f32 v[4:5], v[0:1], v[100:101], v[4:5]
	global_store_dwordx4 v[22:23], v[4:7], off
	s_waitcnt vmcnt(15)
	s_nop 1
	v_mov_b64_e32 v[4:5], v[180:181]
	v_mov_b64_e32 v[6:7], v[182:183]
	v_lshl_add_u64 v[22:23], v[20:21], 0, v[24:25]
	v_lshlrev_b64 v[24:25], 2, v[8:9]
	v_lshl_add_u64 v[26:27], v[18:19], 0, v[24:25]
	v_add_lshl_u32 v8, s20, v40, 10
	v_pk_fma_f32 v[6:7], v[2:3], v[32:33], v[6:7]
	v_pk_fma_f32 v[4:5], v[0:1], v[30:31], v[4:5]
	global_store_dwordx4 v[22:23], v[4:7], off
	s_waitcnt vmcnt(15)
	s_nop 1
	v_mov_b64_e32 v[4:5], v[176:177]
	v_mov_b64_e32 v[6:7], v[178:179]
	ds_read2_b32 v[28:29], v55 offset0:2 offset1:3
	ds_read2_b32 v[30:31], v56 offset1:1
	ds_read2_b32 v[32:33], v56 offset0:2 offset1:3
	ds_read2_b32 v[100:101], v55 offset1:1
	v_lshl_add_u64 v[22:23], v[20:21], 0, v[24:25]
	v_lshlrev_b64 v[24:25], 2, v[8:9]
	v_lshl_add_u64 v[26:27], v[18:19], 0, v[24:25]
	v_add_lshl_u32 v8, s20, v41, 10
	s_waitcnt lgkmcnt(3)
	v_pk_fma_f32 v[6:7], v[2:3], v[28:29], v[6:7]
	s_waitcnt lgkmcnt(0)
	v_pk_fma_f32 v[4:5], v[0:1], v[100:101], v[4:5]
	global_store_dwordx4 v[22:23], v[4:7], off
	s_waitcnt vmcnt(15)
	s_nop 1
	v_mov_b64_e32 v[4:5], v[172:173]
	v_mov_b64_e32 v[6:7], v[174:175]
	v_lshl_add_u64 v[22:23], v[20:21], 0, v[24:25]
	v_lshlrev_b64 v[24:25], 2, v[8:9]
	v_lshl_add_u64 v[18:19], v[18:19], 0, v[24:25]
	v_pk_fma_f32 v[6:7], v[2:3], v[32:33], v[6:7]
	v_pk_fma_f32 v[4:5], v[0:1], v[30:31], v[4:5]
	global_store_dwordx4 v[22:23], v[4:7], off
	s_waitcnt vmcnt(15)
	s_nop 1
	v_mov_b64_e32 v[4:5], v[168:169]
	v_mov_b64_e32 v[6:7], v[170:171]
	v_lshl_add_u64 v[18:19], v[20:21], 0, v[24:25]
	ds_read2_b32 v[20:21], v57 offset0:2 offset1:3
	ds_read2_b32 v[22:23], v57 offset1:1
	s_waitcnt lgkmcnt(1)
	v_pk_fma_f32 v[2:3], v[2:3], v[20:21], v[6:7]
	s_waitcnt lgkmcnt(0)
	v_pk_fma_f32 v[0:1], v[0:1], v[22:23], v[4:5]
	global_store_dwordx4 v[18:19], v[0:3], off
	s_barrier
	s_cbranch_scc1 .LBB0_656
	s_load_dwordx2 s[2:3], s[0:1], 0x130
	v_accvgpr_read_b32 v104, a206
	v_mov_b32_e32 v20, v135

.LBB0_1145:
	s_lshr_b32 s13, s6, 3
	s_add_i32 s13, s13, s7
	s_lshl_b32 s4, s13, 19
	v_lshl_add_u64 v[0:1], v[18:19], 0, s[4:5]
	v_add_co_u32_e32 v4, vcc, 0x10000, v0
	s_and_b32 s12, s6, 7
	s_nop 0
	v_addc_co_u32_e32 v5, vcc, 0, v1, vcc
	v_add_co_u32_e32 v6, vcc, 0x20000, v0
	s_lshl_b32 s4, s12, 18
	s_nop 0
	v_addc_co_u32_e32 v7, vcc, 0, v1, vcc
	v_add_co_u32_e32 v8, vcc, 0x30000, v0
	v_lshl_add_u64 v[2:3], v[20:21], 0, s[4:5]
	s_nop 0
	v_addc_co_u32_e32 v9, vcc, 0, v1, vcc
	v_add_co_u32_e32 v10, vcc, 0x40000, v0
	global_load_dwordx4 v[100:103], v[0:1], off
	global_load_dwordx4 v[104:107], v[0:1], off offset:128
	v_addc_co_u32_e32 v11, vcc, 0, v1, vcc
	v_add_co_u32_e32 v12, vcc, 0x50000, v0
	global_load_dwordx4 v[108:111], v[2:3], off
	global_load_dwordx4 v[112:115], v[2:3], off offset:128
	v_addc_co_u32_e32 v13, vcc, 0, v1, vcc
	v_add_co_u32_e32 v14, vcc, 0x60000, v0
	global_load_dwordx4 v[116:119], v[4:5], off
	global_load_dwordx4 v[120:123], v[4:5], off offset:128
	v_addc_co_u32_e32 v15, vcc, 0, v1, vcc
	v_add_co_u32_e32 v26, vcc, 0x70000, v0
	global_load_dwordx4 v[124:127], v[6:7], off
	global_load_dwordx4 v[128:131], v[6:7], off offset:128
	v_addc_co_u32_e32 v27, vcc, 0, v1, vcc
	v_add_co_u32_e32 v28, vcc, s8, v2
	global_load_dwordx4 v[140:143], v[8:9], off
	global_load_dwordx4 v[144:147], v[8:9], off offset:128
	v_addc_co_u32_e32 v29, vcc, 0, v3, vcc
	v_add_co_u32_e32 v30, vcc, s9, v2
	global_load_dwordx4 v[148:151], v[10:11], off
	global_load_dwordx4 v[152:155], v[10:11], off offset:128
	v_addc_co_u32_e32 v31, vcc, 0, v3, vcc
	v_add_co_u32_e32 v32, vcc, s10, v2
	global_load_dwordx4 v[156:159], v[12:13], off
	global_load_dwordx4 v[160:163], v[12:13], off offset:128
	global_load_dwordx4 v[164:167], v[14:15], off
	global_load_dwordx4 v[168:171], v[14:15], off offset:128
	global_load_dwordx4 v[172:175], v[26:27], off
	global_load_dwordx4 v[176:179], v[26:27], off offset:128
	global_load_dwordx4 v[180:183], v[28:29], off
	global_load_dwordx4 v[184:187], v[28:29], off offset:128
	v_addc_co_u32_e32 v33, vcc, 0, v3, vcc
	global_load_dwordx4 v[188:191], v[30:31], off
	global_load_dwordx4 v[192:195], v[30:31], off offset:128
	global_load_dwordx4 v[196:199], v[32:33], off
	global_load_dwordx4 v[200:203], v[32:33], off offset:128
	s_lshl_b32 s14, s13, 8
	s_add_i32 s4, s14, 0xffffe000
	s_add_i32 s15, s14, 0xffffe080
	s_lshr_b32 s4, s4, 12
	s_lshr_b32 s15, s15, 12
	s_add_i32 s4, s4, 6
	s_add_i32 s15, s15, 6
	s_cmp_lt_u32 s13, 32
	s_cselect_b32 s4, 5, s4
	s_cselect_b32 s13, 5, s15
	s_mul_hi_u32 s15, s4, 0x6000
	s_mulk_i32 s4, 0x6000
	s_add_u32 s16, s2, s4
	s_addc_u32 s15, s3, s15
	s_lshl_b32 s4, s12, 9
	v_or_b32_e32 v16, s14, v135
	s_add_u32 s16, s16, s4
	v_lshlrev_b32_e32 v16, 10, v16
	s_addc_u32 s17, s15, 0
	s_mul_hi_u32 s12, s13, 0x6000
	s_mulk_i32 s13, 0x6000
	s_waitcnt vmcnt(23)
	ds_write_b128 v60, v[100:103]
	s_waitcnt vmcnt(21)
	ds_write_b128 v60, v[108:111] offset:36864
	s_waitcnt vmcnt(19)
	ds_write_b128 v60, v[116:119] offset:4608
	s_waitcnt vmcnt(17)
	ds_write_b128 v60, v[124:127] offset:9216
	s_waitcnt vmcnt(15)
	ds_write_b128 v60, v[140:143] offset:13824
	s_waitcnt vmcnt(13)
	ds_write_b128 v60, v[148:151] offset:18432
	s_waitcnt vmcnt(11)
	ds_write_b128 v60, v[156:159] offset:23040
	s_waitcnt vmcnt(9)
	ds_write_b128 v60, v[164:167] offset:27648
	s_waitcnt vmcnt(7)
	ds_write_b128 v60, v[172:175] offset:32256
	s_waitcnt vmcnt(5)
	ds_write_b128 v60, v[180:183] offset:41472
	s_waitcnt vmcnt(3)
	ds_write_b128 v60, v[188:191] offset:46080
	s_waitcnt vmcnt(1)
	ds_write_b128 v60, v[196:199] offset:50688
	s_waitcnt lgkmcnt(0)
	s_barrier
	ds_read_b128 v[100:103], v59
	ds_read_b128 v[108:111], v62 offset:36864
	ds_read_b128 v[116:119], v59 offset:4608
	ds_read_b128 v[124:127], v62 offset:41472
	s_waitcnt lgkmcnt(2)
	v_mfma_f32_32x32x16_bf16 a[112:127], v[100:103], v[108:111], 0
	s_waitcnt lgkmcnt(0)
	v_mfma_f32_32x32x16_bf16 a[96:111], v[100:103], v[124:127], 0
	ds_read_b128 v[100:103], v59 offset:9216
	s_waitcnt lgkmcnt(0)
	v_mfma_f32_32x32x16_bf16 a[48:63], v[100:103], v[108:111], 0
	v_mfma_f32_32x32x16_bf16 a[32:47], v[100:103], v[124:127], 0
	ds_read_b128 v[100:103], v61
	ds_write_b128 v60, v[104:107] offset:55296
	ds_write_b128 v60, v[120:123] offset:59904
	ds_write_b128 v60, v[128:131] offset:64512
	ds_write_b128 v63, v[144:147] offset:55296
	ds_write_b128 v64, v[152:155] offset:55296
	ds_write_b128 v65, v[160:163] offset:55296
	ds_write_b128 v66, v[168:171] offset:55296
	ds_write_b128 v67, v[176:179] offset:55296
	ds_write_b128 v68, v[112:115]
	ds_write_b128 v68, v[184:187] offset:4608
	ds_write_b128 v68, v[192:195] offset:9216
	s_waitcnt vmcnt(0)
	ds_write_b128 v68, v[200:203] offset:13824
	v_mfma_f32_32x32x16_bf16 a[80:95], v[116:119], v[108:111], 0
	v_mfma_f32_32x32x16_bf16 a[64:79], v[116:119], v[124:127], 0
	s_waitcnt lgkmcnt(12)
	v_mfma_f32_32x32x16_bf16 a[16:31], v[100:103], v[108:111], 0
	v_mfma_f32_32x32x16_bf16 a[0:15], v[100:103], v[124:127], 0
	ds_read_b128 v[100:103], v59 offset:32
	ds_read_b128 v[104:107], v62 offset:36896
	ds_read_b128 v[108:111], v62 offset:36928
	ds_read_b128 v[112:115], v59 offset:64
	ds_read_b128 v[116:119], v62 offset:41504
	ds_read_b128 v[120:123], v62 offset:36960
	s_waitcnt lgkmcnt(4)
	v_mfma_f32_32x32x16_bf16 a[112:127], v[100:103], v[104:107], a[112:127]
	s_waitcnt lgkmcnt(1)
	v_mfma_f32_32x32x16_bf16 a[96:111], v[100:103], v[116:119], a[96:111]
	ds_read_b128 v[100:103], v59 offset:4640
	ds_read_b128 v[124:127], v59 offset:96
	s_waitcnt lgkmcnt(1)
	v_mfma_f32_32x32x16_bf16 a[80:95], v[100:103], v[104:107], a[80:95]
	v_mfma_f32_32x32x16_bf16 a[64:79], v[100:103], v[116:119], a[64:79]
	ds_read_b128 v[100:103], v59 offset:9248
	ds_read_b128 v[128:131], v59 offset:9280
	s_waitcnt lgkmcnt(1)
	v_mfma_f32_32x32x16_bf16 a[48:63], v[100:103], v[104:107], a[48:63]
	v_mfma_f32_32x32x16_bf16 a[32:47], v[100:103], v[116:119], a[32:47]
	ds_read_b128 v[100:103], v61 offset:32
	ds_read_b128 v[140:143], v59 offset:9312
	s_waitcnt lgkmcnt(1)
	v_mfma_f32_32x32x16_bf16 a[16:31], v[100:103], v[104:107], a[16:31]
	v_mfma_f32_32x32x16_bf16 a[0:15], v[100:103], v[116:119], a[0:15]
	ds_read_b128 v[100:103], v62 offset:41536
	ds_read_b128 v[104:107], v62 offset:41568
	v_mfma_f32_32x32x16_bf16 a[112:127], v[112:115], v[108:111], a[112:127]
	s_waitcnt lgkmcnt(1)
	v_mfma_f32_32x32x16_bf16 a[96:111], v[112:115], v[100:103], a[96:111]
	ds_read_b128 v[112:115], v59 offset:4672
	ds_read_b128 v[116:119], v59 offset:4704
	s_waitcnt lgkmcnt(1)
	v_mfma_f32_32x32x16_bf16 a[80:95], v[112:115], v[108:111], a[80:95]
	v_mfma_f32_32x32x16_bf16 a[64:79], v[112:115], v[100:103], a[64:79]
	v_mfma_f32_32x32x16_bf16 a[48:63], v[128:131], v[108:111], a[48:63]
	v_mfma_f32_32x32x16_bf16 a[32:47], v[128:131], v[100:103], a[32:47]
	ds_read_b128 v[112:115], v61 offset:64
	ds_read_b128 v[128:131], v61 offset:96
	s_waitcnt lgkmcnt(1)
	v_mfma_f32_32x32x16_bf16 a[16:31], v[112:115], v[108:111], a[16:31]
	v_mfma_f32_32x32x16_bf16 a[0:15], v[112:115], v[100:103], a[0:15]
	global_load_dwordx4 v[100:103], v[32:33], off offset:256
	v_mfma_f32_32x32x16_bf16 a[112:127], v[124:127], v[120:123], a[112:127]
	v_mfma_f32_32x32x16_bf16 a[96:111], v[124:127], v[104:107], a[96:111]
	v_mfma_f32_32x32x16_bf16 a[80:95], v[116:119], v[120:123], a[80:95]
	v_mfma_f32_32x32x16_bf16 a[64:79], v[116:119], v[104:107], a[64:79]
	v_mfma_f32_32x32x16_bf16 a[48:63], v[140:143], v[120:123], a[48:63]
	v_mfma_f32_32x32x16_bf16 a[32:47], v[140:143], v[104:107], a[32:47]
	global_load_dwordx4 v[108:111], v[30:31], off offset:256
	global_load_dwordx4 v[112:115], v[28:29], off offset:256
	global_load_dwordx4 v[116:119], v[2:3], off offset:256
	global_load_dwordx4 v[124:127], v[8:9], off offset:256
	global_load_dwordx4 v[140:143], v[6:7], off offset:256
	global_load_dwordx4 v[144:147], v[4:5], off offset:256
	global_load_dwordx4 v[148:151], v[0:1], off offset:256
	s_waitcnt lgkmcnt(0)
	v_mfma_f32_32x32x16_bf16 a[16:31], v[128:131], v[120:123], a[16:31]
	global_load_dwordx4 v[120:123], v[12:13], off offset:256
	global_load_dwordx4 v[152:155], v[10:11], off offset:256
	global_load_dwordx4 v[156:159], v[26:27], off offset:256
	global_load_dwordx4 v[160:163], v[14:15], off offset:256
	s_barrier
	v_mfma_f32_32x32x16_bf16 a[0:15], v[128:131], v[104:107], a[0:15]
	ds_read_b128 v[104:107], v59 offset:55296
	ds_read_b128 v[128:131], v69
	ds_read_b128 v[164:167], v59 offset:59904
	ds_read_b128 v[168:171], v69 offset:4608
	s_waitcnt lgkmcnt(2)
	v_mfma_f32_32x32x16_bf16 a[112:127], v[104:107], v[128:131], a[112:127]
	s_waitcnt lgkmcnt(0)
	v_mfma_f32_32x32x16_bf16 a[96:111], v[104:107], v[168:171], a[96:111]
	ds_read_b128 v[104:107], v59 offset:64512
	s_waitcnt lgkmcnt(0)
	v_mfma_f32_32x32x16_bf16 a[48:63], v[104:107], v[128:131], a[48:63]
	v_mfma_f32_32x32x16_bf16 a[32:47], v[104:107], v[168:171], a[32:47]
	ds_read_b128 v[104:107], v61 offset:55296
	s_waitcnt vmcnt(4)
	ds_write_b128 v60, v[148:151]
	ds_write_b128 v60, v[144:147] offset:4608
	ds_write_b128 v60, v[140:143] offset:9216
	ds_write_b128 v60, v[124:127] offset:13824
	s_waitcnt vmcnt(2)
	ds_write_b128 v60, v[152:155] offset:18432
	ds_write_b128 v60, v[120:123] offset:23040
	s_waitcnt vmcnt(0)
	ds_write_b128 v60, v[160:163] offset:27648
	ds_write_b128 v60, v[156:159] offset:32256
	ds_write_b128 v60, v[116:119] offset:36864
	ds_write_b128 v60, v[112:115] offset:41472
	ds_write_b128 v60, v[108:111] offset:46080
	ds_write_b128 v60, v[100:103] offset:50688
	v_mfma_f32_32x32x16_bf16 a[80:95], v[164:167], v[128:131], a[80:95]
	v_mfma_f32_32x32x16_bf16 a[64:79], v[164:167], v[168:171], a[64:79]
	s_waitcnt lgkmcnt(12)
	v_mfma_f32_32x32x16_bf16 a[16:31], v[104:107], v[128:131], a[16:31]
	v_mfma_f32_32x32x16_bf16 a[0:15], v[104:107], v[168:171], a[0:15]
	ds_read_b128 v[100:103], v59 offset:55328
	ds_read_b128 v[104:107], v69 offset:32
	ds_read_b128 v[108:111], v69 offset:64
	ds_read_b128 v[112:115], v59 offset:55360
	ds_read_b128 v[116:119], v69 offset:4640
	ds_read_b128 v[120:123], v69 offset:96
	s_waitcnt lgkmcnt(4)
	v_mfma_f32_32x32x16_bf16 a[112:127], v[100:103], v[104:107], a[112:127]
	s_waitcnt lgkmcnt(1)
	v_mfma_f32_32x32x16_bf16 a[96:111], v[100:103], v[116:119], a[96:111]
	ds_read_b128 v[100:103], v59 offset:59936
	ds_read_b128 v[124:127], v59 offset:55392
	s_waitcnt lgkmcnt(1)
	v_mfma_f32_32x32x16_bf16 a[80:95], v[100:103], v[104:107], a[80:95]
	v_mfma_f32_32x32x16_bf16 a[64:79], v[100:103], v[116:119], a[64:79]
	ds_read_b128 v[100:103], v59 offset:64544
	ds_read_b128 v[128:131], v59 offset:64576
	s_waitcnt lgkmcnt(1)
	v_mfma_f32_32x32x16_bf16 a[48:63], v[100:103], v[104:107], a[48:63]
	v_mfma_f32_32x32x16_bf16 a[32:47], v[100:103], v[116:119], a[32:47]
	ds_read_b128 v[100:103], v61 offset:55328
	ds_read_b128 v[140:143], v59 offset:64608
	s_waitcnt lgkmcnt(1)
	v_mfma_f32_32x32x16_bf16 a[16:31], v[100:103], v[104:107], a[16:31]
	v_mfma_f32_32x32x16_bf16 a[0:15], v[100:103], v[116:119], a[0:15]
	ds_read_b128 v[100:103], v69 offset:4672
	ds_read_b128 v[104:107], v69 offset:4704
	v_mfma_f32_32x32x16_bf16 a[112:127], v[112:115], v[108:111], a[112:127]
	s_waitcnt lgkmcnt(1)
	v_mfma_f32_32x32x16_bf16 a[96:111], v[112:115], v[100:103], a[96:111]
	ds_read_b128 v[112:115], v59 offset:59968
	ds_read_b128 v[116:119], v59 offset:60000
	s_waitcnt lgkmcnt(1)
	v_mfma_f32_32x32x16_bf16 a[80:95], v[112:115], v[108:111], a[80:95]
	v_mfma_f32_32x32x16_bf16 a[64:79], v[112:115], v[100:103], a[64:79]
	v_mfma_f32_32x32x16_bf16 a[48:63], v[128:131], v[108:111], a[48:63]
	v_mfma_f32_32x32x16_bf16 a[32:47], v[128:131], v[100:103], a[32:47]
	ds_read_b128 v[112:115], v61 offset:55360
	ds_read_b128 v[128:131], v61 offset:55392
	s_waitcnt lgkmcnt(1)
	v_mfma_f32_32x32x16_bf16 a[16:31], v[112:115], v[108:111], a[16:31]
	v_mfma_f32_32x32x16_bf16 a[0:15], v[112:115], v[100:103], a[0:15]
	v_mfma_f32_32x32x16_bf16 a[112:127], v[124:127], v[120:123], a[112:127]
	v_mfma_f32_32x32x16_bf16 a[96:111], v[124:127], v[104:107], a[96:111]
	v_mfma_f32_32x32x16_bf16 a[80:95], v[116:119], v[120:123], a[80:95]
	v_mfma_f32_32x32x16_bf16 a[64:79], v[116:119], v[104:107], a[64:79]
	global_load_dwordx4 v[100:103], v[4:5], off offset:384
	global_load_dwordx4 v[108:111], v[0:1], off offset:384
	global_load_dwordx4 v[112:115], v[8:9], off offset:384
	global_load_dwordx4 v[116:119], v[6:7], off offset:384
	v_mfma_f32_32x32x16_bf16 a[48:63], v[140:143], v[120:123], a[48:63]
	v_mfma_f32_32x32x16_bf16 a[32:47], v[140:143], v[104:107], a[32:47]
	global_load_dwordx4 v[124:127], v[10:11], off offset:384
	global_load_dwordx4 v[140:143], v[12:13], off offset:384
	global_load_dwordx4 v[144:147], v[26:27], off offset:384
	global_load_dwordx4 v[148:151], v[14:15], off offset:384
	global_load_dwordx4 v[152:155], v[28:29], off offset:384
	global_load_dwordx4 v[156:159], v[2:3], off offset:384
	global_load_dwordx4 v[160:163], v[30:31], off offset:384
	s_waitcnt lgkmcnt(0)
	v_mfma_f32_32x32x16_bf16 a[16:31], v[128:131], v[120:123], a[16:31]
	global_load_dwordx4 v[120:123], v[32:33], off offset:384
	s_barrier
	v_mfma_f32_32x32x16_bf16 a[0:15], v[128:131], v[104:107], a[0:15]
	ds_read_b128 v[104:107], v59
	ds_read_b128 v[128:131], v62 offset:36864
	ds_read_b128 v[164:167], v59 offset:4608
	ds_read_b128 v[168:171], v62 offset:41472
	s_waitcnt lgkmcnt(2)
	v_mfma_f32_32x32x16_bf16 a[112:127], v[104:107], v[128:131], a[112:127]
	s_waitcnt lgkmcnt(0)
	v_mfma_f32_32x32x16_bf16 a[96:111], v[104:107], v[168:171], a[96:111]
	ds_read_b128 v[104:107], v59 offset:9216
	s_waitcnt lgkmcnt(0)
	v_mfma_f32_32x32x16_bf16 a[48:63], v[104:107], v[128:131], a[48:63]
	v_mfma_f32_32x32x16_bf16 a[32:47], v[104:107], v[168:171], a[32:47]
	ds_read_b128 v[104:107], v61
	s_waitcnt vmcnt(10)
	ds_write_b128 v60, v[108:111] offset:55296
	ds_write_b128 v60, v[100:103] offset:59904
	s_waitcnt vmcnt(8)
	ds_write_b128 v60, v[116:119] offset:64512
	ds_write_b128 v63, v[112:115] offset:55296
	s_waitcnt vmcnt(7)
	ds_write_b128 v64, v[124:127] offset:55296
	s_waitcnt vmcnt(6)
	ds_write_b128 v65, v[140:143] offset:55296
	s_waitcnt vmcnt(4)
	ds_write_b128 v66, v[148:151] offset:55296
	ds_write_b128 v67, v[144:147] offset:55296
	s_waitcnt vmcnt(2)
	ds_write_b128 v68, v[156:159]
	ds_write_b128 v68, v[152:155] offset:4608
	s_waitcnt vmcnt(1)
	ds_write_b128 v68, v[160:163] offset:9216
	s_waitcnt vmcnt(0)
	ds_write_b128 v68, v[120:123] offset:13824
	v_mfma_f32_32x32x16_bf16 a[80:95], v[164:167], v[128:131], a[80:95]
	v_mfma_f32_32x32x16_bf16 a[64:79], v[164:167], v[168:171], a[64:79]
	s_waitcnt lgkmcnt(12)
	v_mfma_f32_32x32x16_bf16 a[16:31], v[104:107], v[128:131], a[16:31]
	v_mfma_f32_32x32x16_bf16 a[0:15], v[104:107], v[168:171], a[0:15]
	ds_read_b128 v[100:103], v59 offset:32
	ds_read_b128 v[104:107], v62 offset:36896
	ds_read_b128 v[108:111], v62 offset:36928
	ds_read_b128 v[112:115], v59 offset:64
	ds_read_b128 v[116:119], v62 offset:41504
	ds_read_b128 v[120:123], v62 offset:36960
	s_waitcnt lgkmcnt(4)
	v_mfma_f32_32x32x16_bf16 a[112:127], v[100:103], v[104:107], a[112:127]
	s_waitcnt lgkmcnt(1)
	v_mfma_f32_32x32x16_bf16 a[96:111], v[100:103], v[116:119], a[96:111]
	ds_read_b128 v[100:103], v59 offset:4640
	ds_read_b128 v[124:127], v59 offset:96
	s_waitcnt lgkmcnt(1)
	v_mfma_f32_32x32x16_bf16 a[80:95], v[100:103], v[104:107], a[80:95]
	v_mfma_f32_32x32x16_bf16 a[64:79], v[100:103], v[116:119], a[64:79]
	ds_read_b128 v[100:103], v59 offset:9248
	ds_read_b128 v[128:131], v59 offset:9280
	s_waitcnt lgkmcnt(1)
	v_mfma_f32_32x32x16_bf16 a[48:63], v[100:103], v[104:107], a[48:63]
	v_mfma_f32_32x32x16_bf16 a[32:47], v[100:103], v[116:119], a[32:47]
	ds_read_b128 v[100:103], v61 offset:32
	ds_read_b128 v[140:143], v59 offset:9312
	s_waitcnt lgkmcnt(1)
	v_mfma_f32_32x32x16_bf16 a[16:31], v[100:103], v[104:107], a[16:31]
	v_mfma_f32_32x32x16_bf16 a[0:15], v[100:103], v[116:119], a[0:15]
	ds_read_b128 v[100:103], v62 offset:41536
	ds_read_b128 v[104:107], v62 offset:41568
	v_mfma_f32_32x32x16_bf16 a[112:127], v[112:115], v[108:111], a[112:127]
	s_waitcnt lgkmcnt(1)
	v_mfma_f32_32x32x16_bf16 a[96:111], v[112:115], v[100:103], a[96:111]
	ds_read_b128 v[112:115], v59 offset:4672
	ds_read_b128 v[116:119], v59 offset:4704
	s_waitcnt lgkmcnt(1)
	v_mfma_f32_32x32x16_bf16 a[80:95], v[112:115], v[108:111], a[80:95]
	v_mfma_f32_32x32x16_bf16 a[64:79], v[112:115], v[100:103], a[64:79]
	v_mfma_f32_32x32x16_bf16 a[48:63], v[128:131], v[108:111], a[48:63]
	v_mfma_f32_32x32x16_bf16 a[32:47], v[128:131], v[100:103], a[32:47]
	ds_read_b128 v[112:115], v61 offset:64
	ds_read_b128 v[128:131], v61 offset:96
	s_waitcnt lgkmcnt(1)
	v_mfma_f32_32x32x16_bf16 a[16:31], v[112:115], v[108:111], a[16:31]
	v_mfma_f32_32x32x16_bf16 a[0:15], v[112:115], v[100:103], a[0:15]
	global_load_dwordx4 v[100:103], v[32:33], off offset:512
	v_mfma_f32_32x32x16_bf16 a[112:127], v[124:127], v[120:123], a[112:127]
	v_mfma_f32_32x32x16_bf16 a[96:111], v[124:127], v[104:107], a[96:111]
	v_mfma_f32_32x32x16_bf16 a[80:95], v[116:119], v[120:123], a[80:95]
	v_mfma_f32_32x32x16_bf16 a[64:79], v[116:119], v[104:107], a[64:79]
	v_mfma_f32_32x32x16_bf16 a[48:63], v[140:143], v[120:123], a[48:63]
	v_mfma_f32_32x32x16_bf16 a[32:47], v[140:143], v[104:107], a[32:47]
	global_load_dwordx4 v[108:111], v[30:31], off offset:512
	global_load_dwordx4 v[112:115], v[28:29], off offset:512
	global_load_dwordx4 v[116:119], v[2:3], off offset:512
	global_load_dwordx4 v[124:127], v[8:9], off offset:512
	global_load_dwordx4 v[140:143], v[6:7], off offset:512
	global_load_dwordx4 v[144:147], v[4:5], off offset:512
	global_load_dwordx4 v[148:151], v[0:1], off offset:512
	s_waitcnt lgkmcnt(0)
	v_mfma_f32_32x32x16_bf16 a[16:31], v[128:131], v[120:123], a[16:31]
	global_load_dwordx4 v[120:123], v[12:13], off offset:512
	global_load_dwordx4 v[152:155], v[10:11], off offset:512
	global_load_dwordx4 v[156:159], v[26:27], off offset:512
	global_load_dwordx4 v[160:163], v[14:15], off offset:512
	s_barrier
	v_mfma_f32_32x32x16_bf16 a[0:15], v[128:131], v[104:107], a[0:15]
	ds_read_b128 v[104:107], v59 offset:55296
	ds_read_b128 v[128:131], v69
	ds_read_b128 v[164:167], v59 offset:59904
	ds_read_b128 v[168:171], v69 offset:4608
	s_waitcnt lgkmcnt(2)
	v_mfma_f32_32x32x16_bf16 a[112:127], v[104:107], v[128:131], a[112:127]
	s_waitcnt lgkmcnt(0)
	v_mfma_f32_32x32x16_bf16 a[96:111], v[104:107], v[168:171], a[96:111]
	ds_read_b128 v[104:107], v59 offset:64512
	s_waitcnt lgkmcnt(0)
	v_mfma_f32_32x32x16_bf16 a[48:63], v[104:107], v[128:131], a[48:63]
	v_mfma_f32_32x32x16_bf16 a[32:47], v[104:107], v[168:171], a[32:47]
	ds_read_b128 v[104:107], v61 offset:55296
	s_waitcnt vmcnt(4)
	ds_write_b128 v60, v[148:151]
	ds_write_b128 v60, v[144:147] offset:4608
	ds_write_b128 v60, v[140:143] offset:9216
	ds_write_b128 v60, v[124:127] offset:13824
	s_waitcnt vmcnt(2)
	ds_write_b128 v60, v[152:155] offset:18432
	ds_write_b128 v60, v[120:123] offset:23040
	s_waitcnt vmcnt(0)
	ds_write_b128 v60, v[160:163] offset:27648
	ds_write_b128 v60, v[156:159] offset:32256
	ds_write_b128 v60, v[116:119] offset:36864
	ds_write_b128 v60, v[112:115] offset:41472
	ds_write_b128 v60, v[108:111] offset:46080
	ds_write_b128 v60, v[100:103] offset:50688
	v_mfma_f32_32x32x16_bf16 a[80:95], v[164:167], v[128:131], a[80:95]
	v_mfma_f32_32x32x16_bf16 a[64:79], v[164:167], v[168:171], a[64:79]
	s_waitcnt lgkmcnt(12)
	v_mfma_f32_32x32x16_bf16 a[16:31], v[104:107], v[128:131], a[16:31]
	v_mfma_f32_32x32x16_bf16 a[0:15], v[104:107], v[168:171], a[0:15]
	ds_read_b128 v[100:103], v59 offset:55328
	ds_read_b128 v[104:107], v69 offset:32
	ds_read_b128 v[108:111], v69 offset:64
	ds_read_b128 v[112:115], v59 offset:55360
	ds_read_b128 v[116:119], v69 offset:4640
	ds_read_b128 v[120:123], v69 offset:96
	s_waitcnt lgkmcnt(4)
	v_mfma_f32_32x32x16_bf16 a[112:127], v[100:103], v[104:107], a[112:127]
	s_waitcnt lgkmcnt(1)
	v_mfma_f32_32x32x16_bf16 a[96:111], v[100:103], v[116:119], a[96:111]
	ds_read_b128 v[100:103], v59 offset:59936
	ds_read_b128 v[124:127], v59 offset:55392
	s_waitcnt lgkmcnt(1)
	v_mfma_f32_32x32x16_bf16 a[80:95], v[100:103], v[104:107], a[80:95]
	v_mfma_f32_32x32x16_bf16 a[64:79], v[100:103], v[116:119], a[64:79]
	ds_read_b128 v[100:103], v59 offset:64544
	ds_read_b128 v[128:131], v59 offset:64576
	s_waitcnt lgkmcnt(1)
	v_mfma_f32_32x32x16_bf16 a[48:63], v[100:103], v[104:107], a[48:63]
	v_mfma_f32_32x32x16_bf16 a[32:47], v[100:103], v[116:119], a[32:47]
	ds_read_b128 v[100:103], v61 offset:55328
	ds_read_b128 v[140:143], v59 offset:64608
	s_waitcnt lgkmcnt(1)
	v_mfma_f32_32x32x16_bf16 a[16:31], v[100:103], v[104:107], a[16:31]
	v_mfma_f32_32x32x16_bf16 a[0:15], v[100:103], v[116:119], a[0:15]
	ds_read_b128 v[100:103], v69 offset:4672
	ds_read_b128 v[104:107], v69 offset:4704
	v_mfma_f32_32x32x16_bf16 a[112:127], v[112:115], v[108:111], a[112:127]
	s_waitcnt lgkmcnt(1)
	v_mfma_f32_32x32x16_bf16 a[96:111], v[112:115], v[100:103], a[96:111]
	ds_read_b128 v[112:115], v59 offset:59968
	ds_read_b128 v[116:119], v59 offset:60000
	s_waitcnt lgkmcnt(1)
	v_mfma_f32_32x32x16_bf16 a[80:95], v[112:115], v[108:111], a[80:95]
	v_mfma_f32_32x32x16_bf16 a[64:79], v[112:115], v[100:103], a[64:79]
	v_mfma_f32_32x32x16_bf16 a[48:63], v[128:131], v[108:111], a[48:63]
	v_mfma_f32_32x32x16_bf16 a[32:47], v[128:131], v[100:103], a[32:47]
	ds_read_b128 v[112:115], v61 offset:55360
	ds_read_b128 v[128:131], v61 offset:55392
	s_waitcnt lgkmcnt(1)
	v_mfma_f32_32x32x16_bf16 a[16:31], v[112:115], v[108:111], a[16:31]
	v_mfma_f32_32x32x16_bf16 a[0:15], v[112:115], v[100:103], a[0:15]
	v_mfma_f32_32x32x16_bf16 a[112:127], v[124:127], v[120:123], a[112:127]
	v_mfma_f32_32x32x16_bf16 a[96:111], v[124:127], v[104:107], a[96:111]
	v_mfma_f32_32x32x16_bf16 a[80:95], v[116:119], v[120:123], a[80:95]
	v_mfma_f32_32x32x16_bf16 a[64:79], v[116:119], v[104:107], a[64:79]
	global_load_dwordx4 v[100:103], v[4:5], off offset:640
	global_load_dwordx4 v[108:111], v[0:1], off offset:640
	global_load_dwordx4 v[112:115], v[8:9], off offset:640
	global_load_dwordx4 v[116:119], v[6:7], off offset:640
	v_mfma_f32_32x32x16_bf16 a[48:63], v[140:143], v[120:123], a[48:63]
	v_mfma_f32_32x32x16_bf16 a[32:47], v[140:143], v[104:107], a[32:47]
	global_load_dwordx4 v[124:127], v[10:11], off offset:640
	global_load_dwordx4 v[140:143], v[12:13], off offset:640
	global_load_dwordx4 v[144:147], v[26:27], off offset:640
	global_load_dwordx4 v[148:151], v[14:15], off offset:640
	global_load_dwordx4 v[152:155], v[28:29], off offset:640
	global_load_dwordx4 v[156:159], v[2:3], off offset:640
	global_load_dwordx4 v[160:163], v[30:31], off offset:640
	s_waitcnt lgkmcnt(0)
	v_mfma_f32_32x32x16_bf16 a[16:31], v[128:131], v[120:123], a[16:31]
	global_load_dwordx4 v[120:123], v[32:33], off offset:640
	s_barrier
	v_mfma_f32_32x32x16_bf16 a[0:15], v[128:131], v[104:107], a[0:15]
	ds_read_b128 v[104:107], v59
	ds_read_b128 v[128:131], v62 offset:36864
	ds_read_b128 v[164:167], v59 offset:4608
	ds_read_b128 v[168:171], v62 offset:41472
	s_waitcnt lgkmcnt(2)
	v_mfma_f32_32x32x16_bf16 a[112:127], v[104:107], v[128:131], a[112:127]
	s_waitcnt lgkmcnt(0)
	v_mfma_f32_32x32x16_bf16 a[96:111], v[104:107], v[168:171], a[96:111]
	ds_read_b128 v[104:107], v59 offset:9216
	s_waitcnt lgkmcnt(0)
	v_mfma_f32_32x32x16_bf16 a[48:63], v[104:107], v[128:131], a[48:63]
	v_mfma_f32_32x32x16_bf16 a[32:47], v[104:107], v[168:171], a[32:47]
	ds_read_b128 v[104:107], v61
	s_waitcnt vmcnt(10)
	ds_write_b128 v60, v[108:111] offset:55296
	ds_write_b128 v60, v[100:103] offset:59904
	s_waitcnt vmcnt(8)
	ds_write_b128 v60, v[116:119] offset:64512
	ds_write_b128 v63, v[112:115] offset:55296
	s_waitcnt vmcnt(7)
	ds_write_b128 v64, v[124:127] offset:55296
	s_waitcnt vmcnt(6)
	ds_write_b128 v65, v[140:143] offset:55296
	s_waitcnt vmcnt(4)
	ds_write_b128 v66, v[148:151] offset:55296
	ds_write_b128 v67, v[144:147] offset:55296
	s_waitcnt vmcnt(2)
	ds_write_b128 v68, v[156:159]
	ds_write_b128 v68, v[152:155] offset:4608
	s_waitcnt vmcnt(1)
	ds_write_b128 v68, v[160:163] offset:9216
	s_waitcnt vmcnt(0)
	ds_write_b128 v68, v[120:123] offset:13824
	v_mfma_f32_32x32x16_bf16 a[80:95], v[164:167], v[128:131], a[80:95]
	v_mfma_f32_32x32x16_bf16 a[64:79], v[164:167], v[168:171], a[64:79]
	s_waitcnt lgkmcnt(12)
	v_mfma_f32_32x32x16_bf16 a[16:31], v[104:107], v[128:131], a[16:31]
	v_mfma_f32_32x32x16_bf16 a[0:15], v[104:107], v[168:171], a[0:15]
	ds_read_b128 v[100:103], v59 offset:32
	ds_read_b128 v[104:107], v62 offset:36896
	ds_read_b128 v[108:111], v62 offset:36928
	ds_read_b128 v[112:115], v59 offset:64
	ds_read_b128 v[116:119], v62 offset:41504
	ds_read_b128 v[120:123], v62 offset:36960
	s_waitcnt lgkmcnt(4)
	v_mfma_f32_32x32x16_bf16 a[112:127], v[100:103], v[104:107], a[112:127]
	s_waitcnt lgkmcnt(1)
	v_mfma_f32_32x32x16_bf16 a[96:111], v[100:103], v[116:119], a[96:111]
	ds_read_b128 v[100:103], v59 offset:4640
	ds_read_b128 v[124:127], v59 offset:96
	s_waitcnt lgkmcnt(1)
	v_mfma_f32_32x32x16_bf16 a[80:95], v[100:103], v[104:107], a[80:95]
	v_mfma_f32_32x32x16_bf16 a[64:79], v[100:103], v[116:119], a[64:79]
	ds_read_b128 v[100:103], v59 offset:9248
	ds_read_b128 v[128:131], v59 offset:9280
	s_waitcnt lgkmcnt(1)
	v_mfma_f32_32x32x16_bf16 a[48:63], v[100:103], v[104:107], a[48:63]
	v_mfma_f32_32x32x16_bf16 a[32:47], v[100:103], v[116:119], a[32:47]
	ds_read_b128 v[100:103], v61 offset:32
	ds_read_b128 v[140:143], v59 offset:9312
	s_waitcnt lgkmcnt(1)
	v_mfma_f32_32x32x16_bf16 a[16:31], v[100:103], v[104:107], a[16:31]
	v_mfma_f32_32x32x16_bf16 a[0:15], v[100:103], v[116:119], a[0:15]
	ds_read_b128 v[100:103], v62 offset:41536
	ds_read_b128 v[104:107], v62 offset:41568
	v_mfma_f32_32x32x16_bf16 a[112:127], v[112:115], v[108:111], a[112:127]
	s_waitcnt lgkmcnt(1)
	v_mfma_f32_32x32x16_bf16 a[96:111], v[112:115], v[100:103], a[96:111]
	ds_read_b128 v[112:115], v59 offset:4672
	ds_read_b128 v[116:119], v59 offset:4704
	s_waitcnt lgkmcnt(1)
	v_mfma_f32_32x32x16_bf16 a[80:95], v[112:115], v[108:111], a[80:95]
	v_mfma_f32_32x32x16_bf16 a[64:79], v[112:115], v[100:103], a[64:79]
	v_mfma_f32_32x32x16_bf16 a[48:63], v[128:131], v[108:111], a[48:63]
	v_mfma_f32_32x32x16_bf16 a[32:47], v[128:131], v[100:103], a[32:47]
	ds_read_b128 v[112:115], v61 offset:64
	ds_read_b128 v[128:131], v61 offset:96
	s_waitcnt lgkmcnt(1)
	v_mfma_f32_32x32x16_bf16 a[16:31], v[112:115], v[108:111], a[16:31]
	v_mfma_f32_32x32x16_bf16 a[0:15], v[112:115], v[100:103], a[0:15]
	global_load_dwordx4 v[100:103], v[32:33], off offset:768
	v_mfma_f32_32x32x16_bf16 a[112:127], v[124:127], v[120:123], a[112:127]
	v_mfma_f32_32x32x16_bf16 a[96:111], v[124:127], v[104:107], a[96:111]
	v_mfma_f32_32x32x16_bf16 a[80:95], v[116:119], v[120:123], a[80:95]
	v_mfma_f32_32x32x16_bf16 a[64:79], v[116:119], v[104:107], a[64:79]
	v_mfma_f32_32x32x16_bf16 a[48:63], v[140:143], v[120:123], a[48:63]
	v_mfma_f32_32x32x16_bf16 a[32:47], v[140:143], v[104:107], a[32:47]
	global_load_dwordx4 v[108:111], v[30:31], off offset:768
	global_load_dwordx4 v[112:115], v[28:29], off offset:768
	global_load_dwordx4 v[116:119], v[2:3], off offset:768
	global_load_dwordx4 v[124:127], v[8:9], off offset:768
	global_load_dwordx4 v[140:143], v[6:7], off offset:768
	global_load_dwordx4 v[144:147], v[4:5], off offset:768
	global_load_dwordx4 v[148:151], v[0:1], off offset:768
	s_waitcnt lgkmcnt(0)
	v_mfma_f32_32x32x16_bf16 a[16:31], v[128:131], v[120:123], a[16:31]
	global_load_dwordx4 v[120:123], v[12:13], off offset:768
	global_load_dwordx4 v[152:155], v[10:11], off offset:768
	global_load_dwordx4 v[156:159], v[26:27], off offset:768
	global_load_dwordx4 v[160:163], v[14:15], off offset:768
	s_barrier
	v_mfma_f32_32x32x16_bf16 a[0:15], v[128:131], v[104:107], a[0:15]
	ds_read_b128 v[104:107], v59 offset:55296
	ds_read_b128 v[128:131], v69
	ds_read_b128 v[164:167], v59 offset:59904
	ds_read_b128 v[168:171], v69 offset:4608
	s_waitcnt lgkmcnt(2)
	v_mfma_f32_32x32x16_bf16 a[112:127], v[104:107], v[128:131], a[112:127]
	s_waitcnt lgkmcnt(0)
	v_mfma_f32_32x32x16_bf16 a[96:111], v[104:107], v[168:171], a[96:111]
	ds_read_b128 v[104:107], v59 offset:64512
	s_waitcnt lgkmcnt(0)
	v_mfma_f32_32x32x16_bf16 a[48:63], v[104:107], v[128:131], a[48:63]
	v_mfma_f32_32x32x16_bf16 a[32:47], v[104:107], v[168:171], a[32:47]
	ds_read_b128 v[104:107], v61 offset:55296
	s_waitcnt vmcnt(4)
	ds_write_b128 v60, v[148:151]
	ds_write_b128 v60, v[144:147] offset:4608
	ds_write_b128 v60, v[140:143] offset:9216
	ds_write_b128 v60, v[124:127] offset:13824
	s_waitcnt vmcnt(2)
	ds_write_b128 v60, v[152:155] offset:18432
	ds_write_b128 v60, v[120:123] offset:23040
	s_waitcnt vmcnt(0)
	ds_write_b128 v60, v[160:163] offset:27648
	ds_write_b128 v60, v[156:159] offset:32256
	ds_write_b128 v60, v[116:119] offset:36864
	ds_write_b128 v60, v[112:115] offset:41472
	ds_write_b128 v60, v[108:111] offset:46080
	ds_write_b128 v60, v[100:103] offset:50688
	v_mfma_f32_32x32x16_bf16 a[80:95], v[164:167], v[128:131], a[80:95]
	v_mfma_f32_32x32x16_bf16 a[64:79], v[164:167], v[168:171], a[64:79]
	s_waitcnt lgkmcnt(12)
	v_mfma_f32_32x32x16_bf16 a[16:31], v[104:107], v[128:131], a[16:31]
	v_mfma_f32_32x32x16_bf16 a[0:15], v[104:107], v[168:171], a[0:15]
	ds_read_b128 v[100:103], v59 offset:55328
	ds_read_b128 v[104:107], v69 offset:32
	ds_read_b128 v[108:111], v69 offset:64
	ds_read_b128 v[112:115], v59 offset:55360
	ds_read_b128 v[116:119], v69 offset:4640
	ds_read_b128 v[120:123], v69 offset:96
	s_waitcnt lgkmcnt(4)
	v_mfma_f32_32x32x16_bf16 a[112:127], v[100:103], v[104:107], a[112:127]
	s_waitcnt lgkmcnt(1)
	v_mfma_f32_32x32x16_bf16 a[96:111], v[100:103], v[116:119], a[96:111]
	ds_read_b128 v[100:103], v59 offset:59936
	ds_read_b128 v[124:127], v59 offset:55392
	s_waitcnt lgkmcnt(1)
	v_mfma_f32_32x32x16_bf16 a[80:95], v[100:103], v[104:107], a[80:95]
	v_mfma_f32_32x32x16_bf16 a[64:79], v[100:103], v[116:119], a[64:79]
	ds_read_b128 v[100:103], v59 offset:64544
	ds_read_b128 v[128:131], v59 offset:64576
	s_waitcnt lgkmcnt(1)
	v_mfma_f32_32x32x16_bf16 a[48:63], v[100:103], v[104:107], a[48:63]
	v_mfma_f32_32x32x16_bf16 a[32:47], v[100:103], v[116:119], a[32:47]
	ds_read_b128 v[100:103], v61 offset:55328
	ds_read_b128 v[140:143], v59 offset:64608
	s_waitcnt lgkmcnt(1)
	v_mfma_f32_32x32x16_bf16 a[16:31], v[100:103], v[104:107], a[16:31]
	v_mfma_f32_32x32x16_bf16 a[0:15], v[100:103], v[116:119], a[0:15]
	ds_read_b128 v[100:103], v69 offset:4672
	ds_read_b128 v[104:107], v69 offset:4704
	v_mfma_f32_32x32x16_bf16 a[112:127], v[112:115], v[108:111], a[112:127]
	s_waitcnt lgkmcnt(1)
	v_mfma_f32_32x32x16_bf16 a[96:111], v[112:115], v[100:103], a[96:111]
	ds_read_b128 v[112:115], v59 offset:59968
	ds_read_b128 v[116:119], v59 offset:60000
	s_waitcnt lgkmcnt(1)
	v_mfma_f32_32x32x16_bf16 a[80:95], v[112:115], v[108:111], a[80:95]
	v_mfma_f32_32x32x16_bf16 a[64:79], v[112:115], v[100:103], a[64:79]
	v_mfma_f32_32x32x16_bf16 a[48:63], v[128:131], v[108:111], a[48:63]
	v_mfma_f32_32x32x16_bf16 a[32:47], v[128:131], v[100:103], a[32:47]
	ds_read_b128 v[112:115], v61 offset:55360
	ds_read_b128 v[128:131], v61 offset:55392
	s_waitcnt lgkmcnt(1)
	v_mfma_f32_32x32x16_bf16 a[16:31], v[112:115], v[108:111], a[16:31]
	v_mfma_f32_32x32x16_bf16 a[0:15], v[112:115], v[100:103], a[0:15]
	v_mfma_f32_32x32x16_bf16 a[112:127], v[124:127], v[120:123], a[112:127]
	v_mfma_f32_32x32x16_bf16 a[96:111], v[124:127], v[104:107], a[96:111]
	v_mfma_f32_32x32x16_bf16 a[80:95], v[116:119], v[120:123], a[80:95]
	v_mfma_f32_32x32x16_bf16 a[64:79], v[116:119], v[104:107], a[64:79]
	global_load_dwordx4 v[100:103], v[4:5], off offset:896
	global_load_dwordx4 v[108:111], v[0:1], off offset:896
	global_load_dwordx4 v[112:115], v[8:9], off offset:896
	global_load_dwordx4 v[116:119], v[6:7], off offset:896
	v_mfma_f32_32x32x16_bf16 a[48:63], v[140:143], v[120:123], a[48:63]
	v_mfma_f32_32x32x16_bf16 a[32:47], v[140:143], v[104:107], a[32:47]
	global_load_dwordx4 v[124:127], v[10:11], off offset:896
	global_load_dwordx4 v[140:143], v[12:13], off offset:896
	global_load_dwordx4 v[144:147], v[26:27], off offset:896
	global_load_dwordx4 v[148:151], v[14:15], off offset:896
	global_load_dwordx4 v[152:155], v[28:29], off offset:896
	global_load_dwordx4 v[156:159], v[2:3], off offset:896
	global_load_dwordx4 v[160:163], v[30:31], off offset:896
	s_waitcnt lgkmcnt(0)
	v_mfma_f32_32x32x16_bf16 a[16:31], v[128:131], v[120:123], a[16:31]
	global_load_dwordx4 v[120:123], v[32:33], off offset:896
	s_barrier
	v_mfma_f32_32x32x16_bf16 a[0:15], v[128:131], v[104:107], a[0:15]
	ds_read_b128 v[104:107], v59
	ds_read_b128 v[128:131], v62 offset:36864
	ds_read_b128 v[164:167], v59 offset:4608
	ds_read_b128 v[168:171], v62 offset:41472
	s_waitcnt lgkmcnt(2)
	v_mfma_f32_32x32x16_bf16 a[112:127], v[104:107], v[128:131], a[112:127]
	s_waitcnt lgkmcnt(0)
	v_mfma_f32_32x32x16_bf16 a[96:111], v[104:107], v[168:171], a[96:111]
	ds_read_b128 v[104:107], v59 offset:9216
	s_waitcnt lgkmcnt(0)
	v_mfma_f32_32x32x16_bf16 a[48:63], v[104:107], v[128:131], a[48:63]
	v_mfma_f32_32x32x16_bf16 a[32:47], v[104:107], v[168:171], a[32:47]
	ds_read_b128 v[104:107], v61
	s_waitcnt vmcnt(10)
	ds_write_b128 v60, v[108:111] offset:55296
	ds_write_b128 v60, v[100:103] offset:59904
	s_waitcnt vmcnt(8)
	ds_write_b128 v60, v[116:119] offset:64512
	ds_write_b128 v63, v[112:115] offset:55296
	s_waitcnt vmcnt(7)
	ds_write_b128 v64, v[124:127] offset:55296
	s_waitcnt vmcnt(6)
	ds_write_b128 v65, v[140:143] offset:55296
	s_waitcnt vmcnt(4)
	ds_write_b128 v66, v[148:151] offset:55296
	ds_write_b128 v67, v[144:147] offset:55296
	s_waitcnt vmcnt(2)
	ds_write_b128 v68, v[156:159]
	ds_write_b128 v68, v[152:155] offset:4608
	s_waitcnt vmcnt(1)
	ds_write_b128 v68, v[160:163] offset:9216
	s_waitcnt vmcnt(0)
	ds_write_b128 v68, v[120:123] offset:13824
	v_mfma_f32_32x32x16_bf16 a[80:95], v[164:167], v[128:131], a[80:95]
	v_mfma_f32_32x32x16_bf16 a[64:79], v[164:167], v[168:171], a[64:79]
	s_waitcnt lgkmcnt(12)
	v_mfma_f32_32x32x16_bf16 a[16:31], v[104:107], v[128:131], a[16:31]
	v_mfma_f32_32x32x16_bf16 a[0:15], v[104:107], v[168:171], a[0:15]
	ds_read_b128 v[100:103], v59 offset:32
	ds_read_b128 v[104:107], v62 offset:36896
	ds_read_b128 v[108:111], v62 offset:36928
	ds_read_b128 v[112:115], v59 offset:64
	ds_read_b128 v[116:119], v62 offset:41504
	ds_read_b128 v[120:123], v62 offset:36960
	s_waitcnt lgkmcnt(4)
	v_mfma_f32_32x32x16_bf16 a[112:127], v[100:103], v[104:107], a[112:127]
	s_waitcnt lgkmcnt(1)
	v_mfma_f32_32x32x16_bf16 a[96:111], v[100:103], v[116:119], a[96:111]
	ds_read_b128 v[100:103], v59 offset:4640
	ds_read_b128 v[124:127], v59 offset:96
	s_waitcnt lgkmcnt(1)
	v_mfma_f32_32x32x16_bf16 a[80:95], v[100:103], v[104:107], a[80:95]
	v_mfma_f32_32x32x16_bf16 a[64:79], v[100:103], v[116:119], a[64:79]
	ds_read_b128 v[100:103], v59 offset:9248
	ds_read_b128 v[128:131], v59 offset:9280
	s_waitcnt lgkmcnt(1)
	v_mfma_f32_32x32x16_bf16 a[48:63], v[100:103], v[104:107], a[48:63]
	v_mfma_f32_32x32x16_bf16 a[32:47], v[100:103], v[116:119], a[32:47]
	ds_read_b128 v[100:103], v61 offset:32
	ds_read_b128 v[140:143], v59 offset:9312
	s_waitcnt lgkmcnt(1)
	v_mfma_f32_32x32x16_bf16 a[16:31], v[100:103], v[104:107], a[16:31]
	v_mfma_f32_32x32x16_bf16 a[0:15], v[100:103], v[116:119], a[0:15]
	ds_read_b128 v[100:103], v62 offset:41536
	ds_read_b128 v[104:107], v62 offset:41568
	v_mfma_f32_32x32x16_bf16 a[112:127], v[112:115], v[108:111], a[112:127]
	s_waitcnt lgkmcnt(1)
	v_mfma_f32_32x32x16_bf16 a[96:111], v[112:115], v[100:103], a[96:111]
	ds_read_b128 v[112:115], v59 offset:4672
	ds_read_b128 v[116:119], v59 offset:4704
	s_waitcnt lgkmcnt(1)
	v_mfma_f32_32x32x16_bf16 a[80:95], v[112:115], v[108:111], a[80:95]
	v_mfma_f32_32x32x16_bf16 a[64:79], v[112:115], v[100:103], a[64:79]
	v_mfma_f32_32x32x16_bf16 a[48:63], v[128:131], v[108:111], a[48:63]
	v_mfma_f32_32x32x16_bf16 a[32:47], v[128:131], v[100:103], a[32:47]
	ds_read_b128 v[112:115], v61 offset:64
	ds_read_b128 v[128:131], v61 offset:96
	s_waitcnt lgkmcnt(1)
	v_mfma_f32_32x32x16_bf16 a[16:31], v[112:115], v[108:111], a[16:31]
	v_mfma_f32_32x32x16_bf16 a[0:15], v[112:115], v[100:103], a[0:15]
	global_load_dwordx4 v[100:103], v[32:33], off offset:1024
	v_mfma_f32_32x32x16_bf16 a[112:127], v[124:127], v[120:123], a[112:127]
	v_mfma_f32_32x32x16_bf16 a[96:111], v[124:127], v[104:107], a[96:111]
	v_mfma_f32_32x32x16_bf16 a[80:95], v[116:119], v[120:123], a[80:95]
	v_mfma_f32_32x32x16_bf16 a[64:79], v[116:119], v[104:107], a[64:79]
	v_mfma_f32_32x32x16_bf16 a[48:63], v[140:143], v[120:123], a[48:63]
	v_mfma_f32_32x32x16_bf16 a[32:47], v[140:143], v[104:107], a[32:47]
	global_load_dwordx4 v[108:111], v[30:31], off offset:1024
	global_load_dwordx4 v[112:115], v[28:29], off offset:1024
	global_load_dwordx4 v[116:119], v[2:3], off offset:1024
	global_load_dwordx4 v[124:127], v[8:9], off offset:1024
	global_load_dwordx4 v[140:143], v[6:7], off offset:1024
	global_load_dwordx4 v[144:147], v[4:5], off offset:1024
	global_load_dwordx4 v[148:151], v[0:1], off offset:1024
	s_waitcnt lgkmcnt(0)
	v_mfma_f32_32x32x16_bf16 a[16:31], v[128:131], v[120:123], a[16:31]
	global_load_dwordx4 v[120:123], v[12:13], off offset:1024
	global_load_dwordx4 v[152:155], v[10:11], off offset:1024
	global_load_dwordx4 v[156:159], v[26:27], off offset:1024
	global_load_dwordx4 v[160:163], v[14:15], off offset:1024
	s_barrier
	v_mfma_f32_32x32x16_bf16 a[0:15], v[128:131], v[104:107], a[0:15]
	ds_read_b128 v[104:107], v59 offset:55296
	ds_read_b128 v[128:131], v69
	ds_read_b128 v[164:167], v59 offset:59904
	ds_read_b128 v[168:171], v69 offset:4608
	s_waitcnt lgkmcnt(2)
	v_mfma_f32_32x32x16_bf16 a[112:127], v[104:107], v[128:131], a[112:127]
	s_waitcnt lgkmcnt(0)
	v_mfma_f32_32x32x16_bf16 a[96:111], v[104:107], v[168:171], a[96:111]
	ds_read_b128 v[104:107], v59 offset:64512
	s_waitcnt lgkmcnt(0)
	v_mfma_f32_32x32x16_bf16 a[48:63], v[104:107], v[128:131], a[48:63]
	v_mfma_f32_32x32x16_bf16 a[32:47], v[104:107], v[168:171], a[32:47]
	ds_read_b128 v[104:107], v61 offset:55296
	s_waitcnt vmcnt(4)
	ds_write_b128 v60, v[148:151]
	ds_write_b128 v60, v[144:147] offset:4608
	ds_write_b128 v60, v[140:143] offset:9216
	ds_write_b128 v60, v[124:127] offset:13824
	s_waitcnt vmcnt(2)
	ds_write_b128 v60, v[152:155] offset:18432
	ds_write_b128 v60, v[120:123] offset:23040
	s_waitcnt vmcnt(0)
	ds_write_b128 v60, v[160:163] offset:27648
	ds_write_b128 v60, v[156:159] offset:32256
	ds_write_b128 v60, v[116:119] offset:36864
	ds_write_b128 v60, v[112:115] offset:41472
	ds_write_b128 v60, v[108:111] offset:46080
	ds_write_b128 v60, v[100:103] offset:50688
	v_mfma_f32_32x32x16_bf16 a[80:95], v[164:167], v[128:131], a[80:95]
	v_mfma_f32_32x32x16_bf16 a[64:79], v[164:167], v[168:171], a[64:79]
	s_waitcnt lgkmcnt(12)
	v_mfma_f32_32x32x16_bf16 a[16:31], v[104:107], v[128:131], a[16:31]
	v_mfma_f32_32x32x16_bf16 a[0:15], v[104:107], v[168:171], a[0:15]
	ds_read_b128 v[100:103], v59 offset:55328
	ds_read_b128 v[104:107], v69 offset:32
	ds_read_b128 v[108:111], v69 offset:64
	ds_read_b128 v[112:115], v59 offset:55360
	ds_read_b128 v[116:119], v69 offset:4640
	ds_read_b128 v[120:123], v69 offset:96
	s_waitcnt lgkmcnt(4)
	v_mfma_f32_32x32x16_bf16 a[112:127], v[100:103], v[104:107], a[112:127]
	s_waitcnt lgkmcnt(1)
	v_mfma_f32_32x32x16_bf16 a[96:111], v[100:103], v[116:119], a[96:111]
	ds_read_b128 v[100:103], v59 offset:59936
	ds_read_b128 v[124:127], v59 offset:55392
	s_waitcnt lgkmcnt(1)
	v_mfma_f32_32x32x16_bf16 a[80:95], v[100:103], v[104:107], a[80:95]
	v_mfma_f32_32x32x16_bf16 a[64:79], v[100:103], v[116:119], a[64:79]
	ds_read_b128 v[100:103], v59 offset:64544
	ds_read_b128 v[128:131], v59 offset:64576
	s_waitcnt lgkmcnt(1)
	v_mfma_f32_32x32x16_bf16 a[48:63], v[100:103], v[104:107], a[48:63]
	v_mfma_f32_32x32x16_bf16 a[32:47], v[100:103], v[116:119], a[32:47]
	ds_read_b128 v[100:103], v61 offset:55328
	ds_read_b128 v[140:143], v59 offset:64608
	s_waitcnt lgkmcnt(1)
	v_mfma_f32_32x32x16_bf16 a[16:31], v[100:103], v[104:107], a[16:31]
	v_mfma_f32_32x32x16_bf16 a[0:15], v[100:103], v[116:119], a[0:15]
	ds_read_b128 v[100:103], v69 offset:4672
	ds_read_b128 v[104:107], v69 offset:4704
	v_mfma_f32_32x32x16_bf16 a[112:127], v[112:115], v[108:111], a[112:127]
	s_waitcnt lgkmcnt(1)
	v_mfma_f32_32x32x16_bf16 a[96:111], v[112:115], v[100:103], a[96:111]
	ds_read_b128 v[112:115], v59 offset:59968
	ds_read_b128 v[116:119], v59 offset:60000
	s_waitcnt lgkmcnt(1)
	v_mfma_f32_32x32x16_bf16 a[80:95], v[112:115], v[108:111], a[80:95]
	v_mfma_f32_32x32x16_bf16 a[64:79], v[112:115], v[100:103], a[64:79]
	v_mfma_f32_32x32x16_bf16 a[48:63], v[128:131], v[108:111], a[48:63]
	v_mfma_f32_32x32x16_bf16 a[32:47], v[128:131], v[100:103], a[32:47]
	ds_read_b128 v[112:115], v61 offset:55360
	ds_read_b128 v[128:131], v61 offset:55392
	s_waitcnt lgkmcnt(1)
	v_mfma_f32_32x32x16_bf16 a[16:31], v[112:115], v[108:111], a[16:31]
	v_mfma_f32_32x32x16_bf16 a[0:15], v[112:115], v[100:103], a[0:15]
	v_mfma_f32_32x32x16_bf16 a[112:127], v[124:127], v[120:123], a[112:127]
	v_mfma_f32_32x32x16_bf16 a[96:111], v[124:127], v[104:107], a[96:111]
	v_mfma_f32_32x32x16_bf16 a[80:95], v[116:119], v[120:123], a[80:95]
	v_mfma_f32_32x32x16_bf16 a[64:79], v[116:119], v[104:107], a[64:79]
	global_load_dwordx4 v[100:103], v[4:5], off offset:1152
	global_load_dwordx4 v[108:111], v[0:1], off offset:1152
	global_load_dwordx4 v[112:115], v[8:9], off offset:1152
	global_load_dwordx4 v[116:119], v[6:7], off offset:1152
	v_mfma_f32_32x32x16_bf16 a[48:63], v[140:143], v[120:123], a[48:63]
	v_mfma_f32_32x32x16_bf16 a[32:47], v[140:143], v[104:107], a[32:47]
	global_load_dwordx4 v[124:127], v[10:11], off offset:1152
	global_load_dwordx4 v[140:143], v[12:13], off offset:1152
	global_load_dwordx4 v[144:147], v[26:27], off offset:1152
	global_load_dwordx4 v[148:151], v[14:15], off offset:1152
	global_load_dwordx4 v[152:155], v[28:29], off offset:1152
	global_load_dwordx4 v[156:159], v[2:3], off offset:1152
	global_load_dwordx4 v[160:163], v[30:31], off offset:1152
	s_waitcnt lgkmcnt(0)
	v_mfma_f32_32x32x16_bf16 a[16:31], v[128:131], v[120:123], a[16:31]
	global_load_dwordx4 v[120:123], v[32:33], off offset:1152
	s_barrier
	v_mfma_f32_32x32x16_bf16 a[0:15], v[128:131], v[104:107], a[0:15]
	ds_read_b128 v[104:107], v59
	ds_read_b128 v[128:131], v62 offset:36864
	ds_read_b128 v[164:167], v59 offset:4608
	ds_read_b128 v[168:171], v62 offset:41472
	s_waitcnt lgkmcnt(2)
	v_mfma_f32_32x32x16_bf16 a[112:127], v[104:107], v[128:131], a[112:127]
	s_waitcnt lgkmcnt(0)
	v_mfma_f32_32x32x16_bf16 a[96:111], v[104:107], v[168:171], a[96:111]
	ds_read_b128 v[104:107], v59 offset:9216
	s_waitcnt lgkmcnt(0)
	v_mfma_f32_32x32x16_bf16 a[48:63], v[104:107], v[128:131], a[48:63]
	v_mfma_f32_32x32x16_bf16 a[32:47], v[104:107], v[168:171], a[32:47]
	ds_read_b128 v[104:107], v61
	s_waitcnt vmcnt(10)
	ds_write_b128 v60, v[108:111] offset:55296
	ds_write_b128 v60, v[100:103] offset:59904
	s_waitcnt vmcnt(8)
	ds_write_b128 v60, v[116:119] offset:64512
	ds_write_b128 v63, v[112:115] offset:55296
	s_waitcnt vmcnt(7)
	ds_write_b128 v64, v[124:127] offset:55296
	s_waitcnt vmcnt(6)
	ds_write_b128 v65, v[140:143] offset:55296
	s_waitcnt vmcnt(4)
	ds_write_b128 v66, v[148:151] offset:55296
	ds_write_b128 v67, v[144:147] offset:55296
	s_waitcnt vmcnt(2)
	ds_write_b128 v68, v[156:159]
	ds_write_b128 v68, v[152:155] offset:4608
	s_waitcnt vmcnt(1)
	ds_write_b128 v68, v[160:163] offset:9216
	s_waitcnt vmcnt(0)
	ds_write_b128 v68, v[120:123] offset:13824
	v_mfma_f32_32x32x16_bf16 a[80:95], v[164:167], v[128:131], a[80:95]
	v_mfma_f32_32x32x16_bf16 a[64:79], v[164:167], v[168:171], a[64:79]
	s_waitcnt lgkmcnt(12)
	v_mfma_f32_32x32x16_bf16 a[16:31], v[104:107], v[128:131], a[16:31]
	v_mfma_f32_32x32x16_bf16 a[0:15], v[104:107], v[168:171], a[0:15]
	ds_read_b128 v[100:103], v59 offset:32
	ds_read_b128 v[104:107], v62 offset:36896
	ds_read_b128 v[108:111], v62 offset:36928
	ds_read_b128 v[112:115], v59 offset:64
	ds_read_b128 v[116:119], v62 offset:41504
	ds_read_b128 v[120:123], v62 offset:36960
	s_waitcnt lgkmcnt(4)
	v_mfma_f32_32x32x16_bf16 a[112:127], v[100:103], v[104:107], a[112:127]
	s_waitcnt lgkmcnt(1)
	v_mfma_f32_32x32x16_bf16 a[96:111], v[100:103], v[116:119], a[96:111]
	ds_read_b128 v[100:103], v59 offset:4640
	ds_read_b128 v[124:127], v59 offset:96
	s_waitcnt lgkmcnt(1)
	v_mfma_f32_32x32x16_bf16 a[80:95], v[100:103], v[104:107], a[80:95]
	v_mfma_f32_32x32x16_bf16 a[64:79], v[100:103], v[116:119], a[64:79]
	ds_read_b128 v[100:103], v59 offset:9248
	ds_read_b128 v[128:131], v59 offset:9280
	s_waitcnt lgkmcnt(1)
	v_mfma_f32_32x32x16_bf16 a[48:63], v[100:103], v[104:107], a[48:63]
	v_mfma_f32_32x32x16_bf16 a[32:47], v[100:103], v[116:119], a[32:47]
	ds_read_b128 v[100:103], v61 offset:32
	ds_read_b128 v[140:143], v59 offset:9312
	s_waitcnt lgkmcnt(1)
	v_mfma_f32_32x32x16_bf16 a[16:31], v[100:103], v[104:107], a[16:31]
	v_mfma_f32_32x32x16_bf16 a[0:15], v[100:103], v[116:119], a[0:15]
	ds_read_b128 v[100:103], v62 offset:41536
	ds_read_b128 v[104:107], v62 offset:41568
	v_mfma_f32_32x32x16_bf16 a[112:127], v[112:115], v[108:111], a[112:127]
	s_waitcnt lgkmcnt(1)
	v_mfma_f32_32x32x16_bf16 a[96:111], v[112:115], v[100:103], a[96:111]
	ds_read_b128 v[112:115], v59 offset:4672
	ds_read_b128 v[116:119], v59 offset:4704
	s_waitcnt lgkmcnt(1)
	v_mfma_f32_32x32x16_bf16 a[80:95], v[112:115], v[108:111], a[80:95]
	v_mfma_f32_32x32x16_bf16 a[64:79], v[112:115], v[100:103], a[64:79]
	v_mfma_f32_32x32x16_bf16 a[48:63], v[128:131], v[108:111], a[48:63]
	v_mfma_f32_32x32x16_bf16 a[32:47], v[128:131], v[100:103], a[32:47]
	ds_read_b128 v[112:115], v61 offset:64
	ds_read_b128 v[128:131], v61 offset:96
	s_waitcnt lgkmcnt(1)
	v_mfma_f32_32x32x16_bf16 a[16:31], v[112:115], v[108:111], a[16:31]
	v_mfma_f32_32x32x16_bf16 a[0:15], v[112:115], v[100:103], a[0:15]
	global_load_dwordx4 v[100:103], v[32:33], off offset:1280
	v_mfma_f32_32x32x16_bf16 a[112:127], v[124:127], v[120:123], a[112:127]
	v_mfma_f32_32x32x16_bf16 a[96:111], v[124:127], v[104:107], a[96:111]
	v_mfma_f32_32x32x16_bf16 a[80:95], v[116:119], v[120:123], a[80:95]
	v_mfma_f32_32x32x16_bf16 a[64:79], v[116:119], v[104:107], a[64:79]
	v_mfma_f32_32x32x16_bf16 a[48:63], v[140:143], v[120:123], a[48:63]
	v_mfma_f32_32x32x16_bf16 a[32:47], v[140:143], v[104:107], a[32:47]
	global_load_dwordx4 v[108:111], v[30:31], off offset:1280
	global_load_dwordx4 v[112:115], v[28:29], off offset:1280
	global_load_dwordx4 v[116:119], v[2:3], off offset:1280
	global_load_dwordx4 v[124:127], v[8:9], off offset:1280
	global_load_dwordx4 v[140:143], v[6:7], off offset:1280
	global_load_dwordx4 v[144:147], v[4:5], off offset:1280
	global_load_dwordx4 v[148:151], v[0:1], off offset:1280
	s_waitcnt lgkmcnt(0)
	v_mfma_f32_32x32x16_bf16 a[16:31], v[128:131], v[120:123], a[16:31]
	global_load_dwordx4 v[120:123], v[12:13], off offset:1280
	global_load_dwordx4 v[152:155], v[10:11], off offset:1280
	global_load_dwordx4 v[156:159], v[26:27], off offset:1280
	global_load_dwordx4 v[160:163], v[14:15], off offset:1280
	s_barrier
	v_mfma_f32_32x32x16_bf16 a[0:15], v[128:131], v[104:107], a[0:15]
	ds_read_b128 v[104:107], v59 offset:55296
	ds_read_b128 v[128:131], v69
	ds_read_b128 v[164:167], v59 offset:59904
	ds_read_b128 v[168:171], v69 offset:4608
	s_waitcnt lgkmcnt(2)
	v_mfma_f32_32x32x16_bf16 a[112:127], v[104:107], v[128:131], a[112:127]
	s_waitcnt lgkmcnt(0)
	v_mfma_f32_32x32x16_bf16 a[96:111], v[104:107], v[168:171], a[96:111]
	ds_read_b128 v[104:107], v59 offset:64512
	s_waitcnt lgkmcnt(0)
	v_mfma_f32_32x32x16_bf16 a[48:63], v[104:107], v[128:131], a[48:63]
	v_mfma_f32_32x32x16_bf16 a[32:47], v[104:107], v[168:171], a[32:47]
	ds_read_b128 v[104:107], v61 offset:55296
	s_waitcnt vmcnt(4)
	ds_write_b128 v60, v[148:151]
	ds_write_b128 v60, v[144:147] offset:4608
	ds_write_b128 v60, v[140:143] offset:9216
	ds_write_b128 v60, v[124:127] offset:13824
	s_waitcnt vmcnt(2)
	ds_write_b128 v60, v[152:155] offset:18432
	ds_write_b128 v60, v[120:123] offset:23040
	s_waitcnt vmcnt(0)
	ds_write_b128 v60, v[160:163] offset:27648
	ds_write_b128 v60, v[156:159] offset:32256
	ds_write_b128 v60, v[116:119] offset:36864
	ds_write_b128 v60, v[112:115] offset:41472
	ds_write_b128 v60, v[108:111] offset:46080
	ds_write_b128 v60, v[100:103] offset:50688
	v_mfma_f32_32x32x16_bf16 a[80:95], v[164:167], v[128:131], a[80:95]
	v_mfma_f32_32x32x16_bf16 a[64:79], v[164:167], v[168:171], a[64:79]
	s_waitcnt lgkmcnt(12)
	v_mfma_f32_32x32x16_bf16 a[16:31], v[104:107], v[128:131], a[16:31]
	v_mfma_f32_32x32x16_bf16 a[0:15], v[104:107], v[168:171], a[0:15]
	ds_read_b128 v[100:103], v59 offset:55328
	ds_read_b128 v[104:107], v69 offset:32
	ds_read_b128 v[108:111], v69 offset:64
	ds_read_b128 v[112:115], v59 offset:55360
	ds_read_b128 v[116:119], v69 offset:4640
	ds_read_b128 v[120:123], v69 offset:96
	s_waitcnt lgkmcnt(4)
	v_mfma_f32_32x32x16_bf16 a[112:127], v[100:103], v[104:107], a[112:127]
	s_waitcnt lgkmcnt(1)
	v_mfma_f32_32x32x16_bf16 a[96:111], v[100:103], v[116:119], a[96:111]
	ds_read_b128 v[100:103], v59 offset:59936
	ds_read_b128 v[124:127], v59 offset:55392
	s_waitcnt lgkmcnt(1)
	v_mfma_f32_32x32x16_bf16 a[80:95], v[100:103], v[104:107], a[80:95]
	v_mfma_f32_32x32x16_bf16 a[64:79], v[100:103], v[116:119], a[64:79]
	ds_read_b128 v[100:103], v59 offset:64544
	ds_read_b128 v[128:131], v59 offset:64576
	s_waitcnt lgkmcnt(1)
	v_mfma_f32_32x32x16_bf16 a[48:63], v[100:103], v[104:107], a[48:63]
	v_mfma_f32_32x32x16_bf16 a[32:47], v[100:103], v[116:119], a[32:47]
	ds_read_b128 v[100:103], v61 offset:55328
	ds_read_b128 v[140:143], v59 offset:64608
	s_waitcnt lgkmcnt(1)
	v_mfma_f32_32x32x16_bf16 a[16:31], v[100:103], v[104:107], a[16:31]
	v_mfma_f32_32x32x16_bf16 a[0:15], v[100:103], v[116:119], a[0:15]
	ds_read_b128 v[100:103], v69 offset:4672
	ds_read_b128 v[104:107], v69 offset:4704
	v_mfma_f32_32x32x16_bf16 a[112:127], v[112:115], v[108:111], a[112:127]
	s_waitcnt lgkmcnt(1)
	v_mfma_f32_32x32x16_bf16 a[96:111], v[112:115], v[100:103], a[96:111]
	ds_read_b128 v[112:115], v59 offset:59968
	ds_read_b128 v[116:119], v59 offset:60000
	s_waitcnt lgkmcnt(1)
	v_mfma_f32_32x32x16_bf16 a[80:95], v[112:115], v[108:111], a[80:95]
	v_mfma_f32_32x32x16_bf16 a[64:79], v[112:115], v[100:103], a[64:79]
	v_mfma_f32_32x32x16_bf16 a[48:63], v[128:131], v[108:111], a[48:63]
	v_mfma_f32_32x32x16_bf16 a[32:47], v[128:131], v[100:103], a[32:47]
	ds_read_b128 v[112:115], v61 offset:55360
	ds_read_b128 v[128:131], v61 offset:55392
	s_waitcnt lgkmcnt(1)
	v_mfma_f32_32x32x16_bf16 a[16:31], v[112:115], v[108:111], a[16:31]
	v_mfma_f32_32x32x16_bf16 a[0:15], v[112:115], v[100:103], a[0:15]
	v_mfma_f32_32x32x16_bf16 a[112:127], v[124:127], v[120:123], a[112:127]
	v_mfma_f32_32x32x16_bf16 a[96:111], v[124:127], v[104:107], a[96:111]
	v_mfma_f32_32x32x16_bf16 a[80:95], v[116:119], v[120:123], a[80:95]
	v_mfma_f32_32x32x16_bf16 a[64:79], v[116:119], v[104:107], a[64:79]
	global_load_dwordx4 v[100:103], v[4:5], off offset:1408
	global_load_dwordx4 v[108:111], v[0:1], off offset:1408
	global_load_dwordx4 v[112:115], v[8:9], off offset:1408
	global_load_dwordx4 v[116:119], v[6:7], off offset:1408
	v_mfma_f32_32x32x16_bf16 a[48:63], v[140:143], v[120:123], a[48:63]
	v_mfma_f32_32x32x16_bf16 a[32:47], v[140:143], v[104:107], a[32:47]
	global_load_dwordx4 v[124:127], v[10:11], off offset:1408
	global_load_dwordx4 v[140:143], v[12:13], off offset:1408
	global_load_dwordx4 v[144:147], v[26:27], off offset:1408
	global_load_dwordx4 v[148:151], v[14:15], off offset:1408
	global_load_dwordx4 v[152:155], v[28:29], off offset:1408
	global_load_dwordx4 v[156:159], v[2:3], off offset:1408
	global_load_dwordx4 v[160:163], v[30:31], off offset:1408
	s_waitcnt lgkmcnt(0)
	v_mfma_f32_32x32x16_bf16 a[16:31], v[128:131], v[120:123], a[16:31]
	global_load_dwordx4 v[120:123], v[32:33], off offset:1408
	s_barrier
	v_mfma_f32_32x32x16_bf16 a[0:15], v[128:131], v[104:107], a[0:15]
	ds_read_b128 v[104:107], v59
	ds_read_b128 v[128:131], v62 offset:36864
	ds_read_b128 v[164:167], v59 offset:4608
	ds_read_b128 v[168:171], v62 offset:41472
	s_waitcnt lgkmcnt(2)
	v_mfma_f32_32x32x16_bf16 a[112:127], v[104:107], v[128:131], a[112:127]
	s_waitcnt lgkmcnt(0)
	v_mfma_f32_32x32x16_bf16 a[96:111], v[104:107], v[168:171], a[96:111]
	ds_read_b128 v[104:107], v59 offset:9216
	s_waitcnt lgkmcnt(0)
	v_mfma_f32_32x32x16_bf16 a[48:63], v[104:107], v[128:131], a[48:63]
	v_mfma_f32_32x32x16_bf16 a[32:47], v[104:107], v[168:171], a[32:47]
	ds_read_b128 v[104:107], v61
	s_waitcnt vmcnt(10)
	ds_write_b128 v60, v[108:111] offset:55296
	ds_write_b128 v60, v[100:103] offset:59904
	s_waitcnt vmcnt(8)
	ds_write_b128 v60, v[116:119] offset:64512
	ds_write_b128 v63, v[112:115] offset:55296
	s_waitcnt vmcnt(7)
	ds_write_b128 v64, v[124:127] offset:55296
	s_waitcnt vmcnt(6)
	ds_write_b128 v65, v[140:143] offset:55296
	s_waitcnt vmcnt(4)
	ds_write_b128 v66, v[148:151] offset:55296
	ds_write_b128 v67, v[144:147] offset:55296
	s_waitcnt vmcnt(2)
	ds_write_b128 v68, v[156:159]
	ds_write_b128 v68, v[152:155] offset:4608
	s_waitcnt vmcnt(1)
	ds_write_b128 v68, v[160:163] offset:9216
	s_waitcnt vmcnt(0)
	ds_write_b128 v68, v[120:123] offset:13824
	v_mfma_f32_32x32x16_bf16 a[80:95], v[164:167], v[128:131], a[80:95]
	v_mfma_f32_32x32x16_bf16 a[64:79], v[164:167], v[168:171], a[64:79]
	s_waitcnt lgkmcnt(12)
	v_mfma_f32_32x32x16_bf16 a[16:31], v[104:107], v[128:131], a[16:31]
	v_mfma_f32_32x32x16_bf16 a[0:15], v[104:107], v[168:171], a[0:15]
	ds_read_b128 v[100:103], v59 offset:32
	ds_read_b128 v[104:107], v62 offset:36896
	ds_read_b128 v[108:111], v62 offset:36928
	ds_read_b128 v[112:115], v59 offset:64
	ds_read_b128 v[116:119], v62 offset:41504
	ds_read_b128 v[120:123], v62 offset:36960
	s_waitcnt lgkmcnt(4)
	v_mfma_f32_32x32x16_bf16 a[112:127], v[100:103], v[104:107], a[112:127]
	s_waitcnt lgkmcnt(1)
	v_mfma_f32_32x32x16_bf16 a[96:111], v[100:103], v[116:119], a[96:111]
	ds_read_b128 v[100:103], v59 offset:4640
	ds_read_b128 v[124:127], v59 offset:96
	s_waitcnt lgkmcnt(1)
	v_mfma_f32_32x32x16_bf16 a[80:95], v[100:103], v[104:107], a[80:95]
	v_mfma_f32_32x32x16_bf16 a[64:79], v[100:103], v[116:119], a[64:79]
	ds_read_b128 v[100:103], v59 offset:9248
	ds_read_b128 v[128:131], v59 offset:9280
	s_waitcnt lgkmcnt(1)
	v_mfma_f32_32x32x16_bf16 a[48:63], v[100:103], v[104:107], a[48:63]
	v_mfma_f32_32x32x16_bf16 a[32:47], v[100:103], v[116:119], a[32:47]
	ds_read_b128 v[100:103], v61 offset:32
	ds_read_b128 v[140:143], v59 offset:9312
	s_waitcnt lgkmcnt(1)
	v_mfma_f32_32x32x16_bf16 a[16:31], v[100:103], v[104:107], a[16:31]
	v_mfma_f32_32x32x16_bf16 a[0:15], v[100:103], v[116:119], a[0:15]
	ds_read_b128 v[100:103], v62 offset:41536
	ds_read_b128 v[104:107], v62 offset:41568
	v_mfma_f32_32x32x16_bf16 a[112:127], v[112:115], v[108:111], a[112:127]
	s_waitcnt lgkmcnt(1)
	v_mfma_f32_32x32x16_bf16 a[96:111], v[112:115], v[100:103], a[96:111]
	ds_read_b128 v[112:115], v59 offset:4672
	ds_read_b128 v[116:119], v59 offset:4704
	s_waitcnt lgkmcnt(1)
	v_mfma_f32_32x32x16_bf16 a[80:95], v[112:115], v[108:111], a[80:95]
	v_mfma_f32_32x32x16_bf16 a[64:79], v[112:115], v[100:103], a[64:79]
	v_mfma_f32_32x32x16_bf16 a[48:63], v[128:131], v[108:111], a[48:63]
	v_mfma_f32_32x32x16_bf16 a[32:47], v[128:131], v[100:103], a[32:47]
	ds_read_b128 v[112:115], v61 offset:64
	ds_read_b128 v[128:131], v61 offset:96
	s_waitcnt lgkmcnt(1)
	v_mfma_f32_32x32x16_bf16 a[16:31], v[112:115], v[108:111], a[16:31]
	v_mfma_f32_32x32x16_bf16 a[0:15], v[112:115], v[100:103], a[0:15]
	global_load_dwordx4 v[100:103], v[32:33], off offset:1536
	v_mfma_f32_32x32x16_bf16 a[112:127], v[124:127], v[120:123], a[112:127]
	v_mfma_f32_32x32x16_bf16 a[96:111], v[124:127], v[104:107], a[96:111]
	v_mfma_f32_32x32x16_bf16 a[80:95], v[116:119], v[120:123], a[80:95]
	v_mfma_f32_32x32x16_bf16 a[64:79], v[116:119], v[104:107], a[64:79]
	v_mfma_f32_32x32x16_bf16 a[48:63], v[140:143], v[120:123], a[48:63]
	v_mfma_f32_32x32x16_bf16 a[32:47], v[140:143], v[104:107], a[32:47]
	global_load_dwordx4 v[108:111], v[30:31], off offset:1536
	global_load_dwordx4 v[112:115], v[28:29], off offset:1536
	global_load_dwordx4 v[116:119], v[2:3], off offset:1536
	global_load_dwordx4 v[124:127], v[8:9], off offset:1536
	global_load_dwordx4 v[140:143], v[6:7], off offset:1536
	global_load_dwordx4 v[144:147], v[4:5], off offset:1536
	global_load_dwordx4 v[148:151], v[0:1], off offset:1536
	s_waitcnt lgkmcnt(0)
	v_mfma_f32_32x32x16_bf16 a[16:31], v[128:131], v[120:123], a[16:31]
	global_load_dwordx4 v[120:123], v[12:13], off offset:1536
	global_load_dwordx4 v[152:155], v[10:11], off offset:1536
	global_load_dwordx4 v[156:159], v[26:27], off offset:1536
	global_load_dwordx4 v[160:163], v[14:15], off offset:1536
	s_barrier
	v_mfma_f32_32x32x16_bf16 a[0:15], v[128:131], v[104:107], a[0:15]
	ds_read_b128 v[104:107], v59 offset:55296
	ds_read_b128 v[128:131], v69
	ds_read_b128 v[164:167], v59 offset:59904
	ds_read_b128 v[168:171], v69 offset:4608
	s_waitcnt lgkmcnt(2)
	v_mfma_f32_32x32x16_bf16 a[112:127], v[104:107], v[128:131], a[112:127]
	s_waitcnt lgkmcnt(0)
	v_mfma_f32_32x32x16_bf16 a[96:111], v[104:107], v[168:171], a[96:111]
	ds_read_b128 v[104:107], v59 offset:64512
	s_waitcnt lgkmcnt(0)
	v_mfma_f32_32x32x16_bf16 a[48:63], v[104:107], v[128:131], a[48:63]
	v_mfma_f32_32x32x16_bf16 a[32:47], v[104:107], v[168:171], a[32:47]
	ds_read_b128 v[104:107], v61 offset:55296
	s_waitcnt vmcnt(4)
	ds_write_b128 v60, v[148:151]
	ds_write_b128 v60, v[144:147] offset:4608
	ds_write_b128 v60, v[140:143] offset:9216
	ds_write_b128 v60, v[124:127] offset:13824
	s_waitcnt vmcnt(2)
	ds_write_b128 v60, v[152:155] offset:18432
	ds_write_b128 v60, v[120:123] offset:23040
	s_waitcnt vmcnt(0)
	ds_write_b128 v60, v[160:163] offset:27648
	ds_write_b128 v60, v[156:159] offset:32256
	ds_write_b128 v60, v[116:119] offset:36864
	ds_write_b128 v60, v[112:115] offset:41472
	ds_write_b128 v60, v[108:111] offset:46080
	ds_write_b128 v60, v[100:103] offset:50688
	v_mfma_f32_32x32x16_bf16 a[80:95], v[164:167], v[128:131], a[80:95]
	v_mfma_f32_32x32x16_bf16 a[64:79], v[164:167], v[168:171], a[64:79]
	s_waitcnt lgkmcnt(12)
	v_mfma_f32_32x32x16_bf16 a[16:31], v[104:107], v[128:131], a[16:31]
	v_mfma_f32_32x32x16_bf16 a[0:15], v[104:107], v[168:171], a[0:15]
	ds_read_b128 v[100:103], v59 offset:55328
	ds_read_b128 v[104:107], v69 offset:32
	ds_read_b128 v[108:111], v69 offset:64
	ds_read_b128 v[112:115], v59 offset:55360
	ds_read_b128 v[116:119], v69 offset:4640
	ds_read_b128 v[120:123], v69 offset:96
	s_waitcnt lgkmcnt(4)
	v_mfma_f32_32x32x16_bf16 a[112:127], v[100:103], v[104:107], a[112:127]
	s_waitcnt lgkmcnt(1)
	v_mfma_f32_32x32x16_bf16 a[96:111], v[100:103], v[116:119], a[96:111]
	ds_read_b128 v[100:103], v59 offset:59936
	ds_read_b128 v[124:127], v59 offset:55392
	s_waitcnt lgkmcnt(1)
	v_mfma_f32_32x32x16_bf16 a[80:95], v[100:103], v[104:107], a[80:95]
	v_mfma_f32_32x32x16_bf16 a[64:79], v[100:103], v[116:119], a[64:79]
	ds_read_b128 v[100:103], v59 offset:64544
	ds_read_b128 v[128:131], v59 offset:64576
	s_waitcnt lgkmcnt(1)
	v_mfma_f32_32x32x16_bf16 a[48:63], v[100:103], v[104:107], a[48:63]
	v_mfma_f32_32x32x16_bf16 a[32:47], v[100:103], v[116:119], a[32:47]
	ds_read_b128 v[100:103], v61 offset:55328
	ds_read_b128 v[140:143], v59 offset:64608
	s_waitcnt lgkmcnt(1)
	v_mfma_f32_32x32x16_bf16 a[16:31], v[100:103], v[104:107], a[16:31]
	v_mfma_f32_32x32x16_bf16 a[0:15], v[100:103], v[116:119], a[0:15]
	ds_read_b128 v[100:103], v69 offset:4672
	ds_read_b128 v[104:107], v69 offset:4704
	v_mfma_f32_32x32x16_bf16 a[112:127], v[112:115], v[108:111], a[112:127]
	s_waitcnt lgkmcnt(1)
	v_mfma_f32_32x32x16_bf16 a[96:111], v[112:115], v[100:103], a[96:111]
	ds_read_b128 v[112:115], v59 offset:59968
	ds_read_b128 v[116:119], v59 offset:60000
	s_waitcnt lgkmcnt(1)
	v_mfma_f32_32x32x16_bf16 a[80:95], v[112:115], v[108:111], a[80:95]
	v_mfma_f32_32x32x16_bf16 a[64:79], v[112:115], v[100:103], a[64:79]
	v_mfma_f32_32x32x16_bf16 a[48:63], v[128:131], v[108:111], a[48:63]
	v_mfma_f32_32x32x16_bf16 a[32:47], v[128:131], v[100:103], a[32:47]
	ds_read_b128 v[112:115], v61 offset:55360
	ds_read_b128 v[128:131], v61 offset:55392
	s_waitcnt lgkmcnt(1)
	v_mfma_f32_32x32x16_bf16 a[16:31], v[112:115], v[108:111], a[16:31]
	v_mfma_f32_32x32x16_bf16 a[0:15], v[112:115], v[100:103], a[0:15]
	v_mfma_f32_32x32x16_bf16 a[112:127], v[124:127], v[120:123], a[112:127]
	v_mfma_f32_32x32x16_bf16 a[96:111], v[124:127], v[104:107], a[96:111]
	v_mfma_f32_32x32x16_bf16 a[80:95], v[116:119], v[120:123], a[80:95]
	v_mfma_f32_32x32x16_bf16 a[64:79], v[116:119], v[104:107], a[64:79]
	global_load_dwordx4 v[100:103], v[4:5], off offset:1664
	global_load_dwordx4 v[108:111], v[0:1], off offset:1664
	global_load_dwordx4 v[112:115], v[8:9], off offset:1664
	global_load_dwordx4 v[116:119], v[6:7], off offset:1664
	v_mfma_f32_32x32x16_bf16 a[48:63], v[140:143], v[120:123], a[48:63]
	v_mfma_f32_32x32x16_bf16 a[32:47], v[140:143], v[104:107], a[32:47]
	global_load_dwordx4 v[124:127], v[10:11], off offset:1664
	global_load_dwordx4 v[140:143], v[12:13], off offset:1664
	global_load_dwordx4 v[144:147], v[26:27], off offset:1664
	global_load_dwordx4 v[148:151], v[14:15], off offset:1664
	global_load_dwordx4 v[152:155], v[28:29], off offset:1664
	global_load_dwordx4 v[156:159], v[2:3], off offset:1664
	global_load_dwordx4 v[160:163], v[30:31], off offset:1664
	s_waitcnt lgkmcnt(0)
	v_mfma_f32_32x32x16_bf16 a[16:31], v[128:131], v[120:123], a[16:31]
	global_load_dwordx4 v[120:123], v[32:33], off offset:1664
	s_barrier
	v_mfma_f32_32x32x16_bf16 a[0:15], v[128:131], v[104:107], a[0:15]
	ds_read_b128 v[104:107], v59
	ds_read_b128 v[128:131], v62 offset:36864
	ds_read_b128 v[164:167], v59 offset:4608
	ds_read_b128 v[168:171], v62 offset:41472
	s_waitcnt lgkmcnt(2)
	v_mfma_f32_32x32x16_bf16 a[112:127], v[104:107], v[128:131], a[112:127]
	s_waitcnt lgkmcnt(0)
	v_mfma_f32_32x32x16_bf16 a[96:111], v[104:107], v[168:171], a[96:111]
	ds_read_b128 v[104:107], v59 offset:9216
	s_waitcnt lgkmcnt(0)
	v_mfma_f32_32x32x16_bf16 a[48:63], v[104:107], v[128:131], a[48:63]
	v_mfma_f32_32x32x16_bf16 a[32:47], v[104:107], v[168:171], a[32:47]
	ds_read_b128 v[104:107], v61
	s_waitcnt vmcnt(10)
	ds_write_b128 v60, v[108:111] offset:55296
	ds_write_b128 v60, v[100:103] offset:59904
	s_waitcnt vmcnt(8)
	ds_write_b128 v60, v[116:119] offset:64512
	ds_write_b128 v63, v[112:115] offset:55296
	s_waitcnt vmcnt(7)
	ds_write_b128 v64, v[124:127] offset:55296
	s_waitcnt vmcnt(6)
	ds_write_b128 v65, v[140:143] offset:55296
	s_waitcnt vmcnt(4)
	ds_write_b128 v66, v[148:151] offset:55296
	ds_write_b128 v67, v[144:147] offset:55296
	s_waitcnt vmcnt(2)
	ds_write_b128 v68, v[156:159]
	ds_write_b128 v68, v[152:155] offset:4608
	s_waitcnt vmcnt(1)
	ds_write_b128 v68, v[160:163] offset:9216
	s_waitcnt vmcnt(0)
	ds_write_b128 v68, v[120:123] offset:13824
	v_mfma_f32_32x32x16_bf16 a[80:95], v[164:167], v[128:131], a[80:95]
	v_mfma_f32_32x32x16_bf16 a[64:79], v[164:167], v[168:171], a[64:79]
	s_waitcnt lgkmcnt(12)
	v_mfma_f32_32x32x16_bf16 a[16:31], v[104:107], v[128:131], a[16:31]
	v_mfma_f32_32x32x16_bf16 a[0:15], v[104:107], v[168:171], a[0:15]
	ds_read_b128 v[100:103], v59 offset:32
	ds_read_b128 v[104:107], v62 offset:36896
	ds_read_b128 v[108:111], v62 offset:36928
	ds_read_b128 v[112:115], v59 offset:64
	ds_read_b128 v[116:119], v62 offset:41504
	ds_read_b128 v[120:123], v62 offset:36960
	s_waitcnt lgkmcnt(4)
	v_mfma_f32_32x32x16_bf16 a[112:127], v[100:103], v[104:107], a[112:127]
	s_waitcnt lgkmcnt(1)
	v_mfma_f32_32x32x16_bf16 a[96:111], v[100:103], v[116:119], a[96:111]
	ds_read_b128 v[100:103], v59 offset:4640
	ds_read_b128 v[124:127], v59 offset:96
	s_waitcnt lgkmcnt(1)
	v_mfma_f32_32x32x16_bf16 a[80:95], v[100:103], v[104:107], a[80:95]
	v_mfma_f32_32x32x16_bf16 a[64:79], v[100:103], v[116:119], a[64:79]
	ds_read_b128 v[100:103], v59 offset:9248
	ds_read_b128 v[128:131], v59 offset:9280
	s_waitcnt lgkmcnt(1)
	v_mfma_f32_32x32x16_bf16 a[48:63], v[100:103], v[104:107], a[48:63]
	v_mfma_f32_32x32x16_bf16 a[32:47], v[100:103], v[116:119], a[32:47]
	ds_read_b128 v[100:103], v61 offset:32
	ds_read_b128 v[140:143], v59 offset:9312
	s_waitcnt lgkmcnt(1)
	v_mfma_f32_32x32x16_bf16 a[16:31], v[100:103], v[104:107], a[16:31]
	v_mfma_f32_32x32x16_bf16 a[0:15], v[100:103], v[116:119], a[0:15]
	ds_read_b128 v[100:103], v62 offset:41536
	ds_read_b128 v[104:107], v62 offset:41568
	v_mfma_f32_32x32x16_bf16 a[112:127], v[112:115], v[108:111], a[112:127]
	s_waitcnt lgkmcnt(1)
	v_mfma_f32_32x32x16_bf16 a[96:111], v[112:115], v[100:103], a[96:111]
	ds_read_b128 v[112:115], v59 offset:4672
	ds_read_b128 v[116:119], v59 offset:4704
	s_waitcnt lgkmcnt(1)
	v_mfma_f32_32x32x16_bf16 a[80:95], v[112:115], v[108:111], a[80:95]
	v_mfma_f32_32x32x16_bf16 a[64:79], v[112:115], v[100:103], a[64:79]
	v_mfma_f32_32x32x16_bf16 a[48:63], v[128:131], v[108:111], a[48:63]
	v_mfma_f32_32x32x16_bf16 a[32:47], v[128:131], v[100:103], a[32:47]
	ds_read_b128 v[112:115], v61 offset:64
	ds_read_b128 v[128:131], v61 offset:96
	s_waitcnt lgkmcnt(1)
	v_mfma_f32_32x32x16_bf16 a[16:31], v[112:115], v[108:111], a[16:31]
	v_mfma_f32_32x32x16_bf16 a[0:15], v[112:115], v[100:103], a[0:15]
	global_load_dwordx4 v[100:103], v[32:33], off offset:1792
	v_mfma_f32_32x32x16_bf16 a[112:127], v[124:127], v[120:123], a[112:127]
	v_mfma_f32_32x32x16_bf16 a[96:111], v[124:127], v[104:107], a[96:111]
	v_mfma_f32_32x32x16_bf16 a[80:95], v[116:119], v[120:123], a[80:95]
	v_mfma_f32_32x32x16_bf16 a[64:79], v[116:119], v[104:107], a[64:79]
	v_mfma_f32_32x32x16_bf16 a[48:63], v[140:143], v[120:123], a[48:63]
	v_mfma_f32_32x32x16_bf16 a[32:47], v[140:143], v[104:107], a[32:47]
	global_load_dwordx4 v[108:111], v[30:31], off offset:1792
	global_load_dwordx4 v[112:115], v[28:29], off offset:1792
	global_load_dwordx4 v[116:119], v[2:3], off offset:1792
	global_load_dwordx4 v[124:127], v[8:9], off offset:1792
	global_load_dwordx4 v[140:143], v[6:7], off offset:1792
	global_load_dwordx4 v[144:147], v[4:5], off offset:1792
	global_load_dwordx4 v[148:151], v[0:1], off offset:1792
	s_waitcnt lgkmcnt(0)
	v_mfma_f32_32x32x16_bf16 a[16:31], v[128:131], v[120:123], a[16:31]
	global_load_dwordx4 v[120:123], v[12:13], off offset:1792
	global_load_dwordx4 v[152:155], v[10:11], off offset:1792
	global_load_dwordx4 v[156:159], v[26:27], off offset:1792
	global_load_dwordx4 v[160:163], v[14:15], off offset:1792
	s_barrier
	v_mfma_f32_32x32x16_bf16 a[0:15], v[128:131], v[104:107], a[0:15]
	ds_read_b128 v[104:107], v59 offset:55296
	ds_read_b128 v[128:131], v69
	ds_read_b128 v[164:167], v59 offset:59904
	ds_read_b128 v[168:171], v69 offset:4608
	s_waitcnt lgkmcnt(2)
	v_mfma_f32_32x32x16_bf16 a[112:127], v[104:107], v[128:131], a[112:127]
	s_waitcnt lgkmcnt(0)
	v_mfma_f32_32x32x16_bf16 a[96:111], v[104:107], v[168:171], a[96:111]
	ds_read_b128 v[104:107], v59 offset:64512
	s_waitcnt lgkmcnt(0)
	v_mfma_f32_32x32x16_bf16 a[48:63], v[104:107], v[128:131], a[48:63]
	v_mfma_f32_32x32x16_bf16 a[32:47], v[104:107], v[168:171], a[32:47]
	ds_read_b128 v[104:107], v61 offset:55296
	s_waitcnt vmcnt(4)
	ds_write_b128 v60, v[148:151]
	ds_write_b128 v60, v[144:147] offset:4608
	ds_write_b128 v60, v[140:143] offset:9216
	ds_write_b128 v60, v[124:127] offset:13824
	s_waitcnt vmcnt(2)
	ds_write_b128 v60, v[152:155] offset:18432
	ds_write_b128 v60, v[120:123] offset:23040
	s_waitcnt vmcnt(0)
	ds_write_b128 v60, v[160:163] offset:27648
	ds_write_b128 v60, v[156:159] offset:32256
	ds_write_b128 v60, v[116:119] offset:36864
	ds_write_b128 v60, v[112:115] offset:41472
	ds_write_b128 v60, v[108:111] offset:46080
	ds_write_b128 v60, v[100:103] offset:50688
	v_mfma_f32_32x32x16_bf16 a[80:95], v[164:167], v[128:131], a[80:95]
	v_mfma_f32_32x32x16_bf16 a[64:79], v[164:167], v[168:171], a[64:79]
	s_waitcnt lgkmcnt(12)
	v_mfma_f32_32x32x16_bf16 a[16:31], v[104:107], v[128:131], a[16:31]
	v_mfma_f32_32x32x16_bf16 a[0:15], v[104:107], v[168:171], a[0:15]
	ds_read_b128 v[100:103], v59 offset:55328
	ds_read_b128 v[104:107], v69 offset:32
	ds_read_b128 v[108:111], v69 offset:64
	ds_read_b128 v[112:115], v59 offset:55360
	ds_read_b128 v[116:119], v69 offset:4640
	ds_read_b128 v[120:123], v69 offset:96
	s_waitcnt lgkmcnt(4)
	v_mfma_f32_32x32x16_bf16 a[112:127], v[100:103], v[104:107], a[112:127]
	s_waitcnt lgkmcnt(1)
	v_mfma_f32_32x32x16_bf16 a[96:111], v[100:103], v[116:119], a[96:111]
	ds_read_b128 v[100:103], v59 offset:59936
	ds_read_b128 v[124:127], v59 offset:55392
	s_waitcnt lgkmcnt(1)
	v_mfma_f32_32x32x16_bf16 a[80:95], v[100:103], v[104:107], a[80:95]
	v_mfma_f32_32x32x16_bf16 a[64:79], v[100:103], v[116:119], a[64:79]
	ds_read_b128 v[100:103], v59 offset:64544
	ds_read_b128 v[128:131], v59 offset:64576
	s_waitcnt lgkmcnt(1)
	v_mfma_f32_32x32x16_bf16 a[48:63], v[100:103], v[104:107], a[48:63]
	v_mfma_f32_32x32x16_bf16 a[32:47], v[100:103], v[116:119], a[32:47]
	ds_read_b128 v[100:103], v61 offset:55328
	ds_read_b128 v[140:143], v59 offset:64608
	s_waitcnt lgkmcnt(1)
	v_mfma_f32_32x32x16_bf16 a[16:31], v[100:103], v[104:107], a[16:31]
	v_mfma_f32_32x32x16_bf16 a[0:15], v[100:103], v[116:119], a[0:15]
	ds_read_b128 v[100:103], v69 offset:4672
	ds_read_b128 v[104:107], v69 offset:4704
	v_mfma_f32_32x32x16_bf16 a[112:127], v[112:115], v[108:111], a[112:127]
	s_waitcnt lgkmcnt(1)
	v_mfma_f32_32x32x16_bf16 a[96:111], v[112:115], v[100:103], a[96:111]
	ds_read_b128 v[112:115], v59 offset:59968
	ds_read_b128 v[116:119], v59 offset:60000
	s_waitcnt lgkmcnt(1)
	v_mfma_f32_32x32x16_bf16 a[80:95], v[112:115], v[108:111], a[80:95]
	v_mfma_f32_32x32x16_bf16 a[64:79], v[112:115], v[100:103], a[64:79]
	v_mfma_f32_32x32x16_bf16 a[48:63], v[128:131], v[108:111], a[48:63]
	v_mfma_f32_32x32x16_bf16 a[32:47], v[128:131], v[100:103], a[32:47]
	ds_read_b128 v[112:115], v61 offset:55360
	ds_read_b128 v[128:131], v61 offset:55392
	s_waitcnt lgkmcnt(1)
	v_mfma_f32_32x32x16_bf16 a[16:31], v[112:115], v[108:111], a[16:31]
	v_mfma_f32_32x32x16_bf16 a[0:15], v[112:115], v[100:103], a[0:15]
	global_load_dwordx4 v[100:103], v[4:5], off offset:1920
	global_load_dwordx4 v[108:111], v[0:1], off offset:1920
	global_load_dwordx4 v[112:115], v[8:9], off offset:1920
	s_nop 0
	global_load_dwordx4 v[4:7], v[6:7], off offset:1920
	v_mfma_f32_32x32x16_bf16 a[112:127], v[124:127], v[120:123], a[112:127]
	v_mfma_f32_32x32x16_bf16 a[96:111], v[124:127], v[104:107], a[96:111]
	v_mfma_f32_32x32x16_bf16 a[80:95], v[116:119], v[120:123], a[80:95]
	v_mfma_f32_32x32x16_bf16 a[64:79], v[116:119], v[104:107], a[64:79]
	v_mfma_f32_32x32x16_bf16 a[48:63], v[140:143], v[120:123], a[48:63]
	v_mfma_f32_32x32x16_bf16 a[32:47], v[140:143], v[104:107], a[32:47]
	global_load_dwordx4 v[8:11], v[10:11], off offset:1920
	s_nop 0
	global_load_dwordx4 v[116:119], v[12:13], off offset:1920
	global_load_dwordx4 v[124:127], v[26:27], off offset:1920
	s_nop 0
	global_load_dwordx4 v[12:15], v[14:15], off offset:1920
	s_nop 0
	global_load_dwordx4 v[26:29], v[28:29], off offset:1920
	s_nop 0
	global_load_dwordx4 v[0:3], v[2:3], off offset:1920
	s_nop 0
	global_load_dwordx4 v[140:143], v[30:31], off offset:1920
	s_nop 0
	global_load_dwordx4 v[30:33], v[32:33], off offset:1920
	s_waitcnt lgkmcnt(0)
	s_barrier
	v_mfma_f32_32x32x16_bf16 a[16:31], v[128:131], v[120:123], a[16:31]
	v_mfma_f32_32x32x16_bf16 a[0:15], v[128:131], v[104:107], a[0:15]
	ds_read_b128 v[104:107], v59
	ds_read_b128 v[120:123], v62 offset:36864
	ds_read_b128 v[128:131], v59 offset:4608
	ds_read_b128 v[144:147], v62 offset:41472
	s_waitcnt lgkmcnt(2)
	v_mfma_f32_32x32x16_bf16 a[112:127], v[104:107], v[120:123], a[112:127]
	s_waitcnt lgkmcnt(0)
	v_mfma_f32_32x32x16_bf16 a[96:111], v[104:107], v[144:147], a[96:111]
	v_mfma_f32_32x32x16_bf16 a[80:95], v[128:131], v[120:123], a[80:95]
	v_mfma_f32_32x32x16_bf16 a[64:79], v[128:131], v[144:147], a[64:79]
	ds_read_b128 v[104:107], v59 offset:9216
	ds_read_b128 v[128:131], v61
	s_waitcnt vmcnt(10)
	ds_write_b128 v60, v[108:111] offset:55296
	ds_write_b128 v60, v[100:103] offset:59904
	s_waitcnt vmcnt(8)
	ds_write_b128 v60, v[4:7] offset:64512
	ds_write_b128 v63, v[112:115] offset:55296
	s_waitcnt vmcnt(7)
	ds_write_b128 v64, v[8:11] offset:55296
	s_waitcnt vmcnt(6)
	ds_write_b128 v65, v[116:119] offset:55296
	s_waitcnt vmcnt(4)
	ds_write_b128 v66, v[12:15] offset:55296
	ds_write_b128 v67, v[124:127] offset:55296
	s_waitcnt vmcnt(2)
	ds_write_b128 v68, v[0:3]
	ds_write_b128 v68, v[26:29] offset:4608
	s_waitcnt vmcnt(1)
	ds_write_b128 v68, v[140:143] offset:9216
	s_waitcnt vmcnt(0)
	ds_write_b128 v68, v[30:33] offset:13824
	ds_read_b128 v[0:3], v59 offset:32
	ds_read_b128 v[4:7], v62 offset:36896
	ds_read_b128 v[8:11], v62 offset:36928
	ds_read_b128 v[12:15], v59 offset:64
	ds_read_b128 v[26:29], v62 offset:41504
	ds_read_b128 v[30:33], v62 offset:36960
	s_waitcnt lgkmcnt(14)
	v_mfma_f32_32x32x16_bf16 a[48:63], v[104:107], v[120:123], a[48:63]
	v_mfma_f32_32x32x16_bf16 a[32:47], v[104:107], v[144:147], a[32:47]
	s_waitcnt lgkmcnt(4)
	v_mfma_f32_32x32x16_bf16 a[112:127], v[0:3], v[4:7], a[112:127]
	s_waitcnt lgkmcnt(1)
	v_mfma_f32_32x32x16_bf16 a[96:111], v[0:3], v[26:29], a[96:111]
	ds_read_b128 v[0:3], v59 offset:4640
	ds_read_b128 v[100:103], v59 offset:96
	v_mfma_f32_32x32x16_bf16 a[16:31], v[128:131], v[120:123], a[16:31]
	v_mfma_f32_32x32x16_bf16 a[0:15], v[128:131], v[144:147], a[0:15]
	s_waitcnt lgkmcnt(1)
	v_mfma_f32_32x32x16_bf16 a[80:95], v[0:3], v[4:7], a[80:95]
	v_mfma_f32_32x32x16_bf16 a[64:79], v[0:3], v[26:29], a[64:79]
	ds_read_b128 v[0:3], v59 offset:9248
	ds_read_b128 v[104:107], v59 offset:9280
	s_waitcnt lgkmcnt(1)
	v_mfma_f32_32x32x16_bf16 a[48:63], v[0:3], v[4:7], a[48:63]
	v_mfma_f32_32x32x16_bf16 a[32:47], v[0:3], v[26:29], a[32:47]
	ds_read_b128 v[0:3], v61 offset:32
	ds_read_b128 v[108:111], v59 offset:9312
	s_waitcnt lgkmcnt(1)
	v_mfma_f32_32x32x16_bf16 a[16:31], v[0:3], v[4:7], a[16:31]
	v_mfma_f32_32x32x16_bf16 a[0:15], v[0:3], v[26:29], a[0:15]
	ds_read_b128 v[0:3], v62 offset:41536
	ds_read_b128 v[4:7], v62 offset:41568
	v_mfma_f32_32x32x16_bf16 a[112:127], v[12:15], v[8:11], a[112:127]
	s_waitcnt lgkmcnt(1)
	v_mfma_f32_32x32x16_bf16 a[96:111], v[12:15], v[0:3], a[96:111]
	ds_read_b128 v[12:15], v59 offset:4672
	ds_read_b128 v[26:29], v59 offset:4704
	s_waitcnt lgkmcnt(1)
	v_mfma_f32_32x32x16_bf16 a[80:95], v[12:15], v[8:11], a[80:95]
	v_mfma_f32_32x32x16_bf16 a[64:79], v[12:15], v[0:3], a[64:79]
	v_mfma_f32_32x32x16_bf16 a[48:63], v[104:107], v[8:11], a[48:63]
	v_mfma_f32_32x32x16_bf16 a[32:47], v[104:107], v[0:3], a[32:47]
	ds_read_b128 v[12:15], v61 offset:64
	ds_read_b128 v[104:107], v61 offset:96
	s_waitcnt lgkmcnt(0)
	s_barrier
	v_mfma_f32_32x32x16_bf16 a[16:31], v[12:15], v[8:11], a[16:31]
	v_mfma_f32_32x32x16_bf16 a[0:15], v[12:15], v[0:3], a[0:15]
	v_mfma_f32_32x32x16_bf16 a[112:127], v[100:103], v[30:33], a[112:127]
	v_mfma_f32_32x32x16_bf16 a[96:111], v[100:103], v[4:7], a[96:111]
	v_mfma_f32_32x32x16_bf16 a[80:95], v[26:29], v[30:33], a[80:95]
	v_mfma_f32_32x32x16_bf16 a[64:79], v[26:29], v[4:7], a[64:79]
	v_mfma_f32_32x32x16_bf16 a[48:63], v[108:111], v[30:33], a[48:63]
	v_mfma_f32_32x32x16_bf16 a[32:47], v[108:111], v[4:7], a[32:47]
	v_mfma_f32_32x32x16_bf16 a[16:31], v[104:107], v[30:33], a[16:31]
	v_mfma_f32_32x32x16_bf16 a[0:15], v[104:107], v[4:7], a[0:15]
	ds_read_b128 v[0:3], v59 offset:55296
	ds_read_b128 v[4:7], v69
	ds_read_b128 v[8:11], v59 offset:55328
	ds_read_b128 v[12:15], v69 offset:32
	ds_read_b128 v[26:29], v69 offset:4608
	ds_read_b128 v[30:33], v69 offset:4640
	s_waitcnt lgkmcnt(4)
	v_mfma_f32_32x32x16_bf16 a[112:127], v[0:3], v[4:7], a[112:127]
	s_waitcnt lgkmcnt(1)
	v_mfma_f32_32x32x16_bf16 a[96:111], v[0:3], v[26:29], a[96:111]
	ds_read_b128 v[0:3], v59 offset:59904
	ds_read_b128 v[100:103], v59 offset:59936
	s_waitcnt lgkmcnt(1)
	v_mfma_f32_32x32x16_bf16 a[80:95], v[0:3], v[4:7], a[80:95]
	v_mfma_f32_32x32x16_bf16 a[64:79], v[0:3], v[26:29], a[64:79]
	ds_read_b128 v[0:3], v59 offset:64512
	ds_read_b128 v[104:107], v59 offset:64544
	s_waitcnt lgkmcnt(1)
	v_mfma_f32_32x32x16_bf16 a[48:63], v[0:3], v[4:7], a[48:63]
	v_mfma_f32_32x32x16_bf16 a[32:47], v[0:3], v[26:29], a[32:47]
	ds_read_b128 v[0:3], v61 offset:55296
	ds_read_b128 v[108:111], v61 offset:55328
	s_waitcnt lgkmcnt(1)
	v_mfma_f32_32x32x16_bf16 a[0:15], v[0:3], v[26:29], a[0:15]
	v_mfma_f32_32x32x16_bf16 a[112:127], v[8:11], v[12:15], a[112:127]
	v_mfma_f32_32x32x16_bf16 a[96:111], v[8:11], v[30:33], a[96:111]
	v_mfma_f32_32x32x16_bf16 a[16:31], v[0:3], v[4:7], a[16:31]
	v_mfma_f32_32x32x16_bf16 a[80:95], v[100:103], v[12:15], a[80:95]
	v_mfma_f32_32x32x16_bf16 a[64:79], v[100:103], v[30:33], a[64:79]
	v_mfma_f32_32x32x16_bf16 a[32:47], v[104:107], v[30:33], a[32:47]
	s_waitcnt lgkmcnt(0)
	v_mfma_f32_32x32x16_bf16 a[0:15], v[108:111], v[30:33], a[0:15]
	ds_read_b128 v[8:11], v59 offset:55360
	ds_read_b128 v[26:29], v69 offset:64
	ds_read_b128 v[30:33], v59 offset:55392
	ds_read_b128 v[4:7], v69 offset:96
	ds_read_b128 v[100:103], v69 offset:4672
	ds_read_b128 v[0:3], v69 offset:4704
	v_mfma_f32_32x32x16_bf16 a[48:63], v[104:107], v[12:15], a[48:63]
	s_waitcnt lgkmcnt(4)
	v_mfma_f32_32x32x16_bf16 a[112:127], v[8:11], v[26:29], a[112:127]
	s_waitcnt lgkmcnt(1)
	v_mfma_f32_32x32x16_bf16 a[96:111], v[8:11], v[100:103], a[96:111]
	ds_read_b128 v[8:11], v59 offset:59968
	ds_read_b128 v[104:107], v59 offset:60000
	v_mfma_f32_32x32x16_bf16 a[16:31], v[108:111], v[12:15], a[16:31]
	s_waitcnt lgkmcnt(1)
	v_mfma_f32_32x32x16_bf16 a[80:95], v[8:11], v[26:29], a[80:95]
	v_mfma_f32_32x32x16_bf16 a[64:79], v[8:11], v[100:103], a[64:79]
	ds_read_b128 v[8:11], v59 offset:64576
	ds_read_b128 v[12:15], v59 offset:64608
	s_waitcnt lgkmcnt(1)
	v_mfma_f32_32x32x16_bf16 a[48:63], v[8:11], v[26:29], a[48:63]
	v_mfma_f32_32x32x16_bf16 a[32:47], v[8:11], v[100:103], a[32:47]
	ds_read_b128 v[108:111], v61 offset:55360
	ds_read_b128 v[8:11], v61 offset:55392
	s_waitcnt lgkmcnt(0)
	s_barrier
	v_mfma_f32_32x32x16_bf16 a[16:31], v[108:111], v[26:29], a[16:31]
	v_or_b32_e32 v28, s14, v139
	v_lshl_add_u64 v[26:27], v[22:23], 0, s[4:5]
	v_or_b32_e32 v29, s14, v204
	v_mfma_f32_32x32x16_bf16 a[0:15], v[108:111], v[100:103], a[0:15]
	v_mfma_f32_32x32x16_bf16 a[112:127], v[30:33], v[4:7], a[112:127]
	v_mfma_f32_32x32x16_bf16 a[48:63], v[12:15], v[4:7], a[48:63]
	v_mfma_f32_32x32x16_bf16 a[32:47], v[12:15], v[0:3], a[32:47]
	v_lshl_add_u64 v[12:13], v[16:17], 2, v[26:27]
	v_lshlrev_b32_e32 v16, 10, v28
	v_lshl_add_u64 v[14:15], s[16:17], 0, v[24:25]
	v_add_co_u32_e32 v14, vcc, s11, v14
	s_nop 1
	v_addc_co_u32_e32 v15, vcc, 0, v15, vcc
	v_mfma_f32_32x32x16_bf16 a[96:111], v[30:33], v[0:3], a[96:111]
	v_or_b32_e32 v30, s14, v205
	v_lshl_add_u64 v[32:33], v[16:17], 2, v[26:27]
	v_lshlrev_b32_e32 v16, 10, v29
	v_mfma_f32_32x32x16_bf16 a[80:95], v[104:107], v[4:7], a[80:95]
	v_mfma_f32_32x32x16_bf16 a[64:79], v[104:107], v[0:3], a[64:79]
	v_lshl_add_u64 v[104:105], v[16:17], 2, v[26:27]
	v_lshlrev_b32_e32 v16, 10, v30
	v_lshl_add_u64 v[106:107], v[16:17], 2, v[26:27]
	v_mfma_f32_32x32x16_bf16 a[16:31], v[8:11], v[4:7], a[16:31]
	v_mfma_f32_32x32x16_bf16 a[0:15], v[8:11], v[0:3], a[0:15]
	ds_write_b32 v58, a112
	ds_write_b32 v58, a113 offset:516
	ds_write_b32 v58, a114 offset:1032
	ds_write_b32 v58, a115 offset:1548
	ds_write_b32 v58, a116 offset:4128
	ds_write_b32 v58, a117 offset:4644
	ds_write_b32 v58, a118 offset:5160
	ds_write_b32 v58, a119 offset:5676
	ds_write_b32 v58, a120 offset:8256
	ds_write_b32 v58, a121 offset:8772
	ds_write_b32 v58, a122 offset:9288
	ds_write_b32 v58, a123 offset:9804
	ds_write_b32 v58, a124 offset:12384
	ds_write_b32 v58, a125 offset:12900
	ds_write_b32 v58, a126 offset:13416
	ds_write_b32 v58, a127 offset:13932
	ds_write_b32 v58, a96 offset:128
	ds_write_b32 v58, a97 offset:644
	ds_write_b32 v58, a98 offset:1160
	ds_write_b32 v58, a99 offset:1676
	ds_write_b32 v58, a100 offset:4256
	ds_write_b32 v58, a101 offset:4772
	ds_write_b32 v58, a102 offset:5288
	ds_write_b32 v58, a103 offset:5804
	ds_write_b32 v58, a104 offset:8384
	ds_write_b32 v58, a105 offset:8900
	ds_write_b32 v58, a106 offset:9416
	ds_write_b32 v58, a107 offset:9932
	ds_write_b32 v58, a108 offset:12512
	ds_write_b32 v58, a109 offset:13028
	ds_write_b32 v58, a110 offset:13544
	ds_write_b32 v58, a111 offset:14060
	ds_write_b32 v58, a80 offset:16512
	ds_write_b32 v58, a81 offset:17028
	ds_write_b32 v58, a82 offset:17544
	ds_write_b32 v58, a83 offset:18060
	ds_write_b32 v58, a84 offset:20640
	ds_write_b32 v58, a85 offset:21156
	ds_write_b32 v58, a86 offset:21672
	ds_write_b32 v58, a87 offset:22188
	ds_write_b32 v58, a88 offset:24768
	ds_write_b32 v58, a89 offset:25284
	ds_write_b32 v58, a90 offset:25800
	ds_write_b32 v58, a91 offset:26316
	ds_write_b32 v58, a92 offset:28896
	ds_write_b32 v58, a93 offset:29412
	ds_write_b32 v58, a94 offset:29928
	ds_write_b32 v58, a95 offset:30444
	ds_write_b32 v58, a64 offset:16640
	ds_write_b32 v58, a65 offset:17156
	ds_write_b32 v58, a66 offset:17672
	ds_write_b32 v58, a67 offset:18188
	ds_write_b32 v58, a68 offset:20768
	ds_write_b32 v58, a69 offset:21284
	ds_write_b32 v58, a70 offset:21800
	ds_write_b32 v58, a71 offset:22316
	ds_write_b32 v58, a72 offset:24896
	ds_write_b32 v58, a73 offset:25412
	ds_write_b32 v58, a74 offset:25928
	ds_write_b32 v58, a75 offset:26444
	ds_write_b32 v58, a76 offset:29024
	ds_write_b32 v58, a77 offset:29540
	ds_write_b32 v58, a78 offset:30056
	ds_write_b32 v58, a79 offset:30572
	ds_write_b32 v58, a48 offset:33024
	ds_write_b32 v58, a49 offset:33540
	ds_write_b32 v58, a50 offset:34056
	ds_write_b32 v58, a51 offset:34572
	ds_write_b32 v58, a52 offset:37152
	ds_write_b32 v58, a53 offset:37668
	ds_write_b32 v58, a54 offset:38184
	ds_write_b32 v58, a55 offset:38700
	ds_write_b32 v58, a56 offset:41280
	ds_write_b32 v58, a57 offset:41796
	ds_write_b32 v58, a58 offset:42312
	ds_write_b32 v58, a59 offset:42828
	ds_write_b32 v58, a60 offset:45408
	ds_write_b32 v58, a61 offset:45924
	ds_write_b32 v58, a62 offset:46440
	ds_write_b32 v58, a63 offset:46956
	ds_write_b32 v58, a32 offset:33152
	ds_write_b32 v58, a33 offset:33668
	ds_write_b32 v58, a34 offset:34184
	ds_write_b32 v58, a35 offset:34700
	ds_write_b32 v58, a36 offset:37280
	ds_write_b32 v58, a37 offset:37796
	ds_write_b32 v58, a38 offset:38312
	ds_write_b32 v58, a39 offset:38828
	ds_write_b32 v58, a40 offset:41408
	ds_write_b32 v58, a41 offset:41924
	ds_write_b32 v58, a42 offset:42440
	ds_write_b32 v58, a43 offset:42956
	ds_write_b32 v58, a44 offset:45536
	ds_write_b32 v58, a45 offset:46052
	ds_write_b32 v58, a46 offset:46568
	ds_write_b32 v58, a47 offset:47084
	ds_write_b32 v58, a16 offset:49536
	ds_write_b32 v58, a17 offset:50052
	ds_write_b32 v58, a18 offset:50568
	ds_write_b32 v58, a19 offset:51084
	ds_write_b32 v58, a20 offset:53664
	ds_write_b32 v58, a21 offset:54180
	ds_write_b32 v58, a22 offset:54696
	ds_write_b32 v58, a23 offset:55212
	ds_write_b32 v58, a24 offset:57792
	ds_write_b32 v58, a25 offset:58308
	ds_write_b32 v58, a26 offset:58824
	ds_write_b32 v58, a27 offset:59340
	ds_write_b32 v58, a28 offset:61920
	ds_write_b32 v58, a29 offset:62436
	ds_write_b32 v58, a30 offset:62952
	ds_write_b32 v58, a31 offset:63468
	ds_write_b32 v58, a0 offset:49664
	ds_write_b32 v58, a1 offset:50180
	ds_write_b32 v58, a2 offset:50696
	ds_write_b32 v58, a3 offset:51212
	ds_write_b32 v58, a4 offset:53792
	ds_write_b32 v58, a5 offset:54308
	ds_write_b32 v58, a6 offset:54824
	ds_write_b32 v58, a7 offset:55340
	ds_write_b32 v58, a8 offset:57920
	ds_write_b32 v58, a9 offset:58436
	ds_write_b32 v58, a10 offset:58952
	ds_write_b32 v58, a11 offset:59468
	ds_write_b32 v58, a12 offset:62048
	ds_write_b32 v58, a13 offset:62564
	ds_write_b32 v58, a14 offset:63080
	ds_write_b32 v58, a15 offset:63596
	s_waitcnt lgkmcnt(0)
	s_barrier
	global_load_dwordx4 v[0:3], v[14:15], off
	v_mov_b32_e32 v144, v14
	v_mov_b32_e32 v145, v15
	v_mov_b32_e32 v146, v16
	v_mov_b32_e32 v147, v17
	v_mov_b32_e32 v148, v28
	v_mov_b32_e32 v149, v29
	v_mov_b32_e32 v150, v32
	v_mov_b32_e32 v151, v33
	v_mov_b32_e32 v152, v104
	v_mov_b32_e32 v153, v105
	v_mov_b32_e32 v154, v106
	v_mov_b32_e32 v155, v107
	v_mov_b32_e32 v156, v108
	v_mov_b32_e32 v157, v109
	v_mov_b32_e32 v158, v110
	v_mov_b32_e32 v159, v111
	global_load_dwordx4 v[250:253], v[150:151], off
	global_load_dwordx4 v[246:249], v[152:153], off
	global_load_dwordx4 v[242:245], v[154:155], off
	global_load_dwordx4 v[238:241], v[12:13], off
	v_or_b32_e32 v144, s14, v206
	v_lshlrev_b32_e32 v146, 10, v144
	v_lshl_add_u64 v[144:145], v[146:147], 2, v[26:27]
	v_or_b32_e32 v146, s14, v207
	v_lshlrev_b32_e32 v146, 10, v146
	global_load_dwordx4 v[234:237], v[144:145], off
	v_or_b32_e32 v148, s14, v208
	v_or_b32_e32 v149, s14, v209
	v_lshl_add_u64 v[150:151], v[146:147], 2, v[26:27]
	v_lshlrev_b32_e32 v146, 10, v148
	v_lshl_add_u64 v[152:153], v[146:147], 2, v[26:27]
	v_lshlrev_b32_e32 v146, 10, v149
	v_lshl_add_u64 v[154:155], v[146:147], 2, v[26:27]
	global_load_dwordx4 v[212:215], v[150:151], off
	global_load_dwordx4 v[200:203], v[152:153], off
	global_load_dwordx4 v[196:199], v[154:155], off
	v_or_b32_e32 v144, s14, v210
	v_lshlrev_b32_e32 v146, 10, v144
	v_lshl_add_u64 v[144:145], v[146:147], 2, v[26:27]
	v_or_b32_e32 v146, s14, v35
	v_lshlrev_b32_e32 v146, 10, v146
	global_load_dwordx4 v[192:195], v[144:145], off
	v_or_b32_e32 v148, s14, v36
	v_or_b32_e32 v149, s14, v37
	v_lshl_add_u64 v[150:151], v[146:147], 2, v[26:27]
	v_lshlrev_b32_e32 v146, 10, v148
	v_lshl_add_u64 v[152:153], v[146:147], 2, v[26:27]
	v_lshlrev_b32_e32 v146, 10, v149
	v_lshl_add_u64 v[154:155], v[146:147], 2, v[26:27]
	global_load_dwordx4 v[188:191], v[150:151], off
	global_load_dwordx4 v[184:187], v[152:153], off
	global_load_dwordx4 v[180:183], v[154:155], off
	v_or_b32_e32 v144, s14, v38
	v_lshlrev_b32_e32 v146, 10, v144
	v_lshl_add_u64 v[144:145], v[146:147], 2, v[26:27]
	v_or_b32_e32 v146, s14, v39
	v_lshlrev_b32_e32 v146, 10, v146
	global_load_dwordx4 v[176:179], v[144:145], off
	v_or_b32_e32 v148, s14, v40
	v_or_b32_e32 v149, s14, v41
	v_lshl_add_u64 v[150:151], v[146:147], 2, v[26:27]
	v_lshlrev_b32_e32 v146, 10, v148
	v_lshl_add_u64 v[156:157], v[146:147], 2, v[26:27]
	v_lshlrev_b32_e32 v146, 10, v149
	v_lshl_add_u64 v[158:159], v[146:147], 2, v[26:27]
	global_load_dwordx4 v[172:175], v[150:151], off
	global_load_dwordx4 v[168:171], v[156:157], off
	global_load_dwordx4 v[164:167], v[158:159], off
	s_waitcnt vmcnt(15)
	s_nop 1
	v_mov_b64_e32 v[8:9], v[250:251]
	v_mov_b64_e32 v[10:11], v[252:253]
	s_waitcnt vmcnt(14)
	s_nop 1
	v_mov_b64_e32 v[28:29], v[246:247]
	v_mov_b64_e32 v[30:31], v[248:249]
	s_waitcnt vmcnt(13)
	s_nop 1
	v_mov_b64_e32 v[100:101], v[242:243]
	v_mov_b64_e32 v[102:103], v[244:245]
	s_waitcnt vmcnt(12)
	s_nop 1
	v_mov_b64_e32 v[4:5], v[238:239]
	v_mov_b64_e32 v[6:7], v[240:241]
	ds_read2_b32 v[108:109], v70 offset1:1
	ds_read2_b32 v[110:111], v71 offset1:1
	ds_read2_b32 v[112:113], v72 offset1:1
	ds_read2_b32 v[114:115], v73 offset1:1
	ds_read2_b32 v[116:117], v74 offset1:1
	ds_read2_b32 v[118:119], v75 offset1:1
	ds_read2_b32 v[120:121], v76 offset1:1
	ds_read2_b32 v[122:123], v77 offset1:1
	v_or_b32_e32 v14, s14, v206
	v_lshlrev_b32_e32 v16, 10, v14
	v_lshl_add_u64 v[14:15], v[16:17], 2, v[26:27]
	v_or_b32_e32 v16, s14, v207
	v_lshlrev_b32_e32 v16, 10, v16
	s_waitcnt lgkmcnt(6)
	v_pk_fma_f32 v[10:11], v[2:3], v[110:111], v[10:11]
	v_pk_fma_f32 v[8:9], v[0:1], v[108:109], v[8:9]
	s_waitcnt lgkmcnt(4)
	v_pk_fma_f32 v[30:31], v[2:3], v[114:115], v[30:31]
	v_pk_fma_f32 v[28:29], v[0:1], v[112:113], v[28:29]
	s_waitcnt lgkmcnt(2)
	v_pk_fma_f32 v[102:103], v[2:3], v[118:119], v[102:103]
	v_pk_fma_f32 v[100:101], v[0:1], v[116:117], v[100:101]
	global_store_dwordx4 v[32:33], v[8:11], off
	global_store_dwordx4 v[104:105], v[28:31], off
	global_store_dwordx4 v[106:107], v[100:103], off
	s_waitcnt vmcnt(14)
	s_nop 1
	v_mov_b64_e32 v[8:9], v[234:235]
	v_mov_b64_e32 v[10:11], v[236:237]
	v_or_b32_e32 v28, s14, v208
	v_or_b32_e32 v29, s14, v209
	v_lshl_add_u64 v[32:33], v[16:17], 2, v[26:27]
	v_lshlrev_b32_e32 v16, 10, v28
	v_lshl_add_u64 v[104:105], v[16:17], 2, v[26:27]
	v_lshlrev_b32_e32 v16, 10, v29
	v_lshl_add_u64 v[106:107], v[16:17], 2, v[26:27]
	s_waitcnt lgkmcnt(0)
	v_pk_fma_f32 v[10:11], v[2:3], v[122:123], v[10:11]
	v_pk_fma_f32 v[8:9], v[0:1], v[120:121], v[8:9]
	global_store_dwordx4 v[14:15], v[8:11], off
	s_waitcnt vmcnt(14)
	s_nop 1
	v_mov_b64_e32 v[8:9], v[212:213]
	v_mov_b64_e32 v[10:11], v[214:215]
	s_nop 0
	s_waitcnt vmcnt(13)
	s_nop 1
	v_mov_b64_e32 v[28:29], v[200:201]
	v_mov_b64_e32 v[30:31], v[202:203]
	s_waitcnt vmcnt(12)
	s_nop 1
	v_mov_b64_e32 v[100:101], v[196:197]
	v_mov_b64_e32 v[102:103], v[198:199]
	ds_read2_b32 v[108:109], v78 offset1:1
	ds_read2_b32 v[110:111], v79 offset1:1
	ds_read2_b32 v[112:113], v80 offset1:1
	ds_read2_b32 v[114:115], v81 offset1:1
	ds_read2_b32 v[116:117], v82 offset1:1
	ds_read2_b32 v[118:119], v83 offset1:1
	ds_read2_b32 v[120:121], v84 offset1:1
	ds_read2_b32 v[122:123], v85 offset1:1
	v_or_b32_e32 v14, s14, v210
	v_lshlrev_b32_e32 v16, 10, v14
	v_lshl_add_u64 v[14:15], v[16:17], 2, v[26:27]
	v_or_b32_e32 v16, s14, v35
	v_lshlrev_b32_e32 v16, 10, v16
	s_waitcnt lgkmcnt(6)
	v_pk_fma_f32 v[10:11], v[2:3], v[110:111], v[10:11]
	v_pk_fma_f32 v[8:9], v[0:1], v[108:109], v[8:9]
	s_waitcnt lgkmcnt(4)
	v_pk_fma_f32 v[30:31], v[2:3], v[114:115], v[30:31]
	v_pk_fma_f32 v[28:29], v[0:1], v[112:113], v[28:29]
	s_waitcnt lgkmcnt(2)
	v_pk_fma_f32 v[102:103], v[2:3], v[118:119], v[102:103]
	v_pk_fma_f32 v[100:101], v[0:1], v[116:117], v[100:101]
	global_store_dwordx4 v[32:33], v[8:11], off
	global_store_dwordx4 v[104:105], v[28:31], off
	global_store_dwordx4 v[106:107], v[100:103], off
	s_waitcnt vmcnt(14)
	s_nop 1
	v_mov_b64_e32 v[8:9], v[192:193]
	v_mov_b64_e32 v[10:11], v[194:195]
	v_or_b32_e32 v28, s14, v36
	v_or_b32_e32 v29, s14, v37
	v_lshl_add_u64 v[32:33], v[16:17], 2, v[26:27]
	v_lshlrev_b32_e32 v16, 10, v28
	v_lshl_add_u64 v[104:105], v[16:17], 2, v[26:27]
	v_lshlrev_b32_e32 v16, 10, v29
	v_lshl_add_u64 v[106:107], v[16:17], 2, v[26:27]
	s_waitcnt lgkmcnt(0)
	v_pk_fma_f32 v[10:11], v[2:3], v[122:123], v[10:11]
	v_pk_fma_f32 v[8:9], v[0:1], v[120:121], v[8:9]
	global_store_dwordx4 v[14:15], v[8:11], off
	s_waitcnt vmcnt(14)
	s_nop 1
	v_mov_b64_e32 v[8:9], v[188:189]
	v_mov_b64_e32 v[10:11], v[190:191]
	s_nop 0
	s_waitcnt vmcnt(13)
	s_nop 1
	v_mov_b64_e32 v[28:29], v[184:185]
	v_mov_b64_e32 v[30:31], v[186:187]
	s_waitcnt vmcnt(12)
	s_nop 1
	v_mov_b64_e32 v[100:101], v[180:181]
	v_mov_b64_e32 v[102:103], v[182:183]
	ds_read2_b32 v[108:109], v86 offset1:1
	ds_read2_b32 v[110:111], v87 offset1:1
	ds_read2_b32 v[112:113], v88 offset1:1
	ds_read2_b32 v[114:115], v89 offset1:1
	ds_read2_b32 v[116:117], v90 offset1:1
	ds_read2_b32 v[118:119], v91 offset1:1
	ds_read2_b32 v[120:121], v92 offset1:1
	ds_read2_b32 v[122:123], v93 offset1:1
	v_or_b32_e32 v14, s14, v38
	v_lshlrev_b32_e32 v16, 10, v14
	v_lshl_add_u64 v[14:15], v[16:17], 2, v[26:27]
	v_or_b32_e32 v16, s14, v39
	v_lshlrev_b32_e32 v16, 10, v16
	s_waitcnt lgkmcnt(6)
	v_pk_fma_f32 v[10:11], v[2:3], v[110:111], v[10:11]
	v_pk_fma_f32 v[8:9], v[0:1], v[108:109], v[8:9]
	s_waitcnt lgkmcnt(4)
	v_pk_fma_f32 v[30:31], v[2:3], v[114:115], v[30:31]
	v_pk_fma_f32 v[28:29], v[0:1], v[112:113], v[28:29]
	s_waitcnt lgkmcnt(2)
	v_pk_fma_f32 v[102:103], v[2:3], v[118:119], v[102:103]
	v_pk_fma_f32 v[100:101], v[0:1], v[116:117], v[100:101]
	global_store_dwordx4 v[32:33], v[8:11], off
	global_store_dwordx4 v[104:105], v[28:31], off
	global_store_dwordx4 v[106:107], v[100:103], off
	s_waitcnt vmcnt(14)
	s_nop 1
	v_mov_b64_e32 v[8:9], v[176:177]
	v_mov_b64_e32 v[10:11], v[178:179]
	v_or_b32_e32 v28, s14, v40
	v_or_b32_e32 v29, s14, v41
	v_lshl_add_u64 v[32:33], v[16:17], 2, v[26:27]
	v_lshlrev_b32_e32 v16, 10, v28
	v_lshl_add_u64 v[108:109], v[16:17], 2, v[26:27]
	v_lshlrev_b32_e32 v16, 10, v29
	v_lshl_add_u64 v[110:111], v[16:17], 2, v[26:27]
	s_bitset1_b32 s14, 7
	s_add_u32 s13, s2, s13
	s_addc_u32 s15, s3, s12
	s_add_u32 s12, s13, s4
	s_addc_u32 s13, s15, 0
	s_add_i32 s6, s6, s77
	s_cmpk_lt_u32 s6, 0x60
	s_waitcnt lgkmcnt(0)
	v_pk_fma_f32 v[10:11], v[2:3], v[122:123], v[10:11]
	v_pk_fma_f32 v[8:9], v[0:1], v[120:121], v[8:9]
	global_store_dwordx4 v[14:15], v[8:11], off
	s_waitcnt vmcnt(14)
	s_nop 1
	v_mov_b64_e32 v[28:29], v[172:173]
	v_mov_b64_e32 v[30:31], v[174:175]
	s_waitcnt vmcnt(13)
	s_nop 1
	v_mov_b64_e32 v[100:101], v[168:169]
	v_mov_b64_e32 v[102:103], v[170:171]
	s_waitcnt vmcnt(12)
	s_nop 1
	v_mov_b64_e32 v[104:105], v[164:165]
	v_mov_b64_e32 v[106:107], v[166:167]
	v_or_b32_e32 v10, s14, v135
	v_lshl_add_u64 v[8:9], s[12:13], 0, v[24:25]
	v_or_b32_e32 v11, s14, v139
	v_add_co_u32_e32 v112, vcc, s11, v8
	v_lshlrev_b32_e32 v16, 10, v10
	v_or_b32_e32 v14, s14, v204
	v_addc_co_u32_e32 v113, vcc, 0, v9, vcc
	v_lshl_add_u64 v[8:9], v[16:17], 2, v[26:27]
	v_lshlrev_b32_e32 v16, 10, v11
	v_or_b32_e32 v15, s14, v205
	v_lshl_add_u64 v[114:115], v[16:17], 2, v[26:27]
	v_lshlrev_b32_e32 v16, 10, v14
	v_lshl_add_u64 v[116:117], v[16:17], 2, v[26:27]
	v_lshlrev_b32_e32 v16, 10, v15
	ds_read2_b32 v[120:121], v34 offset1:1
	ds_read2_b32 v[122:123], v34 offset0:2 offset1:3
	ds_read2_b32 v[124:125], v94 offset1:1
	ds_read2_b32 v[126:127], v95 offset1:1
	ds_read2_b32 v[128:129], v96 offset1:1
	ds_read2_b32 v[130:131], v97 offset1:1
	ds_read2_b32 v[132:133], v98 offset1:1
	ds_read2_b32 v[136:137], v99 offset1:1
	ds_read2_b32 v[10:11], v42 offset1:1
	ds_read2_b32 v[14:15], v42 offset0:2 offset1:3
	s_waitcnt lgkmcnt(8)
	v_pk_fma_f32 v[6:7], v[2:3], v[122:123], v[6:7]
	v_pk_fma_f32 v[4:5], v[0:1], v[120:121], v[4:5]
	global_store_dwordx4 v[12:13], v[4:7], off
	v_lshl_add_u64 v[118:119], v[16:17], 2, v[26:27]
	v_or_b32_e32 v12, s14, v206
	v_lshlrev_b32_e32 v16, 10, v12
	v_lshl_add_u64 v[12:13], v[16:17], 2, v[26:27]
	v_or_b32_e32 v16, s14, v207
	v_lshlrev_b32_e32 v16, 10, v16
	s_waitcnt lgkmcnt(6)
	v_pk_fma_f32 v[6:7], v[2:3], v[126:127], v[30:31]
	v_pk_fma_f32 v[4:5], v[0:1], v[124:125], v[28:29]
	s_waitcnt lgkmcnt(4)
	v_pk_fma_f32 v[30:31], v[2:3], v[130:131], v[102:103]
	v_pk_fma_f32 v[28:29], v[0:1], v[128:129], v[100:101]
	s_waitcnt lgkmcnt(2)
	v_pk_fma_f32 v[2:3], v[2:3], v[136:137], v[106:107]
	v_pk_fma_f32 v[0:1], v[0:1], v[132:133], v[104:105]
	global_store_dwordx4 v[32:33], v[4:7], off
	global_store_dwordx4 v[108:109], v[28:31], off
	global_store_dwordx4 v[110:111], v[0:3], off
	global_load_dwordx4 v[0:3], v[112:113], off
	s_nop 0
	v_mov_b32_e32 v128, v12
	v_mov_b32_e32 v129, v13
	v_mov_b32_e32 v130, v16
	v_mov_b32_e32 v131, v17
	v_mov_b32_e32 v132, v26
	v_mov_b32_e32 v133, v27
	v_mov_b32_e32 v136, v32
	v_mov_b32_e32 v137, v33
	v_mov_b32_e32 v144, v100
	v_mov_b32_e32 v145, v101
	v_mov_b32_e32 v146, v108
	v_mov_b32_e32 v147, v109
	v_mov_b32_e32 v148, v110
	v_mov_b32_e32 v149, v111
	global_load_dwordx4 v[250:253], v[114:115], off
	global_load_dwordx4 v[246:249], v[116:117], off
	global_load_dwordx4 v[242:245], v[118:119], off
	global_load_dwordx4 v[238:241], v[8:9], off
	global_load_dwordx4 v[234:237], v[128:129], off
	v_or_b32_e32 v144, s14, v208
	v_or_b32_e32 v145, s14, v209
	v_lshl_add_u64 v[136:137], v[130:131], 2, v[132:133]
	v_lshlrev_b32_e32 v130, 10, v144
	v_lshl_add_u64 v[146:147], v[130:131], 2, v[132:133]
	v_lshlrev_b32_e32 v130, 10, v145
	v_lshl_add_u64 v[148:149], v[130:131], 2, v[132:133]
	global_load_dwordx4 v[212:215], v[136:137], off
	global_load_dwordx4 v[200:203], v[146:147], off
	global_load_dwordx4 v[196:199], v[148:149], off
	v_or_b32_e32 v128, s14, v210
	v_lshlrev_b32_e32 v130, 10, v128
	v_lshl_add_u64 v[128:129], v[130:131], 2, v[132:133]
	v_or_b32_e32 v130, s14, v35
	v_lshlrev_b32_e32 v130, 10, v130
	global_load_dwordx4 v[192:195], v[128:129], off
	v_or_b32_e32 v144, s14, v36
	v_or_b32_e32 v145, s14, v37
	v_lshl_add_u64 v[136:137], v[130:131], 2, v[132:133]
	v_lshlrev_b32_e32 v130, 10, v144
	v_lshl_add_u64 v[146:147], v[130:131], 2, v[132:133]
	v_lshlrev_b32_e32 v130, 10, v145
	v_lshl_add_u64 v[148:149], v[130:131], 2, v[132:133]
	global_load_dwordx4 v[188:191], v[136:137], off
	global_load_dwordx4 v[184:187], v[146:147], off
	global_load_dwordx4 v[180:183], v[148:149], off
	v_or_b32_e32 v128, s14, v38
	v_lshlrev_b32_e32 v130, 10, v128
	v_lshl_add_u64 v[128:129], v[130:131], 2, v[132:133]
	v_add_lshl_u32 v130, s14, v39, 10
	global_load_dwordx4 v[176:179], v[128:129], off
	v_lshl_add_u64 v[136:137], v[130:131], 2, v[132:133]
	v_add_lshl_u32 v130, s14, v40, 10
	v_lshl_add_u64 v[144:145], v[130:131], 2, v[132:133]
	v_add_lshl_u32 v130, s14, v41, 10
	v_lshl_add_u64 v[132:133], v[130:131], 2, v[132:133]
	global_load_dwordx4 v[172:175], v[136:137], off
	global_load_dwordx4 v[168:171], v[144:145], off
	global_load_dwordx4 v[164:167], v[132:133], off
	s_waitcnt vmcnt(15)
	s_nop 1
	v_mov_b64_e32 v[28:29], v[250:251]
	v_mov_b64_e32 v[30:31], v[252:253]
	s_waitcnt vmcnt(14)
	s_nop 1
	v_mov_b64_e32 v[100:101], v[246:247]
	v_mov_b64_e32 v[102:103], v[248:249]
	s_waitcnt vmcnt(13)
	s_nop 1
	v_mov_b64_e32 v[104:105], v[242:243]
	v_mov_b64_e32 v[106:107], v[244:245]
	s_waitcnt vmcnt(12)
	s_nop 1
	v_mov_b64_e32 v[4:5], v[238:239]
	v_mov_b64_e32 v[6:7], v[240:241]
	ds_read2_b32 v[32:33], v43 offset1:1
	ds_read2_b32 v[108:109], v43 offset0:2 offset1:3
	ds_read2_b32 v[110:111], v44 offset1:1
	ds_read2_b32 v[112:113], v44 offset0:2 offset1:3
	ds_read2_b32 v[120:121], v45 offset1:1
	ds_read2_b32 v[122:123], v45 offset0:2 offset1:3
	ds_read2_b32 v[124:125], v46 offset1:1
	ds_read2_b32 v[126:127], v46 offset0:2 offset1:3
	s_waitcnt lgkmcnt(6)
	v_pk_fma_f32 v[30:31], v[2:3], v[108:109], v[30:31]
	v_pk_fma_f32 v[28:29], v[0:1], v[32:33], v[28:29]
	s_waitcnt lgkmcnt(4)
	v_pk_fma_f32 v[102:103], v[2:3], v[112:113], v[102:103]
	v_pk_fma_f32 v[100:101], v[0:1], v[110:111], v[100:101]
	s_waitcnt lgkmcnt(2)
	v_pk_fma_f32 v[106:107], v[2:3], v[122:123], v[106:107]
	v_pk_fma_f32 v[104:105], v[0:1], v[120:121], v[104:105]
	global_store_dwordx4 v[114:115], v[28:31], off
	global_store_dwordx4 v[116:117], v[100:103], off
	global_store_dwordx4 v[118:119], v[104:107], off
	s_waitcnt vmcnt(14)
	s_nop 1
	v_mov_b64_e32 v[28:29], v[234:235]
	v_mov_b64_e32 v[30:31], v[236:237]
	v_or_b32_e32 v100, s14, v208
	v_or_b32_e32 v101, s14, v209
	v_lshl_add_u64 v[32:33], v[16:17], 2, v[26:27]
	v_lshlrev_b32_e32 v16, 10, v100
	v_lshl_add_u64 v[108:109], v[16:17], 2, v[26:27]
	v_lshlrev_b32_e32 v16, 10, v101
	v_lshl_add_u64 v[110:111], v[16:17], 2, v[26:27]
	v_pk_fma_f32 v[6:7], v[2:3], v[14:15], v[6:7]
	v_pk_fma_f32 v[4:5], v[0:1], v[10:11], v[4:5]
	s_waitcnt lgkmcnt(0)
	v_pk_fma_f32 v[30:31], v[2:3], v[126:127], v[30:31]
	v_pk_fma_f32 v[28:29], v[0:1], v[124:125], v[28:29]
	global_store_dwordx4 v[12:13], v[28:31], off
	s_waitcnt vmcnt(14)
	s_nop 1
	v_mov_b64_e32 v[28:29], v[212:213]
	v_mov_b64_e32 v[30:31], v[214:215]
	s_nop 0
	s_waitcnt vmcnt(13)
	s_nop 1
	v_mov_b64_e32 v[100:101], v[200:201]
	v_mov_b64_e32 v[102:103], v[202:203]
	s_waitcnt vmcnt(12)
	s_nop 1
	v_mov_b64_e32 v[104:105], v[196:197]
	v_mov_b64_e32 v[106:107], v[198:199]
	ds_read2_b32 v[112:113], v47 offset1:1
	ds_read2_b32 v[114:115], v47 offset0:2 offset1:3
	ds_read2_b32 v[116:117], v48 offset1:1
	ds_read2_b32 v[118:119], v48 offset0:2 offset1:3
	ds_read2_b32 v[120:121], v49 offset1:1
	ds_read2_b32 v[122:123], v49 offset0:2 offset1:3
	ds_read2_b32 v[124:125], v50 offset1:1
	ds_read2_b32 v[126:127], v50 offset0:2 offset1:3
	v_or_b32_e32 v12, s14, v210
	v_lshlrev_b32_e32 v16, 10, v12
	v_lshl_add_u64 v[12:13], v[16:17], 2, v[26:27]
	v_or_b32_e32 v16, s14, v35
	v_lshlrev_b32_e32 v16, 10, v16
	s_waitcnt lgkmcnt(6)
	v_pk_fma_f32 v[30:31], v[2:3], v[114:115], v[30:31]
	v_pk_fma_f32 v[28:29], v[0:1], v[112:113], v[28:29]
	s_waitcnt lgkmcnt(4)
	v_pk_fma_f32 v[102:103], v[2:3], v[118:119], v[102:103]
	v_pk_fma_f32 v[100:101], v[0:1], v[116:117], v[100:101]
	s_waitcnt lgkmcnt(2)
	v_pk_fma_f32 v[106:107], v[2:3], v[122:123], v[106:107]
	v_pk_fma_f32 v[104:105], v[0:1], v[120:121], v[104:105]
	global_store_dwordx4 v[32:33], v[28:31], off
	global_store_dwordx4 v[108:109], v[100:103], off
	global_store_dwordx4 v[110:111], v[104:107], off
	s_waitcnt vmcnt(14)
	s_nop 1
	v_mov_b64_e32 v[28:29], v[192:193]
	v_mov_b64_e32 v[30:31], v[194:195]
	v_or_b32_e32 v100, s14, v36
	v_or_b32_e32 v101, s14, v37
	v_lshl_add_u64 v[32:33], v[16:17], 2, v[26:27]
	v_lshlrev_b32_e32 v16, 10, v100
	v_lshl_add_u64 v[108:109], v[16:17], 2, v[26:27]
	v_lshlrev_b32_e32 v16, 10, v101
	v_lshl_add_u64 v[110:111], v[16:17], 2, v[26:27]
	s_waitcnt lgkmcnt(0)
	v_pk_fma_f32 v[30:31], v[2:3], v[126:127], v[30:31]
	v_pk_fma_f32 v[28:29], v[0:1], v[124:125], v[28:29]
	global_store_dwordx4 v[12:13], v[28:31], off
	s_waitcnt vmcnt(14)
	s_nop 1
	v_mov_b64_e32 v[28:29], v[188:189]
	v_mov_b64_e32 v[30:31], v[190:191]
	s_nop 0
	s_waitcnt vmcnt(13)
	s_nop 1
	v_mov_b64_e32 v[100:101], v[184:185]
	v_mov_b64_e32 v[102:103], v[186:187]
	s_waitcnt vmcnt(12)
	s_nop 1
	v_mov_b64_e32 v[104:105], v[180:181]
	v_mov_b64_e32 v[106:107], v[182:183]
	ds_read2_b32 v[112:113], v51 offset1:1
	ds_read2_b32 v[114:115], v51 offset0:2 offset1:3
	ds_read2_b32 v[116:117], v52 offset1:1
	ds_read2_b32 v[118:119], v52 offset0:2 offset1:3
	ds_read2_b32 v[120:121], v53 offset1:1
	ds_read2_b32 v[122:123], v53 offset0:2 offset1:3
	ds_read2_b32 v[124:125], v54 offset1:1
	ds_read2_b32 v[126:127], v54 offset0:2 offset1:3
	v_or_b32_e32 v12, s14, v38
	v_lshlrev_b32_e32 v16, 10, v12
	v_lshl_add_u64 v[12:13], v[16:17], 2, v[26:27]
	v_add_lshl_u32 v16, s14, v39, 10
	s_waitcnt lgkmcnt(6)
	v_pk_fma_f32 v[30:31], v[2:3], v[114:115], v[30:31]
	v_pk_fma_f32 v[28:29], v[0:1], v[112:113], v[28:29]
	s_waitcnt lgkmcnt(4)
	v_pk_fma_f32 v[102:103], v[2:3], v[118:119], v[102:103]
	v_pk_fma_f32 v[100:101], v[0:1], v[116:117], v[100:101]
	s_waitcnt lgkmcnt(2)
	v_pk_fma_f32 v[106:107], v[2:3], v[122:123], v[106:107]
	v_pk_fma_f32 v[104:105], v[0:1], v[120:121], v[104:105]
	global_store_dwordx4 v[32:33], v[28:31], off
	global_store_dwordx4 v[108:109], v[100:103], off
	global_store_dwordx4 v[110:111], v[104:107], off
	s_waitcnt vmcnt(14)
	s_nop 1
	v_mov_b64_e32 v[28:29], v[176:177]
	v_mov_b64_e32 v[30:31], v[178:179]
	v_lshl_add_u64 v[32:33], v[16:17], 2, v[26:27]
	v_add_lshl_u32 v16, s14, v40, 10
	global_store_dwordx4 v[8:9], v[4:7], off
	v_lshl_add_u64 v[100:101], v[16:17], 2, v[26:27]
	v_add_lshl_u32 v16, s14, v41, 10
	v_lshl_add_u64 v[26:27], v[16:17], 2, v[26:27]
	s_waitcnt lgkmcnt(0)
	v_pk_fma_f32 v[6:7], v[2:3], v[126:127], v[30:31]
	v_pk_fma_f32 v[4:5], v[0:1], v[124:125], v[28:29]
	global_store_dwordx4 v[12:13], v[4:7], off
	s_waitcnt vmcnt(15)
	s_nop 1
	v_mov_b64_e32 v[4:5], v[172:173]
	v_mov_b64_e32 v[6:7], v[174:175]
	s_nop 0
	s_waitcnt vmcnt(14)
	s_nop 1
	v_mov_b64_e32 v[8:9], v[168:169]
	v_mov_b64_e32 v[10:11], v[170:171]
	s_waitcnt vmcnt(13)
	s_nop 1
	v_mov_b64_e32 v[12:13], v[164:165]
	v_mov_b64_e32 v[14:15], v[166:167]
	ds_read2_b32 v[28:29], v55 offset1:1
	ds_read2_b32 v[30:31], v55 offset0:2 offset1:3
	ds_read2_b32 v[102:103], v56 offset1:1
	ds_read2_b32 v[104:105], v56 offset0:2 offset1:3
	ds_read2_b32 v[106:107], v57 offset1:1
	ds_read2_b32 v[108:109], v57 offset0:2 offset1:3
	s_waitcnt lgkmcnt(4)
	v_pk_fma_f32 v[6:7], v[2:3], v[30:31], v[6:7]
	v_pk_fma_f32 v[4:5], v[0:1], v[28:29], v[4:5]
	s_waitcnt lgkmcnt(2)
	v_pk_fma_f32 v[10:11], v[2:3], v[104:105], v[10:11]
	v_pk_fma_f32 v[8:9], v[0:1], v[102:103], v[8:9]
	s_waitcnt lgkmcnt(0)
	v_pk_fma_f32 v[2:3], v[2:3], v[108:109], v[14:15]
	v_pk_fma_f32 v[0:1], v[0:1], v[106:107], v[12:13]
	global_store_dwordx4 v[32:33], v[4:7], off
	global_store_dwordx4 v[100:101], v[8:11], off
	global_store_dwordx4 v[26:27], v[0:3], off
	s_barrier
	s_cbranch_scc1 .LBB0_1145
	s_load_dwordx2 s[2:3], s[0:1], 0x130

.LBB0_1844:
	s_lshr_b32 s13, s6, 3
	s_add_i32 s13, s13, s7
	s_lshl_b32 s4, s13, 19
	v_lshl_add_u64 v[0:1], v[18:19], 0, s[4:5]
	v_add_co_u32_e32 v4, vcc, 0x10000, v0
	s_and_b32 s12, s6, 7
	s_nop 0
	v_addc_co_u32_e32 v5, vcc, 0, v1, vcc
	v_add_co_u32_e32 v6, vcc, 0x20000, v0
	s_lshl_b32 s4, s12, 18
	s_nop 0
	v_addc_co_u32_e32 v7, vcc, 0, v1, vcc
	v_add_co_u32_e32 v8, vcc, 0x30000, v0
	v_lshl_add_u64 v[2:3], v[20:21], 0, s[4:5]
	s_nop 0
	v_addc_co_u32_e32 v9, vcc, 0, v1, vcc
	v_add_co_u32_e32 v10, vcc, 0x40000, v0
	global_load_dwordx4 v[100:103], v[0:1], off
	global_load_dwordx4 v[104:107], v[0:1], off offset:128
	v_addc_co_u32_e32 v11, vcc, 0, v1, vcc
	v_add_co_u32_e32 v12, vcc, 0x50000, v0
	global_load_dwordx4 v[108:111], v[2:3], off
	global_load_dwordx4 v[112:115], v[2:3], off offset:128
	v_addc_co_u32_e32 v13, vcc, 0, v1, vcc
	v_add_co_u32_e32 v14, vcc, 0x60000, v0
	global_load_dwordx4 v[116:119], v[4:5], off
	global_load_dwordx4 v[120:123], v[4:5], off offset:128
	v_addc_co_u32_e32 v15, vcc, 0, v1, vcc
	v_add_co_u32_e32 v26, vcc, 0x70000, v0
	global_load_dwordx4 v[124:127], v[6:7], off
	global_load_dwordx4 v[128:131], v[6:7], off offset:128
	v_addc_co_u32_e32 v27, vcc, 0, v1, vcc
	v_add_co_u32_e32 v28, vcc, s8, v2
	global_load_dwordx4 v[140:143], v[8:9], off
	global_load_dwordx4 v[144:147], v[8:9], off offset:128
	v_addc_co_u32_e32 v29, vcc, 0, v3, vcc
	s_waitcnt vmcnt(14)
	v_add_co_u32_e32 v30, vcc, s9, v2
	global_load_dwordx4 v[148:151], v[10:11], off
	global_load_dwordx4 v[152:155], v[10:11], off offset:128
	v_addc_co_u32_e32 v31, vcc, 0, v3, vcc
	v_add_co_u32_e32 v32, vcc, s10, v2
	global_load_dwordx4 v[156:159], v[12:13], off
	global_load_dwordx4 v[160:163], v[12:13], off offset:128
	global_load_dwordx4 v[164:167], v[14:15], off
	global_load_dwordx4 v[168:171], v[14:15], off offset:128
	global_load_dwordx4 v[172:175], v[26:27], off
	global_load_dwordx4 v[176:179], v[26:27], off offset:128
	global_load_dwordx4 v[180:183], v[28:29], off
	global_load_dwordx4 v[184:187], v[28:29], off offset:128
	v_addc_co_u32_e32 v33, vcc, 0, v3, vcc
	global_load_dwordx4 v[188:191], v[30:31], off
	global_load_dwordx4 v[192:195], v[30:31], off offset:128
	global_load_dwordx4 v[196:199], v[32:33], off
	global_load_dwordx4 v[200:203], v[32:33], off offset:128
	s_lshl_b32 s14, s13, 8
	s_add_i32 s4, s14, 0xffffe000
	s_add_i32 s15, s14, 0xffffe080
	s_lshr_b32 s4, s4, 12
	s_lshr_b32 s15, s15, 12
	s_add_i32 s4, s4, 11
	s_add_i32 s15, s15, 11
	s_cmp_lt_u32 s13, 32
	s_cselect_b32 s4, 10, s4
	s_cselect_b32 s13, 10, s15
	s_mul_hi_u32 s15, s4, 0x6000
	s_mulk_i32 s4, 0x6000
	s_add_u32 s16, s2, s4
	s_addc_u32 s15, s3, s15
	s_lshl_b32 s4, s12, 9
	v_or_b32_e32 v16, s14, v135
	s_add_u32 s16, s16, s4
	v_lshlrev_b32_e32 v16, 10, v16
	s_addc_u32 s17, s15, 0
	s_mul_hi_u32 s12, s13, 0x6000
	s_mulk_i32 s13, 0x6000
	s_waitcnt vmcnt(23)
	ds_write_b128 v60, v[100:103]
	s_waitcnt vmcnt(21)
	ds_write_b128 v60, v[108:111] offset:36864
	s_waitcnt vmcnt(19)
	ds_write_b128 v60, v[116:119] offset:4608
	s_waitcnt vmcnt(17)
	ds_write_b128 v60, v[124:127] offset:9216
	s_waitcnt vmcnt(15)
	ds_write_b128 v60, v[140:143] offset:13824
	s_waitcnt vmcnt(13)
	ds_write_b128 v60, v[148:151] offset:18432
	s_waitcnt vmcnt(11)
	ds_write_b128 v60, v[156:159] offset:23040
	s_waitcnt vmcnt(9)
	ds_write_b128 v60, v[164:167] offset:27648
	s_waitcnt vmcnt(7)
	ds_write_b128 v60, v[172:175] offset:32256
	s_waitcnt vmcnt(5)
	ds_write_b128 v60, v[180:183] offset:41472
	s_waitcnt vmcnt(3)
	ds_write_b128 v60, v[188:191] offset:46080
	s_waitcnt vmcnt(1)
	ds_write_b128 v60, v[196:199] offset:50688
	s_waitcnt lgkmcnt(0)
	s_barrier
	ds_read_b128 v[100:103], v59
	ds_read_b128 v[108:111], v62 offset:36864
	ds_read_b128 v[116:119], v59 offset:4608
	ds_read_b128 v[124:127], v62 offset:41472
	s_waitcnt lgkmcnt(2)
	v_mfma_f32_32x32x16_bf16 a[112:127], v[100:103], v[108:111], 0
	s_waitcnt lgkmcnt(0)
	v_mfma_f32_32x32x16_bf16 a[96:111], v[100:103], v[124:127], 0
	ds_read_b128 v[100:103], v59 offset:9216
	s_waitcnt lgkmcnt(0)
	v_mfma_f32_32x32x16_bf16 a[48:63], v[100:103], v[108:111], 0
	v_mfma_f32_32x32x16_bf16 a[32:47], v[100:103], v[124:127], 0
	ds_read_b128 v[100:103], v61
	ds_write_b128 v60, v[104:107] offset:55296
	ds_write_b128 v60, v[120:123] offset:59904
	ds_write_b128 v60, v[128:131] offset:64512
	ds_write_b128 v63, v[144:147] offset:55296
	ds_write_b128 v64, v[152:155] offset:55296
	ds_write_b128 v65, v[160:163] offset:55296
	ds_write_b128 v66, v[168:171] offset:55296
	ds_write_b128 v67, v[176:179] offset:55296
	ds_write_b128 v68, v[112:115]
	ds_write_b128 v68, v[184:187] offset:4608
	ds_write_b128 v68, v[192:195] offset:9216
	s_waitcnt vmcnt(0)
	ds_write_b128 v68, v[200:203] offset:13824
	v_mfma_f32_32x32x16_bf16 a[80:95], v[116:119], v[108:111], 0
	v_mfma_f32_32x32x16_bf16 a[64:79], v[116:119], v[124:127], 0
	s_waitcnt lgkmcnt(12)
	v_mfma_f32_32x32x16_bf16 a[16:31], v[100:103], v[108:111], 0
	v_mfma_f32_32x32x16_bf16 a[0:15], v[100:103], v[124:127], 0
	ds_read_b128 v[100:103], v59 offset:32
	ds_read_b128 v[104:107], v62 offset:36896
	ds_read_b128 v[108:111], v62 offset:36928
	ds_read_b128 v[112:115], v59 offset:64
	ds_read_b128 v[116:119], v62 offset:41504
	ds_read_b128 v[120:123], v62 offset:36960
	s_waitcnt lgkmcnt(4)
	v_mfma_f32_32x32x16_bf16 a[112:127], v[100:103], v[104:107], a[112:127]
	s_waitcnt lgkmcnt(1)
	v_mfma_f32_32x32x16_bf16 a[96:111], v[100:103], v[116:119], a[96:111]
	ds_read_b128 v[100:103], v59 offset:4640
	ds_read_b128 v[124:127], v59 offset:96
	s_waitcnt lgkmcnt(1)
	v_mfma_f32_32x32x16_bf16 a[80:95], v[100:103], v[104:107], a[80:95]
	v_mfma_f32_32x32x16_bf16 a[64:79], v[100:103], v[116:119], a[64:79]
	ds_read_b128 v[100:103], v59 offset:9248
	ds_read_b128 v[128:131], v59 offset:9280
	s_waitcnt lgkmcnt(1)
	v_mfma_f32_32x32x16_bf16 a[48:63], v[100:103], v[104:107], a[48:63]
	v_mfma_f32_32x32x16_bf16 a[32:47], v[100:103], v[116:119], a[32:47]
	ds_read_b128 v[100:103], v61 offset:32
	ds_read_b128 v[140:143], v59 offset:9312
	s_waitcnt lgkmcnt(1)
	v_mfma_f32_32x32x16_bf16 a[16:31], v[100:103], v[104:107], a[16:31]
	v_mfma_f32_32x32x16_bf16 a[0:15], v[100:103], v[116:119], a[0:15]
	ds_read_b128 v[100:103], v62 offset:41536
	ds_read_b128 v[104:107], v62 offset:41568
	v_mfma_f32_32x32x16_bf16 a[112:127], v[112:115], v[108:111], a[112:127]
	s_waitcnt lgkmcnt(1)
	v_mfma_f32_32x32x16_bf16 a[96:111], v[112:115], v[100:103], a[96:111]
	ds_read_b128 v[112:115], v59 offset:4672
	ds_read_b128 v[116:119], v59 offset:4704
	s_waitcnt lgkmcnt(1)
	v_mfma_f32_32x32x16_bf16 a[80:95], v[112:115], v[108:111], a[80:95]
	v_mfma_f32_32x32x16_bf16 a[64:79], v[112:115], v[100:103], a[64:79]
	v_mfma_f32_32x32x16_bf16 a[48:63], v[128:131], v[108:111], a[48:63]
	v_mfma_f32_32x32x16_bf16 a[32:47], v[128:131], v[100:103], a[32:47]
	ds_read_b128 v[112:115], v61 offset:64
	ds_read_b128 v[128:131], v61 offset:96
	s_waitcnt lgkmcnt(1)
	v_mfma_f32_32x32x16_bf16 a[16:31], v[112:115], v[108:111], a[16:31]
	v_mfma_f32_32x32x16_bf16 a[0:15], v[112:115], v[100:103], a[0:15]
	global_load_dwordx4 v[100:103], v[32:33], off offset:256
	v_mfma_f32_32x32x16_bf16 a[112:127], v[124:127], v[120:123], a[112:127]
	v_mfma_f32_32x32x16_bf16 a[96:111], v[124:127], v[104:107], a[96:111]
	v_mfma_f32_32x32x16_bf16 a[80:95], v[116:119], v[120:123], a[80:95]
	v_mfma_f32_32x32x16_bf16 a[64:79], v[116:119], v[104:107], a[64:79]
	v_mfma_f32_32x32x16_bf16 a[48:63], v[140:143], v[120:123], a[48:63]
	v_mfma_f32_32x32x16_bf16 a[32:47], v[140:143], v[104:107], a[32:47]
	global_load_dwordx4 v[108:111], v[30:31], off offset:256
	global_load_dwordx4 v[112:115], v[28:29], off offset:256
	global_load_dwordx4 v[116:119], v[2:3], off offset:256
	global_load_dwordx4 v[124:127], v[8:9], off offset:256
	global_load_dwordx4 v[140:143], v[6:7], off offset:256
	global_load_dwordx4 v[144:147], v[4:5], off offset:256
	global_load_dwordx4 v[148:151], v[0:1], off offset:256
	s_waitcnt lgkmcnt(0)
	v_mfma_f32_32x32x16_bf16 a[16:31], v[128:131], v[120:123], a[16:31]
	global_load_dwordx4 v[120:123], v[12:13], off offset:256
	global_load_dwordx4 v[152:155], v[10:11], off offset:256
	global_load_dwordx4 v[156:159], v[26:27], off offset:256
	global_load_dwordx4 v[160:163], v[14:15], off offset:256
	s_barrier
	v_mfma_f32_32x32x16_bf16 a[0:15], v[128:131], v[104:107], a[0:15]
	ds_read_b128 v[104:107], v59 offset:55296
	ds_read_b128 v[128:131], v69
	ds_read_b128 v[164:167], v59 offset:59904
	ds_read_b128 v[168:171], v69 offset:4608
	s_waitcnt lgkmcnt(2)
	v_mfma_f32_32x32x16_bf16 a[112:127], v[104:107], v[128:131], a[112:127]
	s_waitcnt lgkmcnt(0)
	v_mfma_f32_32x32x16_bf16 a[96:111], v[104:107], v[168:171], a[96:111]
	ds_read_b128 v[104:107], v59 offset:64512
	s_waitcnt lgkmcnt(0)
	v_mfma_f32_32x32x16_bf16 a[48:63], v[104:107], v[128:131], a[48:63]
	v_mfma_f32_32x32x16_bf16 a[32:47], v[104:107], v[168:171], a[32:47]
	ds_read_b128 v[104:107], v61 offset:55296
	s_waitcnt vmcnt(4)
	ds_write_b128 v60, v[148:151]
	ds_write_b128 v60, v[144:147] offset:4608
	ds_write_b128 v60, v[140:143] offset:9216
	ds_write_b128 v60, v[124:127] offset:13824
	s_waitcnt vmcnt(2)
	ds_write_b128 v60, v[152:155] offset:18432
	ds_write_b128 v60, v[120:123] offset:23040
	s_waitcnt vmcnt(0)
	ds_write_b128 v60, v[160:163] offset:27648
	ds_write_b128 v60, v[156:159] offset:32256
	ds_write_b128 v60, v[116:119] offset:36864
	ds_write_b128 v60, v[112:115] offset:41472
	ds_write_b128 v60, v[108:111] offset:46080
	ds_write_b128 v60, v[100:103] offset:50688
	v_mfma_f32_32x32x16_bf16 a[80:95], v[164:167], v[128:131], a[80:95]
	v_mfma_f32_32x32x16_bf16 a[64:79], v[164:167], v[168:171], a[64:79]
	s_waitcnt lgkmcnt(12)
	v_mfma_f32_32x32x16_bf16 a[16:31], v[104:107], v[128:131], a[16:31]
	v_mfma_f32_32x32x16_bf16 a[0:15], v[104:107], v[168:171], a[0:15]
	ds_read_b128 v[100:103], v59 offset:55328
	ds_read_b128 v[104:107], v69 offset:32
	ds_read_b128 v[108:111], v69 offset:64
	ds_read_b128 v[112:115], v59 offset:55360
	ds_read_b128 v[116:119], v69 offset:4640
	ds_read_b128 v[120:123], v69 offset:96
	s_waitcnt lgkmcnt(4)
	v_mfma_f32_32x32x16_bf16 a[112:127], v[100:103], v[104:107], a[112:127]
	s_waitcnt lgkmcnt(1)
	v_mfma_f32_32x32x16_bf16 a[96:111], v[100:103], v[116:119], a[96:111]
	ds_read_b128 v[100:103], v59 offset:59936
	ds_read_b128 v[124:127], v59 offset:55392
	s_waitcnt lgkmcnt(1)
	v_mfma_f32_32x32x16_bf16 a[80:95], v[100:103], v[104:107], a[80:95]
	v_mfma_f32_32x32x16_bf16 a[64:79], v[100:103], v[116:119], a[64:79]
	ds_read_b128 v[100:103], v59 offset:64544
	ds_read_b128 v[128:131], v59 offset:64576
	s_waitcnt lgkmcnt(1)
	v_mfma_f32_32x32x16_bf16 a[48:63], v[100:103], v[104:107], a[48:63]
	v_mfma_f32_32x32x16_bf16 a[32:47], v[100:103], v[116:119], a[32:47]
	ds_read_b128 v[100:103], v61 offset:55328
	ds_read_b128 v[140:143], v59 offset:64608
	s_waitcnt lgkmcnt(1)
	v_mfma_f32_32x32x16_bf16 a[16:31], v[100:103], v[104:107], a[16:31]
	v_mfma_f32_32x32x16_bf16 a[0:15], v[100:103], v[116:119], a[0:15]
	ds_read_b128 v[100:103], v69 offset:4672
	ds_read_b128 v[104:107], v69 offset:4704
	v_mfma_f32_32x32x16_bf16 a[112:127], v[112:115], v[108:111], a[112:127]
	s_waitcnt lgkmcnt(1)
	v_mfma_f32_32x32x16_bf16 a[96:111], v[112:115], v[100:103], a[96:111]
	ds_read_b128 v[112:115], v59 offset:59968
	ds_read_b128 v[116:119], v59 offset:60000
	s_waitcnt lgkmcnt(1)
	v_mfma_f32_32x32x16_bf16 a[80:95], v[112:115], v[108:111], a[80:95]
	v_mfma_f32_32x32x16_bf16 a[64:79], v[112:115], v[100:103], a[64:79]
	v_mfma_f32_32x32x16_bf16 a[48:63], v[128:131], v[108:111], a[48:63]
	v_mfma_f32_32x32x16_bf16 a[32:47], v[128:131], v[100:103], a[32:47]
	ds_read_b128 v[112:115], v61 offset:55360
	ds_read_b128 v[128:131], v61 offset:55392
	s_waitcnt lgkmcnt(1)
	v_mfma_f32_32x32x16_bf16 a[16:31], v[112:115], v[108:111], a[16:31]
	v_mfma_f32_32x32x16_bf16 a[0:15], v[112:115], v[100:103], a[0:15]
	v_mfma_f32_32x32x16_bf16 a[112:127], v[124:127], v[120:123], a[112:127]
	v_mfma_f32_32x32x16_bf16 a[96:111], v[124:127], v[104:107], a[96:111]
	v_mfma_f32_32x32x16_bf16 a[80:95], v[116:119], v[120:123], a[80:95]
	v_mfma_f32_32x32x16_bf16 a[64:79], v[116:119], v[104:107], a[64:79]
	global_load_dwordx4 v[100:103], v[4:5], off offset:384
	global_load_dwordx4 v[108:111], v[0:1], off offset:384
	global_load_dwordx4 v[112:115], v[8:9], off offset:384
	global_load_dwordx4 v[116:119], v[6:7], off offset:384
	v_mfma_f32_32x32x16_bf16 a[48:63], v[140:143], v[120:123], a[48:63]
	v_mfma_f32_32x32x16_bf16 a[32:47], v[140:143], v[104:107], a[32:47]
	global_load_dwordx4 v[124:127], v[10:11], off offset:384
	global_load_dwordx4 v[140:143], v[12:13], off offset:384
	global_load_dwordx4 v[144:147], v[26:27], off offset:384
	global_load_dwordx4 v[148:151], v[14:15], off offset:384
	global_load_dwordx4 v[152:155], v[28:29], off offset:384
	global_load_dwordx4 v[156:159], v[2:3], off offset:384
	global_load_dwordx4 v[160:163], v[30:31], off offset:384
	s_waitcnt lgkmcnt(0)
	v_mfma_f32_32x32x16_bf16 a[16:31], v[128:131], v[120:123], a[16:31]
	global_load_dwordx4 v[120:123], v[32:33], off offset:384
	s_barrier
	v_mfma_f32_32x32x16_bf16 a[0:15], v[128:131], v[104:107], a[0:15]
	ds_read_b128 v[104:107], v59
	ds_read_b128 v[128:131], v62 offset:36864
	ds_read_b128 v[164:167], v59 offset:4608
	ds_read_b128 v[168:171], v62 offset:41472
	s_waitcnt lgkmcnt(2)
	v_mfma_f32_32x32x16_bf16 a[112:127], v[104:107], v[128:131], a[112:127]
	s_waitcnt lgkmcnt(0)
	v_mfma_f32_32x32x16_bf16 a[96:111], v[104:107], v[168:171], a[96:111]
	ds_read_b128 v[104:107], v59 offset:9216
	s_waitcnt lgkmcnt(0)
	v_mfma_f32_32x32x16_bf16 a[48:63], v[104:107], v[128:131], a[48:63]
	v_mfma_f32_32x32x16_bf16 a[32:47], v[104:107], v[168:171], a[32:47]
	ds_read_b128 v[104:107], v61
	s_waitcnt vmcnt(10)
	ds_write_b128 v60, v[108:111] offset:55296
	ds_write_b128 v60, v[100:103] offset:59904
	s_waitcnt vmcnt(8)
	ds_write_b128 v60, v[116:119] offset:64512
	ds_write_b128 v63, v[112:115] offset:55296
	s_waitcnt vmcnt(7)
	ds_write_b128 v64, v[124:127] offset:55296
	s_waitcnt vmcnt(6)
	ds_write_b128 v65, v[140:143] offset:55296
	s_waitcnt vmcnt(4)
	ds_write_b128 v66, v[148:151] offset:55296
	ds_write_b128 v67, v[144:147] offset:55296
	s_waitcnt vmcnt(2)
	ds_write_b128 v68, v[156:159]
	ds_write_b128 v68, v[152:155] offset:4608
	s_waitcnt vmcnt(1)
	ds_write_b128 v68, v[160:163] offset:9216
	s_waitcnt vmcnt(0)
	ds_write_b128 v68, v[120:123] offset:13824
	v_mfma_f32_32x32x16_bf16 a[80:95], v[164:167], v[128:131], a[80:95]
	v_mfma_f32_32x32x16_bf16 a[64:79], v[164:167], v[168:171], a[64:79]
	s_waitcnt lgkmcnt(12)
	v_mfma_f32_32x32x16_bf16 a[16:31], v[104:107], v[128:131], a[16:31]
	v_mfma_f32_32x32x16_bf16 a[0:15], v[104:107], v[168:171], a[0:15]
	ds_read_b128 v[100:103], v59 offset:32
	ds_read_b128 v[104:107], v62 offset:36896
	ds_read_b128 v[108:111], v62 offset:36928
	ds_read_b128 v[112:115], v59 offset:64
	ds_read_b128 v[116:119], v62 offset:41504
	ds_read_b128 v[120:123], v62 offset:36960
	s_waitcnt lgkmcnt(4)
	v_mfma_f32_32x32x16_bf16 a[112:127], v[100:103], v[104:107], a[112:127]
	s_waitcnt lgkmcnt(1)
	v_mfma_f32_32x32x16_bf16 a[96:111], v[100:103], v[116:119], a[96:111]
	ds_read_b128 v[100:103], v59 offset:4640
	ds_read_b128 v[124:127], v59 offset:96
	s_waitcnt lgkmcnt(1)
	v_mfma_f32_32x32x16_bf16 a[80:95], v[100:103], v[104:107], a[80:95]
	v_mfma_f32_32x32x16_bf16 a[64:79], v[100:103], v[116:119], a[64:79]
	ds_read_b128 v[100:103], v59 offset:9248
	ds_read_b128 v[128:131], v59 offset:9280
	s_waitcnt lgkmcnt(1)
	v_mfma_f32_32x32x16_bf16 a[48:63], v[100:103], v[104:107], a[48:63]
	v_mfma_f32_32x32x16_bf16 a[32:47], v[100:103], v[116:119], a[32:47]
	ds_read_b128 v[100:103], v61 offset:32
	ds_read_b128 v[140:143], v59 offset:9312
	s_waitcnt lgkmcnt(1)
	v_mfma_f32_32x32x16_bf16 a[16:31], v[100:103], v[104:107], a[16:31]
	v_mfma_f32_32x32x16_bf16 a[0:15], v[100:103], v[116:119], a[0:15]
	ds_read_b128 v[100:103], v62 offset:41536
	ds_read_b128 v[104:107], v62 offset:41568
	v_mfma_f32_32x32x16_bf16 a[112:127], v[112:115], v[108:111], a[112:127]
	s_waitcnt lgkmcnt(1)
	v_mfma_f32_32x32x16_bf16 a[96:111], v[112:115], v[100:103], a[96:111]
	ds_read_b128 v[112:115], v59 offset:4672
	ds_read_b128 v[116:119], v59 offset:4704
	s_waitcnt lgkmcnt(1)
	v_mfma_f32_32x32x16_bf16 a[80:95], v[112:115], v[108:111], a[80:95]
	v_mfma_f32_32x32x16_bf16 a[64:79], v[112:115], v[100:103], a[64:79]
	v_mfma_f32_32x32x16_bf16 a[48:63], v[128:131], v[108:111], a[48:63]
	v_mfma_f32_32x32x16_bf16 a[32:47], v[128:131], v[100:103], a[32:47]
	ds_read_b128 v[112:115], v61 offset:64
	ds_read_b128 v[128:131], v61 offset:96
	s_waitcnt lgkmcnt(1)
	v_mfma_f32_32x32x16_bf16 a[16:31], v[112:115], v[108:111], a[16:31]
	v_mfma_f32_32x32x16_bf16 a[0:15], v[112:115], v[100:103], a[0:15]
	global_load_dwordx4 v[100:103], v[32:33], off offset:512
	v_mfma_f32_32x32x16_bf16 a[112:127], v[124:127], v[120:123], a[112:127]
	v_mfma_f32_32x32x16_bf16 a[96:111], v[124:127], v[104:107], a[96:111]
	v_mfma_f32_32x32x16_bf16 a[80:95], v[116:119], v[120:123], a[80:95]
	v_mfma_f32_32x32x16_bf16 a[64:79], v[116:119], v[104:107], a[64:79]
	v_mfma_f32_32x32x16_bf16 a[48:63], v[140:143], v[120:123], a[48:63]
	v_mfma_f32_32x32x16_bf16 a[32:47], v[140:143], v[104:107], a[32:47]
	global_load_dwordx4 v[108:111], v[30:31], off offset:512
	global_load_dwordx4 v[112:115], v[28:29], off offset:512
	global_load_dwordx4 v[116:119], v[2:3], off offset:512
	global_load_dwordx4 v[124:127], v[8:9], off offset:512
	global_load_dwordx4 v[140:143], v[6:7], off offset:512
	global_load_dwordx4 v[144:147], v[4:5], off offset:512
	global_load_dwordx4 v[148:151], v[0:1], off offset:512
	s_waitcnt lgkmcnt(0)
	v_mfma_f32_32x32x16_bf16 a[16:31], v[128:131], v[120:123], a[16:31]
	global_load_dwordx4 v[120:123], v[12:13], off offset:512
	global_load_dwordx4 v[152:155], v[10:11], off offset:512
	global_load_dwordx4 v[156:159], v[26:27], off offset:512
	global_load_dwordx4 v[160:163], v[14:15], off offset:512
	s_barrier
	v_mfma_f32_32x32x16_bf16 a[0:15], v[128:131], v[104:107], a[0:15]
	ds_read_b128 v[104:107], v59 offset:55296
	ds_read_b128 v[128:131], v69
	ds_read_b128 v[164:167], v59 offset:59904
	ds_read_b128 v[168:171], v69 offset:4608
	s_waitcnt lgkmcnt(2)
	v_mfma_f32_32x32x16_bf16 a[112:127], v[104:107], v[128:131], a[112:127]
	s_waitcnt lgkmcnt(0)
	v_mfma_f32_32x32x16_bf16 a[96:111], v[104:107], v[168:171], a[96:111]
	ds_read_b128 v[104:107], v59 offset:64512
	s_waitcnt lgkmcnt(0)
	v_mfma_f32_32x32x16_bf16 a[48:63], v[104:107], v[128:131], a[48:63]
	v_mfma_f32_32x32x16_bf16 a[32:47], v[104:107], v[168:171], a[32:47]
	ds_read_b128 v[104:107], v61 offset:55296
	s_waitcnt vmcnt(4)
	ds_write_b128 v60, v[148:151]
	ds_write_b128 v60, v[144:147] offset:4608
	ds_write_b128 v60, v[140:143] offset:9216
	ds_write_b128 v60, v[124:127] offset:13824
	s_waitcnt vmcnt(2)
	ds_write_b128 v60, v[152:155] offset:18432
	ds_write_b128 v60, v[120:123] offset:23040
	s_waitcnt vmcnt(0)
	ds_write_b128 v60, v[160:163] offset:27648
	ds_write_b128 v60, v[156:159] offset:32256
	ds_write_b128 v60, v[116:119] offset:36864
	ds_write_b128 v60, v[112:115] offset:41472
	ds_write_b128 v60, v[108:111] offset:46080
	ds_write_b128 v60, v[100:103] offset:50688
	v_mfma_f32_32x32x16_bf16 a[80:95], v[164:167], v[128:131], a[80:95]
	v_mfma_f32_32x32x16_bf16 a[64:79], v[164:167], v[168:171], a[64:79]
	s_waitcnt lgkmcnt(12)
	v_mfma_f32_32x32x16_bf16 a[16:31], v[104:107], v[128:131], a[16:31]
	v_mfma_f32_32x32x16_bf16 a[0:15], v[104:107], v[168:171], a[0:15]
	ds_read_b128 v[100:103], v59 offset:55328
	ds_read_b128 v[104:107], v69 offset:32
	ds_read_b128 v[108:111], v69 offset:64
	ds_read_b128 v[112:115], v59 offset:55360
	ds_read_b128 v[116:119], v69 offset:4640
	ds_read_b128 v[120:123], v69 offset:96
	s_waitcnt lgkmcnt(4)
	v_mfma_f32_32x32x16_bf16 a[112:127], v[100:103], v[104:107], a[112:127]
	s_waitcnt lgkmcnt(1)
	v_mfma_f32_32x32x16_bf16 a[96:111], v[100:103], v[116:119], a[96:111]
	ds_read_b128 v[100:103], v59 offset:59936
	ds_read_b128 v[124:127], v59 offset:55392
	s_waitcnt lgkmcnt(1)
	v_mfma_f32_32x32x16_bf16 a[80:95], v[100:103], v[104:107], a[80:95]
	v_mfma_f32_32x32x16_bf16 a[64:79], v[100:103], v[116:119], a[64:79]
	ds_read_b128 v[100:103], v59 offset:64544
	ds_read_b128 v[128:131], v59 offset:64576
	s_waitcnt lgkmcnt(1)
	v_mfma_f32_32x32x16_bf16 a[48:63], v[100:103], v[104:107], a[48:63]
	v_mfma_f32_32x32x16_bf16 a[32:47], v[100:103], v[116:119], a[32:47]
	ds_read_b128 v[100:103], v61 offset:55328
	ds_read_b128 v[140:143], v59 offset:64608
	s_waitcnt lgkmcnt(1)
	v_mfma_f32_32x32x16_bf16 a[16:31], v[100:103], v[104:107], a[16:31]
	v_mfma_f32_32x32x16_bf16 a[0:15], v[100:103], v[116:119], a[0:15]
	ds_read_b128 v[100:103], v69 offset:4672
	ds_read_b128 v[104:107], v69 offset:4704
	v_mfma_f32_32x32x16_bf16 a[112:127], v[112:115], v[108:111], a[112:127]
	s_waitcnt lgkmcnt(1)
	v_mfma_f32_32x32x16_bf16 a[96:111], v[112:115], v[100:103], a[96:111]
	ds_read_b128 v[112:115], v59 offset:59968
	ds_read_b128 v[116:119], v59 offset:60000
	s_waitcnt lgkmcnt(1)
	v_mfma_f32_32x32x16_bf16 a[80:95], v[112:115], v[108:111], a[80:95]
	v_mfma_f32_32x32x16_bf16 a[64:79], v[112:115], v[100:103], a[64:79]
	v_mfma_f32_32x32x16_bf16 a[48:63], v[128:131], v[108:111], a[48:63]
	v_mfma_f32_32x32x16_bf16 a[32:47], v[128:131], v[100:103], a[32:47]
	ds_read_b128 v[112:115], v61 offset:55360
	ds_read_b128 v[128:131], v61 offset:55392
	s_waitcnt lgkmcnt(1)
	v_mfma_f32_32x32x16_bf16 a[16:31], v[112:115], v[108:111], a[16:31]
	v_mfma_f32_32x32x16_bf16 a[0:15], v[112:115], v[100:103], a[0:15]
	v_mfma_f32_32x32x16_bf16 a[112:127], v[124:127], v[120:123], a[112:127]
	v_mfma_f32_32x32x16_bf16 a[96:111], v[124:127], v[104:107], a[96:111]
	v_mfma_f32_32x32x16_bf16 a[80:95], v[116:119], v[120:123], a[80:95]
	v_mfma_f32_32x32x16_bf16 a[64:79], v[116:119], v[104:107], a[64:79]
	global_load_dwordx4 v[100:103], v[4:5], off offset:640
	global_load_dwordx4 v[108:111], v[0:1], off offset:640
	global_load_dwordx4 v[112:115], v[8:9], off offset:640
	global_load_dwordx4 v[116:119], v[6:7], off offset:640
	v_mfma_f32_32x32x16_bf16 a[48:63], v[140:143], v[120:123], a[48:63]
	v_mfma_f32_32x32x16_bf16 a[32:47], v[140:143], v[104:107], a[32:47]
	global_load_dwordx4 v[124:127], v[10:11], off offset:640
	global_load_dwordx4 v[140:143], v[12:13], off offset:640
	global_load_dwordx4 v[144:147], v[26:27], off offset:640
	global_load_dwordx4 v[148:151], v[14:15], off offset:640
	global_load_dwordx4 v[152:155], v[28:29], off offset:640
	global_load_dwordx4 v[156:159], v[2:3], off offset:640
	global_load_dwordx4 v[160:163], v[30:31], off offset:640
	s_waitcnt lgkmcnt(0)
	v_mfma_f32_32x32x16_bf16 a[16:31], v[128:131], v[120:123], a[16:31]
	global_load_dwordx4 v[120:123], v[32:33], off offset:640
	s_barrier
	v_mfma_f32_32x32x16_bf16 a[0:15], v[128:131], v[104:107], a[0:15]
	ds_read_b128 v[104:107], v59
	ds_read_b128 v[128:131], v62 offset:36864
	ds_read_b128 v[164:167], v59 offset:4608
	ds_read_b128 v[168:171], v62 offset:41472
	s_waitcnt lgkmcnt(2)
	v_mfma_f32_32x32x16_bf16 a[112:127], v[104:107], v[128:131], a[112:127]
	s_waitcnt lgkmcnt(0)
	v_mfma_f32_32x32x16_bf16 a[96:111], v[104:107], v[168:171], a[96:111]
	ds_read_b128 v[104:107], v59 offset:9216
	s_waitcnt lgkmcnt(0)
	v_mfma_f32_32x32x16_bf16 a[48:63], v[104:107], v[128:131], a[48:63]
	v_mfma_f32_32x32x16_bf16 a[32:47], v[104:107], v[168:171], a[32:47]
	ds_read_b128 v[104:107], v61
	s_waitcnt vmcnt(10)
	ds_write_b128 v60, v[108:111] offset:55296
	ds_write_b128 v60, v[100:103] offset:59904
	s_waitcnt vmcnt(8)
	ds_write_b128 v60, v[116:119] offset:64512
	ds_write_b128 v63, v[112:115] offset:55296
	s_waitcnt vmcnt(7)
	ds_write_b128 v64, v[124:127] offset:55296
	s_waitcnt vmcnt(6)
	ds_write_b128 v65, v[140:143] offset:55296
	s_waitcnt vmcnt(4)
	ds_write_b128 v66, v[148:151] offset:55296
	ds_write_b128 v67, v[144:147] offset:55296
	s_waitcnt vmcnt(2)
	ds_write_b128 v68, v[156:159]
	ds_write_b128 v68, v[152:155] offset:4608
	s_waitcnt vmcnt(1)
	ds_write_b128 v68, v[160:163] offset:9216
	s_waitcnt vmcnt(0)
	ds_write_b128 v68, v[120:123] offset:13824
	v_mfma_f32_32x32x16_bf16 a[80:95], v[164:167], v[128:131], a[80:95]
	v_mfma_f32_32x32x16_bf16 a[64:79], v[164:167], v[168:171], a[64:79]
	s_waitcnt lgkmcnt(12)
	v_mfma_f32_32x32x16_bf16 a[16:31], v[104:107], v[128:131], a[16:31]
	v_mfma_f32_32x32x16_bf16 a[0:15], v[104:107], v[168:171], a[0:15]
	ds_read_b128 v[100:103], v59 offset:32
	ds_read_b128 v[104:107], v62 offset:36896
	ds_read_b128 v[108:111], v62 offset:36928
	ds_read_b128 v[112:115], v59 offset:64
	ds_read_b128 v[116:119], v62 offset:41504
	ds_read_b128 v[120:123], v62 offset:36960
	s_waitcnt lgkmcnt(4)
	v_mfma_f32_32x32x16_bf16 a[112:127], v[100:103], v[104:107], a[112:127]
	s_waitcnt lgkmcnt(1)
	v_mfma_f32_32x32x16_bf16 a[96:111], v[100:103], v[116:119], a[96:111]
	ds_read_b128 v[100:103], v59 offset:4640
	ds_read_b128 v[124:127], v59 offset:96
	s_waitcnt lgkmcnt(1)
	v_mfma_f32_32x32x16_bf16 a[80:95], v[100:103], v[104:107], a[80:95]
	v_mfma_f32_32x32x16_bf16 a[64:79], v[100:103], v[116:119], a[64:79]
	ds_read_b128 v[100:103], v59 offset:9248
	ds_read_b128 v[128:131], v59 offset:9280
	s_waitcnt lgkmcnt(1)
	v_mfma_f32_32x32x16_bf16 a[48:63], v[100:103], v[104:107], a[48:63]
	v_mfma_f32_32x32x16_bf16 a[32:47], v[100:103], v[116:119], a[32:47]
	ds_read_b128 v[100:103], v61 offset:32
	ds_read_b128 v[140:143], v59 offset:9312
	s_waitcnt lgkmcnt(1)
	v_mfma_f32_32x32x16_bf16 a[16:31], v[100:103], v[104:107], a[16:31]
	v_mfma_f32_32x32x16_bf16 a[0:15], v[100:103], v[116:119], a[0:15]
	ds_read_b128 v[100:103], v62 offset:41536
	ds_read_b128 v[104:107], v62 offset:41568
	v_mfma_f32_32x32x16_bf16 a[112:127], v[112:115], v[108:111], a[112:127]
	s_waitcnt lgkmcnt(1)
	v_mfma_f32_32x32x16_bf16 a[96:111], v[112:115], v[100:103], a[96:111]
	ds_read_b128 v[112:115], v59 offset:4672
	ds_read_b128 v[116:119], v59 offset:4704
	s_waitcnt lgkmcnt(1)
	v_mfma_f32_32x32x16_bf16 a[80:95], v[112:115], v[108:111], a[80:95]
	v_mfma_f32_32x32x16_bf16 a[64:79], v[112:115], v[100:103], a[64:79]
	v_mfma_f32_32x32x16_bf16 a[48:63], v[128:131], v[108:111], a[48:63]
	v_mfma_f32_32x32x16_bf16 a[32:47], v[128:131], v[100:103], a[32:47]
	ds_read_b128 v[112:115], v61 offset:64
	ds_read_b128 v[128:131], v61 offset:96
	s_waitcnt lgkmcnt(1)
	v_mfma_f32_32x32x16_bf16 a[16:31], v[112:115], v[108:111], a[16:31]
	v_mfma_f32_32x32x16_bf16 a[0:15], v[112:115], v[100:103], a[0:15]
	global_load_dwordx4 v[100:103], v[32:33], off offset:768
	v_mfma_f32_32x32x16_bf16 a[112:127], v[124:127], v[120:123], a[112:127]
	v_mfma_f32_32x32x16_bf16 a[96:111], v[124:127], v[104:107], a[96:111]
	v_mfma_f32_32x32x16_bf16 a[80:95], v[116:119], v[120:123], a[80:95]
	v_mfma_f32_32x32x16_bf16 a[64:79], v[116:119], v[104:107], a[64:79]
	v_mfma_f32_32x32x16_bf16 a[48:63], v[140:143], v[120:123], a[48:63]
	v_mfma_f32_32x32x16_bf16 a[32:47], v[140:143], v[104:107], a[32:47]
	global_load_dwordx4 v[108:111], v[30:31], off offset:768
	global_load_dwordx4 v[112:115], v[28:29], off offset:768
	global_load_dwordx4 v[116:119], v[2:3], off offset:768
	global_load_dwordx4 v[124:127], v[8:9], off offset:768
	global_load_dwordx4 v[140:143], v[6:7], off offset:768
	global_load_dwordx4 v[144:147], v[4:5], off offset:768
	global_load_dwordx4 v[148:151], v[0:1], off offset:768
	s_waitcnt lgkmcnt(0)
	v_mfma_f32_32x32x16_bf16 a[16:31], v[128:131], v[120:123], a[16:31]
	global_load_dwordx4 v[120:123], v[12:13], off offset:768
	global_load_dwordx4 v[152:155], v[10:11], off offset:768
	global_load_dwordx4 v[156:159], v[26:27], off offset:768
	global_load_dwordx4 v[160:163], v[14:15], off offset:768
	s_barrier
	v_mfma_f32_32x32x16_bf16 a[0:15], v[128:131], v[104:107], a[0:15]
	ds_read_b128 v[104:107], v59 offset:55296
	ds_read_b128 v[128:131], v69
	ds_read_b128 v[164:167], v59 offset:59904
	ds_read_b128 v[168:171], v69 offset:4608
	s_waitcnt lgkmcnt(2)
	v_mfma_f32_32x32x16_bf16 a[112:127], v[104:107], v[128:131], a[112:127]
	s_waitcnt lgkmcnt(0)
	v_mfma_f32_32x32x16_bf16 a[96:111], v[104:107], v[168:171], a[96:111]
	ds_read_b128 v[104:107], v59 offset:64512
	s_waitcnt lgkmcnt(0)
	v_mfma_f32_32x32x16_bf16 a[48:63], v[104:107], v[128:131], a[48:63]
	v_mfma_f32_32x32x16_bf16 a[32:47], v[104:107], v[168:171], a[32:47]
	ds_read_b128 v[104:107], v61 offset:55296
	s_waitcnt vmcnt(4)
	ds_write_b128 v60, v[148:151]
	ds_write_b128 v60, v[144:147] offset:4608
	ds_write_b128 v60, v[140:143] offset:9216
	ds_write_b128 v60, v[124:127] offset:13824
	s_waitcnt vmcnt(2)
	ds_write_b128 v60, v[152:155] offset:18432
	ds_write_b128 v60, v[120:123] offset:23040
	s_waitcnt vmcnt(0)
	ds_write_b128 v60, v[160:163] offset:27648
	ds_write_b128 v60, v[156:159] offset:32256
	ds_write_b128 v60, v[116:119] offset:36864
	ds_write_b128 v60, v[112:115] offset:41472
	ds_write_b128 v60, v[108:111] offset:46080
	ds_write_b128 v60, v[100:103] offset:50688
	v_mfma_f32_32x32x16_bf16 a[80:95], v[164:167], v[128:131], a[80:95]
	v_mfma_f32_32x32x16_bf16 a[64:79], v[164:167], v[168:171], a[64:79]
	s_waitcnt lgkmcnt(12)
	v_mfma_f32_32x32x16_bf16 a[16:31], v[104:107], v[128:131], a[16:31]
	v_mfma_f32_32x32x16_bf16 a[0:15], v[104:107], v[168:171], a[0:15]
	ds_read_b128 v[100:103], v59 offset:55328
	ds_read_b128 v[104:107], v69 offset:32
	ds_read_b128 v[108:111], v69 offset:64
	ds_read_b128 v[112:115], v59 offset:55360
	ds_read_b128 v[116:119], v69 offset:4640
	ds_read_b128 v[120:123], v69 offset:96
	s_waitcnt lgkmcnt(4)
	v_mfma_f32_32x32x16_bf16 a[112:127], v[100:103], v[104:107], a[112:127]
	s_waitcnt lgkmcnt(1)
	v_mfma_f32_32x32x16_bf16 a[96:111], v[100:103], v[116:119], a[96:111]
	ds_read_b128 v[100:103], v59 offset:59936
	ds_read_b128 v[124:127], v59 offset:55392
	s_waitcnt lgkmcnt(1)
	v_mfma_f32_32x32x16_bf16 a[80:95], v[100:103], v[104:107], a[80:95]
	v_mfma_f32_32x32x16_bf16 a[64:79], v[100:103], v[116:119], a[64:79]
	ds_read_b128 v[100:103], v59 offset:64544
	ds_read_b128 v[128:131], v59 offset:64576
	s_waitcnt lgkmcnt(1)
	v_mfma_f32_32x32x16_bf16 a[48:63], v[100:103], v[104:107], a[48:63]
	v_mfma_f32_32x32x16_bf16 a[32:47], v[100:103], v[116:119], a[32:47]
	ds_read_b128 v[100:103], v61 offset:55328
	ds_read_b128 v[140:143], v59 offset:64608
	s_waitcnt lgkmcnt(1)
	v_mfma_f32_32x32x16_bf16 a[16:31], v[100:103], v[104:107], a[16:31]
	v_mfma_f32_32x32x16_bf16 a[0:15], v[100:103], v[116:119], a[0:15]
	ds_read_b128 v[100:103], v69 offset:4672
	ds_read_b128 v[104:107], v69 offset:4704
	v_mfma_f32_32x32x16_bf16 a[112:127], v[112:115], v[108:111], a[112:127]
	s_waitcnt lgkmcnt(1)
	v_mfma_f32_32x32x16_bf16 a[96:111], v[112:115], v[100:103], a[96:111]
	ds_read_b128 v[112:115], v59 offset:59968
	ds_read_b128 v[116:119], v59 offset:60000
	s_waitcnt lgkmcnt(1)
	v_mfma_f32_32x32x16_bf16 a[80:95], v[112:115], v[108:111], a[80:95]
	v_mfma_f32_32x32x16_bf16 a[64:79], v[112:115], v[100:103], a[64:79]
	v_mfma_f32_32x32x16_bf16 a[48:63], v[128:131], v[108:111], a[48:63]
	v_mfma_f32_32x32x16_bf16 a[32:47], v[128:131], v[100:103], a[32:47]
	ds_read_b128 v[112:115], v61 offset:55360
	ds_read_b128 v[128:131], v61 offset:55392
	s_waitcnt lgkmcnt(1)
	v_mfma_f32_32x32x16_bf16 a[16:31], v[112:115], v[108:111], a[16:31]
	v_mfma_f32_32x32x16_bf16 a[0:15], v[112:115], v[100:103], a[0:15]
	v_mfma_f32_32x32x16_bf16 a[112:127], v[124:127], v[120:123], a[112:127]
	v_mfma_f32_32x32x16_bf16 a[96:111], v[124:127], v[104:107], a[96:111]
	v_mfma_f32_32x32x16_bf16 a[80:95], v[116:119], v[120:123], a[80:95]
	v_mfma_f32_32x32x16_bf16 a[64:79], v[116:119], v[104:107], a[64:79]
	global_load_dwordx4 v[100:103], v[4:5], off offset:896
	global_load_dwordx4 v[108:111], v[0:1], off offset:896
	global_load_dwordx4 v[112:115], v[8:9], off offset:896
	global_load_dwordx4 v[116:119], v[6:7], off offset:896
	v_mfma_f32_32x32x16_bf16 a[48:63], v[140:143], v[120:123], a[48:63]
	v_mfma_f32_32x32x16_bf16 a[32:47], v[140:143], v[104:107], a[32:47]
	global_load_dwordx4 v[124:127], v[10:11], off offset:896
	global_load_dwordx4 v[140:143], v[12:13], off offset:896
	global_load_dwordx4 v[144:147], v[26:27], off offset:896
	global_load_dwordx4 v[148:151], v[14:15], off offset:896
	global_load_dwordx4 v[152:155], v[28:29], off offset:896
	global_load_dwordx4 v[156:159], v[2:3], off offset:896
	global_load_dwordx4 v[160:163], v[30:31], off offset:896
	s_waitcnt lgkmcnt(0)
	v_mfma_f32_32x32x16_bf16 a[16:31], v[128:131], v[120:123], a[16:31]
	global_load_dwordx4 v[120:123], v[32:33], off offset:896
	s_barrier
	v_mfma_f32_32x32x16_bf16 a[0:15], v[128:131], v[104:107], a[0:15]
	ds_read_b128 v[104:107], v59
	ds_read_b128 v[128:131], v62 offset:36864
	ds_read_b128 v[164:167], v59 offset:4608
	ds_read_b128 v[168:171], v62 offset:41472
	s_waitcnt lgkmcnt(2)
	v_mfma_f32_32x32x16_bf16 a[112:127], v[104:107], v[128:131], a[112:127]
	s_waitcnt lgkmcnt(0)
	v_mfma_f32_32x32x16_bf16 a[96:111], v[104:107], v[168:171], a[96:111]
	ds_read_b128 v[104:107], v59 offset:9216
	s_waitcnt lgkmcnt(0)
	v_mfma_f32_32x32x16_bf16 a[48:63], v[104:107], v[128:131], a[48:63]
	v_mfma_f32_32x32x16_bf16 a[32:47], v[104:107], v[168:171], a[32:47]
	ds_read_b128 v[104:107], v61
	s_waitcnt vmcnt(10)
	ds_write_b128 v60, v[108:111] offset:55296
	ds_write_b128 v60, v[100:103] offset:59904
	s_waitcnt vmcnt(8)
	ds_write_b128 v60, v[116:119] offset:64512
	ds_write_b128 v63, v[112:115] offset:55296
	s_waitcnt vmcnt(7)
	ds_write_b128 v64, v[124:127] offset:55296
	s_waitcnt vmcnt(6)
	ds_write_b128 v65, v[140:143] offset:55296
	s_waitcnt vmcnt(4)
	ds_write_b128 v66, v[148:151] offset:55296
	ds_write_b128 v67, v[144:147] offset:55296
	s_waitcnt vmcnt(2)
	ds_write_b128 v68, v[156:159]
	ds_write_b128 v68, v[152:155] offset:4608
	s_waitcnt vmcnt(1)
	ds_write_b128 v68, v[160:163] offset:9216
	s_waitcnt vmcnt(0)
	ds_write_b128 v68, v[120:123] offset:13824
	v_mfma_f32_32x32x16_bf16 a[80:95], v[164:167], v[128:131], a[80:95]
	v_mfma_f32_32x32x16_bf16 a[64:79], v[164:167], v[168:171], a[64:79]
	s_waitcnt lgkmcnt(12)
	v_mfma_f32_32x32x16_bf16 a[16:31], v[104:107], v[128:131], a[16:31]
	v_mfma_f32_32x32x16_bf16 a[0:15], v[104:107], v[168:171], a[0:15]
	ds_read_b128 v[100:103], v59 offset:32
	ds_read_b128 v[104:107], v62 offset:36896
	ds_read_b128 v[108:111], v62 offset:36928
	ds_read_b128 v[112:115], v59 offset:64
	ds_read_b128 v[116:119], v62 offset:41504
	ds_read_b128 v[120:123], v62 offset:36960
	s_waitcnt lgkmcnt(4)
	v_mfma_f32_32x32x16_bf16 a[112:127], v[100:103], v[104:107], a[112:127]
	s_waitcnt lgkmcnt(1)
	v_mfma_f32_32x32x16_bf16 a[96:111], v[100:103], v[116:119], a[96:111]
	ds_read_b128 v[100:103], v59 offset:4640
	ds_read_b128 v[124:127], v59 offset:96
	s_waitcnt lgkmcnt(1)
	v_mfma_f32_32x32x16_bf16 a[80:95], v[100:103], v[104:107], a[80:95]
	v_mfma_f32_32x32x16_bf16 a[64:79], v[100:103], v[116:119], a[64:79]
	ds_read_b128 v[100:103], v59 offset:9248
	ds_read_b128 v[128:131], v59 offset:9280
	s_waitcnt lgkmcnt(1)
	v_mfma_f32_32x32x16_bf16 a[48:63], v[100:103], v[104:107], a[48:63]
	v_mfma_f32_32x32x16_bf16 a[32:47], v[100:103], v[116:119], a[32:47]
	ds_read_b128 v[100:103], v61 offset:32
	ds_read_b128 v[140:143], v59 offset:9312
	s_waitcnt lgkmcnt(1)
	v_mfma_f32_32x32x16_bf16 a[16:31], v[100:103], v[104:107], a[16:31]
	v_mfma_f32_32x32x16_bf16 a[0:15], v[100:103], v[116:119], a[0:15]
	ds_read_b128 v[100:103], v62 offset:41536
	ds_read_b128 v[104:107], v62 offset:41568
	v_mfma_f32_32x32x16_bf16 a[112:127], v[112:115], v[108:111], a[112:127]
	s_waitcnt lgkmcnt(1)
	v_mfma_f32_32x32x16_bf16 a[96:111], v[112:115], v[100:103], a[96:111]
	ds_read_b128 v[112:115], v59 offset:4672
	ds_read_b128 v[116:119], v59 offset:4704
	s_waitcnt lgkmcnt(1)
	v_mfma_f32_32x32x16_bf16 a[80:95], v[112:115], v[108:111], a[80:95]
	v_mfma_f32_32x32x16_bf16 a[64:79], v[112:115], v[100:103], a[64:79]
	v_mfma_f32_32x32x16_bf16 a[48:63], v[128:131], v[108:111], a[48:63]
	v_mfma_f32_32x32x16_bf16 a[32:47], v[128:131], v[100:103], a[32:47]
	ds_read_b128 v[112:115], v61 offset:64
	ds_read_b128 v[128:131], v61 offset:96
	s_waitcnt lgkmcnt(1)
	v_mfma_f32_32x32x16_bf16 a[16:31], v[112:115], v[108:111], a[16:31]
	v_mfma_f32_32x32x16_bf16 a[0:15], v[112:115], v[100:103], a[0:15]
	global_load_dwordx4 v[100:103], v[32:33], off offset:1024
	v_mfma_f32_32x32x16_bf16 a[112:127], v[124:127], v[120:123], a[112:127]
	v_mfma_f32_32x32x16_bf16 a[96:111], v[124:127], v[104:107], a[96:111]
	v_mfma_f32_32x32x16_bf16 a[80:95], v[116:119], v[120:123], a[80:95]
	v_mfma_f32_32x32x16_bf16 a[64:79], v[116:119], v[104:107], a[64:79]
	v_mfma_f32_32x32x16_bf16 a[48:63], v[140:143], v[120:123], a[48:63]
	v_mfma_f32_32x32x16_bf16 a[32:47], v[140:143], v[104:107], a[32:47]
	global_load_dwordx4 v[108:111], v[30:31], off offset:1024
	global_load_dwordx4 v[112:115], v[28:29], off offset:1024
	global_load_dwordx4 v[116:119], v[2:3], off offset:1024
	global_load_dwordx4 v[124:127], v[8:9], off offset:1024
	global_load_dwordx4 v[140:143], v[6:7], off offset:1024
	global_load_dwordx4 v[144:147], v[4:5], off offset:1024
	global_load_dwordx4 v[148:151], v[0:1], off offset:1024
	s_waitcnt lgkmcnt(0)
	v_mfma_f32_32x32x16_bf16 a[16:31], v[128:131], v[120:123], a[16:31]
	global_load_dwordx4 v[120:123], v[12:13], off offset:1024
	global_load_dwordx4 v[152:155], v[10:11], off offset:1024
	global_load_dwordx4 v[156:159], v[26:27], off offset:1024
	global_load_dwordx4 v[160:163], v[14:15], off offset:1024
	s_barrier
	v_mfma_f32_32x32x16_bf16 a[0:15], v[128:131], v[104:107], a[0:15]
	ds_read_b128 v[104:107], v59 offset:55296
	ds_read_b128 v[128:131], v69
	ds_read_b128 v[164:167], v59 offset:59904
	ds_read_b128 v[168:171], v69 offset:4608
	s_waitcnt lgkmcnt(2)
	v_mfma_f32_32x32x16_bf16 a[112:127], v[104:107], v[128:131], a[112:127]
	s_waitcnt lgkmcnt(0)
	v_mfma_f32_32x32x16_bf16 a[96:111], v[104:107], v[168:171], a[96:111]
	ds_read_b128 v[104:107], v59 offset:64512
	s_waitcnt lgkmcnt(0)
	v_mfma_f32_32x32x16_bf16 a[48:63], v[104:107], v[128:131], a[48:63]
	v_mfma_f32_32x32x16_bf16 a[32:47], v[104:107], v[168:171], a[32:47]
	ds_read_b128 v[104:107], v61 offset:55296
	s_waitcnt vmcnt(4)
	ds_write_b128 v60, v[148:151]
	ds_write_b128 v60, v[144:147] offset:4608
	ds_write_b128 v60, v[140:143] offset:9216
	ds_write_b128 v60, v[124:127] offset:13824
	s_waitcnt vmcnt(2)
	ds_write_b128 v60, v[152:155] offset:18432
	ds_write_b128 v60, v[120:123] offset:23040
	s_waitcnt vmcnt(0)
	ds_write_b128 v60, v[160:163] offset:27648
	ds_write_b128 v60, v[156:159] offset:32256
	ds_write_b128 v60, v[116:119] offset:36864
	ds_write_b128 v60, v[112:115] offset:41472
	ds_write_b128 v60, v[108:111] offset:46080
	ds_write_b128 v60, v[100:103] offset:50688
	v_mfma_f32_32x32x16_bf16 a[80:95], v[164:167], v[128:131], a[80:95]
	v_mfma_f32_32x32x16_bf16 a[64:79], v[164:167], v[168:171], a[64:79]
	s_waitcnt lgkmcnt(12)
	v_mfma_f32_32x32x16_bf16 a[16:31], v[104:107], v[128:131], a[16:31]
	v_mfma_f32_32x32x16_bf16 a[0:15], v[104:107], v[168:171], a[0:15]
	ds_read_b128 v[100:103], v59 offset:55328
	ds_read_b128 v[104:107], v69 offset:32
	ds_read_b128 v[108:111], v69 offset:64
	ds_read_b128 v[112:115], v59 offset:55360
	ds_read_b128 v[116:119], v69 offset:4640
	ds_read_b128 v[120:123], v69 offset:96
	s_waitcnt lgkmcnt(4)
	v_mfma_f32_32x32x16_bf16 a[112:127], v[100:103], v[104:107], a[112:127]
	s_waitcnt lgkmcnt(1)
	v_mfma_f32_32x32x16_bf16 a[96:111], v[100:103], v[116:119], a[96:111]
	ds_read_b128 v[100:103], v59 offset:59936
	ds_read_b128 v[124:127], v59 offset:55392
	s_waitcnt lgkmcnt(1)
	v_mfma_f32_32x32x16_bf16 a[80:95], v[100:103], v[104:107], a[80:95]
	v_mfma_f32_32x32x16_bf16 a[64:79], v[100:103], v[116:119], a[64:79]
	ds_read_b128 v[100:103], v59 offset:64544
	ds_read_b128 v[128:131], v59 offset:64576
	s_waitcnt lgkmcnt(1)
	v_mfma_f32_32x32x16_bf16 a[48:63], v[100:103], v[104:107], a[48:63]
	v_mfma_f32_32x32x16_bf16 a[32:47], v[100:103], v[116:119], a[32:47]
	ds_read_b128 v[100:103], v61 offset:55328
	ds_read_b128 v[140:143], v59 offset:64608
	s_waitcnt lgkmcnt(1)
	v_mfma_f32_32x32x16_bf16 a[16:31], v[100:103], v[104:107], a[16:31]
	v_mfma_f32_32x32x16_bf16 a[0:15], v[100:103], v[116:119], a[0:15]
	ds_read_b128 v[100:103], v69 offset:4672
	ds_read_b128 v[104:107], v69 offset:4704
	v_mfma_f32_32x32x16_bf16 a[112:127], v[112:115], v[108:111], a[112:127]
	s_waitcnt lgkmcnt(1)
	v_mfma_f32_32x32x16_bf16 a[96:111], v[112:115], v[100:103], a[96:111]
	ds_read_b128 v[112:115], v59 offset:59968
	ds_read_b128 v[116:119], v59 offset:60000
	s_waitcnt lgkmcnt(1)
	v_mfma_f32_32x32x16_bf16 a[80:95], v[112:115], v[108:111], a[80:95]
	v_mfma_f32_32x32x16_bf16 a[64:79], v[112:115], v[100:103], a[64:79]
	v_mfma_f32_32x32x16_bf16 a[48:63], v[128:131], v[108:111], a[48:63]
	v_mfma_f32_32x32x16_bf16 a[32:47], v[128:131], v[100:103], a[32:47]
	ds_read_b128 v[112:115], v61 offset:55360
	ds_read_b128 v[128:131], v61 offset:55392
	s_waitcnt lgkmcnt(1)
	v_mfma_f32_32x32x16_bf16 a[16:31], v[112:115], v[108:111], a[16:31]
	v_mfma_f32_32x32x16_bf16 a[0:15], v[112:115], v[100:103], a[0:15]
	v_mfma_f32_32x32x16_bf16 a[112:127], v[124:127], v[120:123], a[112:127]
	v_mfma_f32_32x32x16_bf16 a[96:111], v[124:127], v[104:107], a[96:111]
	v_mfma_f32_32x32x16_bf16 a[80:95], v[116:119], v[120:123], a[80:95]
	v_mfma_f32_32x32x16_bf16 a[64:79], v[116:119], v[104:107], a[64:79]
	global_load_dwordx4 v[100:103], v[4:5], off offset:1152
	global_load_dwordx4 v[108:111], v[0:1], off offset:1152
	global_load_dwordx4 v[112:115], v[8:9], off offset:1152
	global_load_dwordx4 v[116:119], v[6:7], off offset:1152
	v_mfma_f32_32x32x16_bf16 a[48:63], v[140:143], v[120:123], a[48:63]
	v_mfma_f32_32x32x16_bf16 a[32:47], v[140:143], v[104:107], a[32:47]
	global_load_dwordx4 v[124:127], v[10:11], off offset:1152
	global_load_dwordx4 v[140:143], v[12:13], off offset:1152
	global_load_dwordx4 v[144:147], v[26:27], off offset:1152
	global_load_dwordx4 v[148:151], v[14:15], off offset:1152
	global_load_dwordx4 v[152:155], v[28:29], off offset:1152
	global_load_dwordx4 v[156:159], v[2:3], off offset:1152
	global_load_dwordx4 v[160:163], v[30:31], off offset:1152
	s_waitcnt lgkmcnt(0)
	v_mfma_f32_32x32x16_bf16 a[16:31], v[128:131], v[120:123], a[16:31]
	global_load_dwordx4 v[120:123], v[32:33], off offset:1152
	s_barrier
	v_mfma_f32_32x32x16_bf16 a[0:15], v[128:131], v[104:107], a[0:15]
	ds_read_b128 v[104:107], v59
	ds_read_b128 v[128:131], v62 offset:36864
	ds_read_b128 v[164:167], v59 offset:4608
	ds_read_b128 v[168:171], v62 offset:41472
	s_waitcnt lgkmcnt(2)
	v_mfma_f32_32x32x16_bf16 a[112:127], v[104:107], v[128:131], a[112:127]
	s_waitcnt lgkmcnt(0)
	v_mfma_f32_32x32x16_bf16 a[96:111], v[104:107], v[168:171], a[96:111]
	ds_read_b128 v[104:107], v59 offset:9216
	s_waitcnt lgkmcnt(0)
	v_mfma_f32_32x32x16_bf16 a[48:63], v[104:107], v[128:131], a[48:63]
	v_mfma_f32_32x32x16_bf16 a[32:47], v[104:107], v[168:171], a[32:47]
	ds_read_b128 v[104:107], v61
	s_waitcnt vmcnt(10)
	ds_write_b128 v60, v[108:111] offset:55296
	ds_write_b128 v60, v[100:103] offset:59904
	s_waitcnt vmcnt(8)
	ds_write_b128 v60, v[116:119] offset:64512
	ds_write_b128 v63, v[112:115] offset:55296
	s_waitcnt vmcnt(7)
	ds_write_b128 v64, v[124:127] offset:55296
	s_waitcnt vmcnt(6)
	ds_write_b128 v65, v[140:143] offset:55296
	s_waitcnt vmcnt(4)
	ds_write_b128 v66, v[148:151] offset:55296
	ds_write_b128 v67, v[144:147] offset:55296
	s_waitcnt vmcnt(2)
	ds_write_b128 v68, v[156:159]
	ds_write_b128 v68, v[152:155] offset:4608
	s_waitcnt vmcnt(1)
	ds_write_b128 v68, v[160:163] offset:9216
	s_waitcnt vmcnt(0)
	ds_write_b128 v68, v[120:123] offset:13824
	v_mfma_f32_32x32x16_bf16 a[80:95], v[164:167], v[128:131], a[80:95]
	v_mfma_f32_32x32x16_bf16 a[64:79], v[164:167], v[168:171], a[64:79]
	s_waitcnt lgkmcnt(12)
	v_mfma_f32_32x32x16_bf16 a[16:31], v[104:107], v[128:131], a[16:31]
	v_mfma_f32_32x32x16_bf16 a[0:15], v[104:107], v[168:171], a[0:15]
	ds_read_b128 v[100:103], v59 offset:32
	ds_read_b128 v[104:107], v62 offset:36896
	ds_read_b128 v[108:111], v62 offset:36928
	ds_read_b128 v[112:115], v59 offset:64
	ds_read_b128 v[116:119], v62 offset:41504
	ds_read_b128 v[120:123], v62 offset:36960
	s_waitcnt lgkmcnt(4)
	v_mfma_f32_32x32x16_bf16 a[112:127], v[100:103], v[104:107], a[112:127]
	s_waitcnt lgkmcnt(1)
	v_mfma_f32_32x32x16_bf16 a[96:111], v[100:103], v[116:119], a[96:111]
	ds_read_b128 v[100:103], v59 offset:4640
	ds_read_b128 v[124:127], v59 offset:96
	s_waitcnt lgkmcnt(1)
	v_mfma_f32_32x32x16_bf16 a[80:95], v[100:103], v[104:107], a[80:95]
	v_mfma_f32_32x32x16_bf16 a[64:79], v[100:103], v[116:119], a[64:79]
	ds_read_b128 v[100:103], v59 offset:9248
	ds_read_b128 v[128:131], v59 offset:9280
	s_waitcnt lgkmcnt(1)
	v_mfma_f32_32x32x16_bf16 a[48:63], v[100:103], v[104:107], a[48:63]
	v_mfma_f32_32x32x16_bf16 a[32:47], v[100:103], v[116:119], a[32:47]
	ds_read_b128 v[100:103], v61 offset:32
	ds_read_b128 v[140:143], v59 offset:9312
	s_waitcnt lgkmcnt(1)
	v_mfma_f32_32x32x16_bf16 a[16:31], v[100:103], v[104:107], a[16:31]
	v_mfma_f32_32x32x16_bf16 a[0:15], v[100:103], v[116:119], a[0:15]
	ds_read_b128 v[100:103], v62 offset:41536
	ds_read_b128 v[104:107], v62 offset:41568
	v_mfma_f32_32x32x16_bf16 a[112:127], v[112:115], v[108:111], a[112:127]
	s_waitcnt lgkmcnt(1)
	v_mfma_f32_32x32x16_bf16 a[96:111], v[112:115], v[100:103], a[96:111]
	ds_read_b128 v[112:115], v59 offset:4672
	ds_read_b128 v[116:119], v59 offset:4704
	s_waitcnt lgkmcnt(1)
	v_mfma_f32_32x32x16_bf16 a[80:95], v[112:115], v[108:111], a[80:95]
	v_mfma_f32_32x32x16_bf16 a[64:79], v[112:115], v[100:103], a[64:79]
	v_mfma_f32_32x32x16_bf16 a[48:63], v[128:131], v[108:111], a[48:63]
	v_mfma_f32_32x32x16_bf16 a[32:47], v[128:131], v[100:103], a[32:47]
	ds_read_b128 v[112:115], v61 offset:64
	ds_read_b128 v[128:131], v61 offset:96
	s_waitcnt lgkmcnt(1)
	v_mfma_f32_32x32x16_bf16 a[16:31], v[112:115], v[108:111], a[16:31]
	v_mfma_f32_32x32x16_bf16 a[0:15], v[112:115], v[100:103], a[0:15]
	global_load_dwordx4 v[100:103], v[32:33], off offset:1280
	v_mfma_f32_32x32x16_bf16 a[112:127], v[124:127], v[120:123], a[112:127]
	v_mfma_f32_32x32x16_bf16 a[96:111], v[124:127], v[104:107], a[96:111]
	v_mfma_f32_32x32x16_bf16 a[80:95], v[116:119], v[120:123], a[80:95]
	v_mfma_f32_32x32x16_bf16 a[64:79], v[116:119], v[104:107], a[64:79]
	v_mfma_f32_32x32x16_bf16 a[48:63], v[140:143], v[120:123], a[48:63]
	v_mfma_f32_32x32x16_bf16 a[32:47], v[140:143], v[104:107], a[32:47]
	global_load_dwordx4 v[108:111], v[30:31], off offset:1280
	global_load_dwordx4 v[112:115], v[28:29], off offset:1280
	global_load_dwordx4 v[116:119], v[2:3], off offset:1280
	global_load_dwordx4 v[124:127], v[8:9], off offset:1280
	global_load_dwordx4 v[140:143], v[6:7], off offset:1280
	global_load_dwordx4 v[144:147], v[4:5], off offset:1280
	global_load_dwordx4 v[148:151], v[0:1], off offset:1280
	s_waitcnt lgkmcnt(0)
	v_mfma_f32_32x32x16_bf16 a[16:31], v[128:131], v[120:123], a[16:31]
	global_load_dwordx4 v[120:123], v[12:13], off offset:1280
	global_load_dwordx4 v[152:155], v[10:11], off offset:1280
	global_load_dwordx4 v[156:159], v[26:27], off offset:1280
	global_load_dwordx4 v[160:163], v[14:15], off offset:1280
	s_barrier
	v_mfma_f32_32x32x16_bf16 a[0:15], v[128:131], v[104:107], a[0:15]
	ds_read_b128 v[104:107], v59 offset:55296
	ds_read_b128 v[128:131], v69
	ds_read_b128 v[164:167], v59 offset:59904
	ds_read_b128 v[168:171], v69 offset:4608
	s_waitcnt lgkmcnt(2)
	v_mfma_f32_32x32x16_bf16 a[112:127], v[104:107], v[128:131], a[112:127]
	s_waitcnt lgkmcnt(0)
	v_mfma_f32_32x32x16_bf16 a[96:111], v[104:107], v[168:171], a[96:111]
	ds_read_b128 v[104:107], v59 offset:64512
	s_waitcnt lgkmcnt(0)
	v_mfma_f32_32x32x16_bf16 a[48:63], v[104:107], v[128:131], a[48:63]
	v_mfma_f32_32x32x16_bf16 a[32:47], v[104:107], v[168:171], a[32:47]
	ds_read_b128 v[104:107], v61 offset:55296
	s_waitcnt vmcnt(4)
	ds_write_b128 v60, v[148:151]
	ds_write_b128 v60, v[144:147] offset:4608
	ds_write_b128 v60, v[140:143] offset:9216
	ds_write_b128 v60, v[124:127] offset:13824
	s_waitcnt vmcnt(2)
	ds_write_b128 v60, v[152:155] offset:18432
	ds_write_b128 v60, v[120:123] offset:23040
	s_waitcnt vmcnt(0)
	ds_write_b128 v60, v[160:163] offset:27648
	ds_write_b128 v60, v[156:159] offset:32256
	ds_write_b128 v60, v[116:119] offset:36864
	ds_write_b128 v60, v[112:115] offset:41472
	ds_write_b128 v60, v[108:111] offset:46080
	ds_write_b128 v60, v[100:103] offset:50688
	v_mfma_f32_32x32x16_bf16 a[80:95], v[164:167], v[128:131], a[80:95]
	v_mfma_f32_32x32x16_bf16 a[64:79], v[164:167], v[168:171], a[64:79]
	s_waitcnt lgkmcnt(12)
	v_mfma_f32_32x32x16_bf16 a[16:31], v[104:107], v[128:131], a[16:31]
	v_mfma_f32_32x32x16_bf16 a[0:15], v[104:107], v[168:171], a[0:15]
	ds_read_b128 v[100:103], v59 offset:55328
	ds_read_b128 v[104:107], v69 offset:32
	ds_read_b128 v[108:111], v69 offset:64
	ds_read_b128 v[112:115], v59 offset:55360
	ds_read_b128 v[116:119], v69 offset:4640
	ds_read_b128 v[120:123], v69 offset:96
	s_waitcnt lgkmcnt(4)
	v_mfma_f32_32x32x16_bf16 a[112:127], v[100:103], v[104:107], a[112:127]
	s_waitcnt lgkmcnt(1)
	v_mfma_f32_32x32x16_bf16 a[96:111], v[100:103], v[116:119], a[96:111]
	ds_read_b128 v[100:103], v59 offset:59936
	ds_read_b128 v[124:127], v59 offset:55392
	s_waitcnt lgkmcnt(1)
	v_mfma_f32_32x32x16_bf16 a[80:95], v[100:103], v[104:107], a[80:95]
	v_mfma_f32_32x32x16_bf16 a[64:79], v[100:103], v[116:119], a[64:79]
	ds_read_b128 v[100:103], v59 offset:64544
	ds_read_b128 v[128:131], v59 offset:64576
	s_waitcnt lgkmcnt(1)
	v_mfma_f32_32x32x16_bf16 a[48:63], v[100:103], v[104:107], a[48:63]
	v_mfma_f32_32x32x16_bf16 a[32:47], v[100:103], v[116:119], a[32:47]
	ds_read_b128 v[100:103], v61 offset:55328
	ds_read_b128 v[140:143], v59 offset:64608
	s_waitcnt lgkmcnt(1)
	v_mfma_f32_32x32x16_bf16 a[16:31], v[100:103], v[104:107], a[16:31]
	v_mfma_f32_32x32x16_bf16 a[0:15], v[100:103], v[116:119], a[0:15]
	ds_read_b128 v[100:103], v69 offset:4672
	ds_read_b128 v[104:107], v69 offset:4704
	v_mfma_f32_32x32x16_bf16 a[112:127], v[112:115], v[108:111], a[112:127]
	s_waitcnt lgkmcnt(1)
	v_mfma_f32_32x32x16_bf16 a[96:111], v[112:115], v[100:103], a[96:111]
	ds_read_b128 v[112:115], v59 offset:59968
	ds_read_b128 v[116:119], v59 offset:60000
	s_waitcnt lgkmcnt(1)
	v_mfma_f32_32x32x16_bf16 a[80:95], v[112:115], v[108:111], a[80:95]
	v_mfma_f32_32x32x16_bf16 a[64:79], v[112:115], v[100:103], a[64:79]
	v_mfma_f32_32x32x16_bf16 a[48:63], v[128:131], v[108:111], a[48:63]
	v_mfma_f32_32x32x16_bf16 a[32:47], v[128:131], v[100:103], a[32:47]
	ds_read_b128 v[112:115], v61 offset:55360
	ds_read_b128 v[128:131], v61 offset:55392
	s_waitcnt lgkmcnt(1)
	v_mfma_f32_32x32x16_bf16 a[16:31], v[112:115], v[108:111], a[16:31]
	v_mfma_f32_32x32x16_bf16 a[0:15], v[112:115], v[100:103], a[0:15]
	v_mfma_f32_32x32x16_bf16 a[112:127], v[124:127], v[120:123], a[112:127]
	v_mfma_f32_32x32x16_bf16 a[96:111], v[124:127], v[104:107], a[96:111]
	v_mfma_f32_32x32x16_bf16 a[80:95], v[116:119], v[120:123], a[80:95]
	v_mfma_f32_32x32x16_bf16 a[64:79], v[116:119], v[104:107], a[64:79]
	global_load_dwordx4 v[100:103], v[4:5], off offset:1408
	global_load_dwordx4 v[108:111], v[0:1], off offset:1408
	global_load_dwordx4 v[112:115], v[8:9], off offset:1408
	global_load_dwordx4 v[116:119], v[6:7], off offset:1408
	v_mfma_f32_32x32x16_bf16 a[48:63], v[140:143], v[120:123], a[48:63]
	v_mfma_f32_32x32x16_bf16 a[32:47], v[140:143], v[104:107], a[32:47]
	global_load_dwordx4 v[124:127], v[10:11], off offset:1408
	global_load_dwordx4 v[140:143], v[12:13], off offset:1408
	global_load_dwordx4 v[144:147], v[26:27], off offset:1408
	global_load_dwordx4 v[148:151], v[14:15], off offset:1408
	global_load_dwordx4 v[152:155], v[28:29], off offset:1408
	global_load_dwordx4 v[156:159], v[2:3], off offset:1408
	global_load_dwordx4 v[160:163], v[30:31], off offset:1408
	s_waitcnt lgkmcnt(0)
	v_mfma_f32_32x32x16_bf16 a[16:31], v[128:131], v[120:123], a[16:31]
	global_load_dwordx4 v[120:123], v[32:33], off offset:1408
	s_barrier
	v_mfma_f32_32x32x16_bf16 a[0:15], v[128:131], v[104:107], a[0:15]
	ds_read_b128 v[104:107], v59
	ds_read_b128 v[128:131], v62 offset:36864
	ds_read_b128 v[164:167], v59 offset:4608
	ds_read_b128 v[168:171], v62 offset:41472
	s_waitcnt lgkmcnt(2)
	v_mfma_f32_32x32x16_bf16 a[112:127], v[104:107], v[128:131], a[112:127]
	s_waitcnt lgkmcnt(0)
	v_mfma_f32_32x32x16_bf16 a[96:111], v[104:107], v[168:171], a[96:111]
	ds_read_b128 v[104:107], v59 offset:9216
	s_waitcnt lgkmcnt(0)
	v_mfma_f32_32x32x16_bf16 a[48:63], v[104:107], v[128:131], a[48:63]
	v_mfma_f32_32x32x16_bf16 a[32:47], v[104:107], v[168:171], a[32:47]
	ds_read_b128 v[104:107], v61
	s_waitcnt vmcnt(10)
	ds_write_b128 v60, v[108:111] offset:55296
	ds_write_b128 v60, v[100:103] offset:59904
	s_waitcnt vmcnt(8)
	ds_write_b128 v60, v[116:119] offset:64512
	ds_write_b128 v63, v[112:115] offset:55296
	s_waitcnt vmcnt(7)
	ds_write_b128 v64, v[124:127] offset:55296
	s_waitcnt vmcnt(6)
	ds_write_b128 v65, v[140:143] offset:55296
	s_waitcnt vmcnt(4)
	ds_write_b128 v66, v[148:151] offset:55296
	ds_write_b128 v67, v[144:147] offset:55296
	s_waitcnt vmcnt(2)
	ds_write_b128 v68, v[156:159]
	ds_write_b128 v68, v[152:155] offset:4608
	s_waitcnt vmcnt(1)
	ds_write_b128 v68, v[160:163] offset:9216
	s_waitcnt vmcnt(0)
	ds_write_b128 v68, v[120:123] offset:13824
	v_mfma_f32_32x32x16_bf16 a[80:95], v[164:167], v[128:131], a[80:95]
	v_mfma_f32_32x32x16_bf16 a[64:79], v[164:167], v[168:171], a[64:79]
	s_waitcnt lgkmcnt(12)
	v_mfma_f32_32x32x16_bf16 a[16:31], v[104:107], v[128:131], a[16:31]
	v_mfma_f32_32x32x16_bf16 a[0:15], v[104:107], v[168:171], a[0:15]
	ds_read_b128 v[100:103], v59 offset:32
	ds_read_b128 v[104:107], v62 offset:36896
	ds_read_b128 v[108:111], v62 offset:36928
	ds_read_b128 v[112:115], v59 offset:64
	ds_read_b128 v[116:119], v62 offset:41504
	ds_read_b128 v[120:123], v62 offset:36960
	s_waitcnt lgkmcnt(4)
	v_mfma_f32_32x32x16_bf16 a[112:127], v[100:103], v[104:107], a[112:127]
	s_waitcnt lgkmcnt(1)
	v_mfma_f32_32x32x16_bf16 a[96:111], v[100:103], v[116:119], a[96:111]
	ds_read_b128 v[100:103], v59 offset:4640
	ds_read_b128 v[124:127], v59 offset:96
	s_waitcnt lgkmcnt(1)
	v_mfma_f32_32x32x16_bf16 a[80:95], v[100:103], v[104:107], a[80:95]
	v_mfma_f32_32x32x16_bf16 a[64:79], v[100:103], v[116:119], a[64:79]
	ds_read_b128 v[100:103], v59 offset:9248
	ds_read_b128 v[128:131], v59 offset:9280
	s_waitcnt lgkmcnt(1)
	v_mfma_f32_32x32x16_bf16 a[48:63], v[100:103], v[104:107], a[48:63]
	v_mfma_f32_32x32x16_bf16 a[32:47], v[100:103], v[116:119], a[32:47]
	ds_read_b128 v[100:103], v61 offset:32
	ds_read_b128 v[140:143], v59 offset:9312
	s_waitcnt lgkmcnt(1)
	v_mfma_f32_32x32x16_bf16 a[16:31], v[100:103], v[104:107], a[16:31]
	v_mfma_f32_32x32x16_bf16 a[0:15], v[100:103], v[116:119], a[0:15]
	ds_read_b128 v[100:103], v62 offset:41536
	ds_read_b128 v[104:107], v62 offset:41568
	v_mfma_f32_32x32x16_bf16 a[112:127], v[112:115], v[108:111], a[112:127]
	s_waitcnt lgkmcnt(1)
	v_mfma_f32_32x32x16_bf16 a[96:111], v[112:115], v[100:103], a[96:111]
	ds_read_b128 v[112:115], v59 offset:4672
	ds_read_b128 v[116:119], v59 offset:4704
	s_waitcnt lgkmcnt(1)
	v_mfma_f32_32x32x16_bf16 a[80:95], v[112:115], v[108:111], a[80:95]
	v_mfma_f32_32x32x16_bf16 a[64:79], v[112:115], v[100:103], a[64:79]
	v_mfma_f32_32x32x16_bf16 a[48:63], v[128:131], v[108:111], a[48:63]
	v_mfma_f32_32x32x16_bf16 a[32:47], v[128:131], v[100:103], a[32:47]
	ds_read_b128 v[112:115], v61 offset:64
	ds_read_b128 v[128:131], v61 offset:96
	s_waitcnt lgkmcnt(1)
	v_mfma_f32_32x32x16_bf16 a[16:31], v[112:115], v[108:111], a[16:31]
	v_mfma_f32_32x32x16_bf16 a[0:15], v[112:115], v[100:103], a[0:15]
	global_load_dwordx4 v[100:103], v[32:33], off offset:1536
	v_mfma_f32_32x32x16_bf16 a[112:127], v[124:127], v[120:123], a[112:127]
	v_mfma_f32_32x32x16_bf16 a[96:111], v[124:127], v[104:107], a[96:111]
	v_mfma_f32_32x32x16_bf16 a[80:95], v[116:119], v[120:123], a[80:95]
	v_mfma_f32_32x32x16_bf16 a[64:79], v[116:119], v[104:107], a[64:79]
	v_mfma_f32_32x32x16_bf16 a[48:63], v[140:143], v[120:123], a[48:63]
	v_mfma_f32_32x32x16_bf16 a[32:47], v[140:143], v[104:107], a[32:47]
	global_load_dwordx4 v[108:111], v[30:31], off offset:1536
	global_load_dwordx4 v[112:115], v[28:29], off offset:1536
	global_load_dwordx4 v[116:119], v[2:3], off offset:1536
	global_load_dwordx4 v[124:127], v[8:9], off offset:1536
	global_load_dwordx4 v[140:143], v[6:7], off offset:1536
	global_load_dwordx4 v[144:147], v[4:5], off offset:1536
	global_load_dwordx4 v[148:151], v[0:1], off offset:1536
	s_waitcnt lgkmcnt(0)
	v_mfma_f32_32x32x16_bf16 a[16:31], v[128:131], v[120:123], a[16:31]
	global_load_dwordx4 v[120:123], v[12:13], off offset:1536
	global_load_dwordx4 v[152:155], v[10:11], off offset:1536
	global_load_dwordx4 v[156:159], v[26:27], off offset:1536
	global_load_dwordx4 v[160:163], v[14:15], off offset:1536
	s_barrier
	v_mfma_f32_32x32x16_bf16 a[0:15], v[128:131], v[104:107], a[0:15]
	ds_read_b128 v[104:107], v59 offset:55296
	ds_read_b128 v[128:131], v69
	ds_read_b128 v[164:167], v59 offset:59904
	ds_read_b128 v[168:171], v69 offset:4608
	s_waitcnt lgkmcnt(2)
	v_mfma_f32_32x32x16_bf16 a[112:127], v[104:107], v[128:131], a[112:127]
	s_waitcnt lgkmcnt(0)
	v_mfma_f32_32x32x16_bf16 a[96:111], v[104:107], v[168:171], a[96:111]
	ds_read_b128 v[104:107], v59 offset:64512
	s_waitcnt lgkmcnt(0)
	v_mfma_f32_32x32x16_bf16 a[48:63], v[104:107], v[128:131], a[48:63]
	v_mfma_f32_32x32x16_bf16 a[32:47], v[104:107], v[168:171], a[32:47]
	ds_read_b128 v[104:107], v61 offset:55296
	s_waitcnt vmcnt(4)
	ds_write_b128 v60, v[148:151]
	ds_write_b128 v60, v[144:147] offset:4608
	ds_write_b128 v60, v[140:143] offset:9216
	ds_write_b128 v60, v[124:127] offset:13824
	s_waitcnt vmcnt(2)
	ds_write_b128 v60, v[152:155] offset:18432
	ds_write_b128 v60, v[120:123] offset:23040
	s_waitcnt vmcnt(0)
	ds_write_b128 v60, v[160:163] offset:27648
	ds_write_b128 v60, v[156:159] offset:32256
	ds_write_b128 v60, v[116:119] offset:36864
	ds_write_b128 v60, v[112:115] offset:41472
	ds_write_b128 v60, v[108:111] offset:46080
	ds_write_b128 v60, v[100:103] offset:50688
	v_mfma_f32_32x32x16_bf16 a[80:95], v[164:167], v[128:131], a[80:95]
	v_mfma_f32_32x32x16_bf16 a[64:79], v[164:167], v[168:171], a[64:79]
	s_waitcnt lgkmcnt(12)
	v_mfma_f32_32x32x16_bf16 a[16:31], v[104:107], v[128:131], a[16:31]
	v_mfma_f32_32x32x16_bf16 a[0:15], v[104:107], v[168:171], a[0:15]
	ds_read_b128 v[100:103], v59 offset:55328
	ds_read_b128 v[104:107], v69 offset:32
	ds_read_b128 v[108:111], v69 offset:64
	ds_read_b128 v[112:115], v59 offset:55360
	ds_read_b128 v[116:119], v69 offset:4640
	ds_read_b128 v[120:123], v69 offset:96
	s_waitcnt lgkmcnt(4)
	v_mfma_f32_32x32x16_bf16 a[112:127], v[100:103], v[104:107], a[112:127]
	s_waitcnt lgkmcnt(1)
	v_mfma_f32_32x32x16_bf16 a[96:111], v[100:103], v[116:119], a[96:111]
	ds_read_b128 v[100:103], v59 offset:59936
	ds_read_b128 v[124:127], v59 offset:55392
	s_waitcnt lgkmcnt(1)
	v_mfma_f32_32x32x16_bf16 a[80:95], v[100:103], v[104:107], a[80:95]
	v_mfma_f32_32x32x16_bf16 a[64:79], v[100:103], v[116:119], a[64:79]
	ds_read_b128 v[100:103], v59 offset:64544
	ds_read_b128 v[128:131], v59 offset:64576
	s_waitcnt lgkmcnt(1)
	v_mfma_f32_32x32x16_bf16 a[48:63], v[100:103], v[104:107], a[48:63]
	v_mfma_f32_32x32x16_bf16 a[32:47], v[100:103], v[116:119], a[32:47]
	ds_read_b128 v[100:103], v61 offset:55328
	ds_read_b128 v[140:143], v59 offset:64608
	s_waitcnt lgkmcnt(1)
	v_mfma_f32_32x32x16_bf16 a[16:31], v[100:103], v[104:107], a[16:31]
	v_mfma_f32_32x32x16_bf16 a[0:15], v[100:103], v[116:119], a[0:15]
	ds_read_b128 v[100:103], v69 offset:4672
	ds_read_b128 v[104:107], v69 offset:4704
	v_mfma_f32_32x32x16_bf16 a[112:127], v[112:115], v[108:111], a[112:127]
	s_waitcnt lgkmcnt(1)
	v_mfma_f32_32x32x16_bf16 a[96:111], v[112:115], v[100:103], a[96:111]
	ds_read_b128 v[112:115], v59 offset:59968
	ds_read_b128 v[116:119], v59 offset:60000
	s_waitcnt lgkmcnt(1)
	v_mfma_f32_32x32x16_bf16 a[80:95], v[112:115], v[108:111], a[80:95]
	v_mfma_f32_32x32x16_bf16 a[64:79], v[112:115], v[100:103], a[64:79]
	v_mfma_f32_32x32x16_bf16 a[48:63], v[128:131], v[108:111], a[48:63]
	v_mfma_f32_32x32x16_bf16 a[32:47], v[128:131], v[100:103], a[32:47]
	ds_read_b128 v[112:115], v61 offset:55360
	ds_read_b128 v[128:131], v61 offset:55392
	s_waitcnt lgkmcnt(1)
	v_mfma_f32_32x32x16_bf16 a[16:31], v[112:115], v[108:111], a[16:31]
	v_mfma_f32_32x32x16_bf16 a[0:15], v[112:115], v[100:103], a[0:15]
	v_mfma_f32_32x32x16_bf16 a[112:127], v[124:127], v[120:123], a[112:127]
	v_mfma_f32_32x32x16_bf16 a[96:111], v[124:127], v[104:107], a[96:111]
	v_mfma_f32_32x32x16_bf16 a[80:95], v[116:119], v[120:123], a[80:95]
	v_mfma_f32_32x32x16_bf16 a[64:79], v[116:119], v[104:107], a[64:79]
	global_load_dwordx4 v[100:103], v[4:5], off offset:1664
	global_load_dwordx4 v[108:111], v[0:1], off offset:1664
	global_load_dwordx4 v[112:115], v[8:9], off offset:1664
	global_load_dwordx4 v[116:119], v[6:7], off offset:1664
	v_mfma_f32_32x32x16_bf16 a[48:63], v[140:143], v[120:123], a[48:63]
	v_mfma_f32_32x32x16_bf16 a[32:47], v[140:143], v[104:107], a[32:47]
	global_load_dwordx4 v[124:127], v[10:11], off offset:1664
	global_load_dwordx4 v[140:143], v[12:13], off offset:1664
	global_load_dwordx4 v[144:147], v[26:27], off offset:1664
	global_load_dwordx4 v[148:151], v[14:15], off offset:1664
	global_load_dwordx4 v[152:155], v[28:29], off offset:1664
	global_load_dwordx4 v[156:159], v[2:3], off offset:1664
	global_load_dwordx4 v[160:163], v[30:31], off offset:1664
	s_waitcnt lgkmcnt(0)
	v_mfma_f32_32x32x16_bf16 a[16:31], v[128:131], v[120:123], a[16:31]
	global_load_dwordx4 v[120:123], v[32:33], off offset:1664
	s_barrier
	v_mfma_f32_32x32x16_bf16 a[0:15], v[128:131], v[104:107], a[0:15]
	ds_read_b128 v[104:107], v59
	ds_read_b128 v[128:131], v62 offset:36864
	ds_read_b128 v[164:167], v59 offset:4608
	ds_read_b128 v[168:171], v62 offset:41472
	s_waitcnt lgkmcnt(2)
	v_mfma_f32_32x32x16_bf16 a[112:127], v[104:107], v[128:131], a[112:127]
	s_waitcnt lgkmcnt(0)
	v_mfma_f32_32x32x16_bf16 a[96:111], v[104:107], v[168:171], a[96:111]
	ds_read_b128 v[104:107], v59 offset:9216
	s_waitcnt lgkmcnt(0)
	v_mfma_f32_32x32x16_bf16 a[48:63], v[104:107], v[128:131], a[48:63]
	v_mfma_f32_32x32x16_bf16 a[32:47], v[104:107], v[168:171], a[32:47]
	ds_read_b128 v[104:107], v61
	s_waitcnt vmcnt(10)
	ds_write_b128 v60, v[108:111] offset:55296
	ds_write_b128 v60, v[100:103] offset:59904
	s_waitcnt vmcnt(8)
	ds_write_b128 v60, v[116:119] offset:64512
	ds_write_b128 v63, v[112:115] offset:55296
	s_waitcnt vmcnt(7)
	ds_write_b128 v64, v[124:127] offset:55296
	s_waitcnt vmcnt(6)
	ds_write_b128 v65, v[140:143] offset:55296
	s_waitcnt vmcnt(4)
	ds_write_b128 v66, v[148:151] offset:55296
	ds_write_b128 v67, v[144:147] offset:55296
	s_waitcnt vmcnt(2)
	ds_write_b128 v68, v[156:159]
	ds_write_b128 v68, v[152:155] offset:4608
	s_waitcnt vmcnt(1)
	ds_write_b128 v68, v[160:163] offset:9216
	s_waitcnt vmcnt(0)
	ds_write_b128 v68, v[120:123] offset:13824
	v_mfma_f32_32x32x16_bf16 a[80:95], v[164:167], v[128:131], a[80:95]
	v_mfma_f32_32x32x16_bf16 a[64:79], v[164:167], v[168:171], a[64:79]
	s_waitcnt lgkmcnt(12)
	v_mfma_f32_32x32x16_bf16 a[16:31], v[104:107], v[128:131], a[16:31]
	v_mfma_f32_32x32x16_bf16 a[0:15], v[104:107], v[168:171], a[0:15]
	ds_read_b128 v[100:103], v59 offset:32
	ds_read_b128 v[104:107], v62 offset:36896
	ds_read_b128 v[108:111], v62 offset:36928
	ds_read_b128 v[112:115], v59 offset:64
	ds_read_b128 v[116:119], v62 offset:41504
	ds_read_b128 v[120:123], v62 offset:36960
	s_waitcnt lgkmcnt(4)
	v_mfma_f32_32x32x16_bf16 a[112:127], v[100:103], v[104:107], a[112:127]
	s_waitcnt lgkmcnt(1)
	v_mfma_f32_32x32x16_bf16 a[96:111], v[100:103], v[116:119], a[96:111]
	ds_read_b128 v[100:103], v59 offset:4640
	ds_read_b128 v[124:127], v59 offset:96
	s_waitcnt lgkmcnt(1)
	v_mfma_f32_32x32x16_bf16 a[80:95], v[100:103], v[104:107], a[80:95]
	v_mfma_f32_32x32x16_bf16 a[64:79], v[100:103], v[116:119], a[64:79]
	ds_read_b128 v[100:103], v59 offset:9248
	ds_read_b128 v[128:131], v59 offset:9280
	s_waitcnt lgkmcnt(1)
	v_mfma_f32_32x32x16_bf16 a[48:63], v[100:103], v[104:107], a[48:63]
	v_mfma_f32_32x32x16_bf16 a[32:47], v[100:103], v[116:119], a[32:47]
	ds_read_b128 v[100:103], v61 offset:32
	ds_read_b128 v[140:143], v59 offset:9312
	s_waitcnt lgkmcnt(1)
	v_mfma_f32_32x32x16_bf16 a[16:31], v[100:103], v[104:107], a[16:31]
	v_mfma_f32_32x32x16_bf16 a[0:15], v[100:103], v[116:119], a[0:15]
	ds_read_b128 v[100:103], v62 offset:41536
	ds_read_b128 v[104:107], v62 offset:41568
	v_mfma_f32_32x32x16_bf16 a[112:127], v[112:115], v[108:111], a[112:127]
	s_waitcnt lgkmcnt(1)
	v_mfma_f32_32x32x16_bf16 a[96:111], v[112:115], v[100:103], a[96:111]
	ds_read_b128 v[112:115], v59 offset:4672
	ds_read_b128 v[116:119], v59 offset:4704
	s_waitcnt lgkmcnt(1)
	v_mfma_f32_32x32x16_bf16 a[80:95], v[112:115], v[108:111], a[80:95]
	v_mfma_f32_32x32x16_bf16 a[64:79], v[112:115], v[100:103], a[64:79]
	v_mfma_f32_32x32x16_bf16 a[48:63], v[128:131], v[108:111], a[48:63]
	v_mfma_f32_32x32x16_bf16 a[32:47], v[128:131], v[100:103], a[32:47]
	ds_read_b128 v[112:115], v61 offset:64
	ds_read_b128 v[128:131], v61 offset:96
	s_waitcnt lgkmcnt(1)
	v_mfma_f32_32x32x16_bf16 a[16:31], v[112:115], v[108:111], a[16:31]
	v_mfma_f32_32x32x16_bf16 a[0:15], v[112:115], v[100:103], a[0:15]
	global_load_dwordx4 v[100:103], v[32:33], off offset:1792
	v_mfma_f32_32x32x16_bf16 a[112:127], v[124:127], v[120:123], a[112:127]
	v_mfma_f32_32x32x16_bf16 a[96:111], v[124:127], v[104:107], a[96:111]
	v_mfma_f32_32x32x16_bf16 a[80:95], v[116:119], v[120:123], a[80:95]
	v_mfma_f32_32x32x16_bf16 a[64:79], v[116:119], v[104:107], a[64:79]
	v_mfma_f32_32x32x16_bf16 a[48:63], v[140:143], v[120:123], a[48:63]
	v_mfma_f32_32x32x16_bf16 a[32:47], v[140:143], v[104:107], a[32:47]
	global_load_dwordx4 v[108:111], v[30:31], off offset:1792
	global_load_dwordx4 v[112:115], v[28:29], off offset:1792
	global_load_dwordx4 v[116:119], v[2:3], off offset:1792
	global_load_dwordx4 v[124:127], v[8:9], off offset:1792
	global_load_dwordx4 v[140:143], v[6:7], off offset:1792
	global_load_dwordx4 v[144:147], v[4:5], off offset:1792
	global_load_dwordx4 v[148:151], v[0:1], off offset:1792
	s_waitcnt lgkmcnt(0)
	v_mfma_f32_32x32x16_bf16 a[16:31], v[128:131], v[120:123], a[16:31]
	global_load_dwordx4 v[120:123], v[12:13], off offset:1792
	global_load_dwordx4 v[152:155], v[10:11], off offset:1792
	global_load_dwordx4 v[156:159], v[26:27], off offset:1792
	global_load_dwordx4 v[160:163], v[14:15], off offset:1792
	s_barrier
	v_mfma_f32_32x32x16_bf16 a[0:15], v[128:131], v[104:107], a[0:15]
	ds_read_b128 v[104:107], v59 offset:55296
	ds_read_b128 v[128:131], v69
	ds_read_b128 v[164:167], v59 offset:59904
	ds_read_b128 v[168:171], v69 offset:4608
	s_waitcnt lgkmcnt(2)
	v_mfma_f32_32x32x16_bf16 a[112:127], v[104:107], v[128:131], a[112:127]
	s_waitcnt lgkmcnt(0)
	v_mfma_f32_32x32x16_bf16 a[96:111], v[104:107], v[168:171], a[96:111]
	ds_read_b128 v[104:107], v59 offset:64512
	s_waitcnt lgkmcnt(0)
	v_mfma_f32_32x32x16_bf16 a[48:63], v[104:107], v[128:131], a[48:63]
	v_mfma_f32_32x32x16_bf16 a[32:47], v[104:107], v[168:171], a[32:47]
	ds_read_b128 v[104:107], v61 offset:55296
	s_waitcnt vmcnt(4)
	ds_write_b128 v60, v[148:151]
	ds_write_b128 v60, v[144:147] offset:4608
	ds_write_b128 v60, v[140:143] offset:9216
	ds_write_b128 v60, v[124:127] offset:13824
	s_waitcnt vmcnt(2)
	ds_write_b128 v60, v[152:155] offset:18432
	ds_write_b128 v60, v[120:123] offset:23040
	s_waitcnt vmcnt(0)
	ds_write_b128 v60, v[160:163] offset:27648
	ds_write_b128 v60, v[156:159] offset:32256
	ds_write_b128 v60, v[116:119] offset:36864
	ds_write_b128 v60, v[112:115] offset:41472
	ds_write_b128 v60, v[108:111] offset:46080
	ds_write_b128 v60, v[100:103] offset:50688
	v_mfma_f32_32x32x16_bf16 a[80:95], v[164:167], v[128:131], a[80:95]
	v_mfma_f32_32x32x16_bf16 a[64:79], v[164:167], v[168:171], a[64:79]
	s_waitcnt lgkmcnt(12)
	v_mfma_f32_32x32x16_bf16 a[16:31], v[104:107], v[128:131], a[16:31]
	v_mfma_f32_32x32x16_bf16 a[0:15], v[104:107], v[168:171], a[0:15]
	ds_read_b128 v[100:103], v59 offset:55328
	ds_read_b128 v[104:107], v69 offset:32
	ds_read_b128 v[108:111], v69 offset:64
	ds_read_b128 v[112:115], v59 offset:55360
	ds_read_b128 v[116:119], v69 offset:4640
	ds_read_b128 v[120:123], v69 offset:96
	s_waitcnt lgkmcnt(4)
	v_mfma_f32_32x32x16_bf16 a[112:127], v[100:103], v[104:107], a[112:127]
	s_waitcnt lgkmcnt(1)
	v_mfma_f32_32x32x16_bf16 a[96:111], v[100:103], v[116:119], a[96:111]
	ds_read_b128 v[100:103], v59 offset:59936
	ds_read_b128 v[124:127], v59 offset:55392
	s_waitcnt lgkmcnt(1)
	v_mfma_f32_32x32x16_bf16 a[80:95], v[100:103], v[104:107], a[80:95]
	v_mfma_f32_32x32x16_bf16 a[64:79], v[100:103], v[116:119], a[64:79]
	ds_read_b128 v[100:103], v59 offset:64544
	ds_read_b128 v[128:131], v59 offset:64576
	s_waitcnt lgkmcnt(1)
	v_mfma_f32_32x32x16_bf16 a[48:63], v[100:103], v[104:107], a[48:63]
	v_mfma_f32_32x32x16_bf16 a[32:47], v[100:103], v[116:119], a[32:47]
	ds_read_b128 v[100:103], v61 offset:55328
	ds_read_b128 v[140:143], v59 offset:64608
	s_waitcnt lgkmcnt(1)
	v_mfma_f32_32x32x16_bf16 a[16:31], v[100:103], v[104:107], a[16:31]
	v_mfma_f32_32x32x16_bf16 a[0:15], v[100:103], v[116:119], a[0:15]
	ds_read_b128 v[100:103], v69 offset:4672
	ds_read_b128 v[104:107], v69 offset:4704
	v_mfma_f32_32x32x16_bf16 a[112:127], v[112:115], v[108:111], a[112:127]
	s_waitcnt lgkmcnt(1)
	v_mfma_f32_32x32x16_bf16 a[96:111], v[112:115], v[100:103], a[96:111]
	ds_read_b128 v[112:115], v59 offset:59968
	ds_read_b128 v[116:119], v59 offset:60000
	s_waitcnt lgkmcnt(1)
	v_mfma_f32_32x32x16_bf16 a[80:95], v[112:115], v[108:111], a[80:95]
	v_mfma_f32_32x32x16_bf16 a[64:79], v[112:115], v[100:103], a[64:79]
	v_mfma_f32_32x32x16_bf16 a[48:63], v[128:131], v[108:111], a[48:63]
	v_mfma_f32_32x32x16_bf16 a[32:47], v[128:131], v[100:103], a[32:47]
	ds_read_b128 v[112:115], v61 offset:55360
	ds_read_b128 v[128:131], v61 offset:55392
	s_waitcnt lgkmcnt(1)
	v_mfma_f32_32x32x16_bf16 a[16:31], v[112:115], v[108:111], a[16:31]
	v_mfma_f32_32x32x16_bf16 a[0:15], v[112:115], v[100:103], a[0:15]
	global_load_dwordx4 v[100:103], v[4:5], off offset:1920
	global_load_dwordx4 v[108:111], v[0:1], off offset:1920
	global_load_dwordx4 v[112:115], v[8:9], off offset:1920
	s_nop 0
	global_load_dwordx4 v[4:7], v[6:7], off offset:1920
	v_mfma_f32_32x32x16_bf16 a[112:127], v[124:127], v[120:123], a[112:127]
	v_mfma_f32_32x32x16_bf16 a[96:111], v[124:127], v[104:107], a[96:111]
	v_mfma_f32_32x32x16_bf16 a[80:95], v[116:119], v[120:123], a[80:95]
	v_mfma_f32_32x32x16_bf16 a[64:79], v[116:119], v[104:107], a[64:79]
	v_mfma_f32_32x32x16_bf16 a[48:63], v[140:143], v[120:123], a[48:63]
	v_mfma_f32_32x32x16_bf16 a[32:47], v[140:143], v[104:107], a[32:47]
	global_load_dwordx4 v[8:11], v[10:11], off offset:1920
	s_nop 0
	global_load_dwordx4 v[116:119], v[12:13], off offset:1920
	global_load_dwordx4 v[124:127], v[26:27], off offset:1920
	s_nop 0
	global_load_dwordx4 v[12:15], v[14:15], off offset:1920
	s_nop 0
	global_load_dwordx4 v[26:29], v[28:29], off offset:1920
	s_nop 0
	global_load_dwordx4 v[0:3], v[2:3], off offset:1920
	s_nop 0
	global_load_dwordx4 v[140:143], v[30:31], off offset:1920
	s_nop 0
	global_load_dwordx4 v[30:33], v[32:33], off offset:1920
	s_waitcnt lgkmcnt(0)
	s_barrier
	v_mfma_f32_32x32x16_bf16 a[16:31], v[128:131], v[120:123], a[16:31]
	v_mfma_f32_32x32x16_bf16 a[0:15], v[128:131], v[104:107], a[0:15]
	ds_read_b128 v[104:107], v59
	ds_read_b128 v[120:123], v62 offset:36864
	ds_read_b128 v[128:131], v59 offset:4608
	ds_read_b128 v[144:147], v62 offset:41472
	s_waitcnt lgkmcnt(2)
	v_mfma_f32_32x32x16_bf16 a[112:127], v[104:107], v[120:123], a[112:127]
	s_waitcnt lgkmcnt(0)
	v_mfma_f32_32x32x16_bf16 a[96:111], v[104:107], v[144:147], a[96:111]
	v_mfma_f32_32x32x16_bf16 a[80:95], v[128:131], v[120:123], a[80:95]
	v_mfma_f32_32x32x16_bf16 a[64:79], v[128:131], v[144:147], a[64:79]
	ds_read_b128 v[104:107], v59 offset:9216
	ds_read_b128 v[128:131], v61
	s_waitcnt vmcnt(10)
	ds_write_b128 v60, v[108:111] offset:55296
	ds_write_b128 v60, v[100:103] offset:59904
	s_waitcnt vmcnt(8)
	ds_write_b128 v60, v[4:7] offset:64512
	ds_write_b128 v63, v[112:115] offset:55296
	s_waitcnt vmcnt(7)
	ds_write_b128 v64, v[8:11] offset:55296
	s_waitcnt vmcnt(6)
	ds_write_b128 v65, v[116:119] offset:55296
	s_waitcnt vmcnt(4)
	ds_write_b128 v66, v[12:15] offset:55296
	ds_write_b128 v67, v[124:127] offset:55296
	s_waitcnt vmcnt(2)
	ds_write_b128 v68, v[0:3]
	ds_write_b128 v68, v[26:29] offset:4608
	s_waitcnt vmcnt(1)
	ds_write_b128 v68, v[140:143] offset:9216
	s_waitcnt vmcnt(0)
	ds_write_b128 v68, v[30:33] offset:13824
	ds_read_b128 v[0:3], v59 offset:32
	ds_read_b128 v[4:7], v62 offset:36896
	ds_read_b128 v[8:11], v62 offset:36928
	ds_read_b128 v[12:15], v59 offset:64
	ds_read_b128 v[26:29], v62 offset:41504
	ds_read_b128 v[30:33], v62 offset:36960
	s_waitcnt lgkmcnt(14)
	v_mfma_f32_32x32x16_bf16 a[48:63], v[104:107], v[120:123], a[48:63]
	v_mfma_f32_32x32x16_bf16 a[32:47], v[104:107], v[144:147], a[32:47]
	s_waitcnt lgkmcnt(4)
	v_mfma_f32_32x32x16_bf16 a[112:127], v[0:3], v[4:7], a[112:127]
	s_waitcnt lgkmcnt(1)
	v_mfma_f32_32x32x16_bf16 a[96:111], v[0:3], v[26:29], a[96:111]
	ds_read_b128 v[0:3], v59 offset:4640
	ds_read_b128 v[100:103], v59 offset:96
	v_mfma_f32_32x32x16_bf16 a[16:31], v[128:131], v[120:123], a[16:31]
	v_mfma_f32_32x32x16_bf16 a[0:15], v[128:131], v[144:147], a[0:15]
	s_waitcnt lgkmcnt(1)
	v_mfma_f32_32x32x16_bf16 a[80:95], v[0:3], v[4:7], a[80:95]
	v_mfma_f32_32x32x16_bf16 a[64:79], v[0:3], v[26:29], a[64:79]
	ds_read_b128 v[0:3], v59 offset:9248
	ds_read_b128 v[104:107], v59 offset:9280
	s_waitcnt lgkmcnt(1)
	v_mfma_f32_32x32x16_bf16 a[48:63], v[0:3], v[4:7], a[48:63]
	v_mfma_f32_32x32x16_bf16 a[32:47], v[0:3], v[26:29], a[32:47]
	ds_read_b128 v[0:3], v61 offset:32
	ds_read_b128 v[108:111], v59 offset:9312
	s_waitcnt lgkmcnt(1)
	v_mfma_f32_32x32x16_bf16 a[16:31], v[0:3], v[4:7], a[16:31]
	v_mfma_f32_32x32x16_bf16 a[0:15], v[0:3], v[26:29], a[0:15]
	ds_read_b128 v[0:3], v62 offset:41536
	ds_read_b128 v[4:7], v62 offset:41568
	v_mfma_f32_32x32x16_bf16 a[112:127], v[12:15], v[8:11], a[112:127]
	s_waitcnt lgkmcnt(1)
	v_mfma_f32_32x32x16_bf16 a[96:111], v[12:15], v[0:3], a[96:111]
	ds_read_b128 v[12:15], v59 offset:4672
	ds_read_b128 v[26:29], v59 offset:4704
	s_waitcnt lgkmcnt(1)
	v_mfma_f32_32x32x16_bf16 a[80:95], v[12:15], v[8:11], a[80:95]
	v_mfma_f32_32x32x16_bf16 a[64:79], v[12:15], v[0:3], a[64:79]
	v_mfma_f32_32x32x16_bf16 a[48:63], v[104:107], v[8:11], a[48:63]
	v_mfma_f32_32x32x16_bf16 a[32:47], v[104:107], v[0:3], a[32:47]
	ds_read_b128 v[12:15], v61 offset:64
	ds_read_b128 v[104:107], v61 offset:96
	s_waitcnt lgkmcnt(0)
	s_barrier
	v_mfma_f32_32x32x16_bf16 a[16:31], v[12:15], v[8:11], a[16:31]
	v_mfma_f32_32x32x16_bf16 a[0:15], v[12:15], v[0:3], a[0:15]
	v_mfma_f32_32x32x16_bf16 a[112:127], v[100:103], v[30:33], a[112:127]
	v_mfma_f32_32x32x16_bf16 a[96:111], v[100:103], v[4:7], a[96:111]
	v_mfma_f32_32x32x16_bf16 a[80:95], v[26:29], v[30:33], a[80:95]
	v_mfma_f32_32x32x16_bf16 a[64:79], v[26:29], v[4:7], a[64:79]
	v_mfma_f32_32x32x16_bf16 a[48:63], v[108:111], v[30:33], a[48:63]
	v_mfma_f32_32x32x16_bf16 a[32:47], v[108:111], v[4:7], a[32:47]
	v_mfma_f32_32x32x16_bf16 a[16:31], v[104:107], v[30:33], a[16:31]
	v_mfma_f32_32x32x16_bf16 a[0:15], v[104:107], v[4:7], a[0:15]
	ds_read_b128 v[0:3], v59 offset:55296
	ds_read_b128 v[4:7], v69
	ds_read_b128 v[8:11], v59 offset:55328
	ds_read_b128 v[12:15], v69 offset:32
	ds_read_b128 v[26:29], v69 offset:4608
	ds_read_b128 v[30:33], v69 offset:4640
	s_waitcnt lgkmcnt(4)
	v_mfma_f32_32x32x16_bf16 a[112:127], v[0:3], v[4:7], a[112:127]
	s_waitcnt lgkmcnt(1)
	v_mfma_f32_32x32x16_bf16 a[96:111], v[0:3], v[26:29], a[96:111]
	ds_read_b128 v[0:3], v59 offset:59904
	ds_read_b128 v[100:103], v59 offset:59936
	s_waitcnt lgkmcnt(1)
	v_mfma_f32_32x32x16_bf16 a[80:95], v[0:3], v[4:7], a[80:95]
	v_mfma_f32_32x32x16_bf16 a[64:79], v[0:3], v[26:29], a[64:79]
	ds_read_b128 v[0:3], v59 offset:64512
	ds_read_b128 v[104:107], v59 offset:64544
	s_waitcnt lgkmcnt(1)
	v_mfma_f32_32x32x16_bf16 a[48:63], v[0:3], v[4:7], a[48:63]
	v_mfma_f32_32x32x16_bf16 a[32:47], v[0:3], v[26:29], a[32:47]
	ds_read_b128 v[0:3], v61 offset:55296
	ds_read_b128 v[108:111], v61 offset:55328
	s_waitcnt lgkmcnt(1)
	v_mfma_f32_32x32x16_bf16 a[0:15], v[0:3], v[26:29], a[0:15]
	v_mfma_f32_32x32x16_bf16 a[112:127], v[8:11], v[12:15], a[112:127]
	v_mfma_f32_32x32x16_bf16 a[96:111], v[8:11], v[30:33], a[96:111]
	v_mfma_f32_32x32x16_bf16 a[16:31], v[0:3], v[4:7], a[16:31]
	v_mfma_f32_32x32x16_bf16 a[80:95], v[100:103], v[12:15], a[80:95]
	v_mfma_f32_32x32x16_bf16 a[64:79], v[100:103], v[30:33], a[64:79]
	v_mfma_f32_32x32x16_bf16 a[32:47], v[104:107], v[30:33], a[32:47]
	s_waitcnt lgkmcnt(0)
	v_mfma_f32_32x32x16_bf16 a[0:15], v[108:111], v[30:33], a[0:15]
	ds_read_b128 v[8:11], v59 offset:55360
	ds_read_b128 v[26:29], v69 offset:64
	ds_read_b128 v[30:33], v59 offset:55392
	ds_read_b128 v[4:7], v69 offset:96
	ds_read_b128 v[100:103], v69 offset:4672
	ds_read_b128 v[0:3], v69 offset:4704
	v_mfma_f32_32x32x16_bf16 a[48:63], v[104:107], v[12:15], a[48:63]
	s_waitcnt lgkmcnt(4)
	v_mfma_f32_32x32x16_bf16 a[112:127], v[8:11], v[26:29], a[112:127]
	s_waitcnt lgkmcnt(1)
	v_mfma_f32_32x32x16_bf16 a[96:111], v[8:11], v[100:103], a[96:111]
	ds_read_b128 v[8:11], v59 offset:59968
	ds_read_b128 v[104:107], v59 offset:60000
	v_mfma_f32_32x32x16_bf16 a[16:31], v[108:111], v[12:15], a[16:31]
	s_waitcnt lgkmcnt(1)
	v_mfma_f32_32x32x16_bf16 a[80:95], v[8:11], v[26:29], a[80:95]
	v_mfma_f32_32x32x16_bf16 a[64:79], v[8:11], v[100:103], a[64:79]
	ds_read_b128 v[8:11], v59 offset:64576
	ds_read_b128 v[12:15], v59 offset:64608
	s_waitcnt lgkmcnt(1)
	v_mfma_f32_32x32x16_bf16 a[48:63], v[8:11], v[26:29], a[48:63]
	v_mfma_f32_32x32x16_bf16 a[32:47], v[8:11], v[100:103], a[32:47]
	ds_read_b128 v[108:111], v61 offset:55360
	ds_read_b128 v[8:11], v61 offset:55392
	s_waitcnt lgkmcnt(0)
	s_barrier
	v_mfma_f32_32x32x16_bf16 a[16:31], v[108:111], v[26:29], a[16:31]
	v_or_b32_e32 v28, s14, v139
	v_lshl_add_u64 v[26:27], v[22:23], 0, s[4:5]
	v_or_b32_e32 v29, s14, v204
	v_mfma_f32_32x32x16_bf16 a[0:15], v[108:111], v[100:103], a[0:15]
	v_mfma_f32_32x32x16_bf16 a[112:127], v[30:33], v[4:7], a[112:127]
	v_mfma_f32_32x32x16_bf16 a[48:63], v[12:15], v[4:7], a[48:63]
	v_mfma_f32_32x32x16_bf16 a[32:47], v[12:15], v[0:3], a[32:47]
	v_lshl_add_u64 v[12:13], v[16:17], 2, v[26:27]
	v_lshlrev_b32_e32 v16, 10, v28
	v_lshl_add_u64 v[14:15], s[16:17], 0, v[24:25]
	v_add_co_u32_e32 v14, vcc, s11, v14
	s_nop 1
	v_addc_co_u32_e32 v15, vcc, 0, v15, vcc
	v_mfma_f32_32x32x16_bf16 a[96:111], v[30:33], v[0:3], a[96:111]
	v_or_b32_e32 v30, s14, v205
	v_lshl_add_u64 v[32:33], v[16:17], 2, v[26:27]
	v_lshlrev_b32_e32 v16, 10, v29
	v_mfma_f32_32x32x16_bf16 a[80:95], v[104:107], v[4:7], a[80:95]
	v_mfma_f32_32x32x16_bf16 a[64:79], v[104:107], v[0:3], a[64:79]
	v_lshl_add_u64 v[104:105], v[16:17], 2, v[26:27]
	v_lshlrev_b32_e32 v16, 10, v30
	v_lshl_add_u64 v[106:107], v[16:17], 2, v[26:27]
	v_mfma_f32_32x32x16_bf16 a[16:31], v[8:11], v[4:7], a[16:31]
	v_mfma_f32_32x32x16_bf16 a[0:15], v[8:11], v[0:3], a[0:15]
	ds_write_b32 v58, a112
	ds_write_b32 v58, a113 offset:516
	ds_write_b32 v58, a114 offset:1032
	ds_write_b32 v58, a115 offset:1548
	ds_write_b32 v58, a116 offset:4128
	ds_write_b32 v58, a117 offset:4644
	ds_write_b32 v58, a118 offset:5160
	ds_write_b32 v58, a119 offset:5676
	ds_write_b32 v58, a120 offset:8256
	ds_write_b32 v58, a121 offset:8772
	ds_write_b32 v58, a122 offset:9288
	ds_write_b32 v58, a123 offset:9804
	ds_write_b32 v58, a124 offset:12384
	ds_write_b32 v58, a125 offset:12900
	ds_write_b32 v58, a126 offset:13416
	ds_write_b32 v58, a127 offset:13932
	ds_write_b32 v58, a96 offset:128
	ds_write_b32 v58, a97 offset:644
	ds_write_b32 v58, a98 offset:1160
	ds_write_b32 v58, a99 offset:1676
	ds_write_b32 v58, a100 offset:4256
	ds_write_b32 v58, a101 offset:4772
	ds_write_b32 v58, a102 offset:5288
	ds_write_b32 v58, a103 offset:5804
	ds_write_b32 v58, a104 offset:8384
	ds_write_b32 v58, a105 offset:8900
	ds_write_b32 v58, a106 offset:9416
	ds_write_b32 v58, a107 offset:9932
	ds_write_b32 v58, a108 offset:12512
	ds_write_b32 v58, a109 offset:13028
	ds_write_b32 v58, a110 offset:13544
	ds_write_b32 v58, a111 offset:14060
	ds_write_b32 v58, a80 offset:16512
	ds_write_b32 v58, a81 offset:17028
	ds_write_b32 v58, a82 offset:17544
	ds_write_b32 v58, a83 offset:18060
	ds_write_b32 v58, a84 offset:20640
	ds_write_b32 v58, a85 offset:21156
	ds_write_b32 v58, a86 offset:21672
	ds_write_b32 v58, a87 offset:22188
	ds_write_b32 v58, a88 offset:24768
	ds_write_b32 v58, a89 offset:25284
	ds_write_b32 v58, a90 offset:25800
	ds_write_b32 v58, a91 offset:26316
	ds_write_b32 v58, a92 offset:28896
	ds_write_b32 v58, a93 offset:29412
	ds_write_b32 v58, a94 offset:29928
	ds_write_b32 v58, a95 offset:30444
	ds_write_b32 v58, a64 offset:16640
	ds_write_b32 v58, a65 offset:17156
	ds_write_b32 v58, a66 offset:17672
	ds_write_b32 v58, a67 offset:18188
	ds_write_b32 v58, a68 offset:20768
	ds_write_b32 v58, a69 offset:21284
	ds_write_b32 v58, a70 offset:21800
	ds_write_b32 v58, a71 offset:22316
	ds_write_b32 v58, a72 offset:24896
	ds_write_b32 v58, a73 offset:25412
	ds_write_b32 v58, a74 offset:25928
	ds_write_b32 v58, a75 offset:26444
	ds_write_b32 v58, a76 offset:29024
	ds_write_b32 v58, a77 offset:29540
	ds_write_b32 v58, a78 offset:30056
	ds_write_b32 v58, a79 offset:30572
	ds_write_b32 v58, a48 offset:33024
	ds_write_b32 v58, a49 offset:33540
	ds_write_b32 v58, a50 offset:34056
	ds_write_b32 v58, a51 offset:34572
	ds_write_b32 v58, a52 offset:37152
	ds_write_b32 v58, a53 offset:37668
	ds_write_b32 v58, a54 offset:38184
	ds_write_b32 v58, a55 offset:38700
	ds_write_b32 v58, a56 offset:41280
	ds_write_b32 v58, a57 offset:41796
	ds_write_b32 v58, a58 offset:42312
	ds_write_b32 v58, a59 offset:42828
	ds_write_b32 v58, a60 offset:45408
	ds_write_b32 v58, a61 offset:45924
	ds_write_b32 v58, a62 offset:46440
	ds_write_b32 v58, a63 offset:46956
	ds_write_b32 v58, a32 offset:33152
	ds_write_b32 v58, a33 offset:33668
	ds_write_b32 v58, a34 offset:34184
	ds_write_b32 v58, a35 offset:34700
	ds_write_b32 v58, a36 offset:37280
	ds_write_b32 v58, a37 offset:37796
	ds_write_b32 v58, a38 offset:38312
	ds_write_b32 v58, a39 offset:38828
	ds_write_b32 v58, a40 offset:41408
	ds_write_b32 v58, a41 offset:41924
	ds_write_b32 v58, a42 offset:42440
	ds_write_b32 v58, a43 offset:42956
	ds_write_b32 v58, a44 offset:45536
	ds_write_b32 v58, a45 offset:46052
	ds_write_b32 v58, a46 offset:46568
	ds_write_b32 v58, a47 offset:47084
	ds_write_b32 v58, a16 offset:49536
	ds_write_b32 v58, a17 offset:50052
	ds_write_b32 v58, a18 offset:50568
	ds_write_b32 v58, a19 offset:51084
	ds_write_b32 v58, a20 offset:53664
	ds_write_b32 v58, a21 offset:54180
	ds_write_b32 v58, a22 offset:54696
	ds_write_b32 v58, a23 offset:55212
	ds_write_b32 v58, a24 offset:57792
	ds_write_b32 v58, a25 offset:58308
	ds_write_b32 v58, a26 offset:58824
	ds_write_b32 v58, a27 offset:59340
	ds_write_b32 v58, a28 offset:61920
	ds_write_b32 v58, a29 offset:62436
	ds_write_b32 v58, a30 offset:62952
	ds_write_b32 v58, a31 offset:63468
	ds_write_b32 v58, a0 offset:49664
	ds_write_b32 v58, a1 offset:50180
	ds_write_b32 v58, a2 offset:50696
	ds_write_b32 v58, a3 offset:51212
	ds_write_b32 v58, a4 offset:53792
	ds_write_b32 v58, a5 offset:54308
	ds_write_b32 v58, a6 offset:54824
	ds_write_b32 v58, a7 offset:55340
	ds_write_b32 v58, a8 offset:57920
	ds_write_b32 v58, a9 offset:58436
	ds_write_b32 v58, a10 offset:58952
	ds_write_b32 v58, a11 offset:59468
	ds_write_b32 v58, a12 offset:62048
	ds_write_b32 v58, a13 offset:62564
	ds_write_b32 v58, a14 offset:63080
	ds_write_b32 v58, a15 offset:63596
	s_waitcnt lgkmcnt(0)
	s_barrier
	global_load_dwordx4 v[0:3], v[14:15], off
	v_mov_b32_e32 v144, v14
	v_mov_b32_e32 v145, v15
	v_mov_b32_e32 v146, v16
	v_mov_b32_e32 v147, v17
	v_mov_b32_e32 v148, v28
	v_mov_b32_e32 v149, v29
	v_mov_b32_e32 v150, v32
	v_mov_b32_e32 v151, v33
	v_mov_b32_e32 v152, v104
	v_mov_b32_e32 v153, v105
	v_mov_b32_e32 v154, v106
	v_mov_b32_e32 v155, v107
	v_mov_b32_e32 v156, v108
	v_mov_b32_e32 v157, v109
	v_mov_b32_e32 v158, v110
	v_mov_b32_e32 v159, v111
	global_load_dwordx4 v[250:253], v[150:151], off
	global_load_dwordx4 v[246:249], v[152:153], off
	global_load_dwordx4 v[242:245], v[154:155], off
	global_load_dwordx4 v[238:241], v[12:13], off
	v_or_b32_e32 v144, s14, v206
	v_lshlrev_b32_e32 v146, 10, v144
	v_lshl_add_u64 v[144:145], v[146:147], 2, v[26:27]
	v_or_b32_e32 v146, s14, v207
	v_lshlrev_b32_e32 v146, 10, v146
	global_load_dwordx4 v[234:237], v[144:145], off
	v_or_b32_e32 v148, s14, v208
	v_or_b32_e32 v149, s14, v209
	v_lshl_add_u64 v[150:151], v[146:147], 2, v[26:27]
	v_lshlrev_b32_e32 v146, 10, v148
	v_lshl_add_u64 v[152:153], v[146:147], 2, v[26:27]
	v_lshlrev_b32_e32 v146, 10, v149
	v_lshl_add_u64 v[154:155], v[146:147], 2, v[26:27]
	global_load_dwordx4 v[212:215], v[150:151], off
	global_load_dwordx4 v[200:203], v[152:153], off
	global_load_dwordx4 v[196:199], v[154:155], off
	v_or_b32_e32 v144, s14, v210
	v_lshlrev_b32_e32 v146, 10, v144
	v_lshl_add_u64 v[144:145], v[146:147], 2, v[26:27]
	v_or_b32_e32 v146, s14, v35
	v_lshlrev_b32_e32 v146, 10, v146
	global_load_dwordx4 v[192:195], v[144:145], off
	v_or_b32_e32 v148, s14, v36
	v_or_b32_e32 v149, s14, v37
	v_lshl_add_u64 v[150:151], v[146:147], 2, v[26:27]
	v_lshlrev_b32_e32 v146, 10, v148
	v_lshl_add_u64 v[152:153], v[146:147], 2, v[26:27]
	v_lshlrev_b32_e32 v146, 10, v149
	v_lshl_add_u64 v[154:155], v[146:147], 2, v[26:27]
	global_load_dwordx4 v[188:191], v[150:151], off
	global_load_dwordx4 v[184:187], v[152:153], off
	global_load_dwordx4 v[180:183], v[154:155], off
	v_or_b32_e32 v144, s14, v38
	v_lshlrev_b32_e32 v146, 10, v144
	v_lshl_add_u64 v[144:145], v[146:147], 2, v[26:27]
	v_or_b32_e32 v146, s14, v39
	v_lshlrev_b32_e32 v146, 10, v146
	global_load_dwordx4 v[176:179], v[144:145], off
	v_or_b32_e32 v148, s14, v40
	v_or_b32_e32 v149, s14, v41
	v_lshl_add_u64 v[150:151], v[146:147], 2, v[26:27]
	v_lshlrev_b32_e32 v146, 10, v148
	v_lshl_add_u64 v[156:157], v[146:147], 2, v[26:27]
	v_lshlrev_b32_e32 v146, 10, v149
	v_lshl_add_u64 v[158:159], v[146:147], 2, v[26:27]
	global_load_dwordx4 v[172:175], v[150:151], off
	global_load_dwordx4 v[168:171], v[156:157], off
	global_load_dwordx4 v[164:167], v[158:159], off
	s_waitcnt vmcnt(15)
	s_nop 1
	v_mov_b64_e32 v[8:9], v[250:251]
	v_mov_b64_e32 v[10:11], v[252:253]
	s_waitcnt vmcnt(14)
	s_nop 1
	v_mov_b64_e32 v[28:29], v[246:247]
	v_mov_b64_e32 v[30:31], v[248:249]
	s_waitcnt vmcnt(13)
	s_nop 1
	v_mov_b64_e32 v[100:101], v[242:243]
	v_mov_b64_e32 v[102:103], v[244:245]
	s_waitcnt vmcnt(12)
	s_nop 1
	v_mov_b64_e32 v[4:5], v[238:239]
	v_mov_b64_e32 v[6:7], v[240:241]
	ds_read2_b32 v[108:109], v70 offset1:1
	ds_read2_b32 v[110:111], v71 offset1:1
	ds_read2_b32 v[112:113], v72 offset1:1
	ds_read2_b32 v[114:115], v73 offset1:1
	ds_read2_b32 v[116:117], v74 offset1:1
	ds_read2_b32 v[118:119], v75 offset1:1
	ds_read2_b32 v[120:121], v76 offset1:1
	ds_read2_b32 v[122:123], v77 offset1:1
	v_or_b32_e32 v14, s14, v206
	v_lshlrev_b32_e32 v16, 10, v14
	v_lshl_add_u64 v[14:15], v[16:17], 2, v[26:27]
	v_or_b32_e32 v16, s14, v207
	v_lshlrev_b32_e32 v16, 10, v16
	s_waitcnt lgkmcnt(6)
	v_pk_fma_f32 v[10:11], v[2:3], v[110:111], v[10:11]
	v_pk_fma_f32 v[8:9], v[0:1], v[108:109], v[8:9]
	s_waitcnt lgkmcnt(4)
	v_pk_fma_f32 v[30:31], v[2:3], v[114:115], v[30:31]
	v_pk_fma_f32 v[28:29], v[0:1], v[112:113], v[28:29]
	s_waitcnt lgkmcnt(2)
	v_pk_fma_f32 v[102:103], v[2:3], v[118:119], v[102:103]
	v_pk_fma_f32 v[100:101], v[0:1], v[116:117], v[100:101]
	global_store_dwordx4 v[32:33], v[8:11], off
	global_store_dwordx4 v[104:105], v[28:31], off
	global_store_dwordx4 v[106:107], v[100:103], off
	s_waitcnt vmcnt(14)
	s_nop 1
	v_mov_b64_e32 v[8:9], v[234:235]
	v_mov_b64_e32 v[10:11], v[236:237]
	v_or_b32_e32 v28, s14, v208
	v_or_b32_e32 v29, s14, v209
	v_lshl_add_u64 v[32:33], v[16:17], 2, v[26:27]
	v_lshlrev_b32_e32 v16, 10, v28
	v_lshl_add_u64 v[104:105], v[16:17], 2, v[26:27]
	v_lshlrev_b32_e32 v16, 10, v29
	v_lshl_add_u64 v[106:107], v[16:17], 2, v[26:27]
	s_waitcnt lgkmcnt(0)
	v_pk_fma_f32 v[10:11], v[2:3], v[122:123], v[10:11]
	v_pk_fma_f32 v[8:9], v[0:1], v[120:121], v[8:9]
	global_store_dwordx4 v[14:15], v[8:11], off
	s_waitcnt vmcnt(14)
	s_nop 1
	v_mov_b64_e32 v[8:9], v[212:213]
	v_mov_b64_e32 v[10:11], v[214:215]
	s_nop 0
	s_waitcnt vmcnt(13)
	s_nop 1
	v_mov_b64_e32 v[28:29], v[200:201]
	v_mov_b64_e32 v[30:31], v[202:203]
	s_waitcnt vmcnt(12)
	s_nop 1
	v_mov_b64_e32 v[100:101], v[196:197]
	v_mov_b64_e32 v[102:103], v[198:199]
	ds_read2_b32 v[108:109], v78 offset1:1
	ds_read2_b32 v[110:111], v79 offset1:1
	ds_read2_b32 v[112:113], v80 offset1:1
	ds_read2_b32 v[114:115], v81 offset1:1
	ds_read2_b32 v[116:117], v82 offset1:1
	ds_read2_b32 v[118:119], v83 offset1:1
	ds_read2_b32 v[120:121], v84 offset1:1
	ds_read2_b32 v[122:123], v85 offset1:1
	v_or_b32_e32 v14, s14, v210
	v_lshlrev_b32_e32 v16, 10, v14
	v_lshl_add_u64 v[14:15], v[16:17], 2, v[26:27]
	v_or_b32_e32 v16, s14, v35
	v_lshlrev_b32_e32 v16, 10, v16
	s_waitcnt lgkmcnt(6)
	v_pk_fma_f32 v[10:11], v[2:3], v[110:111], v[10:11]
	v_pk_fma_f32 v[8:9], v[0:1], v[108:109], v[8:9]
	s_waitcnt lgkmcnt(4)
	v_pk_fma_f32 v[30:31], v[2:3], v[114:115], v[30:31]
	v_pk_fma_f32 v[28:29], v[0:1], v[112:113], v[28:29]
	s_waitcnt lgkmcnt(2)
	v_pk_fma_f32 v[102:103], v[2:3], v[118:119], v[102:103]
	v_pk_fma_f32 v[100:101], v[0:1], v[116:117], v[100:101]
	global_store_dwordx4 v[32:33], v[8:11], off
	global_store_dwordx4 v[104:105], v[28:31], off
	global_store_dwordx4 v[106:107], v[100:103], off
	s_waitcnt vmcnt(14)
	s_nop 1
	v_mov_b64_e32 v[8:9], v[192:193]
	v_mov_b64_e32 v[10:11], v[194:195]
	v_or_b32_e32 v28, s14, v36
	v_or_b32_e32 v29, s14, v37
	v_lshl_add_u64 v[32:33], v[16:17], 2, v[26:27]
	v_lshlrev_b32_e32 v16, 10, v28
	v_lshl_add_u64 v[104:105], v[16:17], 2, v[26:27]
	v_lshlrev_b32_e32 v16, 10, v29
	v_lshl_add_u64 v[106:107], v[16:17], 2, v[26:27]
	s_waitcnt lgkmcnt(0)
	v_pk_fma_f32 v[10:11], v[2:3], v[122:123], v[10:11]
	v_pk_fma_f32 v[8:9], v[0:1], v[120:121], v[8:9]
	global_store_dwordx4 v[14:15], v[8:11], off
	s_waitcnt vmcnt(14)
	s_nop 1
	v_mov_b64_e32 v[8:9], v[188:189]
	v_mov_b64_e32 v[10:11], v[190:191]
	s_nop 0
	s_waitcnt vmcnt(13)
	s_nop 1
	v_mov_b64_e32 v[28:29], v[184:185]
	v_mov_b64_e32 v[30:31], v[186:187]
	s_waitcnt vmcnt(12)
	s_nop 1
	v_mov_b64_e32 v[100:101], v[180:181]
	v_mov_b64_e32 v[102:103], v[182:183]
	ds_read2_b32 v[108:109], v86 offset1:1
	ds_read2_b32 v[110:111], v87 offset1:1
	ds_read2_b32 v[112:113], v88 offset1:1
	ds_read2_b32 v[114:115], v89 offset1:1
	ds_read2_b32 v[116:117], v90 offset1:1
	ds_read2_b32 v[118:119], v91 offset1:1
	ds_read2_b32 v[120:121], v92 offset1:1
	ds_read2_b32 v[122:123], v93 offset1:1
	v_or_b32_e32 v14, s14, v38
	v_lshlrev_b32_e32 v16, 10, v14
	v_lshl_add_u64 v[14:15], v[16:17], 2, v[26:27]
	v_or_b32_e32 v16, s14, v39
	v_lshlrev_b32_e32 v16, 10, v16
	s_waitcnt lgkmcnt(6)
	v_pk_fma_f32 v[10:11], v[2:3], v[110:111], v[10:11]
	v_pk_fma_f32 v[8:9], v[0:1], v[108:109], v[8:9]
	s_waitcnt lgkmcnt(4)
	v_pk_fma_f32 v[30:31], v[2:3], v[114:115], v[30:31]
	v_pk_fma_f32 v[28:29], v[0:1], v[112:113], v[28:29]
	s_waitcnt lgkmcnt(2)
	v_pk_fma_f32 v[102:103], v[2:3], v[118:119], v[102:103]
	v_pk_fma_f32 v[100:101], v[0:1], v[116:117], v[100:101]
	global_store_dwordx4 v[32:33], v[8:11], off
	global_store_dwordx4 v[104:105], v[28:31], off
	global_store_dwordx4 v[106:107], v[100:103], off
	s_waitcnt vmcnt(14)
	s_nop 1
	v_mov_b64_e32 v[8:9], v[176:177]
	v_mov_b64_e32 v[10:11], v[178:179]
	v_or_b32_e32 v28, s14, v40
	v_or_b32_e32 v29, s14, v41
	v_lshl_add_u64 v[32:33], v[16:17], 2, v[26:27]
	v_lshlrev_b32_e32 v16, 10, v28
	v_lshl_add_u64 v[108:109], v[16:17], 2, v[26:27]
	v_lshlrev_b32_e32 v16, 10, v29
	v_lshl_add_u64 v[110:111], v[16:17], 2, v[26:27]
	s_bitset1_b32 s14, 7
	s_add_u32 s13, s2, s13
	s_addc_u32 s15, s3, s12
	s_add_u32 s12, s13, s4
	s_addc_u32 s13, s15, 0
	s_add_i32 s6, s6, s77
	s_cmpk_lt_u32 s6, 0x60
	s_waitcnt lgkmcnt(0)
	v_pk_fma_f32 v[10:11], v[2:3], v[122:123], v[10:11]
	v_pk_fma_f32 v[8:9], v[0:1], v[120:121], v[8:9]
	global_store_dwordx4 v[14:15], v[8:11], off
	s_waitcnt vmcnt(14)
	s_nop 1
	v_mov_b64_e32 v[28:29], v[172:173]
	v_mov_b64_e32 v[30:31], v[174:175]
	s_waitcnt vmcnt(13)
	s_nop 1
	v_mov_b64_e32 v[100:101], v[168:169]
	v_mov_b64_e32 v[102:103], v[170:171]
	s_waitcnt vmcnt(12)
	s_nop 1
	v_mov_b64_e32 v[104:105], v[164:165]
	v_mov_b64_e32 v[106:107], v[166:167]
	v_or_b32_e32 v10, s14, v135
	v_lshl_add_u64 v[8:9], s[12:13], 0, v[24:25]
	v_or_b32_e32 v11, s14, v139
	v_add_co_u32_e32 v112, vcc, s11, v8
	v_lshlrev_b32_e32 v16, 10, v10
	v_or_b32_e32 v14, s14, v204
	v_addc_co_u32_e32 v113, vcc, 0, v9, vcc
	v_lshl_add_u64 v[8:9], v[16:17], 2, v[26:27]
	v_lshlrev_b32_e32 v16, 10, v11
	v_or_b32_e32 v15, s14, v205
	v_lshl_add_u64 v[114:115], v[16:17], 2, v[26:27]
	v_lshlrev_b32_e32 v16, 10, v14
	v_lshl_add_u64 v[116:117], v[16:17], 2, v[26:27]
	v_lshlrev_b32_e32 v16, 10, v15
	ds_read2_b32 v[120:121], v34 offset1:1
	ds_read2_b32 v[122:123], v34 offset0:2 offset1:3
	ds_read2_b32 v[124:125], v94 offset1:1
	ds_read2_b32 v[126:127], v95 offset1:1
	ds_read2_b32 v[128:129], v96 offset1:1
	ds_read2_b32 v[130:131], v97 offset1:1
	ds_read2_b32 v[132:133], v98 offset1:1
	ds_read2_b32 v[136:137], v99 offset1:1
	ds_read2_b32 v[10:11], v42 offset1:1
	ds_read2_b32 v[14:15], v42 offset0:2 offset1:3
	s_waitcnt lgkmcnt(8)
	v_pk_fma_f32 v[6:7], v[2:3], v[122:123], v[6:7]
	v_pk_fma_f32 v[4:5], v[0:1], v[120:121], v[4:5]
	global_store_dwordx4 v[12:13], v[4:7], off
	v_lshl_add_u64 v[118:119], v[16:17], 2, v[26:27]
	v_or_b32_e32 v12, s14, v206
	v_lshlrev_b32_e32 v16, 10, v12
	v_lshl_add_u64 v[12:13], v[16:17], 2, v[26:27]
	v_or_b32_e32 v16, s14, v207
	v_lshlrev_b32_e32 v16, 10, v16
	s_waitcnt lgkmcnt(6)
	v_pk_fma_f32 v[6:7], v[2:3], v[126:127], v[30:31]
	v_pk_fma_f32 v[4:5], v[0:1], v[124:125], v[28:29]
	s_waitcnt lgkmcnt(4)
	v_pk_fma_f32 v[30:31], v[2:3], v[130:131], v[102:103]
	v_pk_fma_f32 v[28:29], v[0:1], v[128:129], v[100:101]
	s_waitcnt lgkmcnt(2)
	v_pk_fma_f32 v[2:3], v[2:3], v[136:137], v[106:107]
	v_pk_fma_f32 v[0:1], v[0:1], v[132:133], v[104:105]
	global_store_dwordx4 v[32:33], v[4:7], off
	global_store_dwordx4 v[108:109], v[28:31], off
	global_store_dwordx4 v[110:111], v[0:3], off
	global_load_dwordx4 v[0:3], v[112:113], off
	s_nop 0
	v_mov_b32_e32 v128, v12
	v_mov_b32_e32 v129, v13
	v_mov_b32_e32 v130, v16
	v_mov_b32_e32 v131, v17
	v_mov_b32_e32 v132, v26
	v_mov_b32_e32 v133, v27
	v_mov_b32_e32 v136, v32
	v_mov_b32_e32 v137, v33
	v_mov_b32_e32 v144, v100
	v_mov_b32_e32 v145, v101
	v_mov_b32_e32 v146, v108
	v_mov_b32_e32 v147, v109
	v_mov_b32_e32 v148, v110
	v_mov_b32_e32 v149, v111
	global_load_dwordx4 v[250:253], v[114:115], off
	global_load_dwordx4 v[246:249], v[116:117], off
	global_load_dwordx4 v[242:245], v[118:119], off
	global_load_dwordx4 v[238:241], v[8:9], off
	global_load_dwordx4 v[234:237], v[128:129], off
	v_or_b32_e32 v144, s14, v208
	v_or_b32_e32 v145, s14, v209
	v_lshl_add_u64 v[136:137], v[130:131], 2, v[132:133]
	v_lshlrev_b32_e32 v130, 10, v144
	v_lshl_add_u64 v[146:147], v[130:131], 2, v[132:133]
	v_lshlrev_b32_e32 v130, 10, v145
	v_lshl_add_u64 v[148:149], v[130:131], 2, v[132:133]
	global_load_dwordx4 v[212:215], v[136:137], off
	global_load_dwordx4 v[200:203], v[146:147], off
	global_load_dwordx4 v[196:199], v[148:149], off
	v_or_b32_e32 v128, s14, v210
	v_lshlrev_b32_e32 v130, 10, v128
	v_lshl_add_u64 v[128:129], v[130:131], 2, v[132:133]
	v_or_b32_e32 v130, s14, v35
	v_lshlrev_b32_e32 v130, 10, v130
	global_load_dwordx4 v[192:195], v[128:129], off
	v_or_b32_e32 v144, s14, v36
	v_or_b32_e32 v145, s14, v37
	v_lshl_add_u64 v[136:137], v[130:131], 2, v[132:133]
	v_lshlrev_b32_e32 v130, 10, v144
	v_lshl_add_u64 v[146:147], v[130:131], 2, v[132:133]
	v_lshlrev_b32_e32 v130, 10, v145
	v_lshl_add_u64 v[148:149], v[130:131], 2, v[132:133]
	global_load_dwordx4 v[188:191], v[136:137], off
	global_load_dwordx4 v[184:187], v[146:147], off
	global_load_dwordx4 v[180:183], v[148:149], off
	v_or_b32_e32 v128, s14, v38
	v_lshlrev_b32_e32 v130, 10, v128
	v_lshl_add_u64 v[128:129], v[130:131], 2, v[132:133]
	v_add_lshl_u32 v130, s14, v39, 10
	global_load_dwordx4 v[176:179], v[128:129], off
	v_lshl_add_u64 v[136:137], v[130:131], 2, v[132:133]
	v_add_lshl_u32 v130, s14, v40, 10
	v_lshl_add_u64 v[144:145], v[130:131], 2, v[132:133]
	v_add_lshl_u32 v130, s14, v41, 10
	v_lshl_add_u64 v[132:133], v[130:131], 2, v[132:133]
	global_load_dwordx4 v[172:175], v[136:137], off
	global_load_dwordx4 v[168:171], v[144:145], off
	global_load_dwordx4 v[164:167], v[132:133], off
	s_waitcnt vmcnt(15)
	s_nop 1
	v_mov_b64_e32 v[28:29], v[250:251]
	v_mov_b64_e32 v[30:31], v[252:253]
	s_waitcnt vmcnt(14)
	s_nop 1
	v_mov_b64_e32 v[100:101], v[246:247]
	v_mov_b64_e32 v[102:103], v[248:249]
	s_waitcnt vmcnt(13)
	s_nop 1
	v_mov_b64_e32 v[104:105], v[242:243]
	v_mov_b64_e32 v[106:107], v[244:245]
	s_waitcnt vmcnt(12)
	s_nop 1
	v_mov_b64_e32 v[4:5], v[238:239]
	v_mov_b64_e32 v[6:7], v[240:241]
	ds_read2_b32 v[32:33], v43 offset1:1
	ds_read2_b32 v[108:109], v43 offset0:2 offset1:3
	ds_read2_b32 v[110:111], v44 offset1:1
	ds_read2_b32 v[112:113], v44 offset0:2 offset1:3
	ds_read2_b32 v[120:121], v45 offset1:1
	ds_read2_b32 v[122:123], v45 offset0:2 offset1:3
	ds_read2_b32 v[124:125], v46 offset1:1
	ds_read2_b32 v[126:127], v46 offset0:2 offset1:3
	s_waitcnt lgkmcnt(6)
	v_pk_fma_f32 v[30:31], v[2:3], v[108:109], v[30:31]
	v_pk_fma_f32 v[28:29], v[0:1], v[32:33], v[28:29]
	s_waitcnt lgkmcnt(4)
	v_pk_fma_f32 v[102:103], v[2:3], v[112:113], v[102:103]
	v_pk_fma_f32 v[100:101], v[0:1], v[110:111], v[100:101]
	s_waitcnt lgkmcnt(2)
	v_pk_fma_f32 v[106:107], v[2:3], v[122:123], v[106:107]
	v_pk_fma_f32 v[104:105], v[0:1], v[120:121], v[104:105]
	global_store_dwordx4 v[114:115], v[28:31], off
	global_store_dwordx4 v[116:117], v[100:103], off
	global_store_dwordx4 v[118:119], v[104:107], off
	s_waitcnt vmcnt(14)
	s_nop 1
	v_mov_b64_e32 v[28:29], v[234:235]
	v_mov_b64_e32 v[30:31], v[236:237]
	v_or_b32_e32 v100, s14, v208
	v_or_b32_e32 v101, s14, v209
	v_lshl_add_u64 v[32:33], v[16:17], 2, v[26:27]
	v_lshlrev_b32_e32 v16, 10, v100
	v_lshl_add_u64 v[108:109], v[16:17], 2, v[26:27]
	v_lshlrev_b32_e32 v16, 10, v101
	v_lshl_add_u64 v[110:111], v[16:17], 2, v[26:27]
	v_pk_fma_f32 v[6:7], v[2:3], v[14:15], v[6:7]
	v_pk_fma_f32 v[4:5], v[0:1], v[10:11], v[4:5]
	s_waitcnt lgkmcnt(0)
	v_pk_fma_f32 v[30:31], v[2:3], v[126:127], v[30:31]
	v_pk_fma_f32 v[28:29], v[0:1], v[124:125], v[28:29]
	global_store_dwordx4 v[12:13], v[28:31], off
	s_waitcnt vmcnt(14)
	s_nop 1
	v_mov_b64_e32 v[28:29], v[212:213]
	v_mov_b64_e32 v[30:31], v[214:215]
	s_nop 0
	s_waitcnt vmcnt(13)
	s_nop 1
	v_mov_b64_e32 v[100:101], v[200:201]
	v_mov_b64_e32 v[102:103], v[202:203]
	s_waitcnt vmcnt(12)
	s_nop 1
	v_mov_b64_e32 v[104:105], v[196:197]
	v_mov_b64_e32 v[106:107], v[198:199]
	ds_read2_b32 v[112:113], v47 offset1:1
	ds_read2_b32 v[114:115], v47 offset0:2 offset1:3
	ds_read2_b32 v[116:117], v48 offset1:1
	ds_read2_b32 v[118:119], v48 offset0:2 offset1:3
	ds_read2_b32 v[120:121], v49 offset1:1
	ds_read2_b32 v[122:123], v49 offset0:2 offset1:3
	ds_read2_b32 v[124:125], v50 offset1:1
	ds_read2_b32 v[126:127], v50 offset0:2 offset1:3
	v_or_b32_e32 v12, s14, v210
	v_lshlrev_b32_e32 v16, 10, v12
	v_lshl_add_u64 v[12:13], v[16:17], 2, v[26:27]
	v_or_b32_e32 v16, s14, v35
	v_lshlrev_b32_e32 v16, 10, v16
	s_waitcnt lgkmcnt(6)
	v_pk_fma_f32 v[30:31], v[2:3], v[114:115], v[30:31]
	v_pk_fma_f32 v[28:29], v[0:1], v[112:113], v[28:29]
	s_waitcnt lgkmcnt(4)
	v_pk_fma_f32 v[102:103], v[2:3], v[118:119], v[102:103]
	v_pk_fma_f32 v[100:101], v[0:1], v[116:117], v[100:101]
	s_waitcnt lgkmcnt(2)
	v_pk_fma_f32 v[106:107], v[2:3], v[122:123], v[106:107]
	v_pk_fma_f32 v[104:105], v[0:1], v[120:121], v[104:105]
	global_store_dwordx4 v[32:33], v[28:31], off
	global_store_dwordx4 v[108:109], v[100:103], off
	global_store_dwordx4 v[110:111], v[104:107], off
	s_waitcnt vmcnt(14)
	s_nop 1
	v_mov_b64_e32 v[28:29], v[192:193]
	v_mov_b64_e32 v[30:31], v[194:195]
	v_or_b32_e32 v100, s14, v36
	v_or_b32_e32 v101, s14, v37
	v_lshl_add_u64 v[32:33], v[16:17], 2, v[26:27]
	v_lshlrev_b32_e32 v16, 10, v100
	v_lshl_add_u64 v[108:109], v[16:17], 2, v[26:27]
	v_lshlrev_b32_e32 v16, 10, v101
	v_lshl_add_u64 v[110:111], v[16:17], 2, v[26:27]
	s_waitcnt lgkmcnt(0)
	v_pk_fma_f32 v[30:31], v[2:3], v[126:127], v[30:31]
	v_pk_fma_f32 v[28:29], v[0:1], v[124:125], v[28:29]
	global_store_dwordx4 v[12:13], v[28:31], off
	s_waitcnt vmcnt(14)
	s_nop 1
	v_mov_b64_e32 v[28:29], v[188:189]
	v_mov_b64_e32 v[30:31], v[190:191]
	s_nop 0
	s_waitcnt vmcnt(13)
	s_nop 1
	v_mov_b64_e32 v[100:101], v[184:185]
	v_mov_b64_e32 v[102:103], v[186:187]
	s_waitcnt vmcnt(12)
	s_nop 1
	v_mov_b64_e32 v[104:105], v[180:181]
	v_mov_b64_e32 v[106:107], v[182:183]
	ds_read2_b32 v[112:113], v51 offset1:1
	ds_read2_b32 v[114:115], v51 offset0:2 offset1:3
	ds_read2_b32 v[116:117], v52 offset1:1
	ds_read2_b32 v[118:119], v52 offset0:2 offset1:3
	ds_read2_b32 v[120:121], v53 offset1:1
	ds_read2_b32 v[122:123], v53 offset0:2 offset1:3
	ds_read2_b32 v[124:125], v54 offset1:1
	ds_read2_b32 v[126:127], v54 offset0:2 offset1:3
	v_or_b32_e32 v12, s14, v38
	v_lshlrev_b32_e32 v16, 10, v12
	v_lshl_add_u64 v[12:13], v[16:17], 2, v[26:27]
	v_add_lshl_u32 v16, s14, v39, 10
	s_waitcnt lgkmcnt(6)
	v_pk_fma_f32 v[30:31], v[2:3], v[114:115], v[30:31]
	v_pk_fma_f32 v[28:29], v[0:1], v[112:113], v[28:29]
	s_waitcnt lgkmcnt(4)
	v_pk_fma_f32 v[102:103], v[2:3], v[118:119], v[102:103]
	v_pk_fma_f32 v[100:101], v[0:1], v[116:117], v[100:101]
	s_waitcnt lgkmcnt(2)
	v_pk_fma_f32 v[106:107], v[2:3], v[122:123], v[106:107]
	v_pk_fma_f32 v[104:105], v[0:1], v[120:121], v[104:105]
	global_store_dwordx4 v[32:33], v[28:31], off
	global_store_dwordx4 v[108:109], v[100:103], off
	global_store_dwordx4 v[110:111], v[104:107], off
	s_waitcnt vmcnt(14)
	s_nop 1
	v_mov_b64_e32 v[28:29], v[176:177]
	v_mov_b64_e32 v[30:31], v[178:179]
	v_lshl_add_u64 v[32:33], v[16:17], 2, v[26:27]
	v_add_lshl_u32 v16, s14, v40, 10
	global_store_dwordx4 v[8:9], v[4:7], off
	v_lshl_add_u64 v[100:101], v[16:17], 2, v[26:27]
	v_add_lshl_u32 v16, s14, v41, 10
	v_lshl_add_u64 v[26:27], v[16:17], 2, v[26:27]
	s_waitcnt lgkmcnt(0)
	v_pk_fma_f32 v[6:7], v[2:3], v[126:127], v[30:31]
	v_pk_fma_f32 v[4:5], v[0:1], v[124:125], v[28:29]
	global_store_dwordx4 v[12:13], v[4:7], off
	s_waitcnt vmcnt(15)
	s_nop 1
	v_mov_b64_e32 v[4:5], v[172:173]
	v_mov_b64_e32 v[6:7], v[174:175]
	s_nop 0
	s_waitcnt vmcnt(14)
	s_nop 1
	v_mov_b64_e32 v[8:9], v[168:169]
	v_mov_b64_e32 v[10:11], v[170:171]
	s_waitcnt vmcnt(13)
	s_nop 1
	v_mov_b64_e32 v[12:13], v[164:165]
	v_mov_b64_e32 v[14:15], v[166:167]
	ds_read2_b32 v[28:29], v55 offset1:1
	ds_read2_b32 v[30:31], v55 offset0:2 offset1:3
	ds_read2_b32 v[102:103], v56 offset1:1
	ds_read2_b32 v[104:105], v56 offset0:2 offset1:3
	ds_read2_b32 v[106:107], v57 offset1:1
	ds_read2_b32 v[108:109], v57 offset0:2 offset1:3
	s_waitcnt lgkmcnt(4)
	v_pk_fma_f32 v[6:7], v[2:3], v[30:31], v[6:7]
	v_pk_fma_f32 v[4:5], v[0:1], v[28:29], v[4:5]
	s_waitcnt lgkmcnt(2)
	v_pk_fma_f32 v[10:11], v[2:3], v[104:105], v[10:11]
	v_pk_fma_f32 v[8:9], v[0:1], v[102:103], v[8:9]
	s_waitcnt lgkmcnt(0)
	v_pk_fma_f32 v[2:3], v[2:3], v[108:109], v[14:15]
	v_pk_fma_f32 v[0:1], v[0:1], v[106:107], v[12:13]
	global_store_dwordx4 v[32:33], v[4:7], off
	global_store_dwordx4 v[100:101], v[8:11], off
	global_store_dwordx4 v[26:27], v[0:3], off
	s_barrier
	s_cbranch_scc1 .LBB0_1844
	s_load_dwordx2 s[2:3], s[0:1], 0x130
	v_accvgpr_read_b32 v110, a206

.LBB0_2329:
	s_lshr_b32 s13, s6, 3
	s_add_i32 s13, s13, s7
	s_lshl_b32 s4, s13, 19
	v_lshl_add_u64 v[0:1], v[18:19], 0, s[4:5]
	v_add_co_u32_e32 v4, vcc, 0x10000, v0
	s_and_b32 s12, s6, 7
	s_nop 0
	v_addc_co_u32_e32 v5, vcc, 0, v1, vcc
	v_add_co_u32_e32 v6, vcc, 0x20000, v0
	s_lshl_b32 s4, s12, 18
	s_nop 0
	v_addc_co_u32_e32 v7, vcc, 0, v1, vcc
	v_add_co_u32_e32 v8, vcc, 0x30000, v0
	v_lshl_add_u64 v[2:3], v[20:21], 0, s[4:5]
	s_nop 0
	v_addc_co_u32_e32 v9, vcc, 0, v1, vcc
	v_add_co_u32_e32 v10, vcc, 0x40000, v0
	global_load_dwordx4 v[100:103], v[0:1], off
	global_load_dwordx4 v[104:107], v[0:1], off offset:128
	v_addc_co_u32_e32 v11, vcc, 0, v1, vcc
	v_add_co_u32_e32 v12, vcc, 0x50000, v0
	global_load_dwordx4 v[108:111], v[2:3], off
	global_load_dwordx4 v[112:115], v[2:3], off offset:128
	v_addc_co_u32_e32 v13, vcc, 0, v1, vcc
	v_add_co_u32_e32 v14, vcc, 0x60000, v0
	global_load_dwordx4 v[116:119], v[4:5], off
	global_load_dwordx4 v[120:123], v[4:5], off offset:128
	v_addc_co_u32_e32 v15, vcc, 0, v1, vcc
	v_add_co_u32_e32 v26, vcc, 0x70000, v0
	global_load_dwordx4 v[124:127], v[6:7], off
	global_load_dwordx4 v[128:131], v[6:7], off offset:128
	v_addc_co_u32_e32 v27, vcc, 0, v1, vcc
	v_add_co_u32_e32 v28, vcc, s8, v2
	global_load_dwordx4 v[140:143], v[8:9], off
	global_load_dwordx4 v[144:147], v[8:9], off offset:128
	v_addc_co_u32_e32 v29, vcc, 0, v3, vcc
	v_add_co_u32_e32 v30, vcc, s9, v2
	global_load_dwordx4 v[148:151], v[10:11], off
	global_load_dwordx4 v[152:155], v[10:11], off offset:128
	v_addc_co_u32_e32 v31, vcc, 0, v3, vcc
	v_add_co_u32_e32 v32, vcc, s10, v2
	global_load_dwordx4 v[156:159], v[12:13], off
	global_load_dwordx4 v[160:163], v[12:13], off offset:128
	global_load_dwordx4 v[164:167], v[14:15], off
	global_load_dwordx4 v[168:171], v[14:15], off offset:128
	global_load_dwordx4 v[172:175], v[26:27], off
	global_load_dwordx4 v[176:179], v[26:27], off offset:128
	global_load_dwordx4 v[180:183], v[28:29], off
	global_load_dwordx4 v[184:187], v[28:29], off offset:128
	v_addc_co_u32_e32 v33, vcc, 0, v3, vcc
	global_load_dwordx4 v[188:191], v[30:31], off
	global_load_dwordx4 v[192:195], v[30:31], off offset:128
	global_load_dwordx4 v[196:199], v[32:33], off
	global_load_dwordx4 v[200:203], v[32:33], off offset:128
	s_lshl_b32 s14, s13, 8
	s_add_i32 s4, s14, 0xffffe000
	s_add_i32 s15, s14, 0xffffe080
	s_lshr_b32 s4, s4, 12
	s_lshr_b32 s15, s15, 12
	s_add_i32 s4, s4, 16
	s_add_i32 s15, s15, 16
	s_cmp_lt_u32 s13, 32
	s_cselect_b32 s4, 15, s4
	s_cselect_b32 s13, 15, s15
	s_mul_hi_u32 s15, s4, 0x6000
	s_mulk_i32 s4, 0x6000
	s_add_u32 s16, s2, s4
	s_addc_u32 s15, s3, s15
	s_lshl_b32 s4, s12, 9
	v_or_b32_e32 v16, s14, v135
	s_add_u32 s16, s16, s4
	v_lshlrev_b32_e32 v16, 10, v16
	s_addc_u32 s17, s15, 0
	s_mul_hi_u32 s12, s13, 0x6000
	s_mulk_i32 s13, 0x6000
	s_waitcnt vmcnt(23)
	ds_write_b128 v60, v[100:103]
	s_waitcnt vmcnt(21)
	ds_write_b128 v60, v[108:111] offset:36864
	s_waitcnt vmcnt(19)
	ds_write_b128 v60, v[116:119] offset:4608
	s_waitcnt vmcnt(17)
	ds_write_b128 v60, v[124:127] offset:9216
	s_waitcnt vmcnt(15)
	ds_write_b128 v60, v[140:143] offset:13824
	s_waitcnt vmcnt(13)
	ds_write_b128 v60, v[148:151] offset:18432
	s_waitcnt vmcnt(11)
	ds_write_b128 v60, v[156:159] offset:23040
	s_waitcnt vmcnt(9)
	ds_write_b128 v60, v[164:167] offset:27648
	s_waitcnt vmcnt(7)
	ds_write_b128 v60, v[172:175] offset:32256
	s_waitcnt vmcnt(5)
	ds_write_b128 v60, v[180:183] offset:41472
	s_waitcnt vmcnt(3)
	ds_write_b128 v60, v[188:191] offset:46080
	s_waitcnt vmcnt(1)
	ds_write_b128 v60, v[196:199] offset:50688
	s_waitcnt lgkmcnt(0)
	s_barrier
	ds_read_b128 v[100:103], v59
	ds_read_b128 v[108:111], v62 offset:36864
	ds_read_b128 v[116:119], v59 offset:4608
	ds_read_b128 v[124:127], v62 offset:41472
	s_waitcnt lgkmcnt(2)
	v_mfma_f32_32x32x16_bf16 a[112:127], v[100:103], v[108:111], 0
	s_waitcnt lgkmcnt(0)
	v_mfma_f32_32x32x16_bf16 a[96:111], v[100:103], v[124:127], 0
	ds_read_b128 v[100:103], v59 offset:9216
	s_waitcnt lgkmcnt(0)
	v_mfma_f32_32x32x16_bf16 a[48:63], v[100:103], v[108:111], 0
	v_mfma_f32_32x32x16_bf16 a[32:47], v[100:103], v[124:127], 0
	ds_read_b128 v[100:103], v61
	ds_write_b128 v60, v[104:107] offset:55296
	ds_write_b128 v60, v[120:123] offset:59904
	ds_write_b128 v60, v[128:131] offset:64512
	ds_write_b128 v63, v[144:147] offset:55296
	ds_write_b128 v64, v[152:155] offset:55296
	ds_write_b128 v65, v[160:163] offset:55296
	ds_write_b128 v66, v[168:171] offset:55296
	ds_write_b128 v67, v[176:179] offset:55296
	ds_write_b128 v68, v[112:115]
	ds_write_b128 v68, v[184:187] offset:4608
	ds_write_b128 v68, v[192:195] offset:9216
	s_waitcnt vmcnt(0)
	ds_write_b128 v68, v[200:203] offset:13824
	v_mfma_f32_32x32x16_bf16 a[80:95], v[116:119], v[108:111], 0
	v_mfma_f32_32x32x16_bf16 a[64:79], v[116:119], v[124:127], 0
	s_waitcnt lgkmcnt(12)
	v_mfma_f32_32x32x16_bf16 a[16:31], v[100:103], v[108:111], 0
	v_mfma_f32_32x32x16_bf16 a[0:15], v[100:103], v[124:127], 0
	ds_read_b128 v[100:103], v59 offset:32
	ds_read_b128 v[104:107], v62 offset:36896
	ds_read_b128 v[108:111], v62 offset:36928
	ds_read_b128 v[112:115], v59 offset:64
	ds_read_b128 v[116:119], v62 offset:41504
	ds_read_b128 v[120:123], v62 offset:36960
	s_waitcnt lgkmcnt(4)
	v_mfma_f32_32x32x16_bf16 a[112:127], v[100:103], v[104:107], a[112:127]
	s_waitcnt lgkmcnt(1)
	v_mfma_f32_32x32x16_bf16 a[96:111], v[100:103], v[116:119], a[96:111]
	ds_read_b128 v[100:103], v59 offset:4640
	ds_read_b128 v[124:127], v59 offset:96
	s_waitcnt lgkmcnt(1)
	v_mfma_f32_32x32x16_bf16 a[80:95], v[100:103], v[104:107], a[80:95]
	v_mfma_f32_32x32x16_bf16 a[64:79], v[100:103], v[116:119], a[64:79]
	ds_read_b128 v[100:103], v59 offset:9248
	ds_read_b128 v[128:131], v59 offset:9280
	s_waitcnt lgkmcnt(1)
	v_mfma_f32_32x32x16_bf16 a[48:63], v[100:103], v[104:107], a[48:63]
	v_mfma_f32_32x32x16_bf16 a[32:47], v[100:103], v[116:119], a[32:47]
	ds_read_b128 v[100:103], v61 offset:32
	ds_read_b128 v[140:143], v59 offset:9312
	s_waitcnt lgkmcnt(1)
	v_mfma_f32_32x32x16_bf16 a[16:31], v[100:103], v[104:107], a[16:31]
	v_mfma_f32_32x32x16_bf16 a[0:15], v[100:103], v[116:119], a[0:15]
	ds_read_b128 v[100:103], v62 offset:41536
	ds_read_b128 v[104:107], v62 offset:41568
	v_mfma_f32_32x32x16_bf16 a[112:127], v[112:115], v[108:111], a[112:127]
	s_waitcnt lgkmcnt(1)
	v_mfma_f32_32x32x16_bf16 a[96:111], v[112:115], v[100:103], a[96:111]
	ds_read_b128 v[112:115], v59 offset:4672
	ds_read_b128 v[116:119], v59 offset:4704
	s_waitcnt lgkmcnt(1)
	v_mfma_f32_32x32x16_bf16 a[80:95], v[112:115], v[108:111], a[80:95]
	v_mfma_f32_32x32x16_bf16 a[64:79], v[112:115], v[100:103], a[64:79]
	v_mfma_f32_32x32x16_bf16 a[48:63], v[128:131], v[108:111], a[48:63]
	v_mfma_f32_32x32x16_bf16 a[32:47], v[128:131], v[100:103], a[32:47]
	ds_read_b128 v[112:115], v61 offset:64
	ds_read_b128 v[128:131], v61 offset:96
	s_waitcnt lgkmcnt(1)
	v_mfma_f32_32x32x16_bf16 a[16:31], v[112:115], v[108:111], a[16:31]
	v_mfma_f32_32x32x16_bf16 a[0:15], v[112:115], v[100:103], a[0:15]
	global_load_dwordx4 v[100:103], v[32:33], off offset:256
	v_mfma_f32_32x32x16_bf16 a[112:127], v[124:127], v[120:123], a[112:127]
	v_mfma_f32_32x32x16_bf16 a[96:111], v[124:127], v[104:107], a[96:111]
	v_mfma_f32_32x32x16_bf16 a[80:95], v[116:119], v[120:123], a[80:95]
	v_mfma_f32_32x32x16_bf16 a[64:79], v[116:119], v[104:107], a[64:79]
	v_mfma_f32_32x32x16_bf16 a[48:63], v[140:143], v[120:123], a[48:63]
	v_mfma_f32_32x32x16_bf16 a[32:47], v[140:143], v[104:107], a[32:47]
	global_load_dwordx4 v[108:111], v[30:31], off offset:256
	global_load_dwordx4 v[112:115], v[28:29], off offset:256
	global_load_dwordx4 v[116:119], v[2:3], off offset:256
	global_load_dwordx4 v[124:127], v[8:9], off offset:256
	global_load_dwordx4 v[140:143], v[6:7], off offset:256
	global_load_dwordx4 v[144:147], v[4:5], off offset:256
	global_load_dwordx4 v[148:151], v[0:1], off offset:256
	s_waitcnt lgkmcnt(0)
	v_mfma_f32_32x32x16_bf16 a[16:31], v[128:131], v[120:123], a[16:31]
	global_load_dwordx4 v[120:123], v[12:13], off offset:256
	global_load_dwordx4 v[152:155], v[10:11], off offset:256
	global_load_dwordx4 v[156:159], v[26:27], off offset:256
	global_load_dwordx4 v[160:163], v[14:15], off offset:256
	s_barrier
	v_mfma_f32_32x32x16_bf16 a[0:15], v[128:131], v[104:107], a[0:15]
	ds_read_b128 v[104:107], v59 offset:55296
	ds_read_b128 v[128:131], v69
	ds_read_b128 v[164:167], v59 offset:59904
	ds_read_b128 v[168:171], v69 offset:4608
	s_waitcnt lgkmcnt(2)
	v_mfma_f32_32x32x16_bf16 a[112:127], v[104:107], v[128:131], a[112:127]
	s_waitcnt lgkmcnt(0)
	v_mfma_f32_32x32x16_bf16 a[96:111], v[104:107], v[168:171], a[96:111]
	ds_read_b128 v[104:107], v59 offset:64512
	s_waitcnt lgkmcnt(0)
	v_mfma_f32_32x32x16_bf16 a[48:63], v[104:107], v[128:131], a[48:63]
	v_mfma_f32_32x32x16_bf16 a[32:47], v[104:107], v[168:171], a[32:47]
	ds_read_b128 v[104:107], v61 offset:55296
	s_waitcnt vmcnt(4)
	ds_write_b128 v60, v[148:151]
	ds_write_b128 v60, v[144:147] offset:4608
	ds_write_b128 v60, v[140:143] offset:9216
	ds_write_b128 v60, v[124:127] offset:13824
	s_waitcnt vmcnt(2)
	ds_write_b128 v60, v[152:155] offset:18432
	ds_write_b128 v60, v[120:123] offset:23040
	s_waitcnt vmcnt(0)
	ds_write_b128 v60, v[160:163] offset:27648
	ds_write_b128 v60, v[156:159] offset:32256
	ds_write_b128 v60, v[116:119] offset:36864
	ds_write_b128 v60, v[112:115] offset:41472
	ds_write_b128 v60, v[108:111] offset:46080
	ds_write_b128 v60, v[100:103] offset:50688
	v_mfma_f32_32x32x16_bf16 a[80:95], v[164:167], v[128:131], a[80:95]
	v_mfma_f32_32x32x16_bf16 a[64:79], v[164:167], v[168:171], a[64:79]
	s_waitcnt lgkmcnt(12)
	v_mfma_f32_32x32x16_bf16 a[16:31], v[104:107], v[128:131], a[16:31]
	v_mfma_f32_32x32x16_bf16 a[0:15], v[104:107], v[168:171], a[0:15]
	ds_read_b128 v[100:103], v59 offset:55328
	ds_read_b128 v[104:107], v69 offset:32
	ds_read_b128 v[108:111], v69 offset:64
	ds_read_b128 v[112:115], v59 offset:55360
	ds_read_b128 v[116:119], v69 offset:4640
	ds_read_b128 v[120:123], v69 offset:96
	s_waitcnt lgkmcnt(4)
	v_mfma_f32_32x32x16_bf16 a[112:127], v[100:103], v[104:107], a[112:127]
	s_waitcnt lgkmcnt(1)
	v_mfma_f32_32x32x16_bf16 a[96:111], v[100:103], v[116:119], a[96:111]
	ds_read_b128 v[100:103], v59 offset:59936
	ds_read_b128 v[124:127], v59 offset:55392
	s_waitcnt lgkmcnt(1)
	v_mfma_f32_32x32x16_bf16 a[80:95], v[100:103], v[104:107], a[80:95]
	v_mfma_f32_32x32x16_bf16 a[64:79], v[100:103], v[116:119], a[64:79]
	ds_read_b128 v[100:103], v59 offset:64544
	ds_read_b128 v[128:131], v59 offset:64576
	s_waitcnt lgkmcnt(1)
	v_mfma_f32_32x32x16_bf16 a[48:63], v[100:103], v[104:107], a[48:63]
	v_mfma_f32_32x32x16_bf16 a[32:47], v[100:103], v[116:119], a[32:47]
	ds_read_b128 v[100:103], v61 offset:55328
	ds_read_b128 v[140:143], v59 offset:64608
	s_waitcnt lgkmcnt(1)
	v_mfma_f32_32x32x16_bf16 a[16:31], v[100:103], v[104:107], a[16:31]
	v_mfma_f32_32x32x16_bf16 a[0:15], v[100:103], v[116:119], a[0:15]
	ds_read_b128 v[100:103], v69 offset:4672
	ds_read_b128 v[104:107], v69 offset:4704
	v_mfma_f32_32x32x16_bf16 a[112:127], v[112:115], v[108:111], a[112:127]
	s_waitcnt lgkmcnt(1)
	v_mfma_f32_32x32x16_bf16 a[96:111], v[112:115], v[100:103], a[96:111]
	ds_read_b128 v[112:115], v59 offset:59968
	ds_read_b128 v[116:119], v59 offset:60000
	s_waitcnt lgkmcnt(1)
	v_mfma_f32_32x32x16_bf16 a[80:95], v[112:115], v[108:111], a[80:95]
	v_mfma_f32_32x32x16_bf16 a[64:79], v[112:115], v[100:103], a[64:79]
	v_mfma_f32_32x32x16_bf16 a[48:63], v[128:131], v[108:111], a[48:63]
	v_mfma_f32_32x32x16_bf16 a[32:47], v[128:131], v[100:103], a[32:47]
	ds_read_b128 v[112:115], v61 offset:55360
	ds_read_b128 v[128:131], v61 offset:55392
	s_waitcnt lgkmcnt(1)
	v_mfma_f32_32x32x16_bf16 a[16:31], v[112:115], v[108:111], a[16:31]
	v_mfma_f32_32x32x16_bf16 a[0:15], v[112:115], v[100:103], a[0:15]
	v_mfma_f32_32x32x16_bf16 a[112:127], v[124:127], v[120:123], a[112:127]
	v_mfma_f32_32x32x16_bf16 a[96:111], v[124:127], v[104:107], a[96:111]
	v_mfma_f32_32x32x16_bf16 a[80:95], v[116:119], v[120:123], a[80:95]
	v_mfma_f32_32x32x16_bf16 a[64:79], v[116:119], v[104:107], a[64:79]
	global_load_dwordx4 v[100:103], v[4:5], off offset:384
	global_load_dwordx4 v[108:111], v[0:1], off offset:384
	global_load_dwordx4 v[112:115], v[8:9], off offset:384
	global_load_dwordx4 v[116:119], v[6:7], off offset:384
	v_mfma_f32_32x32x16_bf16 a[48:63], v[140:143], v[120:123], a[48:63]
	v_mfma_f32_32x32x16_bf16 a[32:47], v[140:143], v[104:107], a[32:47]
	global_load_dwordx4 v[124:127], v[10:11], off offset:384
	global_load_dwordx4 v[140:143], v[12:13], off offset:384
	global_load_dwordx4 v[144:147], v[26:27], off offset:384
	global_load_dwordx4 v[148:151], v[14:15], off offset:384
	global_load_dwordx4 v[152:155], v[28:29], off offset:384
	global_load_dwordx4 v[156:159], v[2:3], off offset:384
	global_load_dwordx4 v[160:163], v[30:31], off offset:384
	s_waitcnt lgkmcnt(0)
	v_mfma_f32_32x32x16_bf16 a[16:31], v[128:131], v[120:123], a[16:31]
	global_load_dwordx4 v[120:123], v[32:33], off offset:384
	s_barrier
	v_mfma_f32_32x32x16_bf16 a[0:15], v[128:131], v[104:107], a[0:15]
	ds_read_b128 v[104:107], v59
	ds_read_b128 v[128:131], v62 offset:36864
	ds_read_b128 v[164:167], v59 offset:4608
	ds_read_b128 v[168:171], v62 offset:41472
	s_waitcnt lgkmcnt(2)
	v_mfma_f32_32x32x16_bf16 a[112:127], v[104:107], v[128:131], a[112:127]
	s_waitcnt lgkmcnt(0)
	v_mfma_f32_32x32x16_bf16 a[96:111], v[104:107], v[168:171], a[96:111]
	ds_read_b128 v[104:107], v59 offset:9216
	s_waitcnt lgkmcnt(0)
	v_mfma_f32_32x32x16_bf16 a[48:63], v[104:107], v[128:131], a[48:63]
	v_mfma_f32_32x32x16_bf16 a[32:47], v[104:107], v[168:171], a[32:47]
	ds_read_b128 v[104:107], v61
	s_waitcnt vmcnt(10)
	ds_write_b128 v60, v[108:111] offset:55296
	ds_write_b128 v60, v[100:103] offset:59904
	s_waitcnt vmcnt(8)
	ds_write_b128 v60, v[116:119] offset:64512
	ds_write_b128 v63, v[112:115] offset:55296
	s_waitcnt vmcnt(7)
	ds_write_b128 v64, v[124:127] offset:55296
	s_waitcnt vmcnt(6)
	ds_write_b128 v65, v[140:143] offset:55296
	s_waitcnt vmcnt(4)
	ds_write_b128 v66, v[148:151] offset:55296
	ds_write_b128 v67, v[144:147] offset:55296
	s_waitcnt vmcnt(2)
	ds_write_b128 v68, v[156:159]
	ds_write_b128 v68, v[152:155] offset:4608
	s_waitcnt vmcnt(1)
	ds_write_b128 v68, v[160:163] offset:9216
	s_waitcnt vmcnt(0)
	ds_write_b128 v68, v[120:123] offset:13824
	v_mfma_f32_32x32x16_bf16 a[80:95], v[164:167], v[128:131], a[80:95]
	v_mfma_f32_32x32x16_bf16 a[64:79], v[164:167], v[168:171], a[64:79]
	s_waitcnt lgkmcnt(12)
	v_mfma_f32_32x32x16_bf16 a[16:31], v[104:107], v[128:131], a[16:31]
	v_mfma_f32_32x32x16_bf16 a[0:15], v[104:107], v[168:171], a[0:15]
	ds_read_b128 v[100:103], v59 offset:32
	ds_read_b128 v[104:107], v62 offset:36896
	ds_read_b128 v[108:111], v62 offset:36928
	ds_read_b128 v[112:115], v59 offset:64
	ds_read_b128 v[116:119], v62 offset:41504
	ds_read_b128 v[120:123], v62 offset:36960
	s_waitcnt lgkmcnt(4)
	v_mfma_f32_32x32x16_bf16 a[112:127], v[100:103], v[104:107], a[112:127]
	s_waitcnt lgkmcnt(1)
	v_mfma_f32_32x32x16_bf16 a[96:111], v[100:103], v[116:119], a[96:111]
	ds_read_b128 v[100:103], v59 offset:4640
	ds_read_b128 v[124:127], v59 offset:96
	s_waitcnt lgkmcnt(1)
	v_mfma_f32_32x32x16_bf16 a[80:95], v[100:103], v[104:107], a[80:95]
	v_mfma_f32_32x32x16_bf16 a[64:79], v[100:103], v[116:119], a[64:79]
	ds_read_b128 v[100:103], v59 offset:9248
	ds_read_b128 v[128:131], v59 offset:9280
	s_waitcnt lgkmcnt(1)
	v_mfma_f32_32x32x16_bf16 a[48:63], v[100:103], v[104:107], a[48:63]
	v_mfma_f32_32x32x16_bf16 a[32:47], v[100:103], v[116:119], a[32:47]
	ds_read_b128 v[100:103], v61 offset:32
	ds_read_b128 v[140:143], v59 offset:9312
	s_waitcnt lgkmcnt(1)
	v_mfma_f32_32x32x16_bf16 a[16:31], v[100:103], v[104:107], a[16:31]
	v_mfma_f32_32x32x16_bf16 a[0:15], v[100:103], v[116:119], a[0:15]
	ds_read_b128 v[100:103], v62 offset:41536
	ds_read_b128 v[104:107], v62 offset:41568
	v_mfma_f32_32x32x16_bf16 a[112:127], v[112:115], v[108:111], a[112:127]
	s_waitcnt lgkmcnt(1)
	v_mfma_f32_32x32x16_bf16 a[96:111], v[112:115], v[100:103], a[96:111]
	ds_read_b128 v[112:115], v59 offset:4672
	ds_read_b128 v[116:119], v59 offset:4704
	s_waitcnt lgkmcnt(1)
	v_mfma_f32_32x32x16_bf16 a[80:95], v[112:115], v[108:111], a[80:95]
	v_mfma_f32_32x32x16_bf16 a[64:79], v[112:115], v[100:103], a[64:79]
	v_mfma_f32_32x32x16_bf16 a[48:63], v[128:131], v[108:111], a[48:63]
	v_mfma_f32_32x32x16_bf16 a[32:47], v[128:131], v[100:103], a[32:47]
	ds_read_b128 v[112:115], v61 offset:64
	ds_read_b128 v[128:131], v61 offset:96
	s_waitcnt lgkmcnt(1)
	v_mfma_f32_32x32x16_bf16 a[16:31], v[112:115], v[108:111], a[16:31]
	v_mfma_f32_32x32x16_bf16 a[0:15], v[112:115], v[100:103], a[0:15]
	global_load_dwordx4 v[100:103], v[32:33], off offset:512
	v_mfma_f32_32x32x16_bf16 a[112:127], v[124:127], v[120:123], a[112:127]
	v_mfma_f32_32x32x16_bf16 a[96:111], v[124:127], v[104:107], a[96:111]
	v_mfma_f32_32x32x16_bf16 a[80:95], v[116:119], v[120:123], a[80:95]
	v_mfma_f32_32x32x16_bf16 a[64:79], v[116:119], v[104:107], a[64:79]
	v_mfma_f32_32x32x16_bf16 a[48:63], v[140:143], v[120:123], a[48:63]
	v_mfma_f32_32x32x16_bf16 a[32:47], v[140:143], v[104:107], a[32:47]
	global_load_dwordx4 v[108:111], v[30:31], off offset:512
	global_load_dwordx4 v[112:115], v[28:29], off offset:512
	global_load_dwordx4 v[116:119], v[2:3], off offset:512
	global_load_dwordx4 v[124:127], v[8:9], off offset:512
	global_load_dwordx4 v[140:143], v[6:7], off offset:512
	global_load_dwordx4 v[144:147], v[4:5], off offset:512
	global_load_dwordx4 v[148:151], v[0:1], off offset:512
	s_waitcnt lgkmcnt(0)
	v_mfma_f32_32x32x16_bf16 a[16:31], v[128:131], v[120:123], a[16:31]
	global_load_dwordx4 v[120:123], v[12:13], off offset:512
	global_load_dwordx4 v[152:155], v[10:11], off offset:512
	global_load_dwordx4 v[156:159], v[26:27], off offset:512
	global_load_dwordx4 v[160:163], v[14:15], off offset:512
	s_barrier
	v_mfma_f32_32x32x16_bf16 a[0:15], v[128:131], v[104:107], a[0:15]
	ds_read_b128 v[104:107], v59 offset:55296
	ds_read_b128 v[128:131], v69
	ds_read_b128 v[164:167], v59 offset:59904
	ds_read_b128 v[168:171], v69 offset:4608
	s_waitcnt lgkmcnt(2)
	v_mfma_f32_32x32x16_bf16 a[112:127], v[104:107], v[128:131], a[112:127]
	s_waitcnt lgkmcnt(0)
	v_mfma_f32_32x32x16_bf16 a[96:111], v[104:107], v[168:171], a[96:111]
	ds_read_b128 v[104:107], v59 offset:64512
	s_waitcnt lgkmcnt(0)
	v_mfma_f32_32x32x16_bf16 a[48:63], v[104:107], v[128:131], a[48:63]
	v_mfma_f32_32x32x16_bf16 a[32:47], v[104:107], v[168:171], a[32:47]
	ds_read_b128 v[104:107], v61 offset:55296
	s_waitcnt vmcnt(4)
	ds_write_b128 v60, v[148:151]
	ds_write_b128 v60, v[144:147] offset:4608
	ds_write_b128 v60, v[140:143] offset:9216
	ds_write_b128 v60, v[124:127] offset:13824
	s_waitcnt vmcnt(2)
	ds_write_b128 v60, v[152:155] offset:18432
	ds_write_b128 v60, v[120:123] offset:23040
	s_waitcnt vmcnt(0)
	ds_write_b128 v60, v[160:163] offset:27648
	ds_write_b128 v60, v[156:159] offset:32256
	ds_write_b128 v60, v[116:119] offset:36864
	ds_write_b128 v60, v[112:115] offset:41472
	ds_write_b128 v60, v[108:111] offset:46080
	ds_write_b128 v60, v[100:103] offset:50688
	v_mfma_f32_32x32x16_bf16 a[80:95], v[164:167], v[128:131], a[80:95]
	v_mfma_f32_32x32x16_bf16 a[64:79], v[164:167], v[168:171], a[64:79]
	s_waitcnt lgkmcnt(12)
	v_mfma_f32_32x32x16_bf16 a[16:31], v[104:107], v[128:131], a[16:31]
	v_mfma_f32_32x32x16_bf16 a[0:15], v[104:107], v[168:171], a[0:15]
	ds_read_b128 v[100:103], v59 offset:55328
	ds_read_b128 v[104:107], v69 offset:32
	ds_read_b128 v[108:111], v69 offset:64
	ds_read_b128 v[112:115], v59 offset:55360
	ds_read_b128 v[116:119], v69 offset:4640
	ds_read_b128 v[120:123], v69 offset:96
	s_waitcnt lgkmcnt(4)
	v_mfma_f32_32x32x16_bf16 a[112:127], v[100:103], v[104:107], a[112:127]
	s_waitcnt lgkmcnt(1)
	v_mfma_f32_32x32x16_bf16 a[96:111], v[100:103], v[116:119], a[96:111]
	ds_read_b128 v[100:103], v59 offset:59936
	ds_read_b128 v[124:127], v59 offset:55392
	s_waitcnt lgkmcnt(1)
	v_mfma_f32_32x32x16_bf16 a[80:95], v[100:103], v[104:107], a[80:95]
	v_mfma_f32_32x32x16_bf16 a[64:79], v[100:103], v[116:119], a[64:79]
	ds_read_b128 v[100:103], v59 offset:64544
	ds_read_b128 v[128:131], v59 offset:64576
	s_waitcnt lgkmcnt(1)
	v_mfma_f32_32x32x16_bf16 a[48:63], v[100:103], v[104:107], a[48:63]
	v_mfma_f32_32x32x16_bf16 a[32:47], v[100:103], v[116:119], a[32:47]
	ds_read_b128 v[100:103], v61 offset:55328
	ds_read_b128 v[140:143], v59 offset:64608
	s_waitcnt lgkmcnt(1)
	v_mfma_f32_32x32x16_bf16 a[16:31], v[100:103], v[104:107], a[16:31]
	v_mfma_f32_32x32x16_bf16 a[0:15], v[100:103], v[116:119], a[0:15]
	ds_read_b128 v[100:103], v69 offset:4672
	ds_read_b128 v[104:107], v69 offset:4704
	v_mfma_f32_32x32x16_bf16 a[112:127], v[112:115], v[108:111], a[112:127]
	s_waitcnt lgkmcnt(1)
	v_mfma_f32_32x32x16_bf16 a[96:111], v[112:115], v[100:103], a[96:111]
	ds_read_b128 v[112:115], v59 offset:59968
	ds_read_b128 v[116:119], v59 offset:60000
	s_waitcnt lgkmcnt(1)
	v_mfma_f32_32x32x16_bf16 a[80:95], v[112:115], v[108:111], a[80:95]
	v_mfma_f32_32x32x16_bf16 a[64:79], v[112:115], v[100:103], a[64:79]
	v_mfma_f32_32x32x16_bf16 a[48:63], v[128:131], v[108:111], a[48:63]
	v_mfma_f32_32x32x16_bf16 a[32:47], v[128:131], v[100:103], a[32:47]
	ds_read_b128 v[112:115], v61 offset:55360
	ds_read_b128 v[128:131], v61 offset:55392
	s_waitcnt lgkmcnt(1)
	v_mfma_f32_32x32x16_bf16 a[16:31], v[112:115], v[108:111], a[16:31]
	v_mfma_f32_32x32x16_bf16 a[0:15], v[112:115], v[100:103], a[0:15]
	v_mfma_f32_32x32x16_bf16 a[112:127], v[124:127], v[120:123], a[112:127]
	v_mfma_f32_32x32x16_bf16 a[96:111], v[124:127], v[104:107], a[96:111]
	v_mfma_f32_32x32x16_bf16 a[80:95], v[116:119], v[120:123], a[80:95]
	v_mfma_f32_32x32x16_bf16 a[64:79], v[116:119], v[104:107], a[64:79]
	global_load_dwordx4 v[100:103], v[4:5], off offset:640
	global_load_dwordx4 v[108:111], v[0:1], off offset:640
	global_load_dwordx4 v[112:115], v[8:9], off offset:640
	global_load_dwordx4 v[116:119], v[6:7], off offset:640
	v_mfma_f32_32x32x16_bf16 a[48:63], v[140:143], v[120:123], a[48:63]
	v_mfma_f32_32x32x16_bf16 a[32:47], v[140:143], v[104:107], a[32:47]
	global_load_dwordx4 v[124:127], v[10:11], off offset:640
	global_load_dwordx4 v[140:143], v[12:13], off offset:640
	global_load_dwordx4 v[144:147], v[26:27], off offset:640
	global_load_dwordx4 v[148:151], v[14:15], off offset:640
	global_load_dwordx4 v[152:155], v[28:29], off offset:640
	global_load_dwordx4 v[156:159], v[2:3], off offset:640
	global_load_dwordx4 v[160:163], v[30:31], off offset:640
	s_waitcnt lgkmcnt(0)
	v_mfma_f32_32x32x16_bf16 a[16:31], v[128:131], v[120:123], a[16:31]
	global_load_dwordx4 v[120:123], v[32:33], off offset:640
	s_barrier
	v_mfma_f32_32x32x16_bf16 a[0:15], v[128:131], v[104:107], a[0:15]
	ds_read_b128 v[104:107], v59
	ds_read_b128 v[128:131], v62 offset:36864
	ds_read_b128 v[164:167], v59 offset:4608
	ds_read_b128 v[168:171], v62 offset:41472
	s_waitcnt lgkmcnt(2)
	v_mfma_f32_32x32x16_bf16 a[112:127], v[104:107], v[128:131], a[112:127]
	s_waitcnt lgkmcnt(0)
	v_mfma_f32_32x32x16_bf16 a[96:111], v[104:107], v[168:171], a[96:111]
	ds_read_b128 v[104:107], v59 offset:9216
	s_waitcnt lgkmcnt(0)
	v_mfma_f32_32x32x16_bf16 a[48:63], v[104:107], v[128:131], a[48:63]
	v_mfma_f32_32x32x16_bf16 a[32:47], v[104:107], v[168:171], a[32:47]
	ds_read_b128 v[104:107], v61
	s_waitcnt vmcnt(10)
	ds_write_b128 v60, v[108:111] offset:55296
	ds_write_b128 v60, v[100:103] offset:59904
	s_waitcnt vmcnt(8)
	ds_write_b128 v60, v[116:119] offset:64512
	ds_write_b128 v63, v[112:115] offset:55296
	s_waitcnt vmcnt(7)
	ds_write_b128 v64, v[124:127] offset:55296
	s_waitcnt vmcnt(6)
	ds_write_b128 v65, v[140:143] offset:55296
	s_waitcnt vmcnt(4)
	ds_write_b128 v66, v[148:151] offset:55296
	ds_write_b128 v67, v[144:147] offset:55296
	s_waitcnt vmcnt(2)
	ds_write_b128 v68, v[156:159]
	ds_write_b128 v68, v[152:155] offset:4608
	s_waitcnt vmcnt(1)
	ds_write_b128 v68, v[160:163] offset:9216
	s_waitcnt vmcnt(0)
	ds_write_b128 v68, v[120:123] offset:13824
	v_mfma_f32_32x32x16_bf16 a[80:95], v[164:167], v[128:131], a[80:95]
	v_mfma_f32_32x32x16_bf16 a[64:79], v[164:167], v[168:171], a[64:79]
	s_waitcnt lgkmcnt(12)
	v_mfma_f32_32x32x16_bf16 a[16:31], v[104:107], v[128:131], a[16:31]
	v_mfma_f32_32x32x16_bf16 a[0:15], v[104:107], v[168:171], a[0:15]
	ds_read_b128 v[100:103], v59 offset:32
	ds_read_b128 v[104:107], v62 offset:36896
	ds_read_b128 v[108:111], v62 offset:36928
	ds_read_b128 v[112:115], v59 offset:64
	ds_read_b128 v[116:119], v62 offset:41504
	ds_read_b128 v[120:123], v62 offset:36960
	s_waitcnt lgkmcnt(4)
	v_mfma_f32_32x32x16_bf16 a[112:127], v[100:103], v[104:107], a[112:127]
	s_waitcnt lgkmcnt(1)
	v_mfma_f32_32x32x16_bf16 a[96:111], v[100:103], v[116:119], a[96:111]
	ds_read_b128 v[100:103], v59 offset:4640
	ds_read_b128 v[124:127], v59 offset:96
	s_waitcnt lgkmcnt(1)
	v_mfma_f32_32x32x16_bf16 a[80:95], v[100:103], v[104:107], a[80:95]
	v_mfma_f32_32x32x16_bf16 a[64:79], v[100:103], v[116:119], a[64:79]
	ds_read_b128 v[100:103], v59 offset:9248
	ds_read_b128 v[128:131], v59 offset:9280
	s_waitcnt lgkmcnt(1)
	v_mfma_f32_32x32x16_bf16 a[48:63], v[100:103], v[104:107], a[48:63]
	v_mfma_f32_32x32x16_bf16 a[32:47], v[100:103], v[116:119], a[32:47]
	ds_read_b128 v[100:103], v61 offset:32
	ds_read_b128 v[140:143], v59 offset:9312
	s_waitcnt lgkmcnt(1)
	v_mfma_f32_32x32x16_bf16 a[16:31], v[100:103], v[104:107], a[16:31]
	v_mfma_f32_32x32x16_bf16 a[0:15], v[100:103], v[116:119], a[0:15]
	ds_read_b128 v[100:103], v62 offset:41536
	ds_read_b128 v[104:107], v62 offset:41568
	v_mfma_f32_32x32x16_bf16 a[112:127], v[112:115], v[108:111], a[112:127]
	s_waitcnt lgkmcnt(1)
	v_mfma_f32_32x32x16_bf16 a[96:111], v[112:115], v[100:103], a[96:111]
	ds_read_b128 v[112:115], v59 offset:4672
	ds_read_b128 v[116:119], v59 offset:4704
	s_waitcnt lgkmcnt(1)
	v_mfma_f32_32x32x16_bf16 a[80:95], v[112:115], v[108:111], a[80:95]
	v_mfma_f32_32x32x16_bf16 a[64:79], v[112:115], v[100:103], a[64:79]
	v_mfma_f32_32x32x16_bf16 a[48:63], v[128:131], v[108:111], a[48:63]
	v_mfma_f32_32x32x16_bf16 a[32:47], v[128:131], v[100:103], a[32:47]
	ds_read_b128 v[112:115], v61 offset:64
	ds_read_b128 v[128:131], v61 offset:96
	s_waitcnt lgkmcnt(1)
	v_mfma_f32_32x32x16_bf16 a[16:31], v[112:115], v[108:111], a[16:31]
	v_mfma_f32_32x32x16_bf16 a[0:15], v[112:115], v[100:103], a[0:15]
	global_load_dwordx4 v[100:103], v[32:33], off offset:768
	v_mfma_f32_32x32x16_bf16 a[112:127], v[124:127], v[120:123], a[112:127]
	v_mfma_f32_32x32x16_bf16 a[96:111], v[124:127], v[104:107], a[96:111]
	v_mfma_f32_32x32x16_bf16 a[80:95], v[116:119], v[120:123], a[80:95]
	v_mfma_f32_32x32x16_bf16 a[64:79], v[116:119], v[104:107], a[64:79]
	v_mfma_f32_32x32x16_bf16 a[48:63], v[140:143], v[120:123], a[48:63]
	v_mfma_f32_32x32x16_bf16 a[32:47], v[140:143], v[104:107], a[32:47]
	global_load_dwordx4 v[108:111], v[30:31], off offset:768
	global_load_dwordx4 v[112:115], v[28:29], off offset:768
	global_load_dwordx4 v[116:119], v[2:3], off offset:768
	global_load_dwordx4 v[124:127], v[8:9], off offset:768
	global_load_dwordx4 v[140:143], v[6:7], off offset:768
	global_load_dwordx4 v[144:147], v[4:5], off offset:768
	global_load_dwordx4 v[148:151], v[0:1], off offset:768
	s_waitcnt lgkmcnt(0)
	v_mfma_f32_32x32x16_bf16 a[16:31], v[128:131], v[120:123], a[16:31]
	global_load_dwordx4 v[120:123], v[12:13], off offset:768
	global_load_dwordx4 v[152:155], v[10:11], off offset:768
	global_load_dwordx4 v[156:159], v[26:27], off offset:768
	global_load_dwordx4 v[160:163], v[14:15], off offset:768
	s_barrier
	v_mfma_f32_32x32x16_bf16 a[0:15], v[128:131], v[104:107], a[0:15]
	ds_read_b128 v[104:107], v59 offset:55296
	ds_read_b128 v[128:131], v69
	ds_read_b128 v[164:167], v59 offset:59904
	ds_read_b128 v[168:171], v69 offset:4608
	s_waitcnt lgkmcnt(2)
	v_mfma_f32_32x32x16_bf16 a[112:127], v[104:107], v[128:131], a[112:127]
	s_waitcnt lgkmcnt(0)
	v_mfma_f32_32x32x16_bf16 a[96:111], v[104:107], v[168:171], a[96:111]
	ds_read_b128 v[104:107], v59 offset:64512
	s_waitcnt lgkmcnt(0)
	v_mfma_f32_32x32x16_bf16 a[48:63], v[104:107], v[128:131], a[48:63]
	v_mfma_f32_32x32x16_bf16 a[32:47], v[104:107], v[168:171], a[32:47]
	ds_read_b128 v[104:107], v61 offset:55296
	s_waitcnt vmcnt(4)
	ds_write_b128 v60, v[148:151]
	ds_write_b128 v60, v[144:147] offset:4608
	ds_write_b128 v60, v[140:143] offset:9216
	ds_write_b128 v60, v[124:127] offset:13824
	s_waitcnt vmcnt(2)
	ds_write_b128 v60, v[152:155] offset:18432
	ds_write_b128 v60, v[120:123] offset:23040
	s_waitcnt vmcnt(0)
	ds_write_b128 v60, v[160:163] offset:27648
	ds_write_b128 v60, v[156:159] offset:32256
	ds_write_b128 v60, v[116:119] offset:36864
	ds_write_b128 v60, v[112:115] offset:41472
	ds_write_b128 v60, v[108:111] offset:46080
	ds_write_b128 v60, v[100:103] offset:50688
	v_mfma_f32_32x32x16_bf16 a[80:95], v[164:167], v[128:131], a[80:95]
	v_mfma_f32_32x32x16_bf16 a[64:79], v[164:167], v[168:171], a[64:79]
	s_waitcnt lgkmcnt(12)
	v_mfma_f32_32x32x16_bf16 a[16:31], v[104:107], v[128:131], a[16:31]
	v_mfma_f32_32x32x16_bf16 a[0:15], v[104:107], v[168:171], a[0:15]
	ds_read_b128 v[100:103], v59 offset:55328
	ds_read_b128 v[104:107], v69 offset:32
	ds_read_b128 v[108:111], v69 offset:64
	ds_read_b128 v[112:115], v59 offset:55360
	ds_read_b128 v[116:119], v69 offset:4640
	ds_read_b128 v[120:123], v69 offset:96
	s_waitcnt lgkmcnt(4)
	v_mfma_f32_32x32x16_bf16 a[112:127], v[100:103], v[104:107], a[112:127]
	s_waitcnt lgkmcnt(1)
	v_mfma_f32_32x32x16_bf16 a[96:111], v[100:103], v[116:119], a[96:111]
	ds_read_b128 v[100:103], v59 offset:59936
	ds_read_b128 v[124:127], v59 offset:55392
	s_waitcnt lgkmcnt(1)
	v_mfma_f32_32x32x16_bf16 a[80:95], v[100:103], v[104:107], a[80:95]
	v_mfma_f32_32x32x16_bf16 a[64:79], v[100:103], v[116:119], a[64:79]
	ds_read_b128 v[100:103], v59 offset:64544
	ds_read_b128 v[128:131], v59 offset:64576
	s_waitcnt lgkmcnt(1)
	v_mfma_f32_32x32x16_bf16 a[48:63], v[100:103], v[104:107], a[48:63]
	v_mfma_f32_32x32x16_bf16 a[32:47], v[100:103], v[116:119], a[32:47]
	ds_read_b128 v[100:103], v61 offset:55328
	ds_read_b128 v[140:143], v59 offset:64608
	s_waitcnt lgkmcnt(1)
	v_mfma_f32_32x32x16_bf16 a[16:31], v[100:103], v[104:107], a[16:31]
	v_mfma_f32_32x32x16_bf16 a[0:15], v[100:103], v[116:119], a[0:15]
	ds_read_b128 v[100:103], v69 offset:4672
	ds_read_b128 v[104:107], v69 offset:4704
	v_mfma_f32_32x32x16_bf16 a[112:127], v[112:115], v[108:111], a[112:127]
	s_waitcnt lgkmcnt(1)
	v_mfma_f32_32x32x16_bf16 a[96:111], v[112:115], v[100:103], a[96:111]
	ds_read_b128 v[112:115], v59 offset:59968
	ds_read_b128 v[116:119], v59 offset:60000
	s_waitcnt lgkmcnt(1)
	v_mfma_f32_32x32x16_bf16 a[80:95], v[112:115], v[108:111], a[80:95]
	v_mfma_f32_32x32x16_bf16 a[64:79], v[112:115], v[100:103], a[64:79]
	v_mfma_f32_32x32x16_bf16 a[48:63], v[128:131], v[108:111], a[48:63]
	v_mfma_f32_32x32x16_bf16 a[32:47], v[128:131], v[100:103], a[32:47]
	ds_read_b128 v[112:115], v61 offset:55360
	ds_read_b128 v[128:131], v61 offset:55392
	s_waitcnt lgkmcnt(1)
	v_mfma_f32_32x32x16_bf16 a[16:31], v[112:115], v[108:111], a[16:31]
	v_mfma_f32_32x32x16_bf16 a[0:15], v[112:115], v[100:103], a[0:15]
	v_mfma_f32_32x32x16_bf16 a[112:127], v[124:127], v[120:123], a[112:127]
	v_mfma_f32_32x32x16_bf16 a[96:111], v[124:127], v[104:107], a[96:111]
	v_mfma_f32_32x32x16_bf16 a[80:95], v[116:119], v[120:123], a[80:95]
	v_mfma_f32_32x32x16_bf16 a[64:79], v[116:119], v[104:107], a[64:79]
	global_load_dwordx4 v[100:103], v[4:5], off offset:896
	global_load_dwordx4 v[108:111], v[0:1], off offset:896
	global_load_dwordx4 v[112:115], v[8:9], off offset:896
	global_load_dwordx4 v[116:119], v[6:7], off offset:896
	v_mfma_f32_32x32x16_bf16 a[48:63], v[140:143], v[120:123], a[48:63]
	v_mfma_f32_32x32x16_bf16 a[32:47], v[140:143], v[104:107], a[32:47]
	global_load_dwordx4 v[124:127], v[10:11], off offset:896
	global_load_dwordx4 v[140:143], v[12:13], off offset:896
	global_load_dwordx4 v[144:147], v[26:27], off offset:896
	global_load_dwordx4 v[148:151], v[14:15], off offset:896
	global_load_dwordx4 v[152:155], v[28:29], off offset:896
	global_load_dwordx4 v[156:159], v[2:3], off offset:896
	global_load_dwordx4 v[160:163], v[30:31], off offset:896
	s_waitcnt lgkmcnt(0)
	v_mfma_f32_32x32x16_bf16 a[16:31], v[128:131], v[120:123], a[16:31]
	global_load_dwordx4 v[120:123], v[32:33], off offset:896
	s_barrier
	v_mfma_f32_32x32x16_bf16 a[0:15], v[128:131], v[104:107], a[0:15]
	ds_read_b128 v[104:107], v59
	ds_read_b128 v[128:131], v62 offset:36864
	ds_read_b128 v[164:167], v59 offset:4608
	ds_read_b128 v[168:171], v62 offset:41472
	s_waitcnt lgkmcnt(2)
	v_mfma_f32_32x32x16_bf16 a[112:127], v[104:107], v[128:131], a[112:127]
	s_waitcnt lgkmcnt(0)
	v_mfma_f32_32x32x16_bf16 a[96:111], v[104:107], v[168:171], a[96:111]
	ds_read_b128 v[104:107], v59 offset:9216
	s_waitcnt lgkmcnt(0)
	v_mfma_f32_32x32x16_bf16 a[48:63], v[104:107], v[128:131], a[48:63]
	v_mfma_f32_32x32x16_bf16 a[32:47], v[104:107], v[168:171], a[32:47]
	ds_read_b128 v[104:107], v61
	s_waitcnt vmcnt(10)
	ds_write_b128 v60, v[108:111] offset:55296
	ds_write_b128 v60, v[100:103] offset:59904
	s_waitcnt vmcnt(8)
	ds_write_b128 v60, v[116:119] offset:64512
	ds_write_b128 v63, v[112:115] offset:55296
	s_waitcnt vmcnt(7)
	ds_write_b128 v64, v[124:127] offset:55296
	s_waitcnt vmcnt(6)
	ds_write_b128 v65, v[140:143] offset:55296
	s_waitcnt vmcnt(4)
	ds_write_b128 v66, v[148:151] offset:55296
	ds_write_b128 v67, v[144:147] offset:55296
	s_waitcnt vmcnt(2)
	ds_write_b128 v68, v[156:159]
	ds_write_b128 v68, v[152:155] offset:4608
	s_waitcnt vmcnt(1)
	ds_write_b128 v68, v[160:163] offset:9216
	s_waitcnt vmcnt(0)
	ds_write_b128 v68, v[120:123] offset:13824
	v_mfma_f32_32x32x16_bf16 a[80:95], v[164:167], v[128:131], a[80:95]
	v_mfma_f32_32x32x16_bf16 a[64:79], v[164:167], v[168:171], a[64:79]
	s_waitcnt lgkmcnt(12)
	v_mfma_f32_32x32x16_bf16 a[16:31], v[104:107], v[128:131], a[16:31]
	v_mfma_f32_32x32x16_bf16 a[0:15], v[104:107], v[168:171], a[0:15]
	ds_read_b128 v[100:103], v59 offset:32
	ds_read_b128 v[104:107], v62 offset:36896
	ds_read_b128 v[108:111], v62 offset:36928
	ds_read_b128 v[112:115], v59 offset:64
	ds_read_b128 v[116:119], v62 offset:41504
	ds_read_b128 v[120:123], v62 offset:36960
	s_waitcnt lgkmcnt(4)
	v_mfma_f32_32x32x16_bf16 a[112:127], v[100:103], v[104:107], a[112:127]
	s_waitcnt lgkmcnt(1)
	v_mfma_f32_32x32x16_bf16 a[96:111], v[100:103], v[116:119], a[96:111]
	ds_read_b128 v[100:103], v59 offset:4640
	ds_read_b128 v[124:127], v59 offset:96
	s_waitcnt lgkmcnt(1)
	v_mfma_f32_32x32x16_bf16 a[80:95], v[100:103], v[104:107], a[80:95]
	v_mfma_f32_32x32x16_bf16 a[64:79], v[100:103], v[116:119], a[64:79]
	ds_read_b128 v[100:103], v59 offset:9248
	ds_read_b128 v[128:131], v59 offset:9280
	s_waitcnt lgkmcnt(1)
	v_mfma_f32_32x32x16_bf16 a[48:63], v[100:103], v[104:107], a[48:63]
	v_mfma_f32_32x32x16_bf16 a[32:47], v[100:103], v[116:119], a[32:47]
	ds_read_b128 v[100:103], v61 offset:32
	ds_read_b128 v[140:143], v59 offset:9312
	s_waitcnt lgkmcnt(1)
	v_mfma_f32_32x32x16_bf16 a[16:31], v[100:103], v[104:107], a[16:31]
	v_mfma_f32_32x32x16_bf16 a[0:15], v[100:103], v[116:119], a[0:15]
	ds_read_b128 v[100:103], v62 offset:41536
	ds_read_b128 v[104:107], v62 offset:41568
	v_mfma_f32_32x32x16_bf16 a[112:127], v[112:115], v[108:111], a[112:127]
	s_waitcnt lgkmcnt(1)
	v_mfma_f32_32x32x16_bf16 a[96:111], v[112:115], v[100:103], a[96:111]
	ds_read_b128 v[112:115], v59 offset:4672
	ds_read_b128 v[116:119], v59 offset:4704
	s_waitcnt lgkmcnt(1)
	v_mfma_f32_32x32x16_bf16 a[80:95], v[112:115], v[108:111], a[80:95]
	v_mfma_f32_32x32x16_bf16 a[64:79], v[112:115], v[100:103], a[64:79]
	v_mfma_f32_32x32x16_bf16 a[48:63], v[128:131], v[108:111], a[48:63]
	v_mfma_f32_32x32x16_bf16 a[32:47], v[128:131], v[100:103], a[32:47]
	ds_read_b128 v[112:115], v61 offset:64
	ds_read_b128 v[128:131], v61 offset:96
	s_waitcnt lgkmcnt(1)
	v_mfma_f32_32x32x16_bf16 a[16:31], v[112:115], v[108:111], a[16:31]
	v_mfma_f32_32x32x16_bf16 a[0:15], v[112:115], v[100:103], a[0:15]
	global_load_dwordx4 v[100:103], v[32:33], off offset:1024
	v_mfma_f32_32x32x16_bf16 a[112:127], v[124:127], v[120:123], a[112:127]
	v_mfma_f32_32x32x16_bf16 a[96:111], v[124:127], v[104:107], a[96:111]
	v_mfma_f32_32x32x16_bf16 a[80:95], v[116:119], v[120:123], a[80:95]
	v_mfma_f32_32x32x16_bf16 a[64:79], v[116:119], v[104:107], a[64:79]
	v_mfma_f32_32x32x16_bf16 a[48:63], v[140:143], v[120:123], a[48:63]
	v_mfma_f32_32x32x16_bf16 a[32:47], v[140:143], v[104:107], a[32:47]
	global_load_dwordx4 v[108:111], v[30:31], off offset:1024
	global_load_dwordx4 v[112:115], v[28:29], off offset:1024
	global_load_dwordx4 v[116:119], v[2:3], off offset:1024
	global_load_dwordx4 v[124:127], v[8:9], off offset:1024
	global_load_dwordx4 v[140:143], v[6:7], off offset:1024
	global_load_dwordx4 v[144:147], v[4:5], off offset:1024
	global_load_dwordx4 v[148:151], v[0:1], off offset:1024
	s_waitcnt lgkmcnt(0)
	v_mfma_f32_32x32x16_bf16 a[16:31], v[128:131], v[120:123], a[16:31]
	global_load_dwordx4 v[120:123], v[12:13], off offset:1024
	global_load_dwordx4 v[152:155], v[10:11], off offset:1024
	global_load_dwordx4 v[156:159], v[26:27], off offset:1024
	global_load_dwordx4 v[160:163], v[14:15], off offset:1024
	s_barrier
	v_mfma_f32_32x32x16_bf16 a[0:15], v[128:131], v[104:107], a[0:15]
	ds_read_b128 v[104:107], v59 offset:55296
	ds_read_b128 v[128:131], v69
	ds_read_b128 v[164:167], v59 offset:59904
	ds_read_b128 v[168:171], v69 offset:4608
	s_waitcnt lgkmcnt(2)
	v_mfma_f32_32x32x16_bf16 a[112:127], v[104:107], v[128:131], a[112:127]
	s_waitcnt lgkmcnt(0)
	v_mfma_f32_32x32x16_bf16 a[96:111], v[104:107], v[168:171], a[96:111]
	ds_read_b128 v[104:107], v59 offset:64512
	s_waitcnt lgkmcnt(0)
	v_mfma_f32_32x32x16_bf16 a[48:63], v[104:107], v[128:131], a[48:63]
	v_mfma_f32_32x32x16_bf16 a[32:47], v[104:107], v[168:171], a[32:47]
	ds_read_b128 v[104:107], v61 offset:55296
	s_waitcnt vmcnt(4)
	ds_write_b128 v60, v[148:151]
	ds_write_b128 v60, v[144:147] offset:4608
	ds_write_b128 v60, v[140:143] offset:9216
	ds_write_b128 v60, v[124:127] offset:13824
	s_waitcnt vmcnt(2)
	ds_write_b128 v60, v[152:155] offset:18432
	ds_write_b128 v60, v[120:123] offset:23040
	s_waitcnt vmcnt(0)
	ds_write_b128 v60, v[160:163] offset:27648
	ds_write_b128 v60, v[156:159] offset:32256
	ds_write_b128 v60, v[116:119] offset:36864
	ds_write_b128 v60, v[112:115] offset:41472
	ds_write_b128 v60, v[108:111] offset:46080
	ds_write_b128 v60, v[100:103] offset:50688
	v_mfma_f32_32x32x16_bf16 a[80:95], v[164:167], v[128:131], a[80:95]
	v_mfma_f32_32x32x16_bf16 a[64:79], v[164:167], v[168:171], a[64:79]
	s_waitcnt lgkmcnt(12)
	v_mfma_f32_32x32x16_bf16 a[16:31], v[104:107], v[128:131], a[16:31]
	v_mfma_f32_32x32x16_bf16 a[0:15], v[104:107], v[168:171], a[0:15]
	ds_read_b128 v[100:103], v59 offset:55328
	ds_read_b128 v[104:107], v69 offset:32
	ds_read_b128 v[108:111], v69 offset:64
	ds_read_b128 v[112:115], v59 offset:55360
	ds_read_b128 v[116:119], v69 offset:4640
	ds_read_b128 v[120:123], v69 offset:96
	s_waitcnt lgkmcnt(4)
	v_mfma_f32_32x32x16_bf16 a[112:127], v[100:103], v[104:107], a[112:127]
	s_waitcnt lgkmcnt(1)
	v_mfma_f32_32x32x16_bf16 a[96:111], v[100:103], v[116:119], a[96:111]
	ds_read_b128 v[100:103], v59 offset:59936
	ds_read_b128 v[124:127], v59 offset:55392
	s_waitcnt lgkmcnt(1)
	v_mfma_f32_32x32x16_bf16 a[80:95], v[100:103], v[104:107], a[80:95]
	v_mfma_f32_32x32x16_bf16 a[64:79], v[100:103], v[116:119], a[64:79]
	ds_read_b128 v[100:103], v59 offset:64544
	ds_read_b128 v[128:131], v59 offset:64576
	s_waitcnt lgkmcnt(1)
	v_mfma_f32_32x32x16_bf16 a[48:63], v[100:103], v[104:107], a[48:63]
	v_mfma_f32_32x32x16_bf16 a[32:47], v[100:103], v[116:119], a[32:47]
	ds_read_b128 v[100:103], v61 offset:55328
	ds_read_b128 v[140:143], v59 offset:64608
	s_waitcnt lgkmcnt(1)
	v_mfma_f32_32x32x16_bf16 a[16:31], v[100:103], v[104:107], a[16:31]
	v_mfma_f32_32x32x16_bf16 a[0:15], v[100:103], v[116:119], a[0:15]
	ds_read_b128 v[100:103], v69 offset:4672
	ds_read_b128 v[104:107], v69 offset:4704
	v_mfma_f32_32x32x16_bf16 a[112:127], v[112:115], v[108:111], a[112:127]
	s_waitcnt lgkmcnt(1)
	v_mfma_f32_32x32x16_bf16 a[96:111], v[112:115], v[100:103], a[96:111]
	ds_read_b128 v[112:115], v59 offset:59968
	ds_read_b128 v[116:119], v59 offset:60000
	s_waitcnt lgkmcnt(1)
	v_mfma_f32_32x32x16_bf16 a[80:95], v[112:115], v[108:111], a[80:95]
	v_mfma_f32_32x32x16_bf16 a[64:79], v[112:115], v[100:103], a[64:79]
	v_mfma_f32_32x32x16_bf16 a[48:63], v[128:131], v[108:111], a[48:63]
	v_mfma_f32_32x32x16_bf16 a[32:47], v[128:131], v[100:103], a[32:47]
	ds_read_b128 v[112:115], v61 offset:55360
	ds_read_b128 v[128:131], v61 offset:55392
	s_waitcnt lgkmcnt(1)
	v_mfma_f32_32x32x16_bf16 a[16:31], v[112:115], v[108:111], a[16:31]
	v_mfma_f32_32x32x16_bf16 a[0:15], v[112:115], v[100:103], a[0:15]
	v_mfma_f32_32x32x16_bf16 a[112:127], v[124:127], v[120:123], a[112:127]
	v_mfma_f32_32x32x16_bf16 a[96:111], v[124:127], v[104:107], a[96:111]
	v_mfma_f32_32x32x16_bf16 a[80:95], v[116:119], v[120:123], a[80:95]
	v_mfma_f32_32x32x16_bf16 a[64:79], v[116:119], v[104:107], a[64:79]
	global_load_dwordx4 v[100:103], v[4:5], off offset:1152
	global_load_dwordx4 v[108:111], v[0:1], off offset:1152
	global_load_dwordx4 v[112:115], v[8:9], off offset:1152
	global_load_dwordx4 v[116:119], v[6:7], off offset:1152
	v_mfma_f32_32x32x16_bf16 a[48:63], v[140:143], v[120:123], a[48:63]
	v_mfma_f32_32x32x16_bf16 a[32:47], v[140:143], v[104:107], a[32:47]
	global_load_dwordx4 v[124:127], v[10:11], off offset:1152
	global_load_dwordx4 v[140:143], v[12:13], off offset:1152
	global_load_dwordx4 v[144:147], v[26:27], off offset:1152
	global_load_dwordx4 v[148:151], v[14:15], off offset:1152
	global_load_dwordx4 v[152:155], v[28:29], off offset:1152
	global_load_dwordx4 v[156:159], v[2:3], off offset:1152
	global_load_dwordx4 v[160:163], v[30:31], off offset:1152
	s_waitcnt lgkmcnt(0)
	v_mfma_f32_32x32x16_bf16 a[16:31], v[128:131], v[120:123], a[16:31]
	global_load_dwordx4 v[120:123], v[32:33], off offset:1152
	s_barrier
	v_mfma_f32_32x32x16_bf16 a[0:15], v[128:131], v[104:107], a[0:15]
	ds_read_b128 v[104:107], v59
	ds_read_b128 v[128:131], v62 offset:36864
	ds_read_b128 v[164:167], v59 offset:4608
	ds_read_b128 v[168:171], v62 offset:41472
	s_waitcnt lgkmcnt(2)
	v_mfma_f32_32x32x16_bf16 a[112:127], v[104:107], v[128:131], a[112:127]
	s_waitcnt lgkmcnt(0)
	v_mfma_f32_32x32x16_bf16 a[96:111], v[104:107], v[168:171], a[96:111]
	ds_read_b128 v[104:107], v59 offset:9216
	s_waitcnt lgkmcnt(0)
	v_mfma_f32_32x32x16_bf16 a[48:63], v[104:107], v[128:131], a[48:63]
	v_mfma_f32_32x32x16_bf16 a[32:47], v[104:107], v[168:171], a[32:47]
	ds_read_b128 v[104:107], v61
	s_waitcnt vmcnt(10)
	ds_write_b128 v60, v[108:111] offset:55296
	ds_write_b128 v60, v[100:103] offset:59904
	s_waitcnt vmcnt(8)
	ds_write_b128 v60, v[116:119] offset:64512
	ds_write_b128 v63, v[112:115] offset:55296
	s_waitcnt vmcnt(7)
	ds_write_b128 v64, v[124:127] offset:55296
	s_waitcnt vmcnt(6)
	ds_write_b128 v65, v[140:143] offset:55296
	s_waitcnt vmcnt(4)
	ds_write_b128 v66, v[148:151] offset:55296
	ds_write_b128 v67, v[144:147] offset:55296
	s_waitcnt vmcnt(2)
	ds_write_b128 v68, v[156:159]
	ds_write_b128 v68, v[152:155] offset:4608
	s_waitcnt vmcnt(1)
	ds_write_b128 v68, v[160:163] offset:9216
	s_waitcnt vmcnt(0)
	ds_write_b128 v68, v[120:123] offset:13824
	v_mfma_f32_32x32x16_bf16 a[80:95], v[164:167], v[128:131], a[80:95]
	v_mfma_f32_32x32x16_bf16 a[64:79], v[164:167], v[168:171], a[64:79]
	s_waitcnt lgkmcnt(12)
	v_mfma_f32_32x32x16_bf16 a[16:31], v[104:107], v[128:131], a[16:31]
	v_mfma_f32_32x32x16_bf16 a[0:15], v[104:107], v[168:171], a[0:15]
	ds_read_b128 v[100:103], v59 offset:32
	ds_read_b128 v[104:107], v62 offset:36896
	ds_read_b128 v[108:111], v62 offset:36928
	ds_read_b128 v[112:115], v59 offset:64
	ds_read_b128 v[116:119], v62 offset:41504
	ds_read_b128 v[120:123], v62 offset:36960
	s_waitcnt lgkmcnt(4)
	v_mfma_f32_32x32x16_bf16 a[112:127], v[100:103], v[104:107], a[112:127]
	s_waitcnt lgkmcnt(1)
	v_mfma_f32_32x32x16_bf16 a[96:111], v[100:103], v[116:119], a[96:111]
	ds_read_b128 v[100:103], v59 offset:4640
	ds_read_b128 v[124:127], v59 offset:96
	s_waitcnt lgkmcnt(1)
	v_mfma_f32_32x32x16_bf16 a[80:95], v[100:103], v[104:107], a[80:95]
	v_mfma_f32_32x32x16_bf16 a[64:79], v[100:103], v[116:119], a[64:79]
	ds_read_b128 v[100:103], v59 offset:9248
	ds_read_b128 v[128:131], v59 offset:9280
	s_waitcnt lgkmcnt(1)
	v_mfma_f32_32x32x16_bf16 a[48:63], v[100:103], v[104:107], a[48:63]
	v_mfma_f32_32x32x16_bf16 a[32:47], v[100:103], v[116:119], a[32:47]
	ds_read_b128 v[100:103], v61 offset:32
	ds_read_b128 v[140:143], v59 offset:9312
	s_waitcnt lgkmcnt(1)
	v_mfma_f32_32x32x16_bf16 a[16:31], v[100:103], v[104:107], a[16:31]
	v_mfma_f32_32x32x16_bf16 a[0:15], v[100:103], v[116:119], a[0:15]
	ds_read_b128 v[100:103], v62 offset:41536
	ds_read_b128 v[104:107], v62 offset:41568
	v_mfma_f32_32x32x16_bf16 a[112:127], v[112:115], v[108:111], a[112:127]
	s_waitcnt lgkmcnt(1)
	v_mfma_f32_32x32x16_bf16 a[96:111], v[112:115], v[100:103], a[96:111]
	ds_read_b128 v[112:115], v59 offset:4672
	ds_read_b128 v[116:119], v59 offset:4704
	s_waitcnt lgkmcnt(1)
	v_mfma_f32_32x32x16_bf16 a[80:95], v[112:115], v[108:111], a[80:95]
	v_mfma_f32_32x32x16_bf16 a[64:79], v[112:115], v[100:103], a[64:79]
	v_mfma_f32_32x32x16_bf16 a[48:63], v[128:131], v[108:111], a[48:63]
	v_mfma_f32_32x32x16_bf16 a[32:47], v[128:131], v[100:103], a[32:47]
	ds_read_b128 v[112:115], v61 offset:64
	ds_read_b128 v[128:131], v61 offset:96
	s_waitcnt lgkmcnt(1)
	v_mfma_f32_32x32x16_bf16 a[16:31], v[112:115], v[108:111], a[16:31]
	v_mfma_f32_32x32x16_bf16 a[0:15], v[112:115], v[100:103], a[0:15]
	global_load_dwordx4 v[100:103], v[32:33], off offset:1280
	v_mfma_f32_32x32x16_bf16 a[112:127], v[124:127], v[120:123], a[112:127]
	v_mfma_f32_32x32x16_bf16 a[96:111], v[124:127], v[104:107], a[96:111]
	v_mfma_f32_32x32x16_bf16 a[80:95], v[116:119], v[120:123], a[80:95]
	v_mfma_f32_32x32x16_bf16 a[64:79], v[116:119], v[104:107], a[64:79]
	v_mfma_f32_32x32x16_bf16 a[48:63], v[140:143], v[120:123], a[48:63]
	v_mfma_f32_32x32x16_bf16 a[32:47], v[140:143], v[104:107], a[32:47]
	global_load_dwordx4 v[108:111], v[30:31], off offset:1280
	global_load_dwordx4 v[112:115], v[28:29], off offset:1280
	global_load_dwordx4 v[116:119], v[2:3], off offset:1280
	global_load_dwordx4 v[124:127], v[8:9], off offset:1280
	global_load_dwordx4 v[140:143], v[6:7], off offset:1280
	global_load_dwordx4 v[144:147], v[4:5], off offset:1280
	global_load_dwordx4 v[148:151], v[0:1], off offset:1280
	s_waitcnt lgkmcnt(0)
	v_mfma_f32_32x32x16_bf16 a[16:31], v[128:131], v[120:123], a[16:31]
	global_load_dwordx4 v[120:123], v[12:13], off offset:1280
	global_load_dwordx4 v[152:155], v[10:11], off offset:1280
	global_load_dwordx4 v[156:159], v[26:27], off offset:1280
	global_load_dwordx4 v[160:163], v[14:15], off offset:1280
	s_barrier
	v_mfma_f32_32x32x16_bf16 a[0:15], v[128:131], v[104:107], a[0:15]
	ds_read_b128 v[104:107], v59 offset:55296
	ds_read_b128 v[128:131], v69
	ds_read_b128 v[164:167], v59 offset:59904
	ds_read_b128 v[168:171], v69 offset:4608
	s_waitcnt lgkmcnt(2)
	v_mfma_f32_32x32x16_bf16 a[112:127], v[104:107], v[128:131], a[112:127]
	s_waitcnt lgkmcnt(0)
	v_mfma_f32_32x32x16_bf16 a[96:111], v[104:107], v[168:171], a[96:111]
	ds_read_b128 v[104:107], v59 offset:64512
	s_waitcnt lgkmcnt(0)
	v_mfma_f32_32x32x16_bf16 a[48:63], v[104:107], v[128:131], a[48:63]
	v_mfma_f32_32x32x16_bf16 a[32:47], v[104:107], v[168:171], a[32:47]
	ds_read_b128 v[104:107], v61 offset:55296
	s_waitcnt vmcnt(4)
	ds_write_b128 v60, v[148:151]
	ds_write_b128 v60, v[144:147] offset:4608
	ds_write_b128 v60, v[140:143] offset:9216
	ds_write_b128 v60, v[124:127] offset:13824
	s_waitcnt vmcnt(2)
	ds_write_b128 v60, v[152:155] offset:18432
	ds_write_b128 v60, v[120:123] offset:23040
	s_waitcnt vmcnt(0)
	ds_write_b128 v60, v[160:163] offset:27648
	ds_write_b128 v60, v[156:159] offset:32256
	ds_write_b128 v60, v[116:119] offset:36864
	ds_write_b128 v60, v[112:115] offset:41472
	ds_write_b128 v60, v[108:111] offset:46080
	ds_write_b128 v60, v[100:103] offset:50688
	v_mfma_f32_32x32x16_bf16 a[80:95], v[164:167], v[128:131], a[80:95]
	v_mfma_f32_32x32x16_bf16 a[64:79], v[164:167], v[168:171], a[64:79]
	s_waitcnt lgkmcnt(12)
	v_mfma_f32_32x32x16_bf16 a[16:31], v[104:107], v[128:131], a[16:31]
	v_mfma_f32_32x32x16_bf16 a[0:15], v[104:107], v[168:171], a[0:15]
	ds_read_b128 v[100:103], v59 offset:55328
	ds_read_b128 v[104:107], v69 offset:32
	ds_read_b128 v[108:111], v69 offset:64
	ds_read_b128 v[112:115], v59 offset:55360
	ds_read_b128 v[116:119], v69 offset:4640
	ds_read_b128 v[120:123], v69 offset:96
	s_waitcnt lgkmcnt(4)
	v_mfma_f32_32x32x16_bf16 a[112:127], v[100:103], v[104:107], a[112:127]
	s_waitcnt lgkmcnt(1)
	v_mfma_f32_32x32x16_bf16 a[96:111], v[100:103], v[116:119], a[96:111]
	ds_read_b128 v[100:103], v59 offset:59936
	ds_read_b128 v[124:127], v59 offset:55392
	s_waitcnt lgkmcnt(1)
	v_mfma_f32_32x32x16_bf16 a[80:95], v[100:103], v[104:107], a[80:95]
	v_mfma_f32_32x32x16_bf16 a[64:79], v[100:103], v[116:119], a[64:79]
	ds_read_b128 v[100:103], v59 offset:64544
	ds_read_b128 v[128:131], v59 offset:64576
	s_waitcnt lgkmcnt(1)
	v_mfma_f32_32x32x16_bf16 a[48:63], v[100:103], v[104:107], a[48:63]
	v_mfma_f32_32x32x16_bf16 a[32:47], v[100:103], v[116:119], a[32:47]
	ds_read_b128 v[100:103], v61 offset:55328
	ds_read_b128 v[140:143], v59 offset:64608
	s_waitcnt lgkmcnt(1)
	v_mfma_f32_32x32x16_bf16 a[16:31], v[100:103], v[104:107], a[16:31]
	v_mfma_f32_32x32x16_bf16 a[0:15], v[100:103], v[116:119], a[0:15]
	ds_read_b128 v[100:103], v69 offset:4672
	ds_read_b128 v[104:107], v69 offset:4704
	v_mfma_f32_32x32x16_bf16 a[112:127], v[112:115], v[108:111], a[112:127]
	s_waitcnt lgkmcnt(1)
	v_mfma_f32_32x32x16_bf16 a[96:111], v[112:115], v[100:103], a[96:111]
	ds_read_b128 v[112:115], v59 offset:59968
	ds_read_b128 v[116:119], v59 offset:60000
	s_waitcnt lgkmcnt(1)
	v_mfma_f32_32x32x16_bf16 a[80:95], v[112:115], v[108:111], a[80:95]
	v_mfma_f32_32x32x16_bf16 a[64:79], v[112:115], v[100:103], a[64:79]
	v_mfma_f32_32x32x16_bf16 a[48:63], v[128:131], v[108:111], a[48:63]
	v_mfma_f32_32x32x16_bf16 a[32:47], v[128:131], v[100:103], a[32:47]
	ds_read_b128 v[112:115], v61 offset:55360
	ds_read_b128 v[128:131], v61 offset:55392
	s_waitcnt lgkmcnt(1)
	v_mfma_f32_32x32x16_bf16 a[16:31], v[112:115], v[108:111], a[16:31]
	v_mfma_f32_32x32x16_bf16 a[0:15], v[112:115], v[100:103], a[0:15]
	v_mfma_f32_32x32x16_bf16 a[112:127], v[124:127], v[120:123], a[112:127]
	v_mfma_f32_32x32x16_bf16 a[96:111], v[124:127], v[104:107], a[96:111]
	v_mfma_f32_32x32x16_bf16 a[80:95], v[116:119], v[120:123], a[80:95]
	v_mfma_f32_32x32x16_bf16 a[64:79], v[116:119], v[104:107], a[64:79]
	global_load_dwordx4 v[100:103], v[4:5], off offset:1408
	global_load_dwordx4 v[108:111], v[0:1], off offset:1408
	global_load_dwordx4 v[112:115], v[8:9], off offset:1408
	global_load_dwordx4 v[116:119], v[6:7], off offset:1408
	v_mfma_f32_32x32x16_bf16 a[48:63], v[140:143], v[120:123], a[48:63]
	v_mfma_f32_32x32x16_bf16 a[32:47], v[140:143], v[104:107], a[32:47]
	global_load_dwordx4 v[124:127], v[10:11], off offset:1408
	global_load_dwordx4 v[140:143], v[12:13], off offset:1408
	global_load_dwordx4 v[144:147], v[26:27], off offset:1408
	global_load_dwordx4 v[148:151], v[14:15], off offset:1408
	global_load_dwordx4 v[152:155], v[28:29], off offset:1408
	global_load_dwordx4 v[156:159], v[2:3], off offset:1408
	global_load_dwordx4 v[160:163], v[30:31], off offset:1408
	s_waitcnt lgkmcnt(0)
	v_mfma_f32_32x32x16_bf16 a[16:31], v[128:131], v[120:123], a[16:31]
	global_load_dwordx4 v[120:123], v[32:33], off offset:1408
	s_barrier
	v_mfma_f32_32x32x16_bf16 a[0:15], v[128:131], v[104:107], a[0:15]
	ds_read_b128 v[104:107], v59
	ds_read_b128 v[128:131], v62 offset:36864
	ds_read_b128 v[164:167], v59 offset:4608
	ds_read_b128 v[168:171], v62 offset:41472
	s_waitcnt lgkmcnt(2)
	v_mfma_f32_32x32x16_bf16 a[112:127], v[104:107], v[128:131], a[112:127]
	s_waitcnt lgkmcnt(0)
	v_mfma_f32_32x32x16_bf16 a[96:111], v[104:107], v[168:171], a[96:111]
	ds_read_b128 v[104:107], v59 offset:9216
	s_waitcnt lgkmcnt(0)
	v_mfma_f32_32x32x16_bf16 a[48:63], v[104:107], v[128:131], a[48:63]
	v_mfma_f32_32x32x16_bf16 a[32:47], v[104:107], v[168:171], a[32:47]
	ds_read_b128 v[104:107], v61
	s_waitcnt vmcnt(10)
	ds_write_b128 v60, v[108:111] offset:55296
	ds_write_b128 v60, v[100:103] offset:59904
	s_waitcnt vmcnt(8)
	ds_write_b128 v60, v[116:119] offset:64512
	ds_write_b128 v63, v[112:115] offset:55296
	s_waitcnt vmcnt(7)
	ds_write_b128 v64, v[124:127] offset:55296
	s_waitcnt vmcnt(6)
	ds_write_b128 v65, v[140:143] offset:55296
	s_waitcnt vmcnt(4)
	ds_write_b128 v66, v[148:151] offset:55296
	ds_write_b128 v67, v[144:147] offset:55296
	s_waitcnt vmcnt(2)
	ds_write_b128 v68, v[156:159]
	ds_write_b128 v68, v[152:155] offset:4608
	s_waitcnt vmcnt(1)
	ds_write_b128 v68, v[160:163] offset:9216
	s_waitcnt vmcnt(0)
	ds_write_b128 v68, v[120:123] offset:13824
	v_mfma_f32_32x32x16_bf16 a[80:95], v[164:167], v[128:131], a[80:95]
	v_mfma_f32_32x32x16_bf16 a[64:79], v[164:167], v[168:171], a[64:79]
	s_waitcnt lgkmcnt(12)
	v_mfma_f32_32x32x16_bf16 a[16:31], v[104:107], v[128:131], a[16:31]
	v_mfma_f32_32x32x16_bf16 a[0:15], v[104:107], v[168:171], a[0:15]
	ds_read_b128 v[100:103], v59 offset:32
	ds_read_b128 v[104:107], v62 offset:36896
	ds_read_b128 v[108:111], v62 offset:36928
	ds_read_b128 v[112:115], v59 offset:64
	ds_read_b128 v[116:119], v62 offset:41504
	ds_read_b128 v[120:123], v62 offset:36960
	s_waitcnt lgkmcnt(4)
	v_mfma_f32_32x32x16_bf16 a[112:127], v[100:103], v[104:107], a[112:127]
	s_waitcnt lgkmcnt(1)
	v_mfma_f32_32x32x16_bf16 a[96:111], v[100:103], v[116:119], a[96:111]
	ds_read_b128 v[100:103], v59 offset:4640
	ds_read_b128 v[124:127], v59 offset:96
	s_waitcnt lgkmcnt(1)
	v_mfma_f32_32x32x16_bf16 a[80:95], v[100:103], v[104:107], a[80:95]
	v_mfma_f32_32x32x16_bf16 a[64:79], v[100:103], v[116:119], a[64:79]
	ds_read_b128 v[100:103], v59 offset:9248
	ds_read_b128 v[128:131], v59 offset:9280
	s_waitcnt lgkmcnt(1)
	v_mfma_f32_32x32x16_bf16 a[48:63], v[100:103], v[104:107], a[48:63]
	v_mfma_f32_32x32x16_bf16 a[32:47], v[100:103], v[116:119], a[32:47]
	ds_read_b128 v[100:103], v61 offset:32
	ds_read_b128 v[140:143], v59 offset:9312
	s_waitcnt lgkmcnt(1)
	v_mfma_f32_32x32x16_bf16 a[16:31], v[100:103], v[104:107], a[16:31]
	v_mfma_f32_32x32x16_bf16 a[0:15], v[100:103], v[116:119], a[0:15]
	ds_read_b128 v[100:103], v62 offset:41536
	ds_read_b128 v[104:107], v62 offset:41568
	v_mfma_f32_32x32x16_bf16 a[112:127], v[112:115], v[108:111], a[112:127]
	s_waitcnt lgkmcnt(1)
	v_mfma_f32_32x32x16_bf16 a[96:111], v[112:115], v[100:103], a[96:111]
	ds_read_b128 v[112:115], v59 offset:4672
	ds_read_b128 v[116:119], v59 offset:4704
	s_waitcnt lgkmcnt(1)
	v_mfma_f32_32x32x16_bf16 a[80:95], v[112:115], v[108:111], a[80:95]
	v_mfma_f32_32x32x16_bf16 a[64:79], v[112:115], v[100:103], a[64:79]
	v_mfma_f32_32x32x16_bf16 a[48:63], v[128:131], v[108:111], a[48:63]
	v_mfma_f32_32x32x16_bf16 a[32:47], v[128:131], v[100:103], a[32:47]
	ds_read_b128 v[112:115], v61 offset:64
	ds_read_b128 v[128:131], v61 offset:96
	s_waitcnt lgkmcnt(1)
	v_mfma_f32_32x32x16_bf16 a[16:31], v[112:115], v[108:111], a[16:31]
	v_mfma_f32_32x32x16_bf16 a[0:15], v[112:115], v[100:103], a[0:15]
	global_load_dwordx4 v[100:103], v[32:33], off offset:1536
	v_mfma_f32_32x32x16_bf16 a[112:127], v[124:127], v[120:123], a[112:127]
	v_mfma_f32_32x32x16_bf16 a[96:111], v[124:127], v[104:107], a[96:111]
	v_mfma_f32_32x32x16_bf16 a[80:95], v[116:119], v[120:123], a[80:95]
	v_mfma_f32_32x32x16_bf16 a[64:79], v[116:119], v[104:107], a[64:79]
	v_mfma_f32_32x32x16_bf16 a[48:63], v[140:143], v[120:123], a[48:63]
	v_mfma_f32_32x32x16_bf16 a[32:47], v[140:143], v[104:107], a[32:47]
	global_load_dwordx4 v[108:111], v[30:31], off offset:1536
	global_load_dwordx4 v[112:115], v[28:29], off offset:1536
	global_load_dwordx4 v[116:119], v[2:3], off offset:1536
	global_load_dwordx4 v[124:127], v[8:9], off offset:1536
	global_load_dwordx4 v[140:143], v[6:7], off offset:1536
	global_load_dwordx4 v[144:147], v[4:5], off offset:1536
	global_load_dwordx4 v[148:151], v[0:1], off offset:1536
	s_waitcnt lgkmcnt(0)
	v_mfma_f32_32x32x16_bf16 a[16:31], v[128:131], v[120:123], a[16:31]
	global_load_dwordx4 v[120:123], v[12:13], off offset:1536
	global_load_dwordx4 v[152:155], v[10:11], off offset:1536
	global_load_dwordx4 v[156:159], v[26:27], off offset:1536
	global_load_dwordx4 v[160:163], v[14:15], off offset:1536
	s_barrier
	v_mfma_f32_32x32x16_bf16 a[0:15], v[128:131], v[104:107], a[0:15]
	ds_read_b128 v[104:107], v59 offset:55296
	ds_read_b128 v[128:131], v69
	ds_read_b128 v[164:167], v59 offset:59904
	ds_read_b128 v[168:171], v69 offset:4608
	s_waitcnt lgkmcnt(2)
	v_mfma_f32_32x32x16_bf16 a[112:127], v[104:107], v[128:131], a[112:127]
	s_waitcnt lgkmcnt(0)
	v_mfma_f32_32x32x16_bf16 a[96:111], v[104:107], v[168:171], a[96:111]
	ds_read_b128 v[104:107], v59 offset:64512
	s_waitcnt lgkmcnt(0)
	v_mfma_f32_32x32x16_bf16 a[48:63], v[104:107], v[128:131], a[48:63]
	v_mfma_f32_32x32x16_bf16 a[32:47], v[104:107], v[168:171], a[32:47]
	ds_read_b128 v[104:107], v61 offset:55296
	s_waitcnt vmcnt(4)
	ds_write_b128 v60, v[148:151]
	ds_write_b128 v60, v[144:147] offset:4608
	ds_write_b128 v60, v[140:143] offset:9216
	ds_write_b128 v60, v[124:127] offset:13824
	s_waitcnt vmcnt(2)
	ds_write_b128 v60, v[152:155] offset:18432
	ds_write_b128 v60, v[120:123] offset:23040
	s_waitcnt vmcnt(0)
	ds_write_b128 v60, v[160:163] offset:27648
	ds_write_b128 v60, v[156:159] offset:32256
	ds_write_b128 v60, v[116:119] offset:36864
	ds_write_b128 v60, v[112:115] offset:41472
	ds_write_b128 v60, v[108:111] offset:46080
	ds_write_b128 v60, v[100:103] offset:50688
	v_mfma_f32_32x32x16_bf16 a[80:95], v[164:167], v[128:131], a[80:95]
	v_mfma_f32_32x32x16_bf16 a[64:79], v[164:167], v[168:171], a[64:79]
	s_waitcnt lgkmcnt(12)
	v_mfma_f32_32x32x16_bf16 a[16:31], v[104:107], v[128:131], a[16:31]
	v_mfma_f32_32x32x16_bf16 a[0:15], v[104:107], v[168:171], a[0:15]
	ds_read_b128 v[100:103], v59 offset:55328
	ds_read_b128 v[104:107], v69 offset:32
	ds_read_b128 v[108:111], v69 offset:64
	ds_read_b128 v[112:115], v59 offset:55360
	ds_read_b128 v[116:119], v69 offset:4640
	ds_read_b128 v[120:123], v69 offset:96
	s_waitcnt lgkmcnt(4)
	v_mfma_f32_32x32x16_bf16 a[112:127], v[100:103], v[104:107], a[112:127]
	s_waitcnt lgkmcnt(1)
	v_mfma_f32_32x32x16_bf16 a[96:111], v[100:103], v[116:119], a[96:111]
	ds_read_b128 v[100:103], v59 offset:59936
	ds_read_b128 v[124:127], v59 offset:55392
	s_waitcnt lgkmcnt(1)
	v_mfma_f32_32x32x16_bf16 a[80:95], v[100:103], v[104:107], a[80:95]
	v_mfma_f32_32x32x16_bf16 a[64:79], v[100:103], v[116:119], a[64:79]
	ds_read_b128 v[100:103], v59 offset:64544
	ds_read_b128 v[128:131], v59 offset:64576
	s_waitcnt lgkmcnt(1)
	v_mfma_f32_32x32x16_bf16 a[48:63], v[100:103], v[104:107], a[48:63]
	v_mfma_f32_32x32x16_bf16 a[32:47], v[100:103], v[116:119], a[32:47]
	ds_read_b128 v[100:103], v61 offset:55328
	ds_read_b128 v[140:143], v59 offset:64608
	s_waitcnt lgkmcnt(1)
	v_mfma_f32_32x32x16_bf16 a[16:31], v[100:103], v[104:107], a[16:31]
	v_mfma_f32_32x32x16_bf16 a[0:15], v[100:103], v[116:119], a[0:15]
	ds_read_b128 v[100:103], v69 offset:4672
	ds_read_b128 v[104:107], v69 offset:4704
	v_mfma_f32_32x32x16_bf16 a[112:127], v[112:115], v[108:111], a[112:127]
	s_waitcnt lgkmcnt(1)
	v_mfma_f32_32x32x16_bf16 a[96:111], v[112:115], v[100:103], a[96:111]
	ds_read_b128 v[112:115], v59 offset:59968
	ds_read_b128 v[116:119], v59 offset:60000
	s_waitcnt lgkmcnt(1)
	v_mfma_f32_32x32x16_bf16 a[80:95], v[112:115], v[108:111], a[80:95]
	v_mfma_f32_32x32x16_bf16 a[64:79], v[112:115], v[100:103], a[64:79]
	v_mfma_f32_32x32x16_bf16 a[48:63], v[128:131], v[108:111], a[48:63]
	v_mfma_f32_32x32x16_bf16 a[32:47], v[128:131], v[100:103], a[32:47]
	ds_read_b128 v[112:115], v61 offset:55360
	ds_read_b128 v[128:131], v61 offset:55392
	s_waitcnt lgkmcnt(1)
	v_mfma_f32_32x32x16_bf16 a[16:31], v[112:115], v[108:111], a[16:31]
	v_mfma_f32_32x32x16_bf16 a[0:15], v[112:115], v[100:103], a[0:15]
	v_mfma_f32_32x32x16_bf16 a[112:127], v[124:127], v[120:123], a[112:127]
	v_mfma_f32_32x32x16_bf16 a[96:111], v[124:127], v[104:107], a[96:111]
	v_mfma_f32_32x32x16_bf16 a[80:95], v[116:119], v[120:123], a[80:95]
	v_mfma_f32_32x32x16_bf16 a[64:79], v[116:119], v[104:107], a[64:79]
	global_load_dwordx4 v[100:103], v[4:5], off offset:1664
	global_load_dwordx4 v[108:111], v[0:1], off offset:1664
	global_load_dwordx4 v[112:115], v[8:9], off offset:1664
	global_load_dwordx4 v[116:119], v[6:7], off offset:1664
	v_mfma_f32_32x32x16_bf16 a[48:63], v[140:143], v[120:123], a[48:63]
	v_mfma_f32_32x32x16_bf16 a[32:47], v[140:143], v[104:107], a[32:47]
	global_load_dwordx4 v[124:127], v[10:11], off offset:1664
	global_load_dwordx4 v[140:143], v[12:13], off offset:1664
	global_load_dwordx4 v[144:147], v[26:27], off offset:1664
	global_load_dwordx4 v[148:151], v[14:15], off offset:1664
	global_load_dwordx4 v[152:155], v[28:29], off offset:1664
	global_load_dwordx4 v[156:159], v[2:3], off offset:1664
	global_load_dwordx4 v[160:163], v[30:31], off offset:1664
	s_waitcnt lgkmcnt(0)
	v_mfma_f32_32x32x16_bf16 a[16:31], v[128:131], v[120:123], a[16:31]
	global_load_dwordx4 v[120:123], v[32:33], off offset:1664
	s_barrier
	v_mfma_f32_32x32x16_bf16 a[0:15], v[128:131], v[104:107], a[0:15]
	ds_read_b128 v[104:107], v59
	ds_read_b128 v[128:131], v62 offset:36864
	ds_read_b128 v[164:167], v59 offset:4608
	ds_read_b128 v[168:171], v62 offset:41472
	s_waitcnt lgkmcnt(2)
	v_mfma_f32_32x32x16_bf16 a[112:127], v[104:107], v[128:131], a[112:127]
	s_waitcnt lgkmcnt(0)
	v_mfma_f32_32x32x16_bf16 a[96:111], v[104:107], v[168:171], a[96:111]
	ds_read_b128 v[104:107], v59 offset:9216
	s_waitcnt lgkmcnt(0)
	v_mfma_f32_32x32x16_bf16 a[48:63], v[104:107], v[128:131], a[48:63]
	v_mfma_f32_32x32x16_bf16 a[32:47], v[104:107], v[168:171], a[32:47]
	ds_read_b128 v[104:107], v61
	s_waitcnt vmcnt(10)
	ds_write_b128 v60, v[108:111] offset:55296
	ds_write_b128 v60, v[100:103] offset:59904
	s_waitcnt vmcnt(8)
	ds_write_b128 v60, v[116:119] offset:64512
	ds_write_b128 v63, v[112:115] offset:55296
	s_waitcnt vmcnt(7)
	ds_write_b128 v64, v[124:127] offset:55296
	s_waitcnt vmcnt(6)
	ds_write_b128 v65, v[140:143] offset:55296
	s_waitcnt vmcnt(4)
	ds_write_b128 v66, v[148:151] offset:55296
	ds_write_b128 v67, v[144:147] offset:55296
	s_waitcnt vmcnt(2)
	ds_write_b128 v68, v[156:159]
	ds_write_b128 v68, v[152:155] offset:4608
	s_waitcnt vmcnt(1)
	ds_write_b128 v68, v[160:163] offset:9216
	s_waitcnt vmcnt(0)
	ds_write_b128 v68, v[120:123] offset:13824
	v_mfma_f32_32x32x16_bf16 a[80:95], v[164:167], v[128:131], a[80:95]
	v_mfma_f32_32x32x16_bf16 a[64:79], v[164:167], v[168:171], a[64:79]
	s_waitcnt lgkmcnt(12)
	v_mfma_f32_32x32x16_bf16 a[16:31], v[104:107], v[128:131], a[16:31]
	v_mfma_f32_32x32x16_bf16 a[0:15], v[104:107], v[168:171], a[0:15]
	ds_read_b128 v[100:103], v59 offset:32
	ds_read_b128 v[104:107], v62 offset:36896
	ds_read_b128 v[108:111], v62 offset:36928
	ds_read_b128 v[112:115], v59 offset:64
	ds_read_b128 v[116:119], v62 offset:41504
	ds_read_b128 v[120:123], v62 offset:36960
	s_waitcnt lgkmcnt(4)
	v_mfma_f32_32x32x16_bf16 a[112:127], v[100:103], v[104:107], a[112:127]
	s_waitcnt lgkmcnt(1)
	v_mfma_f32_32x32x16_bf16 a[96:111], v[100:103], v[116:119], a[96:111]
	ds_read_b128 v[100:103], v59 offset:4640
	ds_read_b128 v[124:127], v59 offset:96
	s_waitcnt lgkmcnt(1)
	v_mfma_f32_32x32x16_bf16 a[80:95], v[100:103], v[104:107], a[80:95]
	v_mfma_f32_32x32x16_bf16 a[64:79], v[100:103], v[116:119], a[64:79]
	ds_read_b128 v[100:103], v59 offset:9248
	ds_read_b128 v[128:131], v59 offset:9280
	s_waitcnt lgkmcnt(1)
	v_mfma_f32_32x32x16_bf16 a[48:63], v[100:103], v[104:107], a[48:63]
	v_mfma_f32_32x32x16_bf16 a[32:47], v[100:103], v[116:119], a[32:47]
	ds_read_b128 v[100:103], v61 offset:32
	ds_read_b128 v[140:143], v59 offset:9312
	s_waitcnt lgkmcnt(1)
	v_mfma_f32_32x32x16_bf16 a[16:31], v[100:103], v[104:107], a[16:31]
	v_mfma_f32_32x32x16_bf16 a[0:15], v[100:103], v[116:119], a[0:15]
	ds_read_b128 v[100:103], v62 offset:41536
	ds_read_b128 v[104:107], v62 offset:41568
	v_mfma_f32_32x32x16_bf16 a[112:127], v[112:115], v[108:111], a[112:127]
	s_waitcnt lgkmcnt(1)
	v_mfma_f32_32x32x16_bf16 a[96:111], v[112:115], v[100:103], a[96:111]
	ds_read_b128 v[112:115], v59 offset:4672
	ds_read_b128 v[116:119], v59 offset:4704
	s_waitcnt lgkmcnt(1)
	v_mfma_f32_32x32x16_bf16 a[80:95], v[112:115], v[108:111], a[80:95]
	v_mfma_f32_32x32x16_bf16 a[64:79], v[112:115], v[100:103], a[64:79]
	v_mfma_f32_32x32x16_bf16 a[48:63], v[128:131], v[108:111], a[48:63]
	v_mfma_f32_32x32x16_bf16 a[32:47], v[128:131], v[100:103], a[32:47]
	ds_read_b128 v[112:115], v61 offset:64
	ds_read_b128 v[128:131], v61 offset:96
	s_waitcnt lgkmcnt(1)
	v_mfma_f32_32x32x16_bf16 a[16:31], v[112:115], v[108:111], a[16:31]
	v_mfma_f32_32x32x16_bf16 a[0:15], v[112:115], v[100:103], a[0:15]
	global_load_dwordx4 v[100:103], v[32:33], off offset:1792
	v_mfma_f32_32x32x16_bf16 a[112:127], v[124:127], v[120:123], a[112:127]
	v_mfma_f32_32x32x16_bf16 a[96:111], v[124:127], v[104:107], a[96:111]
	v_mfma_f32_32x32x16_bf16 a[80:95], v[116:119], v[120:123], a[80:95]
	v_mfma_f32_32x32x16_bf16 a[64:79], v[116:119], v[104:107], a[64:79]
	v_mfma_f32_32x32x16_bf16 a[48:63], v[140:143], v[120:123], a[48:63]
	v_mfma_f32_32x32x16_bf16 a[32:47], v[140:143], v[104:107], a[32:47]
	global_load_dwordx4 v[108:111], v[30:31], off offset:1792
	global_load_dwordx4 v[112:115], v[28:29], off offset:1792
	global_load_dwordx4 v[116:119], v[2:3], off offset:1792
	global_load_dwordx4 v[124:127], v[8:9], off offset:1792
	global_load_dwordx4 v[140:143], v[6:7], off offset:1792
	global_load_dwordx4 v[144:147], v[4:5], off offset:1792
	global_load_dwordx4 v[148:151], v[0:1], off offset:1792
	s_waitcnt lgkmcnt(0)
	v_mfma_f32_32x32x16_bf16 a[16:31], v[128:131], v[120:123], a[16:31]
	global_load_dwordx4 v[120:123], v[12:13], off offset:1792
	global_load_dwordx4 v[152:155], v[10:11], off offset:1792
	global_load_dwordx4 v[156:159], v[26:27], off offset:1792
	global_load_dwordx4 v[160:163], v[14:15], off offset:1792
	s_barrier
	v_mfma_f32_32x32x16_bf16 a[0:15], v[128:131], v[104:107], a[0:15]
	ds_read_b128 v[104:107], v59 offset:55296
	ds_read_b128 v[128:131], v69
	ds_read_b128 v[164:167], v59 offset:59904
	ds_read_b128 v[168:171], v69 offset:4608
	s_waitcnt lgkmcnt(2)
	v_mfma_f32_32x32x16_bf16 a[112:127], v[104:107], v[128:131], a[112:127]
	s_waitcnt lgkmcnt(0)
	v_mfma_f32_32x32x16_bf16 a[96:111], v[104:107], v[168:171], a[96:111]
	ds_read_b128 v[104:107], v59 offset:64512
	s_waitcnt lgkmcnt(0)
	v_mfma_f32_32x32x16_bf16 a[48:63], v[104:107], v[128:131], a[48:63]
	v_mfma_f32_32x32x16_bf16 a[32:47], v[104:107], v[168:171], a[32:47]
	ds_read_b128 v[104:107], v61 offset:55296
	s_waitcnt vmcnt(4)
	ds_write_b128 v60, v[148:151]
	ds_write_b128 v60, v[144:147] offset:4608
	ds_write_b128 v60, v[140:143] offset:9216
	ds_write_b128 v60, v[124:127] offset:13824
	s_waitcnt vmcnt(2)
	ds_write_b128 v60, v[152:155] offset:18432
	ds_write_b128 v60, v[120:123] offset:23040
	s_waitcnt vmcnt(0)
	ds_write_b128 v60, v[160:163] offset:27648
	ds_write_b128 v60, v[156:159] offset:32256
	ds_write_b128 v60, v[116:119] offset:36864
	ds_write_b128 v60, v[112:115] offset:41472
	ds_write_b128 v60, v[108:111] offset:46080
	ds_write_b128 v60, v[100:103] offset:50688
	v_mfma_f32_32x32x16_bf16 a[80:95], v[164:167], v[128:131], a[80:95]
	v_mfma_f32_32x32x16_bf16 a[64:79], v[164:167], v[168:171], a[64:79]
	s_waitcnt lgkmcnt(12)
	v_mfma_f32_32x32x16_bf16 a[16:31], v[104:107], v[128:131], a[16:31]
	v_mfma_f32_32x32x16_bf16 a[0:15], v[104:107], v[168:171], a[0:15]
	ds_read_b128 v[100:103], v59 offset:55328
	ds_read_b128 v[104:107], v69 offset:32
	ds_read_b128 v[108:111], v69 offset:64
	ds_read_b128 v[112:115], v59 offset:55360
	ds_read_b128 v[116:119], v69 offset:4640
	ds_read_b128 v[120:123], v69 offset:96
	s_waitcnt lgkmcnt(4)
	v_mfma_f32_32x32x16_bf16 a[112:127], v[100:103], v[104:107], a[112:127]
	s_waitcnt lgkmcnt(1)
	v_mfma_f32_32x32x16_bf16 a[96:111], v[100:103], v[116:119], a[96:111]
	ds_read_b128 v[100:103], v59 offset:59936
	ds_read_b128 v[124:127], v59 offset:55392
	s_waitcnt lgkmcnt(1)
	v_mfma_f32_32x32x16_bf16 a[80:95], v[100:103], v[104:107], a[80:95]
	v_mfma_f32_32x32x16_bf16 a[64:79], v[100:103], v[116:119], a[64:79]
	ds_read_b128 v[100:103], v59 offset:64544
	ds_read_b128 v[128:131], v59 offset:64576
	s_waitcnt lgkmcnt(1)
	v_mfma_f32_32x32x16_bf16 a[48:63], v[100:103], v[104:107], a[48:63]
	v_mfma_f32_32x32x16_bf16 a[32:47], v[100:103], v[116:119], a[32:47]
	ds_read_b128 v[100:103], v61 offset:55328
	ds_read_b128 v[140:143], v59 offset:64608
	s_waitcnt lgkmcnt(1)
	v_mfma_f32_32x32x16_bf16 a[16:31], v[100:103], v[104:107], a[16:31]
	v_mfma_f32_32x32x16_bf16 a[0:15], v[100:103], v[116:119], a[0:15]
	ds_read_b128 v[100:103], v69 offset:4672
	ds_read_b128 v[104:107], v69 offset:4704
	v_mfma_f32_32x32x16_bf16 a[112:127], v[112:115], v[108:111], a[112:127]
	s_waitcnt lgkmcnt(1)
	v_mfma_f32_32x32x16_bf16 a[96:111], v[112:115], v[100:103], a[96:111]
	ds_read_b128 v[112:115], v59 offset:59968
	ds_read_b128 v[116:119], v59 offset:60000
	s_waitcnt lgkmcnt(1)
	v_mfma_f32_32x32x16_bf16 a[80:95], v[112:115], v[108:111], a[80:95]
	v_mfma_f32_32x32x16_bf16 a[64:79], v[112:115], v[100:103], a[64:79]
	v_mfma_f32_32x32x16_bf16 a[48:63], v[128:131], v[108:111], a[48:63]
	v_mfma_f32_32x32x16_bf16 a[32:47], v[128:131], v[100:103], a[32:47]
	ds_read_b128 v[112:115], v61 offset:55360
	ds_read_b128 v[128:131], v61 offset:55392
	s_waitcnt lgkmcnt(1)
	v_mfma_f32_32x32x16_bf16 a[16:31], v[112:115], v[108:111], a[16:31]
	v_mfma_f32_32x32x16_bf16 a[0:15], v[112:115], v[100:103], a[0:15]
	global_load_dwordx4 v[100:103], v[4:5], off offset:1920
	global_load_dwordx4 v[108:111], v[0:1], off offset:1920
	global_load_dwordx4 v[112:115], v[8:9], off offset:1920
	s_nop 0
	global_load_dwordx4 v[4:7], v[6:7], off offset:1920
	v_mfma_f32_32x32x16_bf16 a[112:127], v[124:127], v[120:123], a[112:127]
	v_mfma_f32_32x32x16_bf16 a[96:111], v[124:127], v[104:107], a[96:111]
	v_mfma_f32_32x32x16_bf16 a[80:95], v[116:119], v[120:123], a[80:95]
	v_mfma_f32_32x32x16_bf16 a[64:79], v[116:119], v[104:107], a[64:79]
	v_mfma_f32_32x32x16_bf16 a[48:63], v[140:143], v[120:123], a[48:63]
	v_mfma_f32_32x32x16_bf16 a[32:47], v[140:143], v[104:107], a[32:47]
	global_load_dwordx4 v[8:11], v[10:11], off offset:1920
	s_nop 0
	global_load_dwordx4 v[116:119], v[12:13], off offset:1920
	global_load_dwordx4 v[124:127], v[26:27], off offset:1920
	s_nop 0
	global_load_dwordx4 v[12:15], v[14:15], off offset:1920
	s_nop 0
	global_load_dwordx4 v[26:29], v[28:29], off offset:1920
	s_nop 0
	global_load_dwordx4 v[0:3], v[2:3], off offset:1920
	s_nop 0
	global_load_dwordx4 v[140:143], v[30:31], off offset:1920
	s_nop 0
	global_load_dwordx4 v[30:33], v[32:33], off offset:1920
	s_waitcnt lgkmcnt(0)
	s_barrier
	v_mfma_f32_32x32x16_bf16 a[16:31], v[128:131], v[120:123], a[16:31]
	v_mfma_f32_32x32x16_bf16 a[0:15], v[128:131], v[104:107], a[0:15]
	ds_read_b128 v[104:107], v59
	ds_read_b128 v[120:123], v62 offset:36864
	ds_read_b128 v[128:131], v59 offset:4608
	ds_read_b128 v[144:147], v62 offset:41472
	s_waitcnt lgkmcnt(2)
	v_mfma_f32_32x32x16_bf16 a[112:127], v[104:107], v[120:123], a[112:127]
	s_waitcnt lgkmcnt(0)
	v_mfma_f32_32x32x16_bf16 a[96:111], v[104:107], v[144:147], a[96:111]
	v_mfma_f32_32x32x16_bf16 a[80:95], v[128:131], v[120:123], a[80:95]
	v_mfma_f32_32x32x16_bf16 a[64:79], v[128:131], v[144:147], a[64:79]
	ds_read_b128 v[104:107], v59 offset:9216
	ds_read_b128 v[128:131], v61
	s_waitcnt vmcnt(10)
	ds_write_b128 v60, v[108:111] offset:55296
	ds_write_b128 v60, v[100:103] offset:59904
	s_waitcnt vmcnt(8)
	ds_write_b128 v60, v[4:7] offset:64512
	ds_write_b128 v63, v[112:115] offset:55296
	s_waitcnt vmcnt(7)
	ds_write_b128 v64, v[8:11] offset:55296
	s_waitcnt vmcnt(6)
	ds_write_b128 v65, v[116:119] offset:55296
	s_waitcnt vmcnt(4)
	ds_write_b128 v66, v[12:15] offset:55296
	ds_write_b128 v67, v[124:127] offset:55296
	s_waitcnt vmcnt(2)
	ds_write_b128 v68, v[0:3]
	ds_write_b128 v68, v[26:29] offset:4608
	s_waitcnt vmcnt(1)
	ds_write_b128 v68, v[140:143] offset:9216
	s_waitcnt vmcnt(0)
	ds_write_b128 v68, v[30:33] offset:13824
	ds_read_b128 v[0:3], v59 offset:32
	ds_read_b128 v[4:7], v62 offset:36896
	ds_read_b128 v[8:11], v62 offset:36928
	ds_read_b128 v[12:15], v59 offset:64
	ds_read_b128 v[26:29], v62 offset:41504
	ds_read_b128 v[30:33], v62 offset:36960
	s_waitcnt lgkmcnt(14)
	v_mfma_f32_32x32x16_bf16 a[48:63], v[104:107], v[120:123], a[48:63]
	v_mfma_f32_32x32x16_bf16 a[32:47], v[104:107], v[144:147], a[32:47]
	s_waitcnt lgkmcnt(4)
	v_mfma_f32_32x32x16_bf16 a[112:127], v[0:3], v[4:7], a[112:127]
	s_waitcnt lgkmcnt(1)
	v_mfma_f32_32x32x16_bf16 a[96:111], v[0:3], v[26:29], a[96:111]
	ds_read_b128 v[0:3], v59 offset:4640
	ds_read_b128 v[100:103], v59 offset:96
	v_mfma_f32_32x32x16_bf16 a[16:31], v[128:131], v[120:123], a[16:31]
	v_mfma_f32_32x32x16_bf16 a[0:15], v[128:131], v[144:147], a[0:15]
	s_waitcnt lgkmcnt(1)
	v_mfma_f32_32x32x16_bf16 a[80:95], v[0:3], v[4:7], a[80:95]
	v_mfma_f32_32x32x16_bf16 a[64:79], v[0:3], v[26:29], a[64:79]
	ds_read_b128 v[0:3], v59 offset:9248
	ds_read_b128 v[104:107], v59 offset:9280
	s_waitcnt lgkmcnt(1)
	v_mfma_f32_32x32x16_bf16 a[48:63], v[0:3], v[4:7], a[48:63]
	v_mfma_f32_32x32x16_bf16 a[32:47], v[0:3], v[26:29], a[32:47]
	ds_read_b128 v[0:3], v61 offset:32
	ds_read_b128 v[108:111], v59 offset:9312
	s_waitcnt lgkmcnt(1)
	v_mfma_f32_32x32x16_bf16 a[16:31], v[0:3], v[4:7], a[16:31]
	v_mfma_f32_32x32x16_bf16 a[0:15], v[0:3], v[26:29], a[0:15]
	ds_read_b128 v[0:3], v62 offset:41536
	ds_read_b128 v[4:7], v62 offset:41568
	v_mfma_f32_32x32x16_bf16 a[112:127], v[12:15], v[8:11], a[112:127]
	s_waitcnt lgkmcnt(1)
	v_mfma_f32_32x32x16_bf16 a[96:111], v[12:15], v[0:3], a[96:111]
	ds_read_b128 v[12:15], v59 offset:4672
	ds_read_b128 v[26:29], v59 offset:4704
	s_waitcnt lgkmcnt(1)
	v_mfma_f32_32x32x16_bf16 a[80:95], v[12:15], v[8:11], a[80:95]
	v_mfma_f32_32x32x16_bf16 a[64:79], v[12:15], v[0:3], a[64:79]
	v_mfma_f32_32x32x16_bf16 a[48:63], v[104:107], v[8:11], a[48:63]
	v_mfma_f32_32x32x16_bf16 a[32:47], v[104:107], v[0:3], a[32:47]
	ds_read_b128 v[12:15], v61 offset:64
	ds_read_b128 v[104:107], v61 offset:96
	s_waitcnt lgkmcnt(0)
	s_barrier
	v_mfma_f32_32x32x16_bf16 a[16:31], v[12:15], v[8:11], a[16:31]
	v_mfma_f32_32x32x16_bf16 a[0:15], v[12:15], v[0:3], a[0:15]
	v_mfma_f32_32x32x16_bf16 a[112:127], v[100:103], v[30:33], a[112:127]
	v_mfma_f32_32x32x16_bf16 a[96:111], v[100:103], v[4:7], a[96:111]
	v_mfma_f32_32x32x16_bf16 a[80:95], v[26:29], v[30:33], a[80:95]
	v_mfma_f32_32x32x16_bf16 a[64:79], v[26:29], v[4:7], a[64:79]
	v_mfma_f32_32x32x16_bf16 a[48:63], v[108:111], v[30:33], a[48:63]
	v_mfma_f32_32x32x16_bf16 a[32:47], v[108:111], v[4:7], a[32:47]
	v_mfma_f32_32x32x16_bf16 a[16:31], v[104:107], v[30:33], a[16:31]
	v_mfma_f32_32x32x16_bf16 a[0:15], v[104:107], v[4:7], a[0:15]
	ds_read_b128 v[0:3], v59 offset:55296
	ds_read_b128 v[4:7], v69
	ds_read_b128 v[8:11], v59 offset:55328
	ds_read_b128 v[12:15], v69 offset:32
	ds_read_b128 v[26:29], v69 offset:4608
	ds_read_b128 v[30:33], v69 offset:4640
	s_waitcnt lgkmcnt(4)
	v_mfma_f32_32x32x16_bf16 a[112:127], v[0:3], v[4:7], a[112:127]
	s_waitcnt lgkmcnt(1)
	v_mfma_f32_32x32x16_bf16 a[96:111], v[0:3], v[26:29], a[96:111]
	ds_read_b128 v[0:3], v59 offset:59904
	ds_read_b128 v[100:103], v59 offset:59936
	s_waitcnt lgkmcnt(1)
	v_mfma_f32_32x32x16_bf16 a[80:95], v[0:3], v[4:7], a[80:95]
	v_mfma_f32_32x32x16_bf16 a[64:79], v[0:3], v[26:29], a[64:79]
	ds_read_b128 v[0:3], v59 offset:64512
	ds_read_b128 v[104:107], v59 offset:64544
	s_waitcnt lgkmcnt(1)
	v_mfma_f32_32x32x16_bf16 a[48:63], v[0:3], v[4:7], a[48:63]
	v_mfma_f32_32x32x16_bf16 a[32:47], v[0:3], v[26:29], a[32:47]
	ds_read_b128 v[0:3], v61 offset:55296
	ds_read_b128 v[108:111], v61 offset:55328
	s_waitcnt lgkmcnt(1)
	v_mfma_f32_32x32x16_bf16 a[0:15], v[0:3], v[26:29], a[0:15]
	v_mfma_f32_32x32x16_bf16 a[112:127], v[8:11], v[12:15], a[112:127]
	v_mfma_f32_32x32x16_bf16 a[96:111], v[8:11], v[30:33], a[96:111]
	v_mfma_f32_32x32x16_bf16 a[16:31], v[0:3], v[4:7], a[16:31]
	v_mfma_f32_32x32x16_bf16 a[80:95], v[100:103], v[12:15], a[80:95]
	v_mfma_f32_32x32x16_bf16 a[64:79], v[100:103], v[30:33], a[64:79]
	v_mfma_f32_32x32x16_bf16 a[32:47], v[104:107], v[30:33], a[32:47]
	s_waitcnt lgkmcnt(0)
	v_mfma_f32_32x32x16_bf16 a[0:15], v[108:111], v[30:33], a[0:15]
	ds_read_b128 v[8:11], v59 offset:55360
	ds_read_b128 v[26:29], v69 offset:64
	ds_read_b128 v[30:33], v59 offset:55392
	ds_read_b128 v[4:7], v69 offset:96
	ds_read_b128 v[100:103], v69 offset:4672
	ds_read_b128 v[0:3], v69 offset:4704
	v_mfma_f32_32x32x16_bf16 a[48:63], v[104:107], v[12:15], a[48:63]
	s_waitcnt lgkmcnt(4)
	v_mfma_f32_32x32x16_bf16 a[112:127], v[8:11], v[26:29], a[112:127]
	s_waitcnt lgkmcnt(1)
	v_mfma_f32_32x32x16_bf16 a[96:111], v[8:11], v[100:103], a[96:111]
	ds_read_b128 v[8:11], v59 offset:59968
	ds_read_b128 v[104:107], v59 offset:60000
	v_mfma_f32_32x32x16_bf16 a[16:31], v[108:111], v[12:15], a[16:31]
	s_waitcnt lgkmcnt(1)
	v_mfma_f32_32x32x16_bf16 a[80:95], v[8:11], v[26:29], a[80:95]
	v_mfma_f32_32x32x16_bf16 a[64:79], v[8:11], v[100:103], a[64:79]
	ds_read_b128 v[8:11], v59 offset:64576
	ds_read_b128 v[12:15], v59 offset:64608
	s_waitcnt lgkmcnt(1)
	v_mfma_f32_32x32x16_bf16 a[48:63], v[8:11], v[26:29], a[48:63]
	v_mfma_f32_32x32x16_bf16 a[32:47], v[8:11], v[100:103], a[32:47]
	ds_read_b128 v[108:111], v61 offset:55360
	ds_read_b128 v[8:11], v61 offset:55392
	s_waitcnt lgkmcnt(0)
	s_barrier
	v_mfma_f32_32x32x16_bf16 a[16:31], v[108:111], v[26:29], a[16:31]
	v_or_b32_e32 v28, s14, v139
	v_lshl_add_u64 v[26:27], v[22:23], 0, s[4:5]
	v_or_b32_e32 v29, s14, v204
	v_mfma_f32_32x32x16_bf16 a[0:15], v[108:111], v[100:103], a[0:15]
	v_mfma_f32_32x32x16_bf16 a[112:127], v[30:33], v[4:7], a[112:127]
	v_mfma_f32_32x32x16_bf16 a[48:63], v[12:15], v[4:7], a[48:63]
	v_mfma_f32_32x32x16_bf16 a[32:47], v[12:15], v[0:3], a[32:47]
	v_lshl_add_u64 v[12:13], v[16:17], 2, v[26:27]
	v_lshlrev_b32_e32 v16, 10, v28
	v_lshl_add_u64 v[14:15], s[16:17], 0, v[24:25]
	v_add_co_u32_e32 v14, vcc, s11, v14
	s_nop 1
	v_addc_co_u32_e32 v15, vcc, 0, v15, vcc
	v_mfma_f32_32x32x16_bf16 a[96:111], v[30:33], v[0:3], a[96:111]
	v_or_b32_e32 v30, s14, v205
	v_lshl_add_u64 v[32:33], v[16:17], 2, v[26:27]
	v_lshlrev_b32_e32 v16, 10, v29
	v_mfma_f32_32x32x16_bf16 a[80:95], v[104:107], v[4:7], a[80:95]
	v_mfma_f32_32x32x16_bf16 a[64:79], v[104:107], v[0:3], a[64:79]
	v_lshl_add_u64 v[104:105], v[16:17], 2, v[26:27]
	v_lshlrev_b32_e32 v16, 10, v30
	v_lshl_add_u64 v[106:107], v[16:17], 2, v[26:27]
	v_mfma_f32_32x32x16_bf16 a[16:31], v[8:11], v[4:7], a[16:31]
	v_mfma_f32_32x32x16_bf16 a[0:15], v[8:11], v[0:3], a[0:15]
	ds_write_b32 v58, a112
	ds_write_b32 v58, a113 offset:516
	ds_write_b32 v58, a114 offset:1032
	ds_write_b32 v58, a115 offset:1548
	ds_write_b32 v58, a116 offset:4128
	ds_write_b32 v58, a117 offset:4644
	ds_write_b32 v58, a118 offset:5160
	ds_write_b32 v58, a119 offset:5676
	ds_write_b32 v58, a120 offset:8256
	ds_write_b32 v58, a121 offset:8772
	ds_write_b32 v58, a122 offset:9288
	ds_write_b32 v58, a123 offset:9804
	ds_write_b32 v58, a124 offset:12384
	ds_write_b32 v58, a125 offset:12900
	ds_write_b32 v58, a126 offset:13416
	ds_write_b32 v58, a127 offset:13932
	ds_write_b32 v58, a96 offset:128
	ds_write_b32 v58, a97 offset:644
	ds_write_b32 v58, a98 offset:1160
	ds_write_b32 v58, a99 offset:1676
	ds_write_b32 v58, a100 offset:4256
	ds_write_b32 v58, a101 offset:4772
	ds_write_b32 v58, a102 offset:5288
	ds_write_b32 v58, a103 offset:5804
	ds_write_b32 v58, a104 offset:8384
	ds_write_b32 v58, a105 offset:8900
	ds_write_b32 v58, a106 offset:9416
	ds_write_b32 v58, a107 offset:9932
	ds_write_b32 v58, a108 offset:12512
	ds_write_b32 v58, a109 offset:13028
	ds_write_b32 v58, a110 offset:13544
	ds_write_b32 v58, a111 offset:14060
	ds_write_b32 v58, a80 offset:16512
	ds_write_b32 v58, a81 offset:17028
	ds_write_b32 v58, a82 offset:17544
	ds_write_b32 v58, a83 offset:18060
	ds_write_b32 v58, a84 offset:20640
	ds_write_b32 v58, a85 offset:21156
	ds_write_b32 v58, a86 offset:21672
	ds_write_b32 v58, a87 offset:22188
	ds_write_b32 v58, a88 offset:24768
	ds_write_b32 v58, a89 offset:25284
	ds_write_b32 v58, a90 offset:25800
	ds_write_b32 v58, a91 offset:26316
	ds_write_b32 v58, a92 offset:28896
	ds_write_b32 v58, a93 offset:29412
	ds_write_b32 v58, a94 offset:29928
	ds_write_b32 v58, a95 offset:30444
	ds_write_b32 v58, a64 offset:16640
	ds_write_b32 v58, a65 offset:17156
	ds_write_b32 v58, a66 offset:17672
	ds_write_b32 v58, a67 offset:18188
	ds_write_b32 v58, a68 offset:20768
	ds_write_b32 v58, a69 offset:21284
	ds_write_b32 v58, a70 offset:21800
	ds_write_b32 v58, a71 offset:22316
	ds_write_b32 v58, a72 offset:24896
	ds_write_b32 v58, a73 offset:25412
	ds_write_b32 v58, a74 offset:25928
	ds_write_b32 v58, a75 offset:26444
	ds_write_b32 v58, a76 offset:29024
	ds_write_b32 v58, a77 offset:29540
	ds_write_b32 v58, a78 offset:30056
	ds_write_b32 v58, a79 offset:30572
	ds_write_b32 v58, a48 offset:33024
	ds_write_b32 v58, a49 offset:33540
	ds_write_b32 v58, a50 offset:34056
	ds_write_b32 v58, a51 offset:34572
	ds_write_b32 v58, a52 offset:37152
	ds_write_b32 v58, a53 offset:37668
	ds_write_b32 v58, a54 offset:38184
	ds_write_b32 v58, a55 offset:38700
	ds_write_b32 v58, a56 offset:41280
	ds_write_b32 v58, a57 offset:41796
	ds_write_b32 v58, a58 offset:42312
	ds_write_b32 v58, a59 offset:42828
	ds_write_b32 v58, a60 offset:45408
	ds_write_b32 v58, a61 offset:45924
	ds_write_b32 v58, a62 offset:46440
	ds_write_b32 v58, a63 offset:46956
	ds_write_b32 v58, a32 offset:33152
	ds_write_b32 v58, a33 offset:33668
	ds_write_b32 v58, a34 offset:34184
	ds_write_b32 v58, a35 offset:34700
	ds_write_b32 v58, a36 offset:37280
	ds_write_b32 v58, a37 offset:37796
	ds_write_b32 v58, a38 offset:38312
	ds_write_b32 v58, a39 offset:38828
	ds_write_b32 v58, a40 offset:41408
	ds_write_b32 v58, a41 offset:41924
	ds_write_b32 v58, a42 offset:42440
	ds_write_b32 v58, a43 offset:42956
	ds_write_b32 v58, a44 offset:45536
	ds_write_b32 v58, a45 offset:46052
	ds_write_b32 v58, a46 offset:46568
	ds_write_b32 v58, a47 offset:47084
	ds_write_b32 v58, a16 offset:49536
	ds_write_b32 v58, a17 offset:50052
	ds_write_b32 v58, a18 offset:50568
	ds_write_b32 v58, a19 offset:51084
	ds_write_b32 v58, a20 offset:53664
	ds_write_b32 v58, a21 offset:54180
	ds_write_b32 v58, a22 offset:54696
	ds_write_b32 v58, a23 offset:55212
	ds_write_b32 v58, a24 offset:57792
	ds_write_b32 v58, a25 offset:58308
	ds_write_b32 v58, a26 offset:58824
	ds_write_b32 v58, a27 offset:59340
	ds_write_b32 v58, a28 offset:61920
	ds_write_b32 v58, a29 offset:62436
	ds_write_b32 v58, a30 offset:62952
	ds_write_b32 v58, a31 offset:63468
	ds_write_b32 v58, a0 offset:49664
	ds_write_b32 v58, a1 offset:50180
	ds_write_b32 v58, a2 offset:50696
	ds_write_b32 v58, a3 offset:51212
	ds_write_b32 v58, a4 offset:53792
	ds_write_b32 v58, a5 offset:54308
	ds_write_b32 v58, a6 offset:54824
	ds_write_b32 v58, a7 offset:55340
	ds_write_b32 v58, a8 offset:57920
	ds_write_b32 v58, a9 offset:58436
	ds_write_b32 v58, a10 offset:58952
	ds_write_b32 v58, a11 offset:59468
	ds_write_b32 v58, a12 offset:62048
	ds_write_b32 v58, a13 offset:62564
	ds_write_b32 v58, a14 offset:63080
	ds_write_b32 v58, a15 offset:63596
	s_waitcnt lgkmcnt(0)
	s_barrier
	global_load_dwordx4 v[0:3], v[14:15], off
	v_mov_b32_e32 v140, v14
	v_mov_b32_e32 v141, v15
	v_mov_b32_e32 v142, v16
	v_mov_b32_e32 v143, v17
	v_mov_b32_e32 v144, v28
	v_mov_b32_e32 v145, v29
	v_mov_b32_e32 v146, v32
	v_mov_b32_e32 v147, v33
	v_mov_b32_e32 v148, v104
	v_mov_b32_e32 v149, v105
	v_mov_b32_e32 v150, v106
	v_mov_b32_e32 v151, v107
	v_mov_b32_e32 v152, v108
	v_mov_b32_e32 v153, v109
	v_mov_b32_e32 v154, v110
	v_mov_b32_e32 v155, v111
	global_load_dwordx4 v[250:253], v[146:147], off
	global_load_dwordx4 v[246:249], v[148:149], off
	global_load_dwordx4 v[242:245], v[150:151], off
	global_load_dwordx4 v[238:241], v[12:13], off
	v_or_b32_e32 v140, s14, v206
	v_lshlrev_b32_e32 v142, 10, v140
	v_lshl_add_u64 v[140:141], v[142:143], 2, v[26:27]
	v_or_b32_e32 v142, s14, v207
	v_lshlrev_b32_e32 v142, 10, v142
	global_load_dwordx4 v[234:237], v[140:141], off
	v_or_b32_e32 v144, s14, v208
	v_or_b32_e32 v145, s14, v209
	v_lshl_add_u64 v[146:147], v[142:143], 2, v[26:27]
	v_lshlrev_b32_e32 v142, 10, v144
	v_lshl_add_u64 v[148:149], v[142:143], 2, v[26:27]
	v_lshlrev_b32_e32 v142, 10, v145
	v_lshl_add_u64 v[150:151], v[142:143], 2, v[26:27]
	global_load_dwordx4 v[230:233], v[146:147], off
	global_load_dwordx4 v[226:229], v[148:149], off
	global_load_dwordx4 v[222:225], v[150:151], off
	v_or_b32_e32 v140, s14, v210
	v_lshlrev_b32_e32 v142, 10, v140
	v_lshl_add_u64 v[140:141], v[142:143], 2, v[26:27]
	v_or_b32_e32 v142, s14, v35
	v_lshlrev_b32_e32 v142, 10, v142
	global_load_dwordx4 v[218:221], v[140:141], off
	v_or_b32_e32 v144, s14, v36
	v_or_b32_e32 v145, s14, v37
	v_lshl_add_u64 v[146:147], v[142:143], 2, v[26:27]
	v_lshlrev_b32_e32 v142, 10, v144
	v_lshl_add_u64 v[148:149], v[142:143], 2, v[26:27]
	v_lshlrev_b32_e32 v142, 10, v145
	v_lshl_add_u64 v[150:151], v[142:143], 2, v[26:27]
	global_load_dwordx4 v[214:217], v[146:147], off
	global_load_dwordx4 v[200:203], v[148:149], off
	global_load_dwordx4 v[196:199], v[150:151], off
	v_or_b32_e32 v140, s14, v38
	v_lshlrev_b32_e32 v142, 10, v140
	v_lshl_add_u64 v[140:141], v[142:143], 2, v[26:27]
	v_or_b32_e32 v142, s14, v39
	v_lshlrev_b32_e32 v142, 10, v142
	global_load_dwordx4 v[192:195], v[140:141], off
	v_or_b32_e32 v144, s14, v40
	v_or_b32_e32 v145, s14, v41
	v_lshl_add_u64 v[146:147], v[142:143], 2, v[26:27]
	v_lshlrev_b32_e32 v142, 10, v144
	v_lshl_add_u64 v[152:153], v[142:143], 2, v[26:27]
	v_lshlrev_b32_e32 v142, 10, v145
	v_lshl_add_u64 v[154:155], v[142:143], 2, v[26:27]
	global_load_dwordx4 v[188:191], v[146:147], off
	global_load_dwordx4 v[184:187], v[152:153], off
	global_load_dwordx4 v[180:183], v[154:155], off
	s_waitcnt vmcnt(15)
	s_nop 1
	v_mov_b64_e32 v[8:9], v[250:251]
	v_mov_b64_e32 v[10:11], v[252:253]
	s_waitcnt vmcnt(14)
	s_nop 1
	v_mov_b64_e32 v[28:29], v[246:247]
	v_mov_b64_e32 v[30:31], v[248:249]
	s_waitcnt vmcnt(13)
	s_nop 1
	v_mov_b64_e32 v[100:101], v[242:243]
	v_mov_b64_e32 v[102:103], v[244:245]
	s_waitcnt vmcnt(12)
	s_nop 1
	v_mov_b64_e32 v[4:5], v[238:239]
	v_mov_b64_e32 v[6:7], v[240:241]
	ds_read2_b32 v[108:109], v70 offset1:1
	ds_read2_b32 v[110:111], v71 offset1:1
	ds_read2_b32 v[112:113], v72 offset1:1
	ds_read2_b32 v[114:115], v73 offset1:1
	ds_read2_b32 v[116:117], v74 offset1:1
	ds_read2_b32 v[118:119], v75 offset1:1
	ds_read2_b32 v[120:121], v76 offset1:1
	ds_read2_b32 v[122:123], v77 offset1:1
	v_or_b32_e32 v14, s14, v206
	v_lshlrev_b32_e32 v16, 10, v14
	v_lshl_add_u64 v[14:15], v[16:17], 2, v[26:27]
	v_or_b32_e32 v16, s14, v207
	v_lshlrev_b32_e32 v16, 10, v16
	s_waitcnt lgkmcnt(6)
	v_pk_fma_f32 v[10:11], v[2:3], v[110:111], v[10:11]
	v_pk_fma_f32 v[8:9], v[0:1], v[108:109], v[8:9]
	s_waitcnt lgkmcnt(4)
	v_pk_fma_f32 v[30:31], v[2:3], v[114:115], v[30:31]
	v_pk_fma_f32 v[28:29], v[0:1], v[112:113], v[28:29]
	s_waitcnt lgkmcnt(2)
	v_pk_fma_f32 v[102:103], v[2:3], v[118:119], v[102:103]
	v_pk_fma_f32 v[100:101], v[0:1], v[116:117], v[100:101]
	global_store_dwordx4 v[32:33], v[8:11], off
	global_store_dwordx4 v[104:105], v[28:31], off
	global_store_dwordx4 v[106:107], v[100:103], off
	s_waitcnt vmcnt(14)
	s_nop 1
	v_mov_b64_e32 v[8:9], v[234:235]
	v_mov_b64_e32 v[10:11], v[236:237]
	v_or_b32_e32 v28, s14, v208
	v_or_b32_e32 v29, s14, v209
	v_lshl_add_u64 v[32:33], v[16:17], 2, v[26:27]
	v_lshlrev_b32_e32 v16, 10, v28
	v_lshl_add_u64 v[104:105], v[16:17], 2, v[26:27]
	v_lshlrev_b32_e32 v16, 10, v29
	v_lshl_add_u64 v[106:107], v[16:17], 2, v[26:27]
	s_waitcnt lgkmcnt(0)
	v_pk_fma_f32 v[10:11], v[2:3], v[122:123], v[10:11]
	v_pk_fma_f32 v[8:9], v[0:1], v[120:121], v[8:9]
	global_store_dwordx4 v[14:15], v[8:11], off
	s_waitcnt vmcnt(14)
	s_nop 1
	v_mov_b64_e32 v[8:9], v[230:231]
	v_mov_b64_e32 v[10:11], v[232:233]
	s_nop 0
	s_waitcnt vmcnt(13)
	s_nop 1
	v_mov_b64_e32 v[28:29], v[226:227]
	v_mov_b64_e32 v[30:31], v[228:229]
	s_waitcnt vmcnt(12)
	s_nop 1
	v_mov_b64_e32 v[100:101], v[222:223]
	v_mov_b64_e32 v[102:103], v[224:225]
	ds_read2_b32 v[108:109], v78 offset1:1
	ds_read2_b32 v[110:111], v79 offset1:1
	ds_read2_b32 v[112:113], v80 offset1:1
	ds_read2_b32 v[114:115], v81 offset1:1
	ds_read2_b32 v[116:117], v82 offset1:1
	ds_read2_b32 v[118:119], v83 offset1:1
	ds_read2_b32 v[120:121], v84 offset1:1
	ds_read2_b32 v[122:123], v85 offset1:1
	v_or_b32_e32 v14, s14, v210
	v_lshlrev_b32_e32 v16, 10, v14
	v_lshl_add_u64 v[14:15], v[16:17], 2, v[26:27]
	v_or_b32_e32 v16, s14, v35
	v_lshlrev_b32_e32 v16, 10, v16
	s_waitcnt lgkmcnt(6)
	v_pk_fma_f32 v[10:11], v[2:3], v[110:111], v[10:11]
	v_pk_fma_f32 v[8:9], v[0:1], v[108:109], v[8:9]
	s_waitcnt lgkmcnt(4)
	v_pk_fma_f32 v[30:31], v[2:3], v[114:115], v[30:31]
	v_pk_fma_f32 v[28:29], v[0:1], v[112:113], v[28:29]
	s_waitcnt lgkmcnt(2)
	v_pk_fma_f32 v[102:103], v[2:3], v[118:119], v[102:103]
	v_pk_fma_f32 v[100:101], v[0:1], v[116:117], v[100:101]
	global_store_dwordx4 v[32:33], v[8:11], off
	global_store_dwordx4 v[104:105], v[28:31], off
	global_store_dwordx4 v[106:107], v[100:103], off
	s_waitcnt vmcnt(14)
	s_nop 1
	v_mov_b64_e32 v[8:9], v[218:219]
	v_mov_b64_e32 v[10:11], v[220:221]
	v_or_b32_e32 v28, s14, v36
	v_or_b32_e32 v29, s14, v37
	v_lshl_add_u64 v[32:33], v[16:17], 2, v[26:27]
	v_lshlrev_b32_e32 v16, 10, v28
	v_lshl_add_u64 v[104:105], v[16:17], 2, v[26:27]
	v_lshlrev_b32_e32 v16, 10, v29
	v_lshl_add_u64 v[106:107], v[16:17], 2, v[26:27]
	s_waitcnt lgkmcnt(0)
	v_pk_fma_f32 v[10:11], v[2:3], v[122:123], v[10:11]
	v_pk_fma_f32 v[8:9], v[0:1], v[120:121], v[8:9]
	global_store_dwordx4 v[14:15], v[8:11], off
	s_waitcnt vmcnt(14)
	s_nop 1
	v_mov_b64_e32 v[8:9], v[214:215]
	v_mov_b64_e32 v[10:11], v[216:217]
	s_nop 0
	s_waitcnt vmcnt(13)
	s_nop 1
	v_mov_b64_e32 v[28:29], v[200:201]
	v_mov_b64_e32 v[30:31], v[202:203]
	s_waitcnt vmcnt(12)
	s_nop 1
	v_mov_b64_e32 v[100:101], v[196:197]
	v_mov_b64_e32 v[102:103], v[198:199]
	ds_read2_b32 v[108:109], v86 offset1:1
	ds_read2_b32 v[110:111], v87 offset1:1
	ds_read2_b32 v[112:113], v88 offset1:1
	ds_read2_b32 v[114:115], v89 offset1:1
	ds_read2_b32 v[116:117], v90 offset1:1
	ds_read2_b32 v[118:119], v91 offset1:1
	ds_read2_b32 v[120:121], v92 offset1:1
	ds_read2_b32 v[122:123], v93 offset1:1
	v_or_b32_e32 v14, s14, v38
	v_lshlrev_b32_e32 v16, 10, v14
	v_lshl_add_u64 v[14:15], v[16:17], 2, v[26:27]
	v_or_b32_e32 v16, s14, v39
	v_lshlrev_b32_e32 v16, 10, v16
	s_waitcnt lgkmcnt(6)
	v_pk_fma_f32 v[10:11], v[2:3], v[110:111], v[10:11]
	v_pk_fma_f32 v[8:9], v[0:1], v[108:109], v[8:9]
	s_waitcnt lgkmcnt(4)
	v_pk_fma_f32 v[30:31], v[2:3], v[114:115], v[30:31]
	v_pk_fma_f32 v[28:29], v[0:1], v[112:113], v[28:29]
	s_waitcnt lgkmcnt(2)
	v_pk_fma_f32 v[102:103], v[2:3], v[118:119], v[102:103]
	v_pk_fma_f32 v[100:101], v[0:1], v[116:117], v[100:101]
	global_store_dwordx4 v[32:33], v[8:11], off
	global_store_dwordx4 v[104:105], v[28:31], off
	global_store_dwordx4 v[106:107], v[100:103], off
	s_waitcnt vmcnt(14)
	s_nop 1
	v_mov_b64_e32 v[8:9], v[192:193]
	v_mov_b64_e32 v[10:11], v[194:195]
	v_or_b32_e32 v28, s14, v40
	v_or_b32_e32 v29, s14, v41
	v_lshl_add_u64 v[32:33], v[16:17], 2, v[26:27]
	v_lshlrev_b32_e32 v16, 10, v28
	v_lshl_add_u64 v[108:109], v[16:17], 2, v[26:27]
	v_lshlrev_b32_e32 v16, 10, v29
	v_lshl_add_u64 v[110:111], v[16:17], 2, v[26:27]
	s_bitset1_b32 s14, 7
	s_add_u32 s13, s2, s13
	s_addc_u32 s15, s3, s12
	s_add_u32 s12, s13, s4
	s_addc_u32 s13, s15, 0
	s_add_i32 s6, s6, s76
	s_cmpk_lt_u32 s6, 0x60
	s_waitcnt lgkmcnt(0)
	v_pk_fma_f32 v[10:11], v[2:3], v[122:123], v[10:11]
	v_pk_fma_f32 v[8:9], v[0:1], v[120:121], v[8:9]
	global_store_dwordx4 v[14:15], v[8:11], off
	s_waitcnt vmcnt(14)
	s_nop 1
	v_mov_b64_e32 v[28:29], v[188:189]
	v_mov_b64_e32 v[30:31], v[190:191]
	s_waitcnt vmcnt(13)
	s_nop 1
	v_mov_b64_e32 v[100:101], v[184:185]
	v_mov_b64_e32 v[102:103], v[186:187]
	s_waitcnt vmcnt(12)
	s_nop 1
	v_mov_b64_e32 v[104:105], v[180:181]
	v_mov_b64_e32 v[106:107], v[182:183]
	v_or_b32_e32 v10, s14, v135
	v_lshl_add_u64 v[8:9], s[12:13], 0, v[24:25]
	v_or_b32_e32 v11, s14, v139
	v_add_co_u32_e32 v112, vcc, s11, v8
	v_lshlrev_b32_e32 v16, 10, v10
	v_or_b32_e32 v14, s14, v204
	v_addc_co_u32_e32 v113, vcc, 0, v9, vcc
	v_lshl_add_u64 v[8:9], v[16:17], 2, v[26:27]
	v_lshlrev_b32_e32 v16, 10, v11
	v_or_b32_e32 v15, s14, v205
	v_lshl_add_u64 v[114:115], v[16:17], 2, v[26:27]
	v_lshlrev_b32_e32 v16, 10, v14
	v_lshl_add_u64 v[116:117], v[16:17], 2, v[26:27]
	v_lshlrev_b32_e32 v16, 10, v15
	ds_read2_b32 v[120:121], v34 offset1:1
	ds_read2_b32 v[122:123], v34 offset0:2 offset1:3
	ds_read2_b32 v[124:125], v94 offset1:1
	ds_read2_b32 v[126:127], v95 offset1:1
	ds_read2_b32 v[128:129], v96 offset1:1
	ds_read2_b32 v[130:131], v97 offset1:1
	ds_read2_b32 v[132:133], v98 offset1:1
	ds_read2_b32 v[136:137], v99 offset1:1
	ds_read2_b32 v[10:11], v42 offset1:1
	ds_read2_b32 v[14:15], v42 offset0:2 offset1:3
	s_waitcnt lgkmcnt(8)
	v_pk_fma_f32 v[6:7], v[2:3], v[122:123], v[6:7]
	v_pk_fma_f32 v[4:5], v[0:1], v[120:121], v[4:5]
	global_store_dwordx4 v[12:13], v[4:7], off
	v_lshl_add_u64 v[118:119], v[16:17], 2, v[26:27]
	v_or_b32_e32 v12, s14, v206
	v_lshlrev_b32_e32 v16, 10, v12
	v_lshl_add_u64 v[12:13], v[16:17], 2, v[26:27]
	v_or_b32_e32 v16, s14, v207
	v_lshlrev_b32_e32 v16, 10, v16
	s_waitcnt lgkmcnt(6)
	v_pk_fma_f32 v[6:7], v[2:3], v[126:127], v[30:31]
	v_pk_fma_f32 v[4:5], v[0:1], v[124:125], v[28:29]
	s_waitcnt lgkmcnt(4)
	v_pk_fma_f32 v[30:31], v[2:3], v[130:131], v[102:103]
	v_pk_fma_f32 v[28:29], v[0:1], v[128:129], v[100:101]
	s_waitcnt lgkmcnt(2)
	v_pk_fma_f32 v[2:3], v[2:3], v[136:137], v[106:107]
	v_pk_fma_f32 v[0:1], v[0:1], v[132:133], v[104:105]
	global_store_dwordx4 v[32:33], v[4:7], off
	global_store_dwordx4 v[108:109], v[28:31], off
	global_store_dwordx4 v[110:111], v[0:3], off
	global_load_dwordx4 v[0:3], v[112:113], off
	s_nop 0
	v_mov_b32_e32 v128, v12
	v_mov_b32_e32 v129, v13
	v_mov_b32_e32 v130, v16
	v_mov_b32_e32 v131, v17
	v_mov_b32_e32 v132, v26
	v_mov_b32_e32 v133, v27
	v_mov_b32_e32 v136, v32
	v_mov_b32_e32 v137, v33
	v_mov_b32_e32 v140, v100
	v_mov_b32_e32 v141, v101
	v_mov_b32_e32 v142, v108
	v_mov_b32_e32 v143, v109
	v_mov_b32_e32 v144, v110
	v_mov_b32_e32 v145, v111
	global_load_dwordx4 v[250:253], v[114:115], off
	global_load_dwordx4 v[246:249], v[116:117], off
	global_load_dwordx4 v[242:245], v[118:119], off
	global_load_dwordx4 v[238:241], v[8:9], off
	global_load_dwordx4 v[234:237], v[128:129], off
	v_or_b32_e32 v140, s14, v208
	v_or_b32_e32 v141, s14, v209
	v_lshl_add_u64 v[136:137], v[130:131], 2, v[132:133]
	v_lshlrev_b32_e32 v130, 10, v140
	v_lshl_add_u64 v[142:143], v[130:131], 2, v[132:133]
	v_lshlrev_b32_e32 v130, 10, v141
	v_lshl_add_u64 v[144:145], v[130:131], 2, v[132:133]
	global_load_dwordx4 v[230:233], v[136:137], off
	global_load_dwordx4 v[226:229], v[142:143], off
	global_load_dwordx4 v[222:225], v[144:145], off
	v_or_b32_e32 v128, s14, v210
	v_lshlrev_b32_e32 v130, 10, v128
	v_lshl_add_u64 v[128:129], v[130:131], 2, v[132:133]
	v_or_b32_e32 v130, s14, v35
	v_lshlrev_b32_e32 v130, 10, v130
	global_load_dwordx4 v[218:221], v[128:129], off
	v_or_b32_e32 v140, s14, v36
	v_or_b32_e32 v141, s14, v37
	v_lshl_add_u64 v[136:137], v[130:131], 2, v[132:133]
	v_lshlrev_b32_e32 v130, 10, v140
	v_lshl_add_u64 v[142:143], v[130:131], 2, v[132:133]
	v_lshlrev_b32_e32 v130, 10, v141
	v_lshl_add_u64 v[144:145], v[130:131], 2, v[132:133]
	global_load_dwordx4 v[214:217], v[136:137], off
	global_load_dwordx4 v[200:203], v[142:143], off
	global_load_dwordx4 v[196:199], v[144:145], off
	v_or_b32_e32 v128, s14, v38
	v_lshlrev_b32_e32 v130, 10, v128
	v_lshl_add_u64 v[128:129], v[130:131], 2, v[132:133]
	v_add_lshl_u32 v130, s14, v39, 10
	global_load_dwordx4 v[192:195], v[128:129], off
	v_lshl_add_u64 v[136:137], v[130:131], 2, v[132:133]
	v_add_lshl_u32 v130, s14, v40, 10
	v_lshl_add_u64 v[140:141], v[130:131], 2, v[132:133]
	v_add_lshl_u32 v130, s14, v41, 10
	v_lshl_add_u64 v[132:133], v[130:131], 2, v[132:133]
	global_load_dwordx4 v[188:191], v[136:137], off
	global_load_dwordx4 v[184:187], v[140:141], off
	global_load_dwordx4 v[180:183], v[132:133], off
	s_waitcnt vmcnt(15)
	s_nop 1
	v_mov_b64_e32 v[28:29], v[250:251]
	v_mov_b64_e32 v[30:31], v[252:253]
	s_waitcnt vmcnt(14)
	s_nop 1
	v_mov_b64_e32 v[100:101], v[246:247]
	v_mov_b64_e32 v[102:103], v[248:249]
	s_waitcnt vmcnt(13)
	s_nop 1
	v_mov_b64_e32 v[104:105], v[242:243]
	v_mov_b64_e32 v[106:107], v[244:245]
	s_waitcnt vmcnt(12)
	s_nop 1
	v_mov_b64_e32 v[4:5], v[238:239]
	v_mov_b64_e32 v[6:7], v[240:241]
	ds_read2_b32 v[32:33], v43 offset1:1
	ds_read2_b32 v[108:109], v43 offset0:2 offset1:3
	ds_read2_b32 v[110:111], v44 offset1:1
	ds_read2_b32 v[112:113], v44 offset0:2 offset1:3
	ds_read2_b32 v[120:121], v45 offset1:1
	ds_read2_b32 v[122:123], v45 offset0:2 offset1:3
	ds_read2_b32 v[124:125], v46 offset1:1
	ds_read2_b32 v[126:127], v46 offset0:2 offset1:3
	s_waitcnt lgkmcnt(6)
	v_pk_fma_f32 v[30:31], v[2:3], v[108:109], v[30:31]
	v_pk_fma_f32 v[28:29], v[0:1], v[32:33], v[28:29]
	s_waitcnt lgkmcnt(4)
	v_pk_fma_f32 v[102:103], v[2:3], v[112:113], v[102:103]
	v_pk_fma_f32 v[100:101], v[0:1], v[110:111], v[100:101]
	s_waitcnt lgkmcnt(2)
	v_pk_fma_f32 v[106:107], v[2:3], v[122:123], v[106:107]
	v_pk_fma_f32 v[104:105], v[0:1], v[120:121], v[104:105]
	global_store_dwordx4 v[114:115], v[28:31], off
	global_store_dwordx4 v[116:117], v[100:103], off
	global_store_dwordx4 v[118:119], v[104:107], off
	s_waitcnt vmcnt(14)
	s_nop 1
	v_mov_b64_e32 v[28:29], v[234:235]
	v_mov_b64_e32 v[30:31], v[236:237]
	v_or_b32_e32 v100, s14, v208
	v_or_b32_e32 v101, s14, v209
	v_lshl_add_u64 v[32:33], v[16:17], 2, v[26:27]
	v_lshlrev_b32_e32 v16, 10, v100
	v_lshl_add_u64 v[108:109], v[16:17], 2, v[26:27]
	v_lshlrev_b32_e32 v16, 10, v101
	v_lshl_add_u64 v[110:111], v[16:17], 2, v[26:27]
	v_pk_fma_f32 v[6:7], v[2:3], v[14:15], v[6:7]
	v_pk_fma_f32 v[4:5], v[0:1], v[10:11], v[4:5]
	s_waitcnt lgkmcnt(0)
	v_pk_fma_f32 v[30:31], v[2:3], v[126:127], v[30:31]
	v_pk_fma_f32 v[28:29], v[0:1], v[124:125], v[28:29]
	global_store_dwordx4 v[12:13], v[28:31], off
	s_waitcnt vmcnt(14)
	s_nop 1
	v_mov_b64_e32 v[28:29], v[230:231]
	v_mov_b64_e32 v[30:31], v[232:233]
	s_nop 0
	s_waitcnt vmcnt(13)
	s_nop 1
	v_mov_b64_e32 v[100:101], v[226:227]
	v_mov_b64_e32 v[102:103], v[228:229]
	s_waitcnt vmcnt(12)
	s_nop 1
	v_mov_b64_e32 v[104:105], v[222:223]
	v_mov_b64_e32 v[106:107], v[224:225]
	ds_read2_b32 v[112:113], v47 offset1:1
	ds_read2_b32 v[114:115], v47 offset0:2 offset1:3
	ds_read2_b32 v[116:117], v48 offset1:1
	ds_read2_b32 v[118:119], v48 offset0:2 offset1:3
	ds_read2_b32 v[120:121], v49 offset1:1
	ds_read2_b32 v[122:123], v49 offset0:2 offset1:3
	ds_read2_b32 v[124:125], v50 offset1:1
	ds_read2_b32 v[126:127], v50 offset0:2 offset1:3
	v_or_b32_e32 v12, s14, v210
	v_lshlrev_b32_e32 v16, 10, v12
	v_lshl_add_u64 v[12:13], v[16:17], 2, v[26:27]
	v_or_b32_e32 v16, s14, v35
	v_lshlrev_b32_e32 v16, 10, v16
	s_waitcnt lgkmcnt(6)
	v_pk_fma_f32 v[30:31], v[2:3], v[114:115], v[30:31]
	v_pk_fma_f32 v[28:29], v[0:1], v[112:113], v[28:29]
	s_waitcnt lgkmcnt(4)
	v_pk_fma_f32 v[102:103], v[2:3], v[118:119], v[102:103]
	v_pk_fma_f32 v[100:101], v[0:1], v[116:117], v[100:101]
	s_waitcnt lgkmcnt(2)
	v_pk_fma_f32 v[106:107], v[2:3], v[122:123], v[106:107]
	v_pk_fma_f32 v[104:105], v[0:1], v[120:121], v[104:105]
	global_store_dwordx4 v[32:33], v[28:31], off
	global_store_dwordx4 v[108:109], v[100:103], off
	global_store_dwordx4 v[110:111], v[104:107], off
	s_waitcnt vmcnt(14)
	s_nop 1
	v_mov_b64_e32 v[28:29], v[218:219]
	v_mov_b64_e32 v[30:31], v[220:221]
	v_or_b32_e32 v100, s14, v36
	v_or_b32_e32 v101, s14, v37
	v_lshl_add_u64 v[32:33], v[16:17], 2, v[26:27]
	v_lshlrev_b32_e32 v16, 10, v100
	v_lshl_add_u64 v[108:109], v[16:17], 2, v[26:27]
	v_lshlrev_b32_e32 v16, 10, v101
	v_lshl_add_u64 v[110:111], v[16:17], 2, v[26:27]
	s_waitcnt lgkmcnt(0)
	v_pk_fma_f32 v[30:31], v[2:3], v[126:127], v[30:31]
	v_pk_fma_f32 v[28:29], v[0:1], v[124:125], v[28:29]
	global_store_dwordx4 v[12:13], v[28:31], off
	s_waitcnt vmcnt(14)
	s_nop 1
	v_mov_b64_e32 v[28:29], v[214:215]
	v_mov_b64_e32 v[30:31], v[216:217]
	s_nop 0
	s_waitcnt vmcnt(13)
	s_nop 1
	v_mov_b64_e32 v[100:101], v[200:201]
	v_mov_b64_e32 v[102:103], v[202:203]
	s_waitcnt vmcnt(12)
	s_nop 1
	v_mov_b64_e32 v[104:105], v[196:197]
	v_mov_b64_e32 v[106:107], v[198:199]
	ds_read2_b32 v[112:113], v51 offset1:1
	ds_read2_b32 v[114:115], v51 offset0:2 offset1:3
	ds_read2_b32 v[116:117], v52 offset1:1
	ds_read2_b32 v[118:119], v52 offset0:2 offset1:3
	ds_read2_b32 v[120:121], v53 offset1:1
	ds_read2_b32 v[122:123], v53 offset0:2 offset1:3
	ds_read2_b32 v[124:125], v54 offset1:1
	ds_read2_b32 v[126:127], v54 offset0:2 offset1:3
	v_or_b32_e32 v12, s14, v38
	v_lshlrev_b32_e32 v16, 10, v12
	v_lshl_add_u64 v[12:13], v[16:17], 2, v[26:27]
	v_add_lshl_u32 v16, s14, v39, 10
	s_waitcnt lgkmcnt(6)
	v_pk_fma_f32 v[30:31], v[2:3], v[114:115], v[30:31]
	v_pk_fma_f32 v[28:29], v[0:1], v[112:113], v[28:29]
	s_waitcnt lgkmcnt(4)
	v_pk_fma_f32 v[102:103], v[2:3], v[118:119], v[102:103]
	v_pk_fma_f32 v[100:101], v[0:1], v[116:117], v[100:101]
	s_waitcnt lgkmcnt(2)
	v_pk_fma_f32 v[106:107], v[2:3], v[122:123], v[106:107]
	v_pk_fma_f32 v[104:105], v[0:1], v[120:121], v[104:105]
	global_store_dwordx4 v[32:33], v[28:31], off
	global_store_dwordx4 v[108:109], v[100:103], off
	global_store_dwordx4 v[110:111], v[104:107], off
	s_waitcnt vmcnt(14)
	s_nop 1
	v_mov_b64_e32 v[28:29], v[192:193]
	v_mov_b64_e32 v[30:31], v[194:195]
	v_lshl_add_u64 v[32:33], v[16:17], 2, v[26:27]
	v_add_lshl_u32 v16, s14, v40, 10
	global_store_dwordx4 v[8:9], v[4:7], off
	v_lshl_add_u64 v[100:101], v[16:17], 2, v[26:27]
	v_add_lshl_u32 v16, s14, v41, 10
	v_lshl_add_u64 v[26:27], v[16:17], 2, v[26:27]
	s_waitcnt lgkmcnt(0)
	v_pk_fma_f32 v[6:7], v[2:3], v[126:127], v[30:31]
	v_pk_fma_f32 v[4:5], v[0:1], v[124:125], v[28:29]
	global_store_dwordx4 v[12:13], v[4:7], off
	s_waitcnt vmcnt(15)
	s_nop 1
	v_mov_b64_e32 v[4:5], v[188:189]
	v_mov_b64_e32 v[6:7], v[190:191]
	s_nop 0
	s_waitcnt vmcnt(14)
	s_nop 1
	v_mov_b64_e32 v[8:9], v[184:185]
	v_mov_b64_e32 v[10:11], v[186:187]
	s_waitcnt vmcnt(13)
	s_nop 1
	v_mov_b64_e32 v[12:13], v[180:181]
	v_mov_b64_e32 v[14:15], v[182:183]
	ds_read2_b32 v[28:29], v55 offset1:1
	ds_read2_b32 v[30:31], v55 offset0:2 offset1:3
	ds_read2_b32 v[102:103], v56 offset1:1
	ds_read2_b32 v[104:105], v56 offset0:2 offset1:3
	ds_read2_b32 v[106:107], v57 offset1:1
	ds_read2_b32 v[108:109], v57 offset0:2 offset1:3
	s_waitcnt lgkmcnt(4)
	v_pk_fma_f32 v[6:7], v[2:3], v[30:31], v[6:7]
	v_pk_fma_f32 v[4:5], v[0:1], v[28:29], v[4:5]
	s_waitcnt lgkmcnt(2)
	v_pk_fma_f32 v[10:11], v[2:3], v[104:105], v[10:11]
	v_pk_fma_f32 v[8:9], v[0:1], v[102:103], v[8:9]
	s_waitcnt lgkmcnt(0)
	v_pk_fma_f32 v[2:3], v[2:3], v[108:109], v[14:15]
	v_pk_fma_f32 v[0:1], v[0:1], v[106:107], v[12:13]
	global_store_dwordx4 v[32:33], v[4:7], off
	global_store_dwordx4 v[100:101], v[8:11], off
	global_store_dwordx4 v[26:27], v[0:3], off
	s_barrier
	s_cbranch_scc1 .LBB0_2329
	s_load_dwordx2 s[2:3], s[0:1], 0x130
